# combo: passC walk batched loads + LDS-transposed V^T epilogue (16B stores) + ss_in hoist + flat->global
# speedup vs baseline: 1.0052x; 1.0012x over previous
; DI void final_norm_phase(const Params& P) {
;     ...
;     for (int mrow = gw; mrow < MT; mrow += NGW) {
;         const u32x4* xr = (const u32x4*)(X + (size_t)mrow * DM) + lane; f32x4* orow = (f32x4*)(P.out + (size_t)mrow * DM); const f32x4* gr = (const f32x4*)P.g_fin;
;         const float r = rsqrtf(SS[mrow] * (1.f / DM) + EPS);
;         u32x4 v[4];
; #pragma unroll
;         for (int j = 0; j < 4; ++j) v[j] = __builtin_nontemporal_load(xr + 64 * j);
; #pragma unroll
;         for (int j = 0; j < 4; ++j) { const int c4 = (64 * j + lane) * 2; const f32x4 g0 = gr[c4], g1 = gr[c4 + 1];
;             orow[c4] = (f32x4){bflo(v[j].x) * r * g0.x, bfhi(v[j].x) * r * g0.y, bflo(v[j].y) * r * g0.z, bfhi(v[j].y) * r * g0.w};
;             orow[c4 + 1] = (f32x4){bflo(v[j].z) * r * g1.x, bfhi(v[j].z) * r * g1.y, bflo(v[j].w) * r * g1.z, bfhi(v[j].w) * r * g1.w}; }
.LBB0_41:
	global_load_dword v0, v[16:17], off
	v_add_u32_e32 v22, s88, v22
	v_lshl_add_u64 v[16:17], v[16:17], 0, s[14:15]
	s_waitcnt vmcnt(0) lgkmcnt(0)
	v_fmamk_f32 v0, v0, 0x3a000000, v229
	v_cmp_gt_f32_e32 vcc, s33, v0
	v_mul_f32_e32 v2, 0x4b800000, v0
	s_nop 0
	v_cndmask_b32_e32 v0, v0, v2, vcc
	global_load_dwordx4 v[24:27], v[18:19], off nt
	global_load_dwordx4 v[28:31], v[18:19], off offset:1024 nt
	global_load_dwordx4 v[6:9], v[18:19], off offset:2048 nt
	global_load_dwordx4 v[2:5], v[18:19], off offset:3072 nt
	global_load_dwordx4 v[32:35], v[10:11], off offset:16
	global_load_dwordx4 v[36:39], v[10:11], off
	v_rsq_f32_e32 v0, v0
	v_lshl_add_u64 v[18:19], v[18:19], 0, s[76:77]
	v_mul_f32_e32 v23, 0x45800000, v0
	v_cndmask_b32_e32 v0, v0, v23, vcc
	v_cmp_lt_i32_e32 vcc, s8, v22
	s_or_b64 s[6:7], vcc, s[6:7]
	s_waitcnt vmcnt(0) lgkmcnt(0)
	v_lshlrev_b32_e32 v40, 16, v24
	v_and_b32_e32 v41, 0xffff0000, v24
	v_lshlrev_b32_e32 v24, 16, v25
	v_and_b32_e32 v25, 0xffff0000, v25
	v_pk_mul_f32 v[24:25], v[0:1], v[24:25] op_sel_hi:[0,1]
	v_pk_mul_f32 v[38:39], v[38:39], v[24:25]
	v_lshlrev_b32_e32 v24, 16, v26
	v_and_b32_e32 v25, 0xffff0000, v26
	v_lshlrev_b32_e32 v26, 16, v27
	v_and_b32_e32 v27, 0xffff0000, v27
	v_pk_mul_f32 v[40:41], v[0:1], v[40:41] op_sel_hi:[0,1]
	v_pk_mul_f32 v[24:25], v[0:1], v[24:25] op_sel_hi:[0,1]
	v_pk_mul_f32 v[26:27], v[0:1], v[26:27] op_sel_hi:[0,1]
	v_pk_mul_f32 v[36:37], v[36:37], v[40:41]
	v_pk_mul_f32 v[24:25], v[32:33], v[24:25]
	v_pk_mul_f32 v[26:27], v[34:35], v[26:27]
	global_store_dwordx4 v[20:21], v[36:39], off offset:-4096
	global_store_dwordx4 v[20:21], v[24:27], off offset:-4080
	global_load_dwordx4 v[24:27], v[10:11], off offset:2064
	s_nop 0
	global_load_dwordx4 v[32:35], v[10:11], off offset:2048
	v_lshlrev_b32_e32 v36, 16, v28
	v_and_b32_e32 v37, 0xffff0000, v28
	v_lshlrev_b32_e32 v28, 16, v29
	v_and_b32_e32 v29, 0xffff0000, v29
	v_pk_mul_f32 v[28:29], v[0:1], v[28:29] op_sel_hi:[0,1]
	v_pk_mul_f32 v[36:37], v[0:1], v[36:37] op_sel_hi:[0,1]
	s_waitcnt vmcnt(0)
	v_pk_mul_f32 v[34:35], v[28:29], v[34:35]
	v_lshlrev_b32_e32 v28, 16, v30
	v_and_b32_e32 v29, 0xffff0000, v30
	v_pk_mul_f32 v[28:29], v[0:1], v[28:29] op_sel_hi:[0,1]
	v_pk_mul_f32 v[24:25], v[28:29], v[24:25]
	v_lshlrev_b32_e32 v28, 16, v31
	v_and_b32_e32 v29, 0xffff0000, v31
	v_pk_mul_f32 v[28:29], v[0:1], v[28:29] op_sel_hi:[0,1]
	v_pk_mul_f32 v[32:33], v[36:37], v[32:33]
	v_pk_mul_f32 v[26:27], v[28:29], v[26:27]
	global_store_dwordx4 v[20:21], v[32:35], off offset:-2048
	global_store_dwordx4 v[20:21], v[24:27], off offset:-2032
	global_load_dwordx4 v[24:27], v[12:13], off offset:16
	s_nop 0
	global_load_dwordx4 v[28:31], v[12:13], off
	v_lshlrev_b32_e32 v32, 16, v6
	v_and_b32_e32 v33, 0xffff0000, v6
	v_lshlrev_b32_e32 v6, 16, v7
	v_and_b32_e32 v7, 0xffff0000, v7
	v_pk_mul_f32 v[6:7], v[0:1], v[6:7] op_sel_hi:[0,1]
	v_pk_mul_f32 v[32:33], v[0:1], v[32:33] op_sel_hi:[0,1]
	s_waitcnt vmcnt(0)
	v_pk_mul_f32 v[30:31], v[6:7], v[30:31]
	v_lshlrev_b32_e32 v6, 16, v8
	v_and_b32_e32 v7, 0xffff0000, v8
	v_lshlrev_b32_e32 v8, 16, v9
	v_and_b32_e32 v9, 0xffff0000, v9
	v_pk_mul_f32 v[6:7], v[0:1], v[6:7] op_sel_hi:[0,1]
	v_pk_mul_f32 v[8:9], v[0:1], v[8:9] op_sel_hi:[0,1]
	v_pk_mul_f32 v[28:29], v[32:33], v[28:29]
	v_pk_mul_f32 v[6:7], v[6:7], v[24:25]
	v_pk_mul_f32 v[8:9], v[8:9], v[26:27]
	global_store_dwordx4 v[20:21], v[28:31], off
	global_store_dwordx4 v[20:21], v[6:9], off offset:16
	global_load_dwordx4 v[6:9], v[14:15], off offset:16
	s_nop 0
	global_load_dwordx4 v[24:27], v[14:15], off
	v_lshlrev_b32_e32 v28, 16, v2
	v_and_b32_e32 v29, 0xffff0000, v2
	v_lshlrev_b32_e32 v2, 16, v3
	v_and_b32_e32 v3, 0xffff0000, v3
	v_pk_mul_f32 v[2:3], v[0:1], v[2:3] op_sel_hi:[0,1]
	v_pk_mul_f32 v[28:29], v[0:1], v[28:29] op_sel_hi:[0,1]
	s_waitcnt vmcnt(0)
	v_pk_mul_f32 v[26:27], v[2:3], v[26:27]
	v_lshlrev_b32_e32 v2, 16, v4
	v_and_b32_e32 v3, 0xffff0000, v4
	v_lshlrev_b32_e32 v4, 16, v5
	v_and_b32_e32 v5, 0xffff0000, v5
	v_pk_mul_f32 v[2:3], v[0:1], v[2:3] op_sel_hi:[0,1]
	v_pk_mul_f32 v[4:5], v[0:1], v[4:5] op_sel_hi:[0,1]
	v_pk_mul_f32 v[24:25], v[28:29], v[24:25]
	v_pk_mul_f32 v[2:3], v[2:3], v[6:7]
	v_pk_mul_f32 v[4:5], v[4:5], v[8:9]
	global_store_dwordx4 v[20:21], v[24:27], off offset:2048
	global_store_dwordx4 v[20:21], v[2:5], off offset:2064
	v_lshl_add_u64 v[20:21], v[20:21], 0, s[74:75]
	s_andn2_b64 exec, exec, s[6:7]
	s_cbranch_execnz .LBB0_41

; #define SB_LOADQ(uu) do { const int qt_ = (uu) & 63, bh_ = (uu) >> 6, b_ = bh_ >> 4, h_ = bh_ & 15; const bf16_t* qp_ = Uall + ((size_t)b_ * SEQ + qt_ * 128 + 16 * w + r16) * LDU_O + h_ * 128 + 8 * g; \
;         _Pragma("unroll") for (int ks = 0; ks < 4; ++ks) qn[ks] = *(const bf16x8*)(qp_ + 32 * ks); } while (0)
; DI void sb_phase(const Params& P, LAS unsigned char* lds) {
;     ...
;     int u = bid, r = 0;
;     if (u >= 2048) return;
;     SB_LOAD(u, 0); SB_LOADQ(u);
.LBB0_44:
	s_andn2_b64 vcc, exec, s[0:1]
	s_cbranch_vccnz .LBB0_80
	s_cmp_eq_u32 s23, 6
	s_cbranch_scc0 .LBB0_79
	v_mov_b32_e32 v34, v228
	s_mov_b32 s58, s28
	s_cmpk_gt_i32 s58, 0x7ff
	s_cbranch_scc1 .LBB0_79
	s_ashr_i32 s6, s58, 10
	s_lshl_b32 s0, s58, 7
	s_and_b32 s0, s0, 0x1f80
	s_ashr_i32 s7, s6, 31
	s_bfe_u32 s1, s58, 0x40006
	s_sub_i32 s8, s0, 64
	s_lshl_b64 s[6:7], s[6:7], 27
	s_add_u32 s6, s20, s6
	s_addc_u32 s7, s21, s7
	s_lshl_b32 s10, s1, 8
	s_add_u32 s12, s6, s10
	s_addc_u32 s13, s7, 0
	s_cmpk_lt_u32 s58, 0x400
	s_mov_b32 s65, 0x100000
	v_lshlrev_b32_e32 v0, 3, v34
	s_cselect_b32 s17, s65, 0x1d600000
	v_and_b32_e32 v162, 0x78, v0
	s_add_u32 s17, s4, s17
	v_lshlrev_b32_e32 v0, 1, v162
	v_ashrrev_i32_e32 v179, 4, v34
	s_addc_u32 s35, s5, 0
	s_lshl_b32 s1, s1, 21
	s_waitcnt vmcnt(0)
	v_lshl_add_u64 v[18:19], s[12:13], 0, v[0:1]
	v_add_u32_e32 v0, s8, v179
	s_add_u32 s34, s17, s1
	v_max_i32_e32 v0, 0, v0
	s_mov_b32 s1, 0x2aaaaaab
	v_lshlrev_b64 v[20:21], 14, v[0:1]
	v_mul_hi_i32 v0, v34, s1
	v_lshrrev_b32_e32 v2, 31, v0
	v_ashrrev_i32_e32 v0, 2, v0
	v_ashrrev_i32_e32 v35, 6, v34
	v_add_u32_e32 v36, v0, v2
	s_movk_i32 s17, 0xffe8
	v_mad_u64_u32 v[70:71], s[12:13], v36, s17, v[34:35]
	v_lshlrev_b32_e32 v186, 3, v70
	v_add_u32_e32 v0, s8, v186
	v_ashrrev_i32_e32 v37, 31, v36
	s_addc_u32 s35, s35, 0
	v_max_i32_e32 v0, 0, v0
	v_lshlrev_b64 v[164:165], 14, v[36:37]
	v_lshl_add_u64 v[2:3], s[34:35], 0, v[164:165]
	v_lshlrev_b32_e32 v0, 1, v0
	v_lshl_add_u64 v[26:27], v[2:3], 0, v[0:1]
	v_add_u32_e32 v2, 0x200, v34
	v_ashrrev_i32_e32 v187, 4, v2
	v_add_u32_e32 v0, s8, v187
	v_max_i32_e32 v0, 0, v0
	v_lshlrev_b64 v[28:29], 14, v[0:1]
	v_mul_hi_i32 v0, v2, s1
	v_lshrrev_b32_e32 v3, 31, v0
	v_ashrrev_i32_e32 v0, 2, v0
	v_add_u32_e32 v72, v0, v3
	v_mad_u64_u32 v[74:75], s[12:13], v72, s17, v[2:3]
	v_lshlrev_b32_e32 v188, 3, v74
	v_add_u32_e32 v0, s8, v188
	v_ashrrev_i32_e32 v73, 31, v72
	v_max_i32_e32 v0, 0, v0
	v_lshlrev_b64 v[166:167], 14, v[72:73]
	v_lshl_add_u64 v[2:3], s[34:35], 0, v[166:167]
	v_lshlrev_b32_e32 v0, 1, v0
	v_lshl_add_u64 v[38:39], v[2:3], 0, v[0:1]
	v_add_u32_e32 v2, 0x400, v34
	v_ashrrev_i32_e32 v189, 4, v2
	v_add_u32_e32 v0, s8, v189
	v_max_i32_e32 v0, 0, v0
	v_lshlrev_b64 v[40:41], 14, v[0:1]
	v_mul_hi_i32 v0, v2, s1
	v_lshrrev_b32_e32 v3, 31, v0
	v_ashrrev_i32_e32 v0, 2, v0
	v_add_u32_e32 v76, v0, v3
	v_mad_u64_u32 v[78:79], s[12:13], v76, s17, v[2:3]
	v_lshlrev_b32_e32 v190, 3, v78
	v_add_u32_e32 v0, s8, v190
	v_ashrrev_i32_e32 v77, 31, v76
	v_max_i32_e32 v0, 0, v0
	v_lshlrev_b64 v[168:169], 14, v[76:77]
	v_lshl_add_u64 v[2:3], s[34:35], 0, v[168:169]
	v_lshlrev_b32_e32 v0, 1, v0
	v_lshl_add_u64 v[46:47], v[2:3], 0, v[0:1]
	v_add_u32_e32 v2, 0x600, v34
	v_ashrrev_i32_e32 v191, 4, v2
	v_add_u32_e32 v0, s8, v191
	v_max_i32_e32 v0, 0, v0
	v_lshlrev_b64 v[48:49], 14, v[0:1]
	v_mul_hi_i32 v0, v2, s1
	v_lshrrev_b32_e32 v3, 31, v0
	v_ashrrev_i32_e32 v0, 2, v0
	v_add_u32_e32 v80, v0, v3
	v_mad_u64_u32 v[82:83], s[12:13], v80, s17, v[2:3]
	v_lshlrev_b32_e32 v192, 3, v82
	v_add_u32_e32 v0, s8, v192
	v_ashrrev_i32_e32 v81, 31, v80
	v_max_i32_e32 v0, 0, v0
	v_lshlrev_b64 v[170:171], 14, v[80:81]
	v_lshl_add_u64 v[2:3], s[34:35], 0, v[170:171]
	v_lshlrev_b32_e32 v0, 1, v0
	v_lshl_add_u64 v[54:55], v[2:3], 0, v[0:1]
	v_add_u32_e32 v2, 0x800, v34
	v_ashrrev_i32_e32 v193, 4, v2
	v_add_u32_e32 v0, s8, v193
	v_max_i32_e32 v0, 0, v0
	v_lshlrev_b64 v[56:57], 14, v[0:1]
	v_mul_hi_i32 v0, v2, s1
	v_lshrrev_b32_e32 v3, 31, v0
	v_ashrrev_i32_e32 v0, 2, v0
	v_add_u32_e32 v84, v0, v3
	v_mad_u64_u32 v[86:87], s[12:13], v84, s17, v[2:3]
	v_lshlrev_b32_e32 v194, 3, v86
	v_add_u32_e32 v0, s8, v194
	v_ashrrev_i32_e32 v85, 31, v84
	v_max_i32_e32 v0, 0, v0
	v_lshlrev_b64 v[172:173], 14, v[84:85]
	v_lshl_add_u64 v[2:3], s[34:35], 0, v[172:173]
	v_lshlrev_b32_e32 v0, 1, v0
	v_lshl_add_u64 v[62:63], v[2:3], 0, v[0:1]
	v_add_u32_e32 v2, 0xa00, v34
	v_ashrrev_i32_e32 v195, 4, v2
	v_add_u32_e32 v0, s8, v195
	v_max_i32_e32 v0, 0, v0
	v_lshlrev_b64 v[64:65], 14, v[0:1]
	v_mul_hi_i32 v0, v2, s1
	v_lshrrev_b32_e32 v3, 31, v0
	v_ashrrev_i32_e32 v0, 2, v0
	v_add_u32_e32 v88, v0, v3
	v_mad_u64_u32 v[90:91], s[12:13], v88, s17, v[2:3]
	v_lshlrev_b32_e32 v196, 3, v90
	v_add_u32_e32 v0, s8, v196
	v_ashrrev_i32_e32 v89, 31, v88
	v_and_b32_e32 v163, 15, v34
	v_max_i32_e32 v0, 0, v0
	v_lshlrev_b64 v[174:175], 14, v[88:89]
	v_lshlrev_b32_e32 v197, 4, v35
	v_lshl_add_u64 v[2:3], s[34:35], 0, v[174:175]
; #define LAS __attribute__((address_space(3)))
; #define SB_LOADQ(uu) do { const int qt_ = (uu) & 63, bh_ = (uu) >> 6, b_ = bh_ >> 4, h_ = bh_ & 15; const bf16_t* qp_ = Uall + ((size_t)b_ * SEQ + qt_ * 128 + 16 * w + r16) * LDU_O + h_ * 128 + 8 * g; \
;         _Pragma("unroll") for (int ks = 0; ks < 4; ++ks) qn[ks] = *(const bf16x8*)(qp_ + 32 * ks); } while (0)
; DI void sb_phase(const Params& P, LAS unsigned char* lds) {
;     ...
;     int u = bid, r = 0;
;     if (u >= 2048) return;
;     SB_LOAD(u, 0); SB_LOADQ(u);
;     bf16x8 qb[4]; f32x4 o[8]; float R = 0.f;
; #pragma unroll
;     for (int ks = 0; ks < 4; ++ks) qb[ks] = qn[ks];
; #pragma unroll
;     for (int vt = 0; vt < 8; ++vt) o[vt] = (f32x4){0.f, 0.f, 0.f, 0.f};
;     for (;;) {
;         const int qt = u & 63, bh = u >> 6, b = bh >> 4, h = bh & 15, t0 = qt * 128, tq = t0 + 16 * w + r16, twmax = t0 + 16 * w + 15;
;         const int kstart = t0 + 128 - 192 * (r + 1);
; #pragma unroll
;         for (int i = 0; i < 6; ++i) { const int p = tid + NTH * i; *(LAS u32x4*)(lds + (p >> 4) * 272 + (p & 15) * 16) = rk[i];
;             const int v_ = p / 24, sg_ = p - 24 * v_; *(LAS u32x4*)(lds + SB_VOFF + v_ * 400 + sg_ * 16) = rv[i]; }
	v_lshlrev_b32_e32 v0, 1, v0
	s_mov_b32 s1, s11
	v_ashrrev_i32_e32 v177, 31, v197
	v_or_b32_e32 v176, v197, v163
	v_lshl_add_u64 v[92:93], v[2:3], 0, v[0:1]
	v_lshl_add_u64 v[2:3], v[176:177], 0, s[0:1]
	v_lshlrev_b64 v[2:3], 14, v[2:3]
	v_lshl_add_u64 v[2:3], s[6:7], 0, v[2:3]
	v_lshl_add_u64 v[2:3], v[2:3], 0, s[10:11]
	v_and_b32_e32 v0, 48, v34
	v_lshl_add_u64 v[66:67], v[18:19], 0, s[72:73]
	v_lshl_add_u64 v[14:15], v[2:3], 0, v[0:1]
	v_lshl_add_u64 v[18:19], v[66:67], 0, v[20:21]
	global_load_dwordx4 v[2:5], v[14:15], off offset:192
	global_load_dwordx4 v[6:9], v[14:15], off offset:128
	global_load_dwordx4 v[10:13], v[14:15], off offset:64
	s_nop 0
	global_load_dwordx4 v[14:17], v[14:15], off
	s_nop 0
	global_load_dwordx4 v[22:25], v[18:19], off
	s_nop 0
	global_load_dwordx4 v[18:21], v[26:27], off
	v_lshl_add_u64 v[26:27], v[66:67], 0, v[28:29]
	global_load_dwordx4 v[30:33], v[26:27], off
	s_nop 0
	global_load_dwordx4 v[26:29], v[38:39], off
	v_lshl_add_u64 v[38:39], v[66:67], 0, v[40:41]
	global_load_dwordx4 v[42:45], v[38:39], off
	s_nop 0
	global_load_dwordx4 v[38:41], v[46:47], off
	v_lshl_add_u64 v[46:47], v[66:67], 0, v[48:49]
	global_load_dwordx4 v[50:53], v[46:47], off
	s_nop 0
	global_load_dwordx4 v[46:49], v[54:55], off
	v_lshl_add_u64 v[54:55], v[66:67], 0, v[56:57]
	global_load_dwordx4 v[58:61], v[54:55], off
	s_nop 0
	global_load_dwordx4 v[54:57], v[62:63], off
	v_lshl_add_u64 v[62:63], v[66:67], 0, v[64:65]
	global_load_dwordx4 v[66:69], v[62:63], off
	s_nop 0
	global_load_dwordx4 v[62:65], v[92:93], off
	v_readlane_b32 s0, v254, 19
	v_and_b32_e32 v37, 63, v34
	v_bfe_u32 v71, v34, 4, 2
	v_lshlrev_b32_e32 v73, 4, v34
	v_and_b32_e32 v34, 16, v34
	v_lshl_add_u32 v199, v35, 2, s0
	s_movk_i32 s0, 0x190
	v_lshlrev_b32_e32 v92, 3, v71
	v_and_b32_e32 v73, 0xf0, v73
	v_cmp_eq_u32_e64 s[36:37], 0, v34
	v_mul_u32_u24_e32 v34, 0x190, v163
	v_lshlrev_b32_e32 v178, 2, v71
	s_movk_i32 s1, 0x110
	v_mul_lo_u32 v35, v36, s0
	v_lshlrev_b32_e32 v36, 4, v70
	v_mul_lo_u32 v70, v72, s0
	v_lshlrev_b32_e32 v71, 4, v74
	v_mul_lo_u32 v74, v76, s0
	v_mul_lo_u32 v77, v80, s0
	v_mul_lo_u32 v80, v84, s0
	v_mul_lo_u32 v83, v88, s0
	v_add_u32_e32 v73, 0, v73
	v_cmp_gt_u32_e64 s[38:39], 32, v37
	v_add3_u32 v198, 0, v92, v34
	v_cmp_eq_u32_e64 s[40:41], 0, v37
	v_mul_lo_u32 v34, v179, s1
	v_add_u32_e32 v35, 0, v35
	v_mul_lo_u32 v37, v187, s1
	v_add_u32_e32 v70, 0, v70
	v_mul_lo_u32 v72, v189, s1
	v_add_u32_e32 v74, 0, v74
	v_lshlrev_b32_e32 v75, 4, v78
	v_mul_lo_u32 v76, v191, s1
	v_add_u32_e32 v77, 0, v77
	v_lshlrev_b32_e32 v78, 4, v82
	v_mul_lo_u32 v79, v193, s1
	v_add_u32_e32 v80, 0, v80
	v_lshlrev_b32_e32 v81, 4, v86
	v_mul_lo_u32 v82, v195, s1
	v_add_u32_e32 v83, 0, v83
	v_lshlrev_b32_e32 v84, 4, v90
	v_mul_u32_u24_e32 v85, 0x110, v163
	v_readlane_b32 s0, v254, 20
	v_mov_b32_e32 v183, 0
	s_mov_b64 s[14:15], s[66:67]
	s_mov_b32 s59, 0
	v_add3_u32 v200, v85, v0, s0
	v_add_u32_e32 v201, v73, v34
	v_add_u32_e32 v202, v35, v36
	v_add_u32_e32 v203, v73, v37
	v_add_u32_e32 v204, v70, v71
	v_add_u32_e32 v205, v73, v72
	v_add_u32_e32 v206, v74, v75
	v_add_u32_e32 v207, v73, v76
	v_add_u32_e32 v208, v77, v78
	v_add_u32_e32 v209, v73, v79
	v_add_u32_e32 v210, v80, v81
	v_add_u32_e32 v211, v73, v82
	v_add_u32_e32 v212, v83, v84
	v_lshlrev_b32_e32 v180, 1, v92
	v_mov_b32_e32 v94, v183
	v_mov_b32_e32 v95, v183
	v_mov_b32_e32 v96, v183
	v_mov_b32_e32 v97, v183
	v_mov_b32_e32 v90, v183
	s_waitcnt vmcnt(0) lgkmcnt(0)
	v_mov_b64_e32 v[100:101], v[4:5]
	v_mov_b64_e32 v[104:105], v[8:9]
	v_mov_b64_e32 v[108:109], v[12:13]
	v_mov_b64_e32 v[112:113], v[16:17]
	v_mov_b64_e32 v[98:99], v[2:3]
	v_mov_b64_e32 v[102:103], v[6:7]
	v_mov_b64_e32 v[106:107], v[10:11]
	v_mov_b64_e32 v[110:111], v[14:15]
	v_mov_b32_e32 v91, v183
	v_mov_b32_e32 v92, v183
	v_mov_b32_e32 v93, v183
	v_mov_b32_e32 v86, v183
	v_mov_b32_e32 v87, v183
	v_mov_b32_e32 v88, v183
	v_mov_b32_e32 v89, v183
	v_mov_b32_e32 v82, v183
	v_mov_b32_e32 v83, v183
	v_mov_b32_e32 v84, v183
	v_mov_b32_e32 v85, v183
	v_mov_b32_e32 v78, v183
	v_mov_b32_e32 v79, v183
	v_mov_b32_e32 v80, v183
	v_mov_b32_e32 v81, v183
	v_mov_b32_e32 v74, v183
	v_mov_b32_e32 v75, v183
	v_mov_b32_e32 v76, v183
	v_mov_b32_e32 v77, v183
	v_mov_b32_e32 v70, v183
	v_mov_b32_e32 v71, v183
	v_mov_b32_e32 v72, v183
	v_mov_b32_e32 v73, v183
	v_mov_b32_e32 v34, v183
	v_mov_b32_e32 v35, v183
	v_mov_b32_e32 v36, v183
	v_mov_b32_e32 v37, v183
	s_branch .LBB0_50

; #define LAS __attribute__((address_space(3)))
; #define SB_LOADQ(uu) do { const int qt_ = (uu) & 63, bh_ = (uu) >> 6, b_ = bh_ >> 4, h_ = bh_ & 15; const bf16_t* qp_ = Uall + ((size_t)b_ * SEQ + qt_ * 128 + 16 * w + r16) * LDU_O + h_ * 128 + 8 * g; \
;         _Pragma("unroll") for (int ks = 0; ks < 4; ++ks) qn[ks] = *(const bf16x8*)(qp_ + 32 * ks); } while (0)
; DI void sb_phase(const Params& P, LAS unsigned char* lds) {
;     ...
;     int u = bid, r = 0;
;     if (u >= 2048) return;
;     SB_LOAD(u, 0); SB_LOADQ(u);
;     bf16x8 qb[4]; f32x4 o[8]; float R = 0.f;
; #pragma unroll
;     for (int ks = 0; ks < 4; ++ks) qb[ks] = qn[ks];
; #pragma unroll
;     for (int vt = 0; vt < 8; ++vt) o[vt] = (f32x4){0.f, 0.f, 0.f, 0.f};
;     for (;;) {
;         const int qt = u & 63, bh = u >> 6, b = bh >> 4, h = bh & 15, t0 = qt * 128, tq = t0 + 16 * w + r16, twmax = t0 + 16 * w + 15;
;         const int kstart = t0 + 128 - 192 * (r + 1);
; #pragma unroll
;         for (int i = 0; i < 6; ++i) { const int p = tid + NTH * i; *(LAS u32x4*)(lds + (p >> 4) * 272 + (p & 15) * 16) = rk[i];
;             const int v_ = p / 24, sg_ = p - 24 * v_; *(LAS u32x4*)(lds + SB_VOFF + v_ * 400 + sg_ * 16) = rv[i]; }
;         const bool spec_same = (r == 0) && (kstart > 0);
;         const int nu = spec_same ? u : u + G, nr = spec_same ? 1 : 0;
;         if (nu < 2048) { SB_LOAD(nu, nr); if (!spec_same) SB_LOADQ(nu); }
.LBB0_50:
	s_lshl_b32 s0, s58, 7
	s_and_b32 s6, s0, 0x1f80
	s_add_i32 s60, s59, 1
	s_mul_i32 s0, s60, 0xffffff40
	s_add_i32 s61, s6, 0x80
	s_add_i32 s67, s61, s0
	s_cmp_eq_u32 s59, 0
	s_cselect_b64 s[0:1], -1, 0
	s_cmp_gt_i32 s67, 0
	s_cselect_b64 s[12:13], -1, 0
	s_and_b64 s[0:1], s[0:1], s[12:13]
	s_xor_b64 s[12:13], s[0:1], -1
	s_and_b64 s[34:35], s[0:1], exec
	s_cselect_b32 s17, 0, s54
	s_add_i32 s17, s17, s58
	v_cndmask_b32_e64 v0, 0, 1, s[12:13]
	s_cmpk_gt_i32 s17, 0x7ff
	v_cmp_ne_u32_e64 s[42:43], 1, v0
	s_waitcnt vmcnt(0)
	ds_write_b128 v201, v[22:25]
	ds_write_b128 v202, v[18:21] offset:52224
	ds_write_b128 v203, v[30:33]
	ds_write_b128 v204, v[26:29] offset:52224
	ds_write_b128 v205, v[42:45]
	ds_write_b128 v206, v[38:41] offset:52224
	ds_write_b128 v207, v[50:53]
	ds_write_b128 v208, v[46:49] offset:52224
	ds_write_b128 v209, v[58:61]
	ds_write_b128 v210, v[54:57] offset:52224
	ds_write_b128 v211, v[66:69]
	ds_write_b128 v212, v[62:65] offset:52224
	s_cbranch_scc1 .LBB0_53
	s_lshl_b32 s8, s17, 7
	s_ashr_i32 s12, s17, 10
	s_bfe_u32 s7, s17, 0x40006
	s_and_b32 s10, s8, 0x1f80
	s_and_b64 s[0:1], s[0:1], exec
	s_movk_i32 s0, 0xff00
	s_cselect_b32 s0, s0, 0xffffffc0
	s_ashr_i32 s13, s12, 31
	s_add_i32 s8, s10, s0
	s_lshl_b64 s[0:1], s[12:13], 27
	s_add_u32 s0, s20, s0
	s_addc_u32 s1, s21, s1
	s_lshl_b32 s12, s7, 8
	s_add_u32 s12, s0, s12
	s_addc_u32 s13, s1, 0
	s_cmpk_lt_u32 s17, 0x400
	s_cselect_b32 s34, s65, 0x1d600000
	v_lshlrev_b32_e32 v0, 1, v162
	s_add_u32 s34, s4, s34
	v_lshl_add_u64 v[18:19], s[12:13], 0, v[0:1]
	v_add_u32_e32 v0, s8, v179
	s_addc_u32 s35, s5, 0
	s_lshl_b32 s44, s7, 21
	v_max_i32_e32 v0, 0, v0
	s_add_u32 s34, s34, s44
	v_lshl_add_u64 v[62:63], v[18:19], 0, s[72:73]
	v_lshlrev_b64 v[18:19], 14, v[0:1]
	v_add_u32_e32 v0, s8, v186
	s_addc_u32 s35, s35, 0
	v_max_i32_e32 v0, 0, v0
	v_lshl_add_u64 v[20:21], s[34:35], 0, v[164:165]
	v_lshlrev_b32_e32 v0, 1, v0
	v_lshl_add_u64 v[20:21], v[20:21], 0, v[0:1]
	v_add_u32_e32 v0, s8, v187
	v_max_i32_e32 v0, 0, v0
	v_lshlrev_b64 v[26:27], 14, v[0:1]
	v_add_u32_e32 v0, s8, v188
	v_max_i32_e32 v0, 0, v0
	v_lshl_add_u64 v[28:29], s[34:35], 0, v[166:167]
	v_lshlrev_b32_e32 v0, 1, v0
	v_lshl_add_u64 v[28:29], v[28:29], 0, v[0:1]
	v_add_u32_e32 v0, s8, v189
	v_max_i32_e32 v0, 0, v0
	v_lshlrev_b64 v[38:39], 14, v[0:1]
	v_add_u32_e32 v0, s8, v190
	v_max_i32_e32 v0, 0, v0
	v_lshl_add_u64 v[40:41], s[34:35], 0, v[168:169]
	v_lshlrev_b32_e32 v0, 1, v0
	v_lshl_add_u64 v[40:41], v[40:41], 0, v[0:1]
	v_add_u32_e32 v0, s8, v191
	v_max_i32_e32 v0, 0, v0
	v_lshlrev_b64 v[46:47], 14, v[0:1]
	v_add_u32_e32 v0, s8, v192
	v_max_i32_e32 v0, 0, v0
	v_lshl_add_u64 v[48:49], s[34:35], 0, v[170:171]
	v_lshlrev_b32_e32 v0, 1, v0
	v_lshl_add_u64 v[48:49], v[48:49], 0, v[0:1]
	v_add_u32_e32 v0, s8, v193
	v_max_i32_e32 v0, 0, v0
	v_lshlrev_b64 v[54:55], 14, v[0:1]
	v_add_u32_e32 v0, s8, v194
	v_max_i32_e32 v0, 0, v0
	v_lshl_add_u64 v[56:57], s[34:35], 0, v[172:173]
	v_lshlrev_b32_e32 v0, 1, v0
	v_lshl_add_u64 v[56:57], v[56:57], 0, v[0:1]
	v_add_u32_e32 v0, s8, v195
	v_max_i32_e32 v0, 0, v0
	v_lshlrev_b64 v[64:65], 14, v[0:1]
	v_add_u32_e32 v0, s8, v196
	v_max_i32_e32 v0, 0, v0
	v_lshl_add_u64 v[18:19], v[62:63], 0, v[18:19]
	v_lshl_add_u64 v[26:27], v[62:63], 0, v[26:27]
	v_lshl_add_u64 v[38:39], v[62:63], 0, v[38:39]
	v_lshl_add_u64 v[46:47], v[62:63], 0, v[46:47]
	v_lshl_add_u64 v[54:55], v[62:63], 0, v[54:55]
	v_lshl_add_u64 v[62:63], v[62:63], 0, v[64:65]
	v_lshl_add_u64 v[64:65], s[34:35], 0, v[174:175]
	v_lshlrev_b32_e32 v0, 1, v0
	v_lshl_add_u64 v[64:65], v[64:65], 0, v[0:1]
	global_load_dwordx4 v[22:25], v[18:19], off
	s_nop 0
	global_load_dwordx4 v[18:21], v[20:21], off
	s_nop 0
	global_load_dwordx4 v[30:33], v[26:27], off
	s_nop 0
	global_load_dwordx4 v[26:29], v[28:29], off
	s_nop 0
	global_load_dwordx4 v[42:45], v[38:39], off
	s_nop 0
	global_load_dwordx4 v[38:41], v[40:41], off
	s_nop 0
	global_load_dwordx4 v[50:53], v[46:47], off
	s_nop 0
	global_load_dwordx4 v[46:49], v[48:49], off
	s_nop 0
	global_load_dwordx4 v[58:61], v[54:55], off
	s_nop 0
	global_load_dwordx4 v[54:57], v[56:57], off
	s_nop 0
	global_load_dwordx4 v[66:69], v[62:63], off
	s_nop 0
	global_load_dwordx4 v[62:65], v[64:65], off
	s_and_b64 vcc, exec, s[42:43]
	s_cbranch_vccnz .LBB0_53
	v_lshl_add_u64 v[2:3], v[176:177], 0, s[10:11]
	s_lshl_b32 s7, s7, 7
	v_lshlrev_b64 v[2:3], 14, v[2:3]
	v_lshl_add_u64 v[2:3], s[0:1], 0, v[2:3]
	s_lshl_b32 s10, s7, 1
	v_lshl_add_u64 v[2:3], v[2:3], 0, s[10:11]
	v_mov_b32_e32 v181, v1
	v_lshl_add_u64 v[2:3], v[2:3], 0, v[180:181]
	global_load_dwordx4 v[14:17], v[2:3], off
	global_load_dwordx4 v[10:13], v[2:3], off offset:64
	global_load_dwordx4 v[6:9], v[2:3], off offset:128
	s_nop 0
	global_load_dwordx4 v[2:5], v[2:3], off offset:192

; DI unsigned pk2(float lo, float hi) { f32x2_t f = {lo, hi}; bf16x2_t v = __builtin_convertvector(f, bf16x2_t); return __builtin_bit_cast(unsigned, v); }
; DI float silu(float v) { return v / (1.f + __expf(-v)); }
; DI void sb_phase(const Params& P, LAS unsigned char* lds) {
;     ...
;         if (lane == 0) flags[w] = __all(R > SB_RDONE) ? 1 : 0;
;         __syncthreads();
;         if (spec_same) { r = 1; continue; }
;         int alld = 1;
; #pragma unroll
;         for (int i = 0; i < 8; ++i) alld &= flags[i];
;         if (alld || kstart <= 0) {
;             { const bf16_t* gp = Uall + ((size_t)b * SEQ + tq) * LDU_O + 6144 + h * 128 + 4 * g; bf16_t* yp = (bf16_t*)Uall + ((size_t)b * SEQ + tq) * LDU_O + h * 128 + 4 * g;
; #pragma unroll
;               for (int vt = 0; vt < 8; ++vt) { const u32x2 gv = *(const u32x2*)(gp + 16 * vt);
;                   u32x2 wv; wv.x = pk2(o[vt][0] * silu(bflo(gv.x)), o[vt][1] * silu(bfhi(gv.x))); wv.y = pk2(o[vt][2] * silu(bflo(gv.y)), o[vt][3] * silu(bfhi(gv.y)));
;                   *(u32x2*)(yp + 16 * vt) = wv; } }
;             u = nu; r = 0; R = 0.f;
;             if (u >= 2048) break;
; #pragma unroll
;             for (int ks = 0; ks < 4; ++ks) qb[ks] = qn[ks];
; #pragma unroll
;             for (int vt = 0; vt < 8; ++vt) o[vt] = (f32x4){0.f, 0.f, 0.f, 0.f};
;         } else {
;             r = r + 1; SB_LOAD(u, r);
;         }
.LBB0_69:
	s_or_b64 exec, exec, s[6:7]
	s_and_saveexec_b64 s[0:1], s[40:41]
	v_cmp_lt_f32_e32 vcc, s97, v183
	s_cmp_eq_u64 vcc, exec
	s_cselect_b64 s[6:7], -1, 0
	v_cndmask_b32_e64 v0, 0, 1, s[6:7]
	ds_write_b32 v199, v0
	s_or_b64 exec, exec, s[0:1]
	s_and_b64 vcc, exec, s[42:43]
	s_mov_b64 s[0:1], -1
	s_waitcnt lgkmcnt(0)
	s_barrier
	s_cbranch_vccnz .LBB0_75
	v_readlane_b32 s7, v254, 19
	s_ashr_i32 s34, s58, 10
	s_bfe_u32 s6, s58, 0x40006
	v_mov_b32_e32 v0, s7
	ds_read_b128 v[114:117], v0
	v_readlane_b32 s7, v254, 21
	s_cmp_lt_i32 s67, 1
	s_cselect_b64 s[12:13], -1, 0
	s_mov_b32 s35, 1
	s_waitcnt lgkmcnt(0)
	v_and_b32_e32 v0, v114, v115
	v_and_b32_e32 v0, v0, v116
	v_mov_b32_e32 v114, s7
	v_and_b32_e32 v0, v0, v117
	ds_read_b128 v[114:117], v114
	s_lshl_b32 s8, s6, 7
	s_waitcnt lgkmcnt(0)
	v_and_b32_e32 v0, v0, v114
	v_and_b32_e32 v0, v0, v115
	v_and_b32_e32 v0, v0, v116
	v_and_b32_e32 v0, v0, v117
	v_and_b32_e32 v0, 1, v0
	v_cmp_eq_u32_e32 vcc, 1, v0
	s_or_b64 s[12:13], vcc, s[12:13]
	s_andn2_b64 vcc, exec, s[12:13]
	s_cbranch_vccz .LBB0_76
	s_mul_i32 s7, s59, 0xffffff40
	s_add_i32 s7, s7, s61
	s_ashr_i32 s35, s34, 31
	s_add_i32 s42, s7, 0xfffffe80
	s_lshl_b64 s[12:13], s[34:35], 27
	s_add_u32 s7, s20, s12
	s_addc_u32 s13, s21, s13
	s_lshl_b32 s12, s8, 1
	s_add_u32 s12, s7, s12
	s_addc_u32 s13, s13, 0
	s_cmpk_lt_u32 s58, 0x400
	s_cselect_b32 s7, s65, 0x1d600000
	v_lshlrev_b32_e32 v0, 1, v162
	s_add_u32 s7, s4, s7
	v_lshl_add_u64 v[114:115], s[12:13], 0, v[0:1]
	v_add_u32_e32 v0, s42, v179
	s_addc_u32 s35, s5, 0
	s_lshl_b32 s6, s6, 21
	v_max_i32_e32 v0, 0, v0
	s_add_u32 s6, s7, s6
	v_lshl_add_u64 v[154:155], v[114:115], 0, s[72:73]
	v_lshlrev_b64 v[114:115], 14, v[0:1]
	v_add_u32_e32 v0, s42, v186
	s_addc_u32 s7, s35, 0
	v_max_i32_e32 v0, 0, v0
	v_lshl_add_u64 v[116:117], s[6:7], 0, v[164:165]
	v_lshlrev_b32_e32 v0, 1, v0
	v_lshl_add_u64 v[118:119], v[116:117], 0, v[0:1]
	v_add_u32_e32 v0, s42, v187
	v_max_i32_e32 v0, 0, v0
	v_lshlrev_b64 v[122:123], 14, v[0:1]
	v_add_u32_e32 v0, s42, v188
	v_max_i32_e32 v0, 0, v0
	v_lshl_add_u64 v[124:125], s[6:7], 0, v[166:167]
	v_lshlrev_b32_e32 v0, 1, v0
	v_lshl_add_u64 v[126:127], v[124:125], 0, v[0:1]
	v_add_u32_e32 v0, s42, v189
	v_max_i32_e32 v0, 0, v0
	v_lshlrev_b64 v[130:131], 14, v[0:1]
	v_add_u32_e32 v0, s42, v190
	v_max_i32_e32 v0, 0, v0
	v_lshl_add_u64 v[132:133], s[6:7], 0, v[168:169]
	v_lshlrev_b32_e32 v0, 1, v0
	v_lshl_add_u64 v[134:135], v[132:133], 0, v[0:1]
	v_add_u32_e32 v0, s42, v191
	v_max_i32_e32 v0, 0, v0
	v_lshlrev_b64 v[138:139], 14, v[0:1]
	v_add_u32_e32 v0, s42, v192
	v_max_i32_e32 v0, 0, v0
	v_lshl_add_u64 v[140:141], s[6:7], 0, v[170:171]
	v_lshlrev_b32_e32 v0, 1, v0
	v_lshl_add_u64 v[142:143], v[140:141], 0, v[0:1]
	v_add_u32_e32 v0, s42, v193
	v_max_i32_e32 v0, 0, v0
	v_lshlrev_b64 v[146:147], 14, v[0:1]
	v_add_u32_e32 v0, s42, v194
	v_max_i32_e32 v0, 0, v0
	v_lshl_add_u64 v[148:149], s[6:7], 0, v[172:173]
	v_lshlrev_b32_e32 v0, 1, v0
	v_lshl_add_u64 v[150:151], v[148:149], 0, v[0:1]
	v_add_u32_e32 v0, s42, v195
	v_max_i32_e32 v0, 0, v0
	v_lshlrev_b64 v[156:157], 14, v[0:1]
	v_add_u32_e32 v0, s42, v196
	v_max_i32_e32 v0, 0, v0
	v_lshl_add_u64 v[114:115], v[154:155], 0, v[114:115]
	v_lshl_add_u64 v[122:123], v[154:155], 0, v[122:123]
	v_lshl_add_u64 v[130:131], v[154:155], 0, v[130:131]
	v_lshl_add_u64 v[138:139], v[154:155], 0, v[138:139]
	v_lshl_add_u64 v[146:147], v[154:155], 0, v[146:147]
	v_lshl_add_u64 v[154:155], v[154:155], 0, v[156:157]
	v_lshl_add_u64 v[156:157], s[6:7], 0, v[174:175]
	v_lshlrev_b32_e32 v0, 1, v0
	v_lshl_add_u64 v[158:159], v[156:157], 0, v[0:1]
	global_load_dwordx4 v[114:117], v[114:115], off
	s_nop 0
	global_load_dwordx4 v[118:121], v[118:119], off
	s_nop 0
	global_load_dwordx4 v[122:125], v[122:123], off
	s_nop 0
	global_load_dwordx4 v[126:129], v[126:127], off
	s_nop 0
	global_load_dwordx4 v[130:133], v[130:131], off
	s_nop 0
	global_load_dwordx4 v[134:137], v[134:135], off
	s_nop 0
	global_load_dwordx4 v[138:141], v[138:139], off
	s_nop 0
	global_load_dwordx4 v[142:145], v[142:143], off
	s_nop 0
	global_load_dwordx4 v[146:149], v[146:147], off
	s_nop 0
	global_load_dwordx4 v[150:153], v[150:151], off
	s_nop 0
	global_load_dwordx4 v[154:157], v[154:155], off
	s_nop 0
	global_load_dwordx4 v[158:161], v[158:159], off
	s_mov_b64 s[6:7], -1
	s_mov_b32 s35, s60
	s_cbranch_execz .LBB0_77
	s_waitcnt vmcnt(0) lgkmcnt(0)
	v_mov_b64_e32 v[18:19], v[118:119]
	v_mov_b64_e32 v[26:27], v[126:127]
	v_mov_b64_e32 v[38:39], v[134:135]
	v_mov_b64_e32 v[46:47], v[142:143]
	v_mov_b64_e32 v[54:55], v[150:151]
	v_mov_b64_e32 v[62:63], v[158:159]
	v_mov_b64_e32 v[22:23], v[114:115]
	v_mov_b64_e32 v[30:31], v[122:123]
	v_mov_b64_e32 v[42:43], v[130:131]
	v_mov_b64_e32 v[50:51], v[138:139]
	v_mov_b64_e32 v[58:59], v[146:147]
	v_mov_b64_e32 v[66:67], v[154:155]
	v_mov_b64_e32 v[20:21], v[120:121]
	v_mov_b64_e32 v[28:29], v[128:129]
	v_mov_b64_e32 v[40:41], v[136:137]
	v_mov_b64_e32 v[48:49], v[144:145]
	v_mov_b64_e32 v[56:57], v[152:153]
	v_mov_b64_e32 v[64:65], v[160:161]
	v_mov_b64_e32 v[24:25], v[116:117]
	v_mov_b64_e32 v[32:33], v[124:125]
	v_mov_b64_e32 v[44:45], v[132:133]
	v_mov_b64_e32 v[52:53], v[140:141]
	v_mov_b64_e32 v[60:61], v[148:149]
	v_mov_b64_e32 v[68:69], v[156:157]
	s_mov_b32 s59, s35
	s_and_b64 vcc, exec, s[6:7]
	s_cbranch_vccz .LBB0_49
	s_branch .LBB0_48

; DI unsigned pk2(float lo, float hi) { f32x2_t f = {lo, hi}; bf16x2_t v = __builtin_convertvector(f, bf16x2_t); return __builtin_bit_cast(unsigned, v); }
; DI float silu(float v) { return v / (1.f + __expf(-v)); }
; DI void sb_phase(const Params& P, LAS unsigned char* lds) {
;     ...
;             { const bf16_t* gp = Uall + ((size_t)b * SEQ + tq) * LDU_O + 6144 + h * 128 + 4 * g; bf16_t* yp = (bf16_t*)Uall + ((size_t)b * SEQ + tq) * LDU_O + h * 128 + 4 * g;
; #pragma unroll
;               for (int vt = 0; vt < 8; ++vt) { const u32x2 gv = *(const u32x2*)(gp + 16 * vt);
;                   u32x2 wv; wv.x = pk2(o[vt][0] * silu(bflo(gv.x)), o[vt][1] * silu(bfhi(gv.x))); wv.y = pk2(o[vt][2] * silu(bflo(gv.y)), o[vt][3] * silu(bfhi(gv.y)));
;                   *(u32x2*)(yp + 16 * vt) = wv; } }
.LBB0_77:
	s_ashr_i32 s35, s34, 31
	s_lshl_b64 s[6:7], s[34:35], 27
	v_ashrrev_i32_e32 v185, 31, v184
	s_add_u32 s6, s20, s6
	s_addc_u32 s7, s21, s7
	v_lshlrev_b64 v[98:99], 14, v[184:185]
	v_lshl_add_u64 v[98:99], s[6:7], 0, v[98:99]
	s_lshl_b32 s10, s8, 1
	v_lshlrev_b32_e32 v0, 1, v178
	v_lshl_add_u64 v[98:99], v[98:99], 0, s[10:11]
	v_lshl_add_u64 v[98:99], v[98:99], 0, v[0:1]
	v_add_co_u32_e32 v102, vcc, s86, v98
	s_mov_b64 s[6:7], 0x3000
	s_nop 0
	v_addc_co_u32_e32 v103, vcc, 0, v99, vcc
	global_load_dwordx2 v[102:103], v[102:103], off
	v_lshl_add_u64 v[100:101], v[98:99], 0, s[6:7]
	s_cmpk_lt_i32 s17, 0x800
	s_mov_b32 s35, 0
	s_mov_b32 s58, s17
	s_waitcnt vmcnt(0) lgkmcnt(0)
	v_lshlrev_b32_e32 v0, 16, v102
	v_and_b32_e32 v102, 0xffff0000, v102
	v_mul_f32_e32 v104, 0xbfb8aa3b, v0
	v_mul_f32_e32 v105, 0xbfb8aa3b, v102
	v_exp_f32_e32 v104, v104
	v_exp_f32_e32 v105, v105
	s_nop 0
	v_pk_add_f32 v[104:105], v[104:105], 1.0 op_sel_hi:[1,0]
	s_nop 0
	v_div_scale_f32 v106, s[6:7], v105, v105, v102
	v_rcp_f32_e32 v107, v106
	s_nop 0
	v_fma_f32 v108, -v106, v107, 1.0
	v_fmac_f32_e32 v107, v108, v107
	v_div_scale_f32 v108, vcc, v102, v105, v102
	v_mul_f32_e32 v109, v108, v107
	v_fma_f32 v110, -v106, v109, v108
	v_fmac_f32_e32 v109, v110, v107
	v_fma_f32 v106, -v106, v109, v108
	v_div_fmas_f32 v106, v106, v107, v109
	v_div_fixup_f32 v105, v106, v105, v102
	v_div_scale_f32 v102, s[6:7], v104, v104, v0
	v_rcp_f32_e32 v106, v102
	v_mov_b64_e32 v[112:113], v[16:17]
	v_mov_b64_e32 v[110:111], v[14:15]
	v_fma_f32 v107, -v102, v106, 1.0
	v_fmac_f32_e32 v106, v107, v106
	v_div_scale_f32 v107, vcc, v0, v104, v0
	v_mul_f32_e32 v108, v107, v106
	v_fma_f32 v109, -v102, v108, v107
	v_fmac_f32_e32 v108, v109, v106
	v_fma_f32 v102, -v102, v108, v107
	v_div_fmas_f32 v102, v102, v106, v108
	v_div_fixup_f32 v104, v102, v104, v0
	v_pk_mul_f32 v[94:95], v[94:95], v[104:105]
	v_lshlrev_b32_e32 v0, 16, v103
	v_cvt_pk_bf16_f32 v94, v94, v95
	v_and_b32_e32 v95, 0xffff0000, v103
	v_mul_f32_e32 v102, 0xbfb8aa3b, v0
	v_mul_f32_e32 v103, 0xbfb8aa3b, v95
	v_exp_f32_e32 v102, v102
	v_exp_f32_e32 v103, v103
	s_nop 0
	v_pk_add_f32 v[102:103], v[102:103], 1.0 op_sel_hi:[1,0]
	s_nop 0
	v_div_scale_f32 v104, s[6:7], v103, v103, v95
	v_rcp_f32_e32 v105, v104
	s_nop 0
	v_fma_f32 v106, -v104, v105, 1.0
	v_fmac_f32_e32 v105, v106, v105
	v_div_scale_f32 v106, vcc, v95, v103, v95
	v_mul_f32_e32 v107, v106, v105
	v_fma_f32 v108, -v104, v107, v106
	v_fmac_f32_e32 v107, v108, v105
	v_fma_f32 v104, -v104, v107, v106
	v_div_fmas_f32 v104, v104, v105, v107
	v_div_fixup_f32 v103, v104, v103, v95
	v_div_scale_f32 v95, s[6:7], v102, v102, v0
	v_rcp_f32_e32 v104, v95
	s_nop 0
	v_fma_f32 v105, -v95, v104, 1.0
	v_fmac_f32_e32 v104, v105, v104
	v_div_scale_f32 v105, vcc, v0, v102, v0
	v_mul_f32_e32 v106, v105, v104
	v_fma_f32 v107, -v95, v106, v105
	v_fmac_f32_e32 v106, v107, v104
	v_fma_f32 v95, -v95, v106, v105
	v_div_fmas_f32 v95, v95, v104, v106
	v_div_fixup_f32 v102, v95, v102, v0
	v_pk_mul_f32 v[96:97], v[96:97], v[102:103]
	s_nop 0
	v_cvt_pk_bf16_f32 v95, v96, v97
	global_store_dwordx2 v[98:99], v[94:95], off
	global_load_dwordx2 v[94:95], v[100:101], off offset:32
	s_waitcnt vmcnt(0) lgkmcnt(0)
	v_lshlrev_b32_e32 v0, 16, v94
	v_and_b32_e32 v94, 0xffff0000, v94
	v_mul_f32_e32 v96, 0xbfb8aa3b, v0
	v_mul_f32_e32 v97, 0xbfb8aa3b, v94
	v_exp_f32_e32 v96, v96
	v_exp_f32_e32 v97, v97
	s_nop 0
	v_pk_add_f32 v[96:97], v[96:97], 1.0 op_sel_hi:[1,0]
	s_nop 0
	v_div_scale_f32 v102, s[6:7], v97, v97, v94
	v_rcp_f32_e32 v103, v102
	s_nop 0
	v_fma_f32 v104, -v102, v103, 1.0
	v_fmac_f32_e32 v103, v104, v103
	v_div_scale_f32 v104, vcc, v94, v97, v94
	v_mul_f32_e32 v105, v104, v103
	v_fma_f32 v106, -v102, v105, v104
	v_fmac_f32_e32 v105, v106, v103
	v_fma_f32 v102, -v102, v105, v104
	v_div_fmas_f32 v102, v102, v103, v105
	v_div_fixup_f32 v97, v102, v97, v94
	v_div_scale_f32 v94, s[6:7], v96, v96, v0
	v_rcp_f32_e32 v102, v94
	v_mov_b64_e32 v[108:109], v[12:13]
	v_mov_b64_e32 v[106:107], v[10:11]
	v_fma_f32 v103, -v94, v102, 1.0
	v_fmac_f32_e32 v102, v103, v102
	v_div_scale_f32 v103, vcc, v0, v96, v0
	v_mul_f32_e32 v104, v103, v102
	v_fma_f32 v105, -v94, v104, v103
	v_fmac_f32_e32 v104, v105, v102
	v_fma_f32 v94, -v94, v104, v103
	v_div_fmas_f32 v94, v94, v102, v104
	v_div_fixup_f32 v96, v94, v96, v0
	v_pk_mul_f32 v[90:91], v[90:91], v[96:97]
	v_lshlrev_b32_e32 v0, 16, v95
	v_cvt_pk_bf16_f32 v90, v90, v91
	v_and_b32_e32 v91, 0xffff0000, v95
	v_mul_f32_e32 v94, 0xbfb8aa3b, v0
	v_mul_f32_e32 v95, 0xbfb8aa3b, v91
	v_exp_f32_e32 v94, v94
	v_exp_f32_e32 v95, v95
	s_nop 0
	v_pk_add_f32 v[94:95], v[94:95], 1.0 op_sel_hi:[1,0]
	s_nop 0
	v_div_scale_f32 v96, s[6:7], v95, v95, v91
	v_rcp_f32_e32 v97, v96
	s_nop 0
	v_fma_f32 v102, -v96, v97, 1.0
	v_fmac_f32_e32 v97, v102, v97
	v_div_scale_f32 v102, vcc, v91, v95, v91
	v_mul_f32_e32 v103, v102, v97
	v_fma_f32 v104, -v96, v103, v102
	v_fmac_f32_e32 v103, v104, v97
	v_fma_f32 v96, -v96, v103, v102
	v_div_fmas_f32 v96, v96, v97, v103
	v_div_fixup_f32 v95, v96, v95, v91
	v_div_scale_f32 v91, s[6:7], v94, v94, v0
	v_rcp_f32_e32 v96, v91
	s_nop 0
	v_fma_f32 v97, -v91, v96, 1.0
	v_fmac_f32_e32 v96, v97, v96
	v_div_scale_f32 v97, vcc, v0, v94, v0
	v_mul_f32_e32 v102, v97, v96
	v_fma_f32 v103, -v91, v102, v97
	v_fmac_f32_e32 v102, v103, v96
	v_fma_f32 v91, -v91, v102, v97
	v_div_fmas_f32 v91, v91, v96, v102
	v_div_fixup_f32 v94, v91, v94, v0
	v_pk_mul_f32 v[92:93], v[92:93], v[94:95]
	s_nop 0
	v_cvt_pk_bf16_f32 v91, v92, v93
	global_store_dwordx2 v[98:99], v[90:91], off offset:32
	global_load_dwordx2 v[90:91], v[100:101], off offset:64
	s_waitcnt vmcnt(0) lgkmcnt(0)
; DI unsigned pk2(float lo, float hi) { f32x2_t f = {lo, hi}; bf16x2_t v = __builtin_convertvector(f, bf16x2_t); return __builtin_bit_cast(unsigned, v); }
; DI float silu(float v) { return v / (1.f + __expf(-v)); }
; DI void sb_phase(const Params& P, LAS unsigned char* lds) {
;     ...
;             { const bf16_t* gp = Uall + ((size_t)b * SEQ + tq) * LDU_O + 6144 + h * 128 + 4 * g; bf16_t* yp = (bf16_t*)Uall + ((size_t)b * SEQ + tq) * LDU_O + h * 128 + 4 * g;
; #pragma unroll
;               for (int vt = 0; vt < 8; ++vt) { const u32x2 gv = *(const u32x2*)(gp + 16 * vt);
;                   u32x2 wv; wv.x = pk2(o[vt][0] * silu(bflo(gv.x)), o[vt][1] * silu(bfhi(gv.x))); wv.y = pk2(o[vt][2] * silu(bflo(gv.y)), o[vt][3] * silu(bfhi(gv.y)));
;                   *(u32x2*)(yp + 16 * vt) = wv; } }
	v_lshlrev_b32_e32 v0, 16, v90
	v_and_b32_e32 v90, 0xffff0000, v90
	v_mul_f32_e32 v92, 0xbfb8aa3b, v0
	v_mul_f32_e32 v93, 0xbfb8aa3b, v90
	v_exp_f32_e32 v92, v92
	v_exp_f32_e32 v93, v93
	s_nop 0
	v_pk_add_f32 v[92:93], v[92:93], 1.0 op_sel_hi:[1,0]
	s_nop 0
	v_div_scale_f32 v94, s[6:7], v93, v93, v90
	v_rcp_f32_e32 v95, v94
	s_nop 0
	v_fma_f32 v96, -v94, v95, 1.0
	v_fmac_f32_e32 v95, v96, v95
	v_div_scale_f32 v96, vcc, v90, v93, v90
	v_mul_f32_e32 v97, v96, v95
	v_fma_f32 v102, -v94, v97, v96
	v_fmac_f32_e32 v97, v102, v95
	v_fma_f32 v94, -v94, v97, v96
	v_div_fmas_f32 v94, v94, v95, v97
	v_div_fixup_f32 v93, v94, v93, v90
	v_div_scale_f32 v90, s[6:7], v92, v92, v0
	v_rcp_f32_e32 v94, v90
	v_mov_b64_e32 v[104:105], v[8:9]
	v_mov_b64_e32 v[102:103], v[6:7]
	v_fma_f32 v95, -v90, v94, 1.0
	v_fmac_f32_e32 v94, v95, v94
	v_div_scale_f32 v95, vcc, v0, v92, v0
	v_mul_f32_e32 v96, v95, v94
	v_fma_f32 v97, -v90, v96, v95
	v_fmac_f32_e32 v96, v97, v94
	v_fma_f32 v90, -v90, v96, v95
	v_div_fmas_f32 v90, v90, v94, v96
	v_div_fixup_f32 v92, v90, v92, v0
	v_pk_mul_f32 v[86:87], v[86:87], v[92:93]
	v_lshlrev_b32_e32 v0, 16, v91
	v_cvt_pk_bf16_f32 v86, v86, v87
	v_and_b32_e32 v87, 0xffff0000, v91
	v_mul_f32_e32 v90, 0xbfb8aa3b, v0
	v_mul_f32_e32 v91, 0xbfb8aa3b, v87
	v_exp_f32_e32 v90, v90
	v_exp_f32_e32 v91, v91
	s_nop 0
	v_pk_add_f32 v[90:91], v[90:91], 1.0 op_sel_hi:[1,0]
	s_nop 0
	v_div_scale_f32 v92, s[6:7], v91, v91, v87
	v_rcp_f32_e32 v93, v92
	s_nop 0
	v_fma_f32 v94, -v92, v93, 1.0
	v_fmac_f32_e32 v93, v94, v93
	v_div_scale_f32 v94, vcc, v87, v91, v87
	v_mul_f32_e32 v95, v94, v93
	v_fma_f32 v96, -v92, v95, v94
	v_fmac_f32_e32 v95, v96, v93
	v_fma_f32 v92, -v92, v95, v94
	v_div_fmas_f32 v92, v92, v93, v95
	v_div_fixup_f32 v91, v92, v91, v87
	v_div_scale_f32 v87, s[6:7], v90, v90, v0
	v_rcp_f32_e32 v92, v87
	s_nop 0
	v_fma_f32 v93, -v87, v92, 1.0
	v_fmac_f32_e32 v92, v93, v92
	v_div_scale_f32 v93, vcc, v0, v90, v0
	v_mul_f32_e32 v94, v93, v92
	v_fma_f32 v95, -v87, v94, v93
	v_fmac_f32_e32 v94, v95, v92
	v_fma_f32 v87, -v87, v94, v93
	v_div_fmas_f32 v87, v87, v92, v94
	v_div_fixup_f32 v90, v87, v90, v0
	v_pk_mul_f32 v[88:89], v[88:89], v[90:91]
	s_nop 0
	v_cvt_pk_bf16_f32 v87, v88, v89
	global_store_dwordx2 v[98:99], v[86:87], off offset:64
	global_load_dwordx2 v[86:87], v[100:101], off offset:96
	s_waitcnt vmcnt(0) lgkmcnt(0)
	v_lshlrev_b32_e32 v0, 16, v86
	v_and_b32_e32 v86, 0xffff0000, v86
	v_mul_f32_e32 v88, 0xbfb8aa3b, v0
	v_mul_f32_e32 v89, 0xbfb8aa3b, v86
	v_exp_f32_e32 v88, v88
	v_exp_f32_e32 v89, v89
	s_nop 0
	v_pk_add_f32 v[88:89], v[88:89], 1.0 op_sel_hi:[1,0]
	s_nop 0
	v_div_scale_f32 v90, s[6:7], v89, v89, v86
	v_rcp_f32_e32 v91, v90
	s_nop 0
	v_fma_f32 v92, -v90, v91, 1.0
	v_fmac_f32_e32 v91, v92, v91
	v_div_scale_f32 v92, vcc, v86, v89, v86
	v_mul_f32_e32 v93, v92, v91
	v_fma_f32 v94, -v90, v93, v92
	v_fmac_f32_e32 v93, v94, v91
	v_fma_f32 v90, -v90, v93, v92
	v_div_fmas_f32 v90, v90, v91, v93
	v_div_fixup_f32 v89, v90, v89, v86
	v_div_scale_f32 v86, s[6:7], v88, v88, v0
	v_rcp_f32_e32 v90, v86
	s_nop 0
	v_fma_f32 v91, -v86, v90, 1.0
	v_fmac_f32_e32 v90, v91, v90
	v_div_scale_f32 v91, vcc, v0, v88, v0
	v_mul_f32_e32 v92, v91, v90
	v_fma_f32 v93, -v86, v92, v91
	v_fmac_f32_e32 v92, v93, v90
	v_fma_f32 v86, -v86, v92, v91
	v_div_fmas_f32 v86, v86, v90, v92
	v_div_fixup_f32 v88, v86, v88, v0
	v_pk_mul_f32 v[82:83], v[82:83], v[88:89]
	v_lshlrev_b32_e32 v0, 16, v87
	v_cvt_pk_bf16_f32 v82, v82, v83
	v_and_b32_e32 v83, 0xffff0000, v87
	v_mul_f32_e32 v86, 0xbfb8aa3b, v0
	v_mul_f32_e32 v87, 0xbfb8aa3b, v83
	v_exp_f32_e32 v86, v86
	v_exp_f32_e32 v87, v87
	s_nop 0
	v_pk_add_f32 v[86:87], v[86:87], 1.0 op_sel_hi:[1,0]
	s_nop 0
	v_div_scale_f32 v88, s[6:7], v87, v87, v83
	v_rcp_f32_e32 v89, v88
	s_nop 0
	v_fma_f32 v90, -v88, v89, 1.0
	v_fmac_f32_e32 v89, v90, v89
	v_div_scale_f32 v90, vcc, v83, v87, v83
	v_mul_f32_e32 v91, v90, v89
	v_fma_f32 v92, -v88, v91, v90
	v_fmac_f32_e32 v91, v92, v89
	v_fma_f32 v88, -v88, v91, v90
	v_div_fmas_f32 v88, v88, v89, v91
	v_div_fixup_f32 v87, v88, v87, v83
	v_div_scale_f32 v83, s[6:7], v86, v86, v0
	v_rcp_f32_e32 v88, v83
	s_nop 0
	v_fma_f32 v89, -v83, v88, 1.0
	v_fmac_f32_e32 v88, v89, v88
	v_div_scale_f32 v89, vcc, v0, v86, v0
	v_mul_f32_e32 v90, v89, v88
	v_fma_f32 v91, -v83, v90, v89
	v_fmac_f32_e32 v90, v91, v88
	v_fma_f32 v83, -v83, v90, v89
	v_div_fmas_f32 v83, v83, v88, v90
	v_div_fixup_f32 v86, v83, v86, v0
	v_pk_mul_f32 v[84:85], v[84:85], v[86:87]
	s_nop 0
	v_cvt_pk_bf16_f32 v83, v84, v85
	global_store_dwordx2 v[98:99], v[82:83], off offset:96
	global_load_dwordx2 v[82:83], v[100:101], off offset:128
	s_waitcnt vmcnt(0) lgkmcnt(0)
; DI unsigned pk2(float lo, float hi) { f32x2_t f = {lo, hi}; bf16x2_t v = __builtin_convertvector(f, bf16x2_t); return __builtin_bit_cast(unsigned, v); }
; DI float silu(float v) { return v / (1.f + __expf(-v)); }
; DI void sb_phase(const Params& P, LAS unsigned char* lds) {
;     ...
;             { const bf16_t* gp = Uall + ((size_t)b * SEQ + tq) * LDU_O + 6144 + h * 128 + 4 * g; bf16_t* yp = (bf16_t*)Uall + ((size_t)b * SEQ + tq) * LDU_O + h * 128 + 4 * g;
; #pragma unroll
;               for (int vt = 0; vt < 8; ++vt) { const u32x2 gv = *(const u32x2*)(gp + 16 * vt);
;                   u32x2 wv; wv.x = pk2(o[vt][0] * silu(bflo(gv.x)), o[vt][1] * silu(bfhi(gv.x))); wv.y = pk2(o[vt][2] * silu(bflo(gv.y)), o[vt][3] * silu(bfhi(gv.y)));
;                   *(u32x2*)(yp + 16 * vt) = wv; } }
	v_lshlrev_b32_e32 v0, 16, v82
	v_and_b32_e32 v82, 0xffff0000, v82
	v_mul_f32_e32 v84, 0xbfb8aa3b, v0
	v_mul_f32_e32 v85, 0xbfb8aa3b, v82
	v_exp_f32_e32 v84, v84
	v_exp_f32_e32 v85, v85
	s_nop 0
	v_pk_add_f32 v[84:85], v[84:85], 1.0 op_sel_hi:[1,0]
	s_nop 0
	v_div_scale_f32 v86, s[6:7], v85, v85, v82
	v_rcp_f32_e32 v87, v86
	s_nop 0
	v_fma_f32 v88, -v86, v87, 1.0
	v_fmac_f32_e32 v87, v88, v87
	v_div_scale_f32 v88, vcc, v82, v85, v82
	v_mul_f32_e32 v89, v88, v87
	v_fma_f32 v90, -v86, v89, v88
	v_fmac_f32_e32 v89, v90, v87
	v_fma_f32 v86, -v86, v89, v88
	v_div_fmas_f32 v86, v86, v87, v89
	v_div_fixup_f32 v85, v86, v85, v82
	v_div_scale_f32 v82, s[6:7], v84, v84, v0
	v_rcp_f32_e32 v86, v82
	s_nop 0
	v_fma_f32 v87, -v82, v86, 1.0
	v_fmac_f32_e32 v86, v87, v86
	v_div_scale_f32 v87, vcc, v0, v84, v0
	v_mul_f32_e32 v88, v87, v86
	v_fma_f32 v89, -v82, v88, v87
	v_fmac_f32_e32 v88, v89, v86
	v_fma_f32 v82, -v82, v88, v87
	v_div_fmas_f32 v82, v82, v86, v88
	v_div_fixup_f32 v84, v82, v84, v0
	v_pk_mul_f32 v[78:79], v[78:79], v[84:85]
	v_lshlrev_b32_e32 v0, 16, v83
	v_cvt_pk_bf16_f32 v78, v78, v79
	v_and_b32_e32 v79, 0xffff0000, v83
	v_mul_f32_e32 v82, 0xbfb8aa3b, v0
	v_mul_f32_e32 v83, 0xbfb8aa3b, v79
	v_exp_f32_e32 v82, v82
	v_exp_f32_e32 v83, v83
	s_nop 0
	v_pk_add_f32 v[82:83], v[82:83], 1.0 op_sel_hi:[1,0]
	s_nop 0
	v_div_scale_f32 v84, s[6:7], v83, v83, v79
	v_rcp_f32_e32 v85, v84
	s_nop 0
	v_fma_f32 v86, -v84, v85, 1.0
	v_fmac_f32_e32 v85, v86, v85
	v_div_scale_f32 v86, vcc, v79, v83, v79
	v_mul_f32_e32 v87, v86, v85
	v_fma_f32 v88, -v84, v87, v86
	v_fmac_f32_e32 v87, v88, v85
	v_fma_f32 v84, -v84, v87, v86
	v_div_fmas_f32 v84, v84, v85, v87
	v_div_fixup_f32 v83, v84, v83, v79
	v_div_scale_f32 v79, s[6:7], v82, v82, v0
	v_rcp_f32_e32 v84, v79
	s_nop 0
	v_fma_f32 v85, -v79, v84, 1.0
	v_fmac_f32_e32 v84, v85, v84
	v_div_scale_f32 v85, vcc, v0, v82, v0
	v_mul_f32_e32 v86, v85, v84
	v_fma_f32 v87, -v79, v86, v85
	v_fmac_f32_e32 v86, v87, v84
	v_fma_f32 v79, -v79, v86, v85
	v_div_fmas_f32 v79, v79, v84, v86
	v_div_fixup_f32 v82, v79, v82, v0
	v_pk_mul_f32 v[80:81], v[80:81], v[82:83]
	s_nop 0
	v_cvt_pk_bf16_f32 v79, v80, v81
	global_store_dwordx2 v[98:99], v[78:79], off offset:128
	global_load_dwordx2 v[78:79], v[100:101], off offset:160
	s_waitcnt vmcnt(0) lgkmcnt(0)
	v_lshlrev_b32_e32 v0, 16, v78
	v_and_b32_e32 v78, 0xffff0000, v78
	v_mul_f32_e32 v80, 0xbfb8aa3b, v0
	v_mul_f32_e32 v81, 0xbfb8aa3b, v78
	v_exp_f32_e32 v80, v80
	v_exp_f32_e32 v81, v81
	s_nop 0
	v_pk_add_f32 v[80:81], v[80:81], 1.0 op_sel_hi:[1,0]
	s_nop 0
	v_div_scale_f32 v82, s[6:7], v81, v81, v78
	v_rcp_f32_e32 v83, v82
	s_nop 0
	v_fma_f32 v84, -v82, v83, 1.0
	v_fmac_f32_e32 v83, v84, v83
	v_div_scale_f32 v84, vcc, v78, v81, v78
	v_mul_f32_e32 v85, v84, v83
	v_fma_f32 v86, -v82, v85, v84
	v_fmac_f32_e32 v85, v86, v83
	v_fma_f32 v82, -v82, v85, v84
	v_div_fmas_f32 v82, v82, v83, v85
	v_div_fixup_f32 v81, v82, v81, v78
	v_div_scale_f32 v78, s[6:7], v80, v80, v0
	v_rcp_f32_e32 v82, v78
	s_nop 0
	v_fma_f32 v83, -v78, v82, 1.0
	v_fmac_f32_e32 v82, v83, v82
	v_div_scale_f32 v83, vcc, v0, v80, v0
	v_mul_f32_e32 v84, v83, v82
	v_fma_f32 v85, -v78, v84, v83
	v_fmac_f32_e32 v84, v85, v82
	v_fma_f32 v78, -v78, v84, v83
	v_div_fmas_f32 v78, v78, v82, v84
	v_div_fixup_f32 v80, v78, v80, v0
	v_pk_mul_f32 v[74:75], v[74:75], v[80:81]
	v_lshlrev_b32_e32 v0, 16, v79
	v_cvt_pk_bf16_f32 v74, v74, v75
	v_and_b32_e32 v75, 0xffff0000, v79
	v_mul_f32_e32 v78, 0xbfb8aa3b, v0
	v_mul_f32_e32 v79, 0xbfb8aa3b, v75
	v_exp_f32_e32 v78, v78
	v_exp_f32_e32 v79, v79
	s_nop 0
	v_pk_add_f32 v[78:79], v[78:79], 1.0 op_sel_hi:[1,0]
	s_nop 0
	v_div_scale_f32 v80, s[6:7], v79, v79, v75
	v_rcp_f32_e32 v81, v80
	s_nop 0
	v_fma_f32 v82, -v80, v81, 1.0
	v_fmac_f32_e32 v81, v82, v81
	v_div_scale_f32 v82, vcc, v75, v79, v75
	v_mul_f32_e32 v83, v82, v81
	v_fma_f32 v84, -v80, v83, v82
	v_fmac_f32_e32 v83, v84, v81
	v_fma_f32 v80, -v80, v83, v82
	v_div_fmas_f32 v80, v80, v81, v83
	v_div_fixup_f32 v79, v80, v79, v75
	v_div_scale_f32 v75, s[6:7], v78, v78, v0
	v_rcp_f32_e32 v80, v75
	s_nop 0
	v_fma_f32 v81, -v75, v80, 1.0
	v_fmac_f32_e32 v80, v81, v80
	v_div_scale_f32 v81, vcc, v0, v78, v0
	v_mul_f32_e32 v82, v81, v80
	v_fma_f32 v83, -v75, v82, v81
	v_fmac_f32_e32 v82, v83, v80
	v_fma_f32 v75, -v75, v82, v81
	v_div_fmas_f32 v75, v75, v80, v82
	v_div_fixup_f32 v78, v75, v78, v0
	v_pk_mul_f32 v[76:77], v[76:77], v[78:79]
	s_nop 0
	v_cvt_pk_bf16_f32 v75, v76, v77
	global_store_dwordx2 v[98:99], v[74:75], off offset:160
	global_load_dwordx2 v[74:75], v[100:101], off offset:192
	s_waitcnt vmcnt(0) lgkmcnt(0)
; DI unsigned pk2(float lo, float hi) { f32x2_t f = {lo, hi}; bf16x2_t v = __builtin_convertvector(f, bf16x2_t); return __builtin_bit_cast(unsigned, v); }
; DI float silu(float v) { return v / (1.f + __expf(-v)); }
; DI void sb_phase(const Params& P, LAS unsigned char* lds) {
;     ...
;             { const bf16_t* gp = Uall + ((size_t)b * SEQ + tq) * LDU_O + 6144 + h * 128 + 4 * g; bf16_t* yp = (bf16_t*)Uall + ((size_t)b * SEQ + tq) * LDU_O + h * 128 + 4 * g;
; #pragma unroll
;               for (int vt = 0; vt < 8; ++vt) { const u32x2 gv = *(const u32x2*)(gp + 16 * vt);
;                   u32x2 wv; wv.x = pk2(o[vt][0] * silu(bflo(gv.x)), o[vt][1] * silu(bfhi(gv.x))); wv.y = pk2(o[vt][2] * silu(bflo(gv.y)), o[vt][3] * silu(bfhi(gv.y)));
;                   *(u32x2*)(yp + 16 * vt) = wv; } }
;             u = nu; r = 0; R = 0.f;
;             if (u >= 2048) break;
; #pragma unroll
;             for (int ks = 0; ks < 4; ++ks) qb[ks] = qn[ks];
; #pragma unroll
;             for (int vt = 0; vt < 8; ++vt) o[vt] = (f32x4){0.f, 0.f, 0.f, 0.f};
	v_lshlrev_b32_e32 v0, 16, v74
	v_and_b32_e32 v74, 0xffff0000, v74
	v_mul_f32_e32 v76, 0xbfb8aa3b, v0
	v_mul_f32_e32 v77, 0xbfb8aa3b, v74
	v_exp_f32_e32 v76, v76
	v_exp_f32_e32 v77, v77
	s_nop 0
	v_pk_add_f32 v[76:77], v[76:77], 1.0 op_sel_hi:[1,0]
	s_nop 0
	v_div_scale_f32 v78, s[6:7], v77, v77, v74
	v_rcp_f32_e32 v79, v78
	s_nop 0
	v_fma_f32 v80, -v78, v79, 1.0
	v_fmac_f32_e32 v79, v80, v79
	v_div_scale_f32 v80, vcc, v74, v77, v74
	v_mul_f32_e32 v81, v80, v79
	v_fma_f32 v82, -v78, v81, v80
	v_fmac_f32_e32 v81, v82, v79
	v_fma_f32 v78, -v78, v81, v80
	v_div_fmas_f32 v78, v78, v79, v81
	v_div_fixup_f32 v77, v78, v77, v74
	v_div_scale_f32 v74, s[6:7], v76, v76, v0
	v_rcp_f32_e32 v78, v74
	s_nop 0
	v_fma_f32 v79, -v74, v78, 1.0
	v_fmac_f32_e32 v78, v79, v78
	v_div_scale_f32 v79, vcc, v0, v76, v0
	v_mul_f32_e32 v80, v79, v78
	v_fma_f32 v81, -v74, v80, v79
	v_fmac_f32_e32 v80, v81, v78
	v_fma_f32 v74, -v74, v80, v79
	v_div_fmas_f32 v74, v74, v78, v80
	v_div_fixup_f32 v76, v74, v76, v0
	v_pk_mul_f32 v[70:71], v[70:71], v[76:77]
	v_lshlrev_b32_e32 v0, 16, v75
	v_cvt_pk_bf16_f32 v70, v70, v71
	v_and_b32_e32 v71, 0xffff0000, v75
	v_mul_f32_e32 v74, 0xbfb8aa3b, v0
	v_mul_f32_e32 v75, 0xbfb8aa3b, v71
	v_exp_f32_e32 v74, v74
	v_exp_f32_e32 v75, v75
	s_nop 0
	v_pk_add_f32 v[74:75], v[74:75], 1.0 op_sel_hi:[1,0]
	s_nop 0
	v_div_scale_f32 v76, s[6:7], v75, v75, v71
	v_rcp_f32_e32 v77, v76
	s_nop 0
	v_fma_f32 v78, -v76, v77, 1.0
	v_fmac_f32_e32 v77, v78, v77
	v_div_scale_f32 v78, vcc, v71, v75, v71
	v_mul_f32_e32 v79, v78, v77
	v_fma_f32 v80, -v76, v79, v78
	v_fmac_f32_e32 v79, v80, v77
	v_fma_f32 v76, -v76, v79, v78
	v_div_fmas_f32 v76, v76, v77, v79
	v_div_fixup_f32 v75, v76, v75, v71
	v_div_scale_f32 v71, s[6:7], v74, v74, v0
	v_rcp_f32_e32 v76, v71
	s_nop 0
	v_fma_f32 v77, -v71, v76, 1.0
	v_fmac_f32_e32 v76, v77, v76
	v_div_scale_f32 v77, vcc, v0, v74, v0
	v_mul_f32_e32 v78, v77, v76
	v_fma_f32 v79, -v71, v78, v77
	v_fmac_f32_e32 v78, v79, v76
	v_fma_f32 v71, -v71, v78, v77
	v_div_fmas_f32 v71, v71, v76, v78
	v_div_fixup_f32 v74, v71, v74, v0
	v_pk_mul_f32 v[72:73], v[72:73], v[74:75]
	s_nop 0
	v_cvt_pk_bf16_f32 v71, v72, v73
	global_store_dwordx2 v[98:99], v[70:71], off offset:192
	global_load_dwordx2 v[70:71], v[100:101], off offset:224
	s_waitcnt vmcnt(0) lgkmcnt(0)
	v_lshlrev_b32_e32 v0, 16, v70
	v_and_b32_e32 v70, 0xffff0000, v70
	v_mul_f32_e32 v72, 0xbfb8aa3b, v0
	v_mul_f32_e32 v73, 0xbfb8aa3b, v70
	v_exp_f32_e32 v72, v72
	v_exp_f32_e32 v73, v73
	s_nop 0
	v_pk_add_f32 v[72:73], v[72:73], 1.0 op_sel_hi:[1,0]
	s_nop 0
	v_div_scale_f32 v74, s[6:7], v73, v73, v70
	v_rcp_f32_e32 v75, v74
	s_nop 0
	v_fma_f32 v76, -v74, v75, 1.0
	v_fmac_f32_e32 v75, v76, v75
	v_div_scale_f32 v76, vcc, v70, v73, v70
	v_mul_f32_e32 v77, v76, v75
	v_fma_f32 v78, -v74, v77, v76
	v_fmac_f32_e32 v77, v78, v75
	v_fma_f32 v74, -v74, v77, v76
	v_div_fmas_f32 v74, v74, v75, v77
	v_div_fixup_f32 v73, v74, v73, v70
	v_div_scale_f32 v70, s[6:7], v72, v72, v0
	v_rcp_f32_e32 v74, v70
	s_nop 0
	v_fma_f32 v75, -v70, v74, 1.0
	v_fmac_f32_e32 v74, v75, v74
	v_div_scale_f32 v75, vcc, v0, v72, v0
	v_mul_f32_e32 v76, v75, v74
	v_fma_f32 v77, -v70, v76, v75
	v_fmac_f32_e32 v76, v77, v74
	v_fma_f32 v70, -v70, v76, v75
	v_div_fmas_f32 v70, v70, v74, v76
	v_div_fixup_f32 v72, v70, v72, v0
	v_pk_mul_f32 v[34:35], v[34:35], v[72:73]
	v_lshlrev_b32_e32 v0, 16, v71
	v_cvt_pk_bf16_f32 v34, v34, v35
	v_and_b32_e32 v35, 0xffff0000, v71
	v_mul_f32_e32 v70, 0xbfb8aa3b, v0
	v_mul_f32_e32 v71, 0xbfb8aa3b, v35
	v_exp_f32_e32 v70, v70
	v_exp_f32_e32 v71, v71
	s_nop 0
	v_pk_add_f32 v[70:71], v[70:71], 1.0 op_sel_hi:[1,0]
	s_nop 0
	v_div_scale_f32 v72, s[6:7], v71, v71, v35
	v_rcp_f32_e32 v73, v72
	s_nop 0
	v_fma_f32 v74, -v72, v73, 1.0
	v_fmac_f32_e32 v73, v74, v73
	v_div_scale_f32 v74, vcc, v35, v71, v35
	v_mul_f32_e32 v75, v74, v73
	v_fma_f32 v76, -v72, v75, v74
	v_fmac_f32_e32 v75, v76, v73
	v_fma_f32 v72, -v72, v75, v74
	v_div_fmas_f32 v72, v72, v73, v75
	v_div_fixup_f32 v71, v72, v71, v35
	v_div_scale_f32 v35, s[6:7], v70, v70, v0
	v_rcp_f32_e32 v72, v35
	s_cselect_b64 s[6:7], -1, 0
	v_fma_f32 v73, -v35, v72, 1.0
	v_fmac_f32_e32 v72, v73, v72
	v_div_scale_f32 v73, vcc, v0, v70, v0
	v_mul_f32_e32 v74, v73, v72
	v_fma_f32 v75, -v35, v74, v73
	v_fmac_f32_e32 v74, v75, v72
	v_fma_f32 v35, -v35, v74, v73
	v_div_fmas_f32 v35, v35, v72, v74
	v_div_fixup_f32 v70, v35, v70, v0
	v_pk_mul_f32 v[36:37], v[36:37], v[70:71]
	s_nop 0
	v_cvt_pk_bf16_f32 v35, v36, v37
	global_store_dwordx2 v[98:99], v[34:35], off offset:224
	v_mov_b32_e32 v37, 0
	v_mov_b64_e32 v[100:101], v[4:5]
	v_mov_b32_e32 v36, v37
	v_mov_b32_e32 v35, v37
	v_mov_b32_e32 v34, v37
	v_mov_b32_e32 v73, v37
	v_mov_b32_e32 v72, v37
	v_mov_b32_e32 v71, v37
	v_mov_b32_e32 v70, v37
	v_mov_b32_e32 v77, v37
	v_mov_b32_e32 v76, v37
	v_mov_b32_e32 v75, v37
	v_mov_b32_e32 v74, v37
	v_mov_b32_e32 v81, v37
	v_mov_b32_e32 v80, v37
	v_mov_b32_e32 v79, v37
	v_mov_b32_e32 v78, v37
	v_mov_b32_e32 v85, v37
	v_mov_b32_e32 v84, v37
	v_mov_b32_e32 v83, v37
	v_mov_b32_e32 v82, v37
	v_mov_b32_e32 v89, v37
	v_mov_b32_e32 v88, v37
	v_mov_b32_e32 v87, v37
	v_mov_b32_e32 v86, v37
	v_mov_b32_e32 v93, v37
	v_mov_b32_e32 v92, v37
	v_mov_b32_e32 v91, v37
	v_mov_b32_e32 v90, v37
	v_mov_b32_e32 v97, v37
	v_mov_b32_e32 v96, v37
	v_mov_b32_e32 v95, v37
	v_mov_b32_e32 v94, v37
	v_mov_b32_e32 v183, v37
	v_mov_b64_e32 v[98:99], v[2:3]
	s_mov_b32 s59, s35
	s_and_b64 vcc, exec, s[6:7]
	s_cbranch_vccz .LBB0_49
	s_branch .LBB0_48

; #define LAS __attribute__((address_space(3)))
; DI unsigned pk2(float lo, float hi) { f32x2_t f = {lo, hi}; bf16x2_t v = __builtin_convertvector(f, bf16x2_t); return __builtin_bit_cast(unsigned, v); }
; DI void hgrn_passC(const Params& P, LAS unsigned char* lds, int u) {
;     ...
; #pragma unroll
;       for (int dt = 0; dt < 8; ++dt) {
;           u32x2 pw; pw.x = pk2(acc[dt][0], acc[dt][1]); pw.y = pk2(acc[dt][2], acc[dt][3]);
;           *(LAS u32x2*)(ST + (16 * w + r16) * 272 + (16 * dt + 4 * g) * 2) = pw; } }
;     const int row = tid & 31, seg = tid >> 5;
;     const bf16_t* src = U + (size_t)(tok0 + row) * LDU_E + h * 128 + seg * 8;
;     u32x4 rq = *(const u32x4*)(src + 2048), rk = *(const u32x4*)(src + 3072), ri = *(const u32x4*)(src + 4096);
;     float rdec = (tid < 128) ? DEC[(size_t)chunk0 * 1024 + h * 128 + tid] : 1.f;
;     const int nc = tid >> 4, nv0 = (tid & 15) * 8;
;     f32x4 ng0 = *(const f32x4*)(P.hg + h * 128 + nv0), ng1 = *(const f32x4*)(P.hg + h * 128 + nv0 + 4);
.LBB0_90:
	v_mul_lo_u32 v0, v58, s14
	v_add_u32_e32 v69, 0, v0
	v_lshlrev_b32_e32 v0, 3, v138
	v_add_u32_e32 v75, v69, v0
	v_cvt_pk_bf16_f32 v2, v32, v33
	v_cvt_pk_bf16_f32 v3, v34, v35
	v_cvt_pk_bf16_f32 v36, v28, v29
	v_cvt_pk_bf16_f32 v37, v30, v31
	v_add_u32_e32 v0, 0x9800, v75
	ds_write2_b64 v0, v[2:3], v[36:37] offset0:192 offset1:196
	v_cvt_pk_bf16_f32 v2, v24, v25
	v_cvt_pk_bf16_f32 v3, v26, v27
	v_cvt_pk_bf16_f32 v36, v20, v21
	v_cvt_pk_bf16_f32 v37, v22, v23
	s_lshl_b32 s6, s50, 5
	ds_write2_b64 v0, v[2:3], v[36:37] offset0:200 offset1:204
	v_cvt_pk_bf16_f32 v2, v16, v17
	v_cvt_pk_bf16_f32 v3, v18, v19
	v_cvt_pk_bf16_f32 v36, v12, v13
	v_cvt_pk_bf16_f32 v37, v14, v15
	s_and_b32 s6, s6, 0xffffe000
	s_lshl_b32 s7, s37, 8
	ds_write2_b64 v0, v[2:3], v[36:37] offset0:208 offset1:212
	v_cvt_pk_bf16_f32 v2, v8, v9
	v_cvt_pk_bf16_f32 v3, v10, v11
	v_cvt_pk_bf16_f32 v36, v4, v5
	v_cvt_pk_bf16_f32 v37, v6, v7
	s_or_b32 s12, s6, s7
	ds_write2_b64 v0, v[2:3], v[36:37] offset0:216 offset1:220
	v_and_b32_e32 v0, 31, v56
	v_or_b32_e32 v36, s12, v0
	v_mov_b64_e32 v[2:3], s[20:21]
	v_mad_i64_i32 v[2:3], s[6:7], v36, s86, v[2:3]
	s_lshl_b32 s6, s50, 2
	s_and_b32 s8, s6, 0x380
	v_ashrrev_i32_e32 v59, 5, v56
	s_lshl_b32 s10, s8, 1
	v_lshl_add_u64 v[36:37], v[2:3], 0, s[10:11]
	v_lshlrev_b32_e32 v2, 3, v59
	v_ashrrev_i32_e32 v3, 31, v2
	v_lshl_add_u64 v[44:45], v[2:3], 1, v[36:37]
	v_add_co_u32_e32 v40, vcc, 0x1000, v44
	s_ashr_i32 s6, s12, 5
	s_nop 0
	v_addc_co_u32_e32 v41, vcc, 0, v45, vcc
	v_add_co_u32_e32 v44, vcc, 0x2000, v44
	global_load_dwordx4 v[36:39], v[40:41], off
	s_nop 0
	global_load_dwordx4 v[40:43], v[40:41], off offset:2048
	v_addc_co_u32_e32 v45, vcc, 0, v45, vcc
	global_load_dwordx4 v[44:47], v[44:45], off
	v_cmp_gt_i32_e64 s[36:37], s84, v56
	v_cmp_lt_i32_e32 vcc, s52, v56
	s_and_saveexec_b64 s[12:13], vcc
	s_xor_b64 s[34:35], exec, s[12:13]
	s_ashr_i32 s7, s6, 31
	s_lshl_b64 s[12:13], s[6:7], 12
	v_mov_b32_e32 v57, v1
	v_mov_b64_e32 v[60:61], s[12:13]
	s_or_saveexec_b64 s[34:35], s[34:35]
	v_mov_b32_e32 v76, 1.0
	s_xor_b64 exec, exec, s[34:35]
	s_cbranch_execz .LBB0_94
	s_ashr_i32 s7, s6, 31
	s_lshl_b64 s[6:7], s[6:7], 12
	s_add_u32 s12, s18, s6
	s_addc_u32 s13, s19, s7
	s_lshl_b32 s39, s8, 2
	s_add_u32 s12, s12, s39
	s_addc_u32 s13, s13, 0
	v_ashrrev_i32_e32 v57, 31, v56
	v_lshl_add_u64 v[48:49], v[56:57], 2, s[12:13]
	global_load_dword v76, v[48:49], off
	v_mov_b64_e32 v[60:61], s[6:7]

; #define LAS __attribute__((address_space(3)))
; DI unsigned pk2(float lo, float hi) { f32x2_t f = {lo, hi}; bf16x2_t v = __builtin_convertvector(f, bf16x2_t); return __builtin_bit_cast(unsigned, v); }
; DI f32x4 mfma16(bf16x8 a, bf16x8 b, f32x4 c) { return __builtin_amdgcn_mfma_f32_16x16x32_bf16(a, b, c, 0, 0, 0); }
; DI void hgrn_passC(const Params& P, LAS unsigned char* lds, int u) {
;     ...
;         const bf16x8 bi = *(const LAS bf16x8*)(IT + (16 * w + r16) * 80 + g * 16);
; #pragma unroll
;         for (int ci = 0; ci < 2; ++ci) { const bf16x8 a = *(const LAS bf16x8*)(Ps + (16 * ci + r16) * 80 + g * 16);
;             ao[ci] = mfma16(a, bi, ao[ci]);
; #pragma unroll
;             for (int j = 0; j < 4; ++j) Os[(16 * ci + 4 * g + j) * 132 + 16 * w + r16] = ao[ci][j]; }
; #pragma unroll
;         for (int dt = 0; dt < 8; ++dt) {
;             const bf16x8 a = *(const LAS bf16x8*)(KT + (16 * dt + r16) * 80 + g * 16);
;             acc[dt] = mfma16(a, bi, acc[dt]);
;             const f32x4 dv = *(const LAS f32x4*)(dec + 16 * dt + 4 * g);
;             acc[dt] *= dv;
;             u32x2 pw; pw.x = pk2(acc[dt][0], acc[dt][1]); pw.y = pk2(acc[dt][2], acc[dt][3]);
;             *(LAS u32x2*)(ST + (16 * w + r16) * 272 + (16 * dt + 4 * g) * 2) = pw;
;         }
;         __syncthreads();
;         { const f32x4 o0 = *(const LAS f32x4*)(Os + nc * 132 + nv0), o1 = *(const LAS f32x4*)(Os + nc * 132 + nv0 + 4);
;           float ss = (o0.x * o0.x + o0.y * o0.y) + (o0.z * o0.z + o0.w * o0.w) + (o1.x * o1.x + o1.y * o1.y) + (o1.z * o1.z + o1.w * o1.w);
;           ss += __shfl_xor(ss, 1); ss += __shfl_xor(ss, 2); ss += __shfl_xor(ss, 4); ss += __shfl_xor(ss, 8);
.LBB0_95:
	s_or_b64 exec, exec, s[34:35]
	s_waitcnt lgkmcnt(0)
	s_barrier
	ds_read_b128 v[96:99], v90 offset:27648
	ds_read_b128 v[100:103], v91 offset:37888
	v_ashrrev_i32_e32 v73, 31, v72
	s_waitcnt lgkmcnt(0)
	v_mfma_f32_16x16x32_bf16 v[60:63], v[100:103], v[96:99], v[60:63]
	s_mov_b32 s8, 0x9600000
	s_add_u32 s6, s6, 0x60000
	s_addc_u32 s7, s7, 0
	s_nop 4
	ds_write2_b32 v92, v60, v61 offset1:132
	v_add_u32_e32 v60, 0x400, v92
	ds_write2_b32 v60, v62, v63 offset0:8 offset1:140
	ds_read_b128 v[60:63], v93 offset:37888
	v_lshl_add_u64 v[70:71], v[70:71], 0, s[72:73]
	s_cmp_lg_u32 s6, 0x300000
	s_waitcnt lgkmcnt(0)
	v_mfma_f32_16x16x32_bf16 v[60:63], v[60:63], v[96:99], v[64:67]
	s_nop 7
	ds_write_b32 v94, v60
	v_add_u32_e32 v60, 0x2200, v92
	ds_write2_b32 v60, v61, v62 offset0:68 offset1:200
	ds_write_b32 v92, v63 offset:10032
	ds_read_b128 v[60:63], v91 offset:17408
	s_waitcnt lgkmcnt(0)
	v_mfma_f32_16x16x32_bf16 v[32:35], v[60:63], v[96:99], v[32:35]
	ds_read_b128 v[60:63], v77
	s_waitcnt lgkmcnt(0)
	s_nop 5
	v_pk_mul_f32 v[34:35], v[34:35], v[62:63]
	v_pk_mul_f32 v[32:33], v[32:33], v[60:61]
	v_cvt_pk_bf16_f32 v61, v34, v35
	v_cvt_pk_bf16_f32 v60, v32, v33
	ds_write_b64 v75, v[60:61] offset:40448
	ds_read_b128 v[60:63], v93 offset:17408
	s_waitcnt lgkmcnt(0)
	v_mfma_f32_16x16x32_bf16 v[28:31], v[60:63], v[96:99], v[28:31]
	ds_read_b128 v[60:63], v77 offset:64
	s_waitcnt lgkmcnt(0)
	s_nop 5
	v_pk_mul_f32 v[30:31], v[30:31], v[62:63]
	v_pk_mul_f32 v[28:29], v[28:29], v[60:61]
	v_cvt_pk_bf16_f32 v61, v30, v31
	v_cvt_pk_bf16_f32 v60, v28, v29
	ds_write_b64 v95, v[60:61] offset:40448
	ds_read_b128 v[60:63], v91 offset:19968
	s_waitcnt lgkmcnt(0)
	v_mfma_f32_16x16x32_bf16 v[24:27], v[60:63], v[96:99], v[24:27]
	ds_read_b128 v[60:63], v77 offset:128
	s_waitcnt lgkmcnt(0)
	s_nop 5
	v_pk_mul_f32 v[26:27], v[26:27], v[62:63]
	v_pk_mul_f32 v[24:25], v[24:25], v[60:61]
	v_cvt_pk_bf16_f32 v61, v26, v27
	v_cvt_pk_bf16_f32 v60, v24, v25
	ds_write_b64 v75, v[60:61] offset:40512
	ds_read_b128 v[60:63], v91 offset:21248
	s_waitcnt lgkmcnt(0)
	v_mfma_f32_16x16x32_bf16 v[20:23], v[60:63], v[96:99], v[20:23]
	ds_read_b128 v[60:63], v77 offset:192
	s_waitcnt lgkmcnt(0)
	s_nop 5
	v_pk_mul_f32 v[22:23], v[22:23], v[62:63]
	v_pk_mul_f32 v[20:21], v[20:21], v[60:61]
	v_cvt_pk_bf16_f32 v61, v22, v23
	v_cvt_pk_bf16_f32 v60, v20, v21
	ds_write_b64 v75, v[60:61] offset:40544
	ds_read_b128 v[60:63], v91 offset:22528
	s_waitcnt lgkmcnt(0)
	v_mfma_f32_16x16x32_bf16 v[16:19], v[60:63], v[96:99], v[16:19]
	ds_read_b128 v[60:63], v77 offset:256
	s_waitcnt lgkmcnt(0)
	s_nop 5
	v_pk_mul_f32 v[18:19], v[18:19], v[62:63]
	v_pk_mul_f32 v[16:17], v[16:17], v[60:61]
	v_cvt_pk_bf16_f32 v61, v18, v19
	v_cvt_pk_bf16_f32 v60, v16, v17
	ds_write_b64 v75, v[60:61] offset:40576
	ds_read_b128 v[60:63], v91 offset:23808
	s_waitcnt lgkmcnt(0)
	v_mfma_f32_16x16x32_bf16 v[12:15], v[60:63], v[96:99], v[12:15]
	ds_read_b128 v[60:63], v77 offset:320
	s_waitcnt lgkmcnt(0)
	s_nop 5
	v_pk_mul_f32 v[14:15], v[14:15], v[62:63]
	v_pk_mul_f32 v[12:13], v[12:13], v[60:61]
	v_cvt_pk_bf16_f32 v61, v14, v15
	v_cvt_pk_bf16_f32 v60, v12, v13
	ds_write_b64 v75, v[60:61] offset:40608
	ds_read_b128 v[60:63], v91 offset:25088
	s_waitcnt lgkmcnt(0)
	v_mfma_f32_16x16x32_bf16 v[8:11], v[60:63], v[96:99], v[8:11]
	ds_read_b128 v[60:63], v77 offset:384
	s_waitcnt lgkmcnt(0)
	s_nop 5
	v_pk_mul_f32 v[10:11], v[10:11], v[62:63]
	v_pk_mul_f32 v[8:9], v[8:9], v[60:61]
	v_cvt_pk_bf16_f32 v61, v10, v11
	v_cvt_pk_bf16_f32 v60, v8, v9
	ds_write_b64 v75, v[60:61] offset:40640
	ds_read_b128 v[60:63], v91 offset:26368
	s_waitcnt lgkmcnt(0)
	v_mfma_f32_16x16x32_bf16 v[4:7], v[60:63], v[96:99], v[4:7]
	ds_read_b128 v[60:63], v77 offset:448
	s_waitcnt lgkmcnt(0)
	s_nop 5
	v_pk_mul_f32 v[6:7], v[6:7], v[62:63]
	v_pk_mul_f32 v[4:5], v[4:5], v[60:61]
	v_cvt_pk_bf16_f32 v61, v6, v7
	v_cvt_pk_bf16_f32 v60, v4, v5
	ds_write_b64 v75, v[60:61] offset:40672
	s_waitcnt lgkmcnt(0)
	s_barrier
	ds_read_b128 v[64:67], v78
	ds_read_b128 v[60:63], v78 offset:16
	s_waitcnt lgkmcnt(0)
	v_pk_mul_f32 v[96:97], v[66:67], v[66:67]
	v_pk_mul_f32 v[98:99], v[64:65], v[64:65]
	s_nop 0
	v_pk_mov_b32 v[100:101], v[98:99], v[96:97] op_sel:[1,0]
	v_mov_b32_e32 v99, v97
	v_pk_add_f32 v[96:97], v[100:101], v[98:99]
	v_pk_mul_f32 v[98:99], v[62:63], v[62:63]
	v_pk_mul_f32 v[100:101], v[60:61], v[60:61]
	v_mov_b32_e32 v102, v98
	v_mov_b32_e32 v103, v100
	v_mov_b32_e32 v100, v99
	v_pk_add_f32 v[98:99], v[102:103], v[100:101]
	v_add_f32_e32 v74, v96, v97
	v_add_f32_e32 v74, v74, v99
	v_add_f32_e32 v74, v98, v74
	ds_bpermute_b32 v96, v79, v74
	s_waitcnt vmcnt(0)
	v_lshlrev_b32_e32 v98, 16, v56
	v_and_b32_e32 v56, 0xffff0000, v56
	v_mul_f32_e32 v97, 0xbfb8aa3b, v56
	v_exp_f32_e32 v97, v97
	s_waitcnt lgkmcnt(0)
	v_add_f32_e32 v74, v74, v96
	ds_bpermute_b32 v96, v80, v74
	s_waitcnt lgkmcnt(0)
	v_add_f32_e32 v74, v74, v96
	ds_bpermute_b32 v96, v81, v74
	s_waitcnt lgkmcnt(0)
	v_add_f32_e32 v74, v74, v96
	ds_bpermute_b32 v96, v82, v74
	s_waitcnt lgkmcnt(0)
; #define LAS __attribute__((address_space(3)))
; DI unsigned pk2(float lo, float hi) { f32x2_t f = {lo, hi}; bf16x2_t v = __builtin_convertvector(f, bf16x2_t); return __builtin_bit_cast(unsigned, v); }
; DI float silu(float v) { return v / (1.f + __expf(-v)); }
; DI void hgrn_passC(const Params& P, LAS unsigned char* lds, int u) {
;     ...
;         *(LAS u32x4*)(Qs + row * 272 + seg * 16) = rq; *(LAS u32x4*)(Ks + row * 272 + seg * 16) = rk;
;         tr_write8(KT, 80, row * 2, seg * 8, rk); tr_write8(IT, 80, row * 2, seg * 8, ri);
;         if (tid < 128) dec[tid] = rdec;
;         if (ch < 7) { const bf16_t* s2 = src + (size_t)(ch + 1) * 32 * LDU_E; rq = *(const u32x4*)(s2 + 2048); rk = *(const u32x4*)(s2 + 3072); ri = *(const u32x4*)(s2 + 4096);
;             if (tid < 128) rdec = DEC[(size_t)(chunk0 + ch + 1) * 1024 + h * 128 + tid]; }
;     ...
;         { const f32x4 o0 = *(const LAS f32x4*)(Os + nc * 132 + nv0), o1 = *(const LAS f32x4*)(Os + nc * 132 + nv0 + 4);
;           float ss = (o0.x * o0.x + o0.y * o0.y) + (o0.z * o0.z + o0.w * o0.w) + (o1.x * o1.x + o1.y * o1.y) + (o1.z * o1.z + o1.w * o1.w);
;           ss += __shfl_xor(ss, 1); ss += __shfl_xor(ss, 2); ss += __shfl_xor(ss, 4); ss += __shfl_xor(ss, 8);
;           const float r = rsqrtf(ss * (1.f / 128.f) + EPS);
;           u32x4 wv;
;           wv.x = pk2(o0.x * r * ng0.x * silu(bflo(gv.x)), o0.y * r * ng0.y * silu(bfhi(gv.x)));
;           wv.y = pk2(o0.z * r * ng0.z * silu(bflo(gv.y)), o0.w * r * ng0.w * silu(bfhi(gv.y)));
;           wv.z = pk2(o1.x * r * ng1.x * silu(bflo(gv.z)), o1.y * r * ng1.y * silu(bfhi(gv.z)));
;           wv.w = pk2(o1.z * r * ng1.z * silu(bflo(gv.w)), o1.w * r * ng1.w * silu(bfhi(gv.w)));
;           *(u32x4*)(Y + (size_t)(tok0 + ch * 32 + nc) * DM + 1024 + h * 128 + nv0) = wv; }
	v_add_f32_e32 v74, v74, v96
	v_fmamk_f32 v74, v74, 0x3c000000, v229
	v_cmp_gt_f32_e32 vcc, s33, v74
	v_mul_f32_e32 v96, 0x4b800000, v74
	s_nop 0
	v_cndmask_b32_e32 v74, v74, v96, vcc
	v_rsq_f32_e32 v74, v74
	s_nop 0
	v_mul_f32_e32 v96, 0x45800000, v74
	v_cndmask_b32_e32 v74, v74, v96, vcc
	v_mul_f32_e32 v96, 0xbfb8aa3b, v98
	v_exp_f32_e32 v96, v96
	v_pk_mul_f32 v[64:65], v[64:65], v[74:75] op_sel_hi:[1,0]
	v_pk_mul_f32 v[66:67], v[66:67], v[74:75] op_sel_hi:[1,0]
	v_pk_mul_f32 v[64:65], v[48:49], v[64:65]
	v_pk_add_f32 v[96:97], v[96:97], 1.0 op_sel_hi:[1,0]
	v_pk_mul_f32 v[66:67], v[50:51], v[66:67]
	v_div_scale_f32 v99, s[12:13], v97, v97, v56
	v_rcp_f32_e32 v100, v99
	v_pk_mul_f32 v[60:61], v[60:61], v[74:75] op_sel_hi:[1,0]
	v_pk_mul_f32 v[62:63], v[62:63], v[74:75] op_sel_hi:[1,0]
	v_pk_mul_f32 v[60:61], v[52:53], v[60:61]
	v_fma_f32 v101, -v99, v100, 1.0
	v_fmac_f32_e32 v100, v101, v100
	v_div_scale_f32 v101, vcc, v56, v97, v56
	v_mul_f32_e32 v102, v101, v100
	v_fma_f32 v103, -v99, v102, v101
	v_fmac_f32_e32 v102, v103, v100
	v_fma_f32 v99, -v99, v102, v101
	v_div_fmas_f32 v99, v99, v100, v102
	v_div_fixup_f32 v97, v99, v97, v56
	v_div_scale_f32 v56, s[12:13], v96, v96, v98
	v_rcp_f32_e32 v99, v56
	v_pk_mul_f32 v[62:63], v[54:55], v[62:63]
	v_fma_f32 v100, -v56, v99, 1.0
	v_fmac_f32_e32 v99, v100, v99
	v_div_scale_f32 v100, vcc, v98, v96, v98
	v_mul_f32_e32 v101, v100, v99
	v_fma_f32 v102, -v56, v101, v100
	v_fmac_f32_e32 v101, v102, v99
	v_fma_f32 v56, -v56, v101, v100
	v_div_fmas_f32 v56, v56, v99, v101
	v_div_fixup_f32 v96, v56, v96, v98
	v_pk_mul_f32 v[64:65], v[96:97], v[64:65]
	v_lshlrev_b32_e32 v96, 16, v57
	v_and_b32_e32 v57, 0xffff0000, v57
	v_cvt_pk_bf16_f32 v56, v64, v65
	v_mul_f32_e32 v64, 0xbfb8aa3b, v96
	v_mul_f32_e32 v65, 0xbfb8aa3b, v57
	v_exp_f32_e32 v64, v64
	v_exp_f32_e32 v65, v65
	s_nop 0
	v_pk_add_f32 v[64:65], v[64:65], 1.0 op_sel_hi:[1,0]
	s_nop 0
	v_div_scale_f32 v97, s[12:13], v65, v65, v57
	v_rcp_f32_e32 v98, v97
	s_nop 0
	v_fma_f32 v99, -v97, v98, 1.0
	v_fmac_f32_e32 v98, v99, v98
	v_div_scale_f32 v99, vcc, v57, v65, v57
	v_mul_f32_e32 v100, v99, v98
	v_fma_f32 v101, -v97, v100, v99
	v_fmac_f32_e32 v100, v101, v98
	v_fma_f32 v97, -v97, v100, v99
	v_div_fmas_f32 v97, v97, v98, v100
	v_div_fixup_f32 v65, v97, v65, v57
	v_div_scale_f32 v57, s[12:13], v64, v64, v96
	v_rcp_f32_e32 v97, v57
	s_nop 0
	v_fma_f32 v98, -v57, v97, 1.0
	v_fmac_f32_e32 v97, v98, v97
	v_div_scale_f32 v98, vcc, v96, v64, v96
	v_mul_f32_e32 v99, v98, v97
	v_fma_f32 v100, -v57, v99, v98
	v_fmac_f32_e32 v99, v100, v97
	v_fma_f32 v57, -v57, v99, v98
	v_div_fmas_f32 v57, v57, v97, v99
	v_div_fixup_f32 v64, v57, v64, v96
	v_pk_mul_f32 v[64:65], v[64:65], v[66:67]
	v_lshlrev_b32_e32 v66, 16, v58
	v_and_b32_e32 v58, 0xffff0000, v58
	v_cvt_pk_bf16_f32 v57, v64, v65
	v_mul_f32_e32 v64, 0xbfb8aa3b, v66
	v_mul_f32_e32 v65, 0xbfb8aa3b, v58
	v_exp_f32_e32 v64, v64
	v_exp_f32_e32 v65, v65
	s_nop 0
	v_pk_add_f32 v[64:65], v[64:65], 1.0 op_sel_hi:[1,0]
	s_nop 0
	v_div_scale_f32 v67, s[12:13], v65, v65, v58
	v_rcp_f32_e32 v96, v67
	s_nop 0
	v_fma_f32 v97, -v67, v96, 1.0
	v_fmac_f32_e32 v96, v97, v96
	v_div_scale_f32 v97, vcc, v58, v65, v58
	v_mul_f32_e32 v98, v97, v96
	v_fma_f32 v99, -v67, v98, v97
	v_fmac_f32_e32 v98, v99, v96
	v_fma_f32 v67, -v67, v98, v97
	v_div_fmas_f32 v67, v67, v96, v98
	v_div_fixup_f32 v65, v67, v65, v58
	v_div_scale_f32 v58, s[12:13], v64, v64, v66
	v_rcp_f32_e32 v67, v58
	s_nop 0
	v_fma_f32 v96, -v58, v67, 1.0
	v_fmac_f32_e32 v67, v96, v67
	v_div_scale_f32 v96, vcc, v66, v64, v66
	v_mul_f32_e32 v97, v96, v67
	v_fma_f32 v98, -v58, v97, v96
	v_fmac_f32_e32 v97, v98, v67
	v_fma_f32 v58, -v58, v97, v96
	v_div_fmas_f32 v58, v58, v67, v97
	v_div_fixup_f32 v64, v58, v64, v66
	v_pk_mul_f32 v[60:61], v[64:65], v[60:61]
	v_lshlrev_b32_e32 v64, 16, v59
	v_and_b32_e32 v59, 0xffff0000, v59
	v_cvt_pk_bf16_f32 v58, v60, v61
	v_mul_f32_e32 v60, 0xbfb8aa3b, v64
	v_mul_f32_e32 v61, 0xbfb8aa3b, v59
	v_exp_f32_e32 v60, v60
	v_exp_f32_e32 v61, v61
	s_nop 0
	v_pk_add_f32 v[60:61], v[60:61], 1.0 op_sel_hi:[1,0]
	s_nop 0
	v_div_scale_f32 v65, s[12:13], v61, v61, v59
	v_rcp_f32_e32 v66, v65
	s_nop 0
	v_fma_f32 v67, -v65, v66, 1.0
	v_fmac_f32_e32 v66, v67, v66
	v_div_scale_f32 v67, vcc, v59, v61, v59
	v_mul_f32_e32 v74, v67, v66
	v_fma_f32 v96, -v65, v74, v67
	v_fmac_f32_e32 v74, v96, v66
	v_fma_f32 v65, -v65, v74, v67
	v_div_fmas_f32 v65, v65, v66, v74
	v_div_fixup_f32 v61, v65, v61, v59
	v_div_scale_f32 v59, s[12:13], v60, v60, v64
	v_rcp_f32_e32 v65, v59
	s_nop 0
	v_fma_f32 v66, -v59, v65, 1.0
	v_fmac_f32_e32 v65, v66, v65
	v_div_scale_f32 v66, vcc, v64, v60, v64
	v_mul_f32_e32 v67, v66, v65
	v_fma_f32 v74, -v59, v67, v66
	v_fmac_f32_e32 v67, v74, v65
	v_fma_f32 v59, -v59, v67, v66
	v_div_fmas_f32 v59, v59, v65, v67
	v_div_fixup_f32 v60, v59, v60, v64
	v_pk_mul_f32 v[60:61], v[60:61], v[62:63]
	s_nop 0
	v_cvt_pk_bf16_f32 v59, v60, v61
	v_lshlrev_b64 v[60:61], 12, v[72:73]
	v_lshl_add_u64 v[60:61], s[4:5], 0, v[60:61]
	v_lshl_add_u64 v[60:61], v[60:61], 0, s[10:11]
	v_lshl_add_u64 v[60:61], v[60:61], 0, v[0:1]
	v_add_co_u32_e32 v60, vcc, s8, v60
	v_add_u32_e32 v72, 32, v72
	s_nop 0
	v_addc_co_u32_e32 v61, vcc, 0, v61, vcc
	global_store_dwordx4 v[60:61], v[56:59], off offset:2048
	s_cbranch_scc0 .LBB0_85
.LBB0_96:
	s_waitcnt vmcnt(0) lgkmcnt(0)
	ds_write_b128 v85, v[36:39]
	ds_write_b128 v85, v[40:43] offset:8704
	ds_write_b16 v86, v40 offset:17408
	ds_write_b16_d16_hi v86, v40 offset:17488
	ds_write_b16 v86, v41 offset:17568
	ds_write_b16_d16_hi v86, v41 offset:17648
	ds_write_b16 v86, v42 offset:17728
	ds_write_b16_d16_hi v86, v42 offset:17808
	ds_write_b16 v86, v43 offset:17888
	ds_write_b16_d16_hi v86, v43 offset:17968
	ds_write_b16 v86, v44 offset:27648
	ds_write_b16_d16_hi v86, v44 offset:27728
	ds_write_b16 v86, v45 offset:27808
	ds_write_b16_d16_hi v86, v45 offset:27888
	ds_write_b16 v86, v46 offset:27968
	ds_write_b16_d16_hi v86, v46 offset:28048
	ds_write_b16 v86, v47 offset:28128
	ds_write_b16_d16_hi v86, v47 offset:28208
	s_and_saveexec_b64 s[34:35], s[36:37]
	ds_write_b32 v83, v76
	s_or_b64 exec, exec, s[34:35]
	s_cmp_eq_u32 s6, 0x2a0000
	s_cbranch_scc1 .LBB0_102
	v_lshl_add_u64 v[44:45], v[2:3], 0, s[6:7]
	v_add_co_u32_e32 v40, vcc, 0xd661000, v44
	s_nop 1
	v_addc_co_u32_e32 v41, vcc, 0, v45, vcc
	v_add_co_u32_e32 v44, vcc, 0xd662000, v44
	global_load_dwordx4 v[36:39], v[40:41], off
	s_nop 0
	global_load_dwordx4 v[40:43], v[40:41], off offset:2048
	v_addc_co_u32_e32 v45, vcc, 0, v45, vcc
	global_load_dwordx4 v[44:47], v[44:45], off
	s_and_saveexec_b64 s[34:35], s[36:37]
	s_cbranch_execz .LBB0_101
	global_load_dword v76, v[70:71], off

; #define LAS __attribute__((address_space(3)))
; DI unsigned f2bf(float f) { unsigned u = __builtin_bit_cast(unsigned, f); return (u + 0x7fffu + ((u >> 16) & 1u)) >> 16; }
; DI f32x4 mfma16(bf16x8 a, bf16x8 b, f32x4 c) { return __builtin_amdgcn_mfma_f32_16x16x32_bf16(a, b, c, 0, 0, 0); }
; DI void hgrn_passC(const Params& P, LAS unsigned char* lds, int u) {
;     ...
;         if (ch < 7) { const bf16_t* s2 = src + (size_t)(ch + 1) * 32 * LDU_E; rq = *(const u32x4*)(s2 + 2048); rk = *(const u32x4*)(s2 + 3072); ri = *(const u32x4*)(s2 + 4096);
;             if (tid < 128) rdec = DEC[(size_t)(chunk0 + ch + 1) * 1024 + h * 128 + tid]; }
;         const u32x4 gv = *(const u32x4*)(U + (size_t)(tok0 + ch * 32 + nc) * LDU_E + 5120 + h * 128 + nv0);
;         __syncthreads();
;         f32x4 ao[2];
; #pragma unroll
;         for (int ci = 0; ci < 2; ++ci) { ao[ci] = (f32x4){0.f, 0.f, 0.f, 0.f};
; #pragma unroll
;             for (int ks = 0; ks < 4; ++ks) { const bf16x8 a = *(const LAS bf16x8*)(Qs + (16 * ci + r16) * 272 + (32 * ks + 8 * g) * 2);
;                 const bf16x8 bs = *(const LAS bf16x8*)(ST + (16 * w + r16) * 272 + (32 * ks + 8 * g) * 2);
;                 ao[ci] = mfma16(a, bs, ao[ci]); } }
;         if (w < 4) { const int ci = w >> 1, si = w & 1; f32x4 s = (f32x4){0.f, 0.f, 0.f, 0.f};
; #pragma unroll
;             for (int ks = 0; ks < 4; ++ks) { const bf16x8 a = *(const LAS bf16x8*)(Qs + (16 * ci + r16) * 272 + (32 * ks + 8 * g) * 2);
;                 const bf16x8 bk = *(const LAS bf16x8*)(Ks + (16 * si + r16) * 272 + (32 * ks + 8 * g) * 2);
;                 s = mfma16(a, bk, s); }
; #pragma unroll
;             for (int j = 0; j < 4; ++j) { const int c = 16 * ci + 4 * g + j, sidx = 16 * si + r16;
;                 *(LAS bf16_t*)(Ps + c * 80 + sidx * 2) = (bf16_t)f2bf(sidx <= c ? s[j] : 0.f); } }
.LBB0_102:
	v_mov_b64_e32 v[56:57], s[20:21]
	v_mad_i64_i32 v[56:57], s[12:13], v72, s86, v[56:57]
	v_lshl_add_u64 v[56:57], v[56:57], 0, s[10:11]
	v_lshl_add_u64 v[56:57], v[56:57], 0, v[0:1]
	v_add_co_u32_e32 v56, vcc, 0x2000, v56
	v_add_u32_e32 v73, v69, v68
	s_nop 0
	v_addc_co_u32_e32 v57, vcc, 0, v57, vcc
	global_load_dwordx4 v[56:59], v[56:57], off offset:2048
	s_waitcnt lgkmcnt(0)
	s_barrier
	ds_read_b128 v[60:63], v87
	ds_read_b128 v[64:67], v73 offset:40448
	ds_read_b128 v[96:99], v87 offset:64
	ds_read_b128 v[100:103], v73 offset:40512
	s_waitcnt lgkmcnt(0)
	v_mfma_f32_16x16x32_bf16 v[60:63], v[60:63], v[64:67], 0
	v_mfma_f32_16x16x32_bf16 v[60:63], v[96:99], v[100:103], v[60:63]
	ds_read_b128 v[96:99], v87 offset:128
	ds_read_b128 v[104:107], v73 offset:40576
	s_waitcnt lgkmcnt(0)
	v_mfma_f32_16x16x32_bf16 v[60:63], v[96:99], v[104:107], v[60:63]
	ds_read_b128 v[96:99], v87 offset:192
	ds_read_b128 v[108:111], v73 offset:40640
	s_waitcnt lgkmcnt(0)
	v_mfma_f32_16x16x32_bf16 v[60:63], v[96:99], v[108:111], v[60:63]
	ds_read_b128 v[96:99], v87 offset:4352
	s_waitcnt lgkmcnt(0)
	v_mfma_f32_16x16x32_bf16 v[64:67], v[96:99], v[64:67], 0
	ds_read_b128 v[96:99], v87 offset:4416
	s_waitcnt lgkmcnt(0)
	v_mfma_f32_16x16x32_bf16 v[64:67], v[96:99], v[100:103], v[64:67]
	ds_read_b128 v[96:99], v87 offset:4480
	s_waitcnt lgkmcnt(0)
	v_mfma_f32_16x16x32_bf16 v[64:67], v[96:99], v[104:107], v[64:67]
	ds_read_b128 v[96:99], v87 offset:4544
	s_waitcnt lgkmcnt(0)
	v_mfma_f32_16x16x32_bf16 v[64:67], v[96:99], v[108:111], v[64:67]
	s_and_saveexec_b64 s[34:35], s[38:39]
	s_cbranch_execz .LBB0_95
	ds_read_b128 v[96:99], v88
	v_add_u32_e32 v73, v84, v68
	ds_read_b128 v[100:103], v73 offset:8704
	s_waitcnt lgkmcnt(0)
	v_mfma_f32_16x16x32_bf16 v[96:99], v[96:99], v[100:103], 0
	ds_read_b128 v[100:103], v88 offset:64
	ds_read_b128 v[104:107], v73 offset:8768
	s_waitcnt lgkmcnt(0)
	v_mfma_f32_16x16x32_bf16 v[96:99], v[100:103], v[104:107], v[96:99]
	ds_read_b128 v[100:103], v88 offset:128
	ds_read_b128 v[104:107], v73 offset:8832
	s_waitcnt lgkmcnt(0)
	v_mfma_f32_16x16x32_bf16 v[96:99], v[100:103], v[104:107], v[96:99]
	ds_read_b128 v[100:103], v88 offset:192
	ds_read_b128 v[104:107], v73 offset:8896
	s_waitcnt lgkmcnt(0)
	v_mfma_f32_16x16x32_bf16 v[96:99], v[100:103], v[104:107], v[96:99]
	s_nop 7
	v_cndmask_b32_e64 v73, v96, 0, s[40:41]
	v_bfe_u32 v74, v73, 16, 1
	v_add3_u32 v73, v73, v74, s92
	ds_write_b16_d16_hi v89, v73 offset:37888
	v_cndmask_b32_e64 v73, v97, 0, s[42:43]
	v_bfe_u32 v74, v73, 16, 1
	v_add3_u32 v73, v73, v74, s92
	ds_write_b16_d16_hi v89, v73 offset:37968
	v_cndmask_b32_e64 v73, v98, 0, s[44:45]
	v_bfe_u32 v74, v73, 16, 1
	v_add3_u32 v73, v73, v74, s92
	ds_write_b16_d16_hi v89, v73 offset:38048
	v_cndmask_b32_e64 v73, v99, 0, s[46:47]
	v_bfe_u32 v74, v73, 16, 1
	v_add3_u32 v73, v73, v74, s92
	ds_write_b16_d16_hi v89, v73 offset:38128
	s_branch .LBB0_95

; DI unsigned pk2(float lo, float hi) { f32x2_t f = {lo, hi}; bf16x2_t v = __builtin_convertvector(f, bf16x2_t); return __builtin_bit_cast(unsigned, v); }
; template <int WIN> DI void pool_mix_group(const bf16_t* U, bf16_t* MIX, int g, size_t first, size_t stride) {
;     ...
;     for (size_t p = first; p < NTOT; p += stride) {
;         const int t = (int)(p >> 5), c0 = g * 256 + (int)(p & 31) * 8, pos = t & (SEQ - 1);
;         const int n = (pos + 1 < WIN) ? pos + 1 : WIN;
;         const bf16_t* src = U + (size_t)t * LDU_E + c0;
;         u32x4 v[WIN];
; #pragma unroll
;         for (int r = 0; r < WIN; ++r) v[r] = *(const u32x4*)(src - (size_t)(r < n ? r : 0) * LDU_E);
;         float a[8] = {0.f, 0.f, 0.f, 0.f, 0.f, 0.f, 0.f, 0.f};
; #pragma unroll
;         for (int r = 0; r < WIN; ++r) { const float m = (r < n) ? 1.f : 0.f;
;             a[0] += m * bflo(v[r].x); a[1] += m * bfhi(v[r].x); a[2] += m * bflo(v[r].y); a[3] += m * bfhi(v[r].y); a[4] += m * bflo(v[r].z); a[5] += m * bfhi(v[r].z); a[6] += m * bflo(v[r].w); a[7] += m * bfhi(v[r].w); }
;         const float inv = 1.f / (float)n;
;         u32x4 w; w.x = pk2(a[0] * inv - bflo(v[0].x), a[1] * inv - bfhi(v[0].x)); w.y = pk2(a[2] * inv - bflo(v[0].y), a[3] * inv - bfhi(v[0].y));
;         w.z = pk2(a[4] * inv - bflo(v[0].z), a[5] * inv - bfhi(v[0].z)); w.w = pk2(a[6] * inv - bflo(v[0].w), a[7] * inv - bfhi(v[0].w));
;         *(u32x4*)(MIX + (size_t)t * 1024 + c0) = w;
.LBB0_110:
	v_and_b32_e32 v0, 0x3ffe0, v8
	v_alignbit_b32 v12, v9, v8, 5
	v_mov_b64_e32 v[10:11], s[20:21]
	v_lshlrev_b32_e32 v13, 1, v6
	v_cmp_eq_u64_e32 vcc, 0, v[0:1]
	v_mad_u64_u32 v[10:11], s[0:1], v12, s86, v[10:11]
	v_and_b32_e32 v0, 0x1f0, v13
	v_cndmask_b32_e64 v15, -1, 0, vcc
	v_lshl_add_u64 v[16:17], v[10:11], 0, v[0:1]
	v_cndmask_b32_e64 v14, v232, 0, vcc
	global_load_dwordx4 v[10:13], v[16:17], off
	v_lshl_add_u64 v[14:15], v[16:17], 0, v[14:15]
	global_load_dwordx4 v[14:17], v[14:15], off
	v_lshrrev_b64 v[18:19], 5, v[8:9]
	v_cndmask_b32_e64 v20, 1.0, 0, vcc
	v_lshl_add_u64 v[8:9], v[8:9], 0, s[90:91]
	v_lshlrev_b64 v[18:19], 11, v[18:19]
	v_cndmask_b32_e64 v22, 0.5, 1.0, vcc
	v_cmp_lt_u64_e64 s[0:1], s[46:47], v[8:9]
	v_lshl_add_u64 v[18:19], s[30:31], 0, v[18:19]
	v_lshl_add_u64 v[6:7], v[6:7], 0, s[64:65]
	s_or_b64 s[34:35], s[0:1], s[34:35]
	v_lshl_add_u64 v[18:19], v[18:19], 0, v[0:1]
	s_waitcnt vmcnt(0) lgkmcnt(0)
	v_lshlrev_b32_e32 v24, 16, v10
	v_and_b32_e32 v25, 0xffff0000, v10
	v_lshlrev_b32_e32 v10, 16, v11
	v_and_b32_e32 v11, 0xffff0000, v11
	v_lshlrev_b32_e32 v26, 16, v12
	v_and_b32_e32 v27, 0xffff0000, v12
	v_lshlrev_b32_e32 v12, 16, v13
	v_and_b32_e32 v13, 0xffff0000, v13
	v_pk_add_f32 v[28:29], v[24:25], 0 op_sel_hi:[1,0]
	v_lshlrev_b32_e32 v30, 16, v14
	v_and_b32_e32 v31, 0xffff0000, v14
	v_pk_add_f32 v[32:33], v[10:11], 0 op_sel_hi:[1,0]
	v_lshlrev_b32_e32 v14, 16, v15
	v_and_b32_e32 v15, 0xffff0000, v15
	v_pk_add_f32 v[34:35], v[26:27], 0 op_sel_hi:[1,0]
	v_lshlrev_b32_e32 v36, 16, v16
	v_and_b32_e32 v37, 0xffff0000, v16
	v_pk_add_f32 v[38:39], v[12:13], 0 op_sel_hi:[1,0]
	v_lshlrev_b32_e32 v16, 16, v17
	v_and_b32_e32 v17, 0xffff0000, v17
	v_pk_fma_f32 v[28:29], v[20:21], v[30:31], v[28:29] op_sel_hi:[0,1,1]
	v_pk_fma_f32 v[14:15], v[20:21], v[14:15], v[32:33] op_sel_hi:[0,1,1]
	v_pk_fma_f32 v[30:31], v[20:21], v[36:37], v[34:35] op_sel_hi:[0,1,1]
	v_pk_fma_f32 v[16:17], v[20:21], v[16:17], v[38:39] op_sel_hi:[0,1,1]
	v_pk_fma_f32 v[20:21], v[22:23], v[28:29], v[24:25] op_sel_hi:[0,1,1] neg_lo:[0,0,1] neg_hi:[0,0,1]
	v_pk_fma_f32 v[14:15], v[22:23], v[14:15], v[10:11] op_sel_hi:[0,1,1] neg_lo:[0,0,1] neg_hi:[0,0,1]
	v_pk_fma_f32 v[24:25], v[22:23], v[30:31], v[26:27] op_sel_hi:[0,1,1] neg_lo:[0,0,1] neg_hi:[0,0,1]
	v_pk_fma_f32 v[16:17], v[22:23], v[16:17], v[12:13] op_sel_hi:[0,1,1] neg_lo:[0,0,1] neg_hi:[0,0,1]
	v_cvt_pk_bf16_f32 v10, v20, v21
	v_cvt_pk_bf16_f32 v11, v14, v15
	v_cvt_pk_bf16_f32 v12, v24, v25
	v_cvt_pk_bf16_f32 v13, v16, v17
	global_store_dwordx4 v[18:19], v[10:13], off
	s_andn2_b64 exec, exec, s[34:35]
	s_cbranch_execnz .LBB0_110
	s_or_b64 exec, exec, s[34:35]
	s_mov_b64 s[34:35], 0
	v_mov_b64_e32 v[6:7], v[4:5]
	v_mov_b64_e32 v[8:9], v[2:3]
.LBB0_112:
	v_alignbit_b32 v0, v9, v8, 5
	v_mov_b64_e32 v[12:13], s[20:21]
	v_lshrrev_b64 v[10:11], 5, v[8:9]
	v_mad_u64_u32 v[12:13], s[0:1], v0, s86, v[12:13]
	v_lshrrev_b32_e32 v14, 5, v9
	v_lshlrev_b64 v[26:27], 11, v[10:11]
	v_mov_b32_e32 v10, v13
	v_lshlrev_b32_e32 v15, 1, v6
	v_mad_u64_u32 v[10:11], s[12:13], v14, s86, v[10:11]
	v_and_b32_e32 v28, 0x1fff, v0
	v_and_b32_e32 v0, 0x1f0, v15
	v_mov_b32_e32 v13, v10
	v_lshl_add_u64 v[20:21], v[12:13], 0, v[0:1]
	v_cmp_eq_u32_e32 vcc, 0, v28
	v_cmp_gt_u32_e64 s[0:1], 2, v28
	v_cmp_gt_u32_e64 s[36:37], 3, v28
	global_load_dwordx4 v[10:13], v[20:21], off offset:512
	v_cndmask_b32_e64 v15, -1, 0, vcc
	v_cndmask_b32_e64 v17, -1, 0, s[0:1]
	v_cndmask_b32_e64 v19, -1, 0, s[36:37]
	v_cndmask_b32_e64 v14, v232, 0, vcc
	v_cndmask_b32_e64 v16, v233, 0, s[0:1]
	v_cndmask_b32_e64 v18, v234, 0, s[36:37]
	v_lshl_add_u64 v[14:15], v[20:21], 0, v[14:15]
	v_lshl_add_u64 v[22:23], v[20:21], 0, v[16:17]
	v_lshl_add_u64 v[24:25], v[20:21], 0, v[18:19]
	global_load_dwordx4 v[14:17], v[14:15], off offset:512
	s_nop 0
	global_load_dwordx4 v[18:21], v[22:23], off offset:512
	s_nop 0
	global_load_dwordx4 v[22:25], v[24:25], off offset:512
	v_min_u32_e32 v29, 3, v28
	v_lshl_add_u64 v[26:27], s[30:31], 0, v[26:27]
	v_add_u32_e32 v29, 1, v29
	v_lshl_add_u64 v[26:27], v[26:27], 0, v[0:1]
	v_cvt_f32_ubyte0_e32 v0, v29
	v_cndmask_b32_e64 v30, 1.0, 0, s[0:1]
	v_div_scale_f32 v29, s[0:1], v0, v0, 1.0
	v_rcp_f32_e32 v33, v29
	v_cndmask_b32_e64 v28, 1.0, 0, vcc
	v_div_scale_f32 v31, vcc, 1.0, v0, 1.0
	v_fma_f32 v34, -v29, v33, 1.0
	v_fmac_f32_e32 v33, v34, v33
	v_mul_f32_e32 v34, v31, v33
	v_fma_f32 v35, -v29, v34, v31
	v_fmac_f32_e32 v34, v35, v33
	v_fma_f32 v29, -v29, v34, v31
	v_div_fmas_f32 v29, v29, v33, v34
	v_cndmask_b32_e64 v32, 1.0, 0, s[36:37]
	v_div_fixup_f32 v0, v29, v0, 1.0
	v_lshl_add_u64 v[8:9], v[8:9], 0, s[90:91]
	v_cmp_lt_u64_e64 s[38:39], s[46:47], v[8:9]
	v_lshl_add_u64 v[6:7], v[6:7], 0, s[64:65]
	s_or_b64 s[34:35], s[38:39], s[34:35]
	s_waitcnt vmcnt(0) lgkmcnt(0)
; DI unsigned pk2(float lo, float hi) { f32x2_t f = {lo, hi}; bf16x2_t v = __builtin_convertvector(f, bf16x2_t); return __builtin_bit_cast(unsigned, v); }
; template <int WIN> DI void pool_mix_group(const bf16_t* U, bf16_t* MIX, int g, size_t first, size_t stride) {
;     const size_t NTOT = (size_t)MT * 32;
;     for (size_t p = first; p < NTOT; p += stride) {
;         const int t = (int)(p >> 5), c0 = g * 256 + (int)(p & 31) * 8, pos = t & (SEQ - 1);
;         const int n = (pos + 1 < WIN) ? pos + 1 : WIN;
;         const bf16_t* src = U + (size_t)t * LDU_E + c0;
;         u32x4 v[WIN];
; #pragma unroll
;         for (int r = 0; r < WIN; ++r) v[r] = *(const u32x4*)(src - (size_t)(r < n ? r : 0) * LDU_E);
;         float a[8] = {0.f, 0.f, 0.f, 0.f, 0.f, 0.f, 0.f, 0.f};
; #pragma unroll
;         for (int r = 0; r < WIN; ++r) { const float m = (r < n) ? 1.f : 0.f;
;             a[0] += m * bflo(v[r].x); a[1] += m * bfhi(v[r].x); a[2] += m * bflo(v[r].y); a[3] += m * bfhi(v[r].y); a[4] += m * bflo(v[r].z); a[5] += m * bfhi(v[r].z); a[6] += m * bflo(v[r].w); a[7] += m * bfhi(v[r].w); }
;         const float inv = 1.f / (float)n;
;         u32x4 w; w.x = pk2(a[0] * inv - bflo(v[0].x), a[1] * inv - bfhi(v[0].x)); w.y = pk2(a[2] * inv - bflo(v[0].y), a[3] * inv - bfhi(v[0].y));
;         w.z = pk2(a[4] * inv - bflo(v[0].z), a[5] * inv - bfhi(v[0].z)); w.w = pk2(a[6] * inv - bflo(v[0].w), a[7] * inv - bfhi(v[0].w));
;         *(u32x4*)(MIX + (size_t)t * 1024 + c0) = w;
;     }
; }
	v_lshlrev_b32_e32 v34, 16, v10
	v_and_b32_e32 v35, 0xffff0000, v10
	v_lshlrev_b32_e32 v10, 16, v11
	v_and_b32_e32 v11, 0xffff0000, v11
	v_lshlrev_b32_e32 v36, 16, v12
	v_and_b32_e32 v37, 0xffff0000, v12
	v_lshlrev_b32_e32 v12, 16, v13
	v_and_b32_e32 v13, 0xffff0000, v13
	v_pk_add_f32 v[38:39], v[34:35], 0 op_sel_hi:[1,0]
	v_lshlrev_b32_e32 v40, 16, v14
	v_and_b32_e32 v41, 0xffff0000, v14
	v_pk_add_f32 v[46:47], v[10:11], 0 op_sel_hi:[1,0]
	v_lshlrev_b32_e32 v14, 16, v15
	v_and_b32_e32 v15, 0xffff0000, v15
	v_pk_add_f32 v[48:49], v[36:37], 0 op_sel_hi:[1,0]
	v_lshlrev_b32_e32 v50, 16, v16
	v_and_b32_e32 v51, 0xffff0000, v16
	v_pk_add_f32 v[56:57], v[12:13], 0 op_sel_hi:[1,0]
	v_lshlrev_b32_e32 v16, 16, v17
	v_and_b32_e32 v17, 0xffff0000, v17
	v_lshlrev_b32_e32 v42, 16, v18
	v_and_b32_e32 v43, 0xffff0000, v18
	v_lshlrev_b32_e32 v18, 16, v19
	v_and_b32_e32 v19, 0xffff0000, v19
	v_lshlrev_b32_e32 v52, 16, v20
	v_and_b32_e32 v53, 0xffff0000, v20
	v_lshlrev_b32_e32 v20, 16, v21
	v_and_b32_e32 v21, 0xffff0000, v21
	v_pk_fma_f32 v[38:39], v[28:29], v[40:41], v[38:39] op_sel_hi:[0,1,1]
	v_pk_fma_f32 v[14:15], v[28:29], v[14:15], v[46:47] op_sel_hi:[0,1,1]
	v_pk_fma_f32 v[40:41], v[28:29], v[50:51], v[48:49] op_sel_hi:[0,1,1]
	v_pk_fma_f32 v[16:17], v[28:29], v[16:17], v[56:57] op_sel_hi:[0,1,1]
	v_lshlrev_b32_e32 v44, 16, v22
	v_and_b32_e32 v45, 0xffff0000, v22
	v_lshlrev_b32_e32 v22, 16, v23
	v_and_b32_e32 v23, 0xffff0000, v23
	v_lshlrev_b32_e32 v54, 16, v24
	v_and_b32_e32 v55, 0xffff0000, v24
	v_lshlrev_b32_e32 v24, 16, v25
	v_and_b32_e32 v25, 0xffff0000, v25
	v_pk_fma_f32 v[28:29], v[30:31], v[42:43], v[38:39] op_sel_hi:[0,1,1]
	v_pk_fma_f32 v[14:15], v[30:31], v[18:19], v[14:15] op_sel_hi:[0,1,1]
	v_pk_fma_f32 v[18:19], v[30:31], v[52:53], v[40:41] op_sel_hi:[0,1,1]
	v_pk_fma_f32 v[16:17], v[30:31], v[20:21], v[16:17] op_sel_hi:[0,1,1]
	v_pk_fma_f32 v[20:21], v[32:33], v[44:45], v[28:29] op_sel_hi:[0,1,1]
	v_pk_fma_f32 v[14:15], v[32:33], v[22:23], v[14:15] op_sel_hi:[0,1,1]
	v_pk_fma_f32 v[18:19], v[32:33], v[54:55], v[18:19] op_sel_hi:[0,1,1]
	v_pk_fma_f32 v[16:17], v[32:33], v[24:25], v[16:17] op_sel_hi:[0,1,1]
	v_pk_fma_f32 v[20:21], v[0:1], v[20:21], v[34:35] op_sel_hi:[0,1,1] neg_lo:[0,0,1] neg_hi:[0,0,1]
	v_pk_fma_f32 v[14:15], v[0:1], v[14:15], v[10:11] op_sel_hi:[0,1,1] neg_lo:[0,0,1] neg_hi:[0,0,1]
	v_pk_fma_f32 v[18:19], v[0:1], v[18:19], v[36:37] op_sel_hi:[0,1,1] neg_lo:[0,0,1] neg_hi:[0,0,1]
	v_pk_fma_f32 v[16:17], v[0:1], v[16:17], v[12:13] op_sel_hi:[0,1,1] neg_lo:[0,0,1] neg_hi:[0,0,1]
	v_cvt_pk_bf16_f32 v10, v20, v21
	v_cvt_pk_bf16_f32 v11, v14, v15
	v_cvt_pk_bf16_f32 v12, v18, v19
	v_cvt_pk_bf16_f32 v13, v16, v17
	global_store_dwordx4 v[26:27], v[10:13], off offset:512
	s_andn2_b64 exec, exec, s[34:35]
	s_cbranch_execnz .LBB0_112
	s_or_b64 exec, exec, s[34:35]
	s_mov_b64 s[34:35], 0
	v_mov_b64_e32 v[6:7], v[4:5]
	v_mov_b64_e32 v[8:9], v[2:3]
.LBB0_114:
	v_lshrrev_b64 v[10:11], 5, v[8:9]
	v_alignbit_b32 v0, v9, v8, 5
	v_lshrrev_b32_e32 v16, 5, v9
	v_lshl_add_u64 v[8:9], v[8:9], 0, s[90:91]
	v_mov_b64_e32 v[12:13], s[20:21]
	v_and_b32_e32 v18, 0x1fff, v0
	v_cmp_lt_u64_e32 vcc, s[46:47], v[8:9]
	v_lshlrev_b32_e32 v14, 1, v6
	v_mad_u64_u32 v[12:13], s[0:1], v0, s86, v[12:13]
	s_or_b64 s[34:35], vcc, s[34:35]
	v_cmp_eq_u32_e32 vcc, 0, v18
	v_and_b32_e32 v0, 0x1f0, v14
	v_mov_b32_e32 v14, v13
	v_cndmask_b32_e64 v15, -1, 0, vcc
	v_min_u32_e32 v30, 7, v18
	v_mad_u64_u32 v[28:29], s[12:13], v16, s86, v[14:15]
	v_lshlrev_b64 v[10:11], 11, v[10:11]
	v_add_u32_e32 v29, 1, v30
	v_mov_b32_e32 v13, v28
	v_lshl_add_u64 v[10:11], s[30:31], 0, v[10:11]
	v_cvt_f32_ubyte0_e32 v43, v29
	v_lshl_add_u64 v[28:29], v[12:13], 0, v[0:1]
	v_lshl_add_u64 v[56:57], v[10:11], 0, v[0:1]
	global_load_dwordx4 v[10:13], v[28:29], off offset:1024
	v_cmp_gt_u32_e64 s[0:1], 2, v18
	v_cmp_gt_u32_e64 s[36:37], 3, v18
	v_cmp_gt_u32_e64 s[38:39], 4, v18
	v_cmp_gt_u32_e64 s[40:41], 5, v18
	v_cmp_gt_u32_e64 s[42:43], 6, v18
	v_cmp_gt_u32_e64 s[44:45], 7, v18
	v_cndmask_b32_e64 v17, -1, 0, s[0:1]
	v_cndmask_b32_e64 v19, -1, 0, s[36:37]
	v_cndmask_b32_e64 v21, -1, 0, s[38:39]
	v_cndmask_b32_e64 v23, -1, 0, s[40:41]
	v_cndmask_b32_e64 v25, -1, 0, s[42:43]
	v_cndmask_b32_e64 v27, -1, 0, s[44:45]
	v_cndmask_b32_e64 v14, v232, 0, vcc
	v_cndmask_b32_e64 v16, v233, 0, s[0:1]
	v_cndmask_b32_e64 v18, v234, 0, s[36:37]
	v_cndmask_b32_e64 v20, v235, 0, s[38:39]
	v_cndmask_b32_e64 v22, v236, 0, s[40:41]
	v_cndmask_b32_e64 v24, v237, 0, s[42:43]
	v_cndmask_b32_e64 v26, v238, 0, s[44:45]
	v_lshl_add_u64 v[14:15], v[28:29], 0, v[14:15]
	v_lshl_add_u64 v[30:31], v[28:29], 0, v[16:17]
	v_lshl_add_u64 v[32:33], v[28:29], 0, v[18:19]
	v_lshl_add_u64 v[34:35], v[28:29], 0, v[20:21]
	v_lshl_add_u64 v[36:37], v[28:29], 0, v[22:23]
	v_lshl_add_u64 v[38:39], v[28:29], 0, v[24:25]
	v_lshl_add_u64 v[40:41], v[28:29], 0, v[26:27]
	global_load_dwordx4 v[14:17], v[14:15], off offset:1024
	s_nop 0
	global_load_dwordx4 v[18:21], v[30:31], off offset:1024
	global_load_dwordx4 v[22:25], v[32:33], off offset:1024
	global_load_dwordx4 v[26:29], v[34:35], off offset:1024
	s_nop 0
	global_load_dwordx4 v[30:33], v[36:37], off offset:1024
	s_nop 0
	global_load_dwordx4 v[34:37], v[38:39], off offset:1024
	s_nop 0
	global_load_dwordx4 v[38:41], v[40:41], off offset:1024
	v_cndmask_b32_e64 v44, 1.0, 0, s[0:1]
	v_div_scale_f32 v0, s[0:1], v43, v43, 1.0
	v_rcp_f32_e32 v47, v0
	v_cndmask_b32_e64 v42, 1.0, 0, vcc
	v_div_scale_f32 v45, vcc, 1.0, v43, 1.0
	v_fma_f32 v49, -v0, v47, 1.0
	v_fmac_f32_e32 v47, v49, v47
	v_mul_f32_e32 v49, v45, v47
	v_fma_f32 v51, -v0, v49, v45
	v_fmac_f32_e32 v49, v51, v47
	v_fma_f32 v0, -v0, v49, v45
	v_div_fmas_f32 v0, v0, v47, v49
	v_cndmask_b32_e64 v46, 1.0, 0, s[36:37]
	v_div_fixup_f32 v0, v0, v43, 1.0
	v_cndmask_b32_e64 v48, 1.0, 0, s[38:39]
	v_cndmask_b32_e64 v50, 1.0, 0, s[40:41]
	v_cndmask_b32_e64 v52, 1.0, 0, s[42:43]
	v_cndmask_b32_e64 v54, 1.0, 0, s[44:45]
	v_lshl_add_u64 v[6:7], v[6:7], 0, s[64:65]
	s_waitcnt vmcnt(0) lgkmcnt(0)
; DI unsigned pk2(float lo, float hi) { f32x2_t f = {lo, hi}; bf16x2_t v = __builtin_convertvector(f, bf16x2_t); return __builtin_bit_cast(unsigned, v); }
; template <int WIN> DI void pool_mix_group(const bf16_t* U, bf16_t* MIX, int g, size_t first, size_t stride) {
;     ...
; #pragma unroll
;         for (int r = 0; r < WIN; ++r) { const float m = (r < n) ? 1.f : 0.f;
;             a[0] += m * bflo(v[r].x); a[1] += m * bfhi(v[r].x); a[2] += m * bflo(v[r].y); a[3] += m * bfhi(v[r].y); a[4] += m * bflo(v[r].z); a[5] += m * bfhi(v[r].z); a[6] += m * bflo(v[r].w); a[7] += m * bfhi(v[r].w); }
;         const float inv = 1.f / (float)n;
;         u32x4 w; w.x = pk2(a[0] * inv - bflo(v[0].x), a[1] * inv - bfhi(v[0].x)); w.y = pk2(a[2] * inv - bflo(v[0].y), a[3] * inv - bfhi(v[0].y));
;         w.z = pk2(a[4] * inv - bflo(v[0].z), a[5] * inv - bfhi(v[0].z)); w.w = pk2(a[6] * inv - bflo(v[0].w), a[7] * inv - bfhi(v[0].w));
;         *(u32x4*)(MIX + (size_t)t * 1024 + c0) = w;
	v_lshlrev_b32_e32 v58, 16, v10
	v_and_b32_e32 v59, 0xffff0000, v10
	v_lshlrev_b32_e32 v10, 16, v11
	v_and_b32_e32 v11, 0xffff0000, v11
	v_lshlrev_b32_e32 v60, 16, v12
	v_and_b32_e32 v61, 0xffff0000, v12
	v_lshlrev_b32_e32 v12, 16, v13
	v_and_b32_e32 v13, 0xffff0000, v13
	v_pk_add_f32 v[70:71], v[58:59], 0 op_sel_hi:[1,0]
	v_pk_add_f32 v[82:83], v[10:11], 0 op_sel_hi:[1,0]
	v_pk_add_f32 v[84:85], v[60:61], 0 op_sel_hi:[1,0]
	v_pk_add_f32 v[96:97], v[12:13], 0 op_sel_hi:[1,0]
	v_lshlrev_b32_e32 v62, 16, v14
	v_and_b32_e32 v63, 0xffff0000, v14
	v_lshlrev_b32_e32 v14, 16, v15
	v_and_b32_e32 v15, 0xffff0000, v15
	v_lshlrev_b32_e32 v64, 16, v16
	v_and_b32_e32 v65, 0xffff0000, v16
	v_lshlrev_b32_e32 v16, 16, v17
	v_and_b32_e32 v17, 0xffff0000, v17
	v_lshlrev_b32_e32 v66, 16, v18
	v_and_b32_e32 v67, 0xffff0000, v18
	v_lshlrev_b32_e32 v18, 16, v19
	v_and_b32_e32 v19, 0xffff0000, v19
	v_lshlrev_b32_e32 v68, 16, v20
	v_and_b32_e32 v69, 0xffff0000, v20
	v_lshlrev_b32_e32 v20, 16, v21
	v_and_b32_e32 v21, 0xffff0000, v21
	v_pk_fma_f32 v[62:63], v[42:43], v[62:63], v[70:71] op_sel_hi:[0,1,1]
	v_pk_fma_f32 v[14:15], v[42:43], v[14:15], v[82:83] op_sel_hi:[0,1,1]
	v_pk_fma_f32 v[64:65], v[42:43], v[64:65], v[84:85] op_sel_hi:[0,1,1]
	v_pk_fma_f32 v[16:17], v[42:43], v[16:17], v[96:97] op_sel_hi:[0,1,1]
	v_lshlrev_b32_e32 v72, 16, v22
	v_and_b32_e32 v73, 0xffff0000, v22
	v_lshlrev_b32_e32 v22, 16, v23
	v_and_b32_e32 v23, 0xffff0000, v23
	v_lshlrev_b32_e32 v86, 16, v24
	v_and_b32_e32 v87, 0xffff0000, v24
	v_lshlrev_b32_e32 v24, 16, v25
	v_and_b32_e32 v25, 0xffff0000, v25
	v_pk_fma_f32 v[42:43], v[44:45], v[66:67], v[62:63] op_sel_hi:[0,1,1]
	v_pk_fma_f32 v[14:15], v[44:45], v[18:19], v[14:15] op_sel_hi:[0,1,1]
	v_pk_fma_f32 v[18:19], v[44:45], v[68:69], v[64:65] op_sel_hi:[0,1,1]
	v_pk_fma_f32 v[16:17], v[44:45], v[20:21], v[16:17] op_sel_hi:[0,1,1]
	v_lshlrev_b32_e32 v74, 16, v26
	v_and_b32_e32 v75, 0xffff0000, v26
	v_lshlrev_b32_e32 v26, 16, v27
	v_and_b32_e32 v27, 0xffff0000, v27
	v_lshlrev_b32_e32 v88, 16, v28
	v_and_b32_e32 v89, 0xffff0000, v28
	v_lshlrev_b32_e32 v28, 16, v29
	v_and_b32_e32 v29, 0xffff0000, v29
	v_pk_fma_f32 v[20:21], v[46:47], v[72:73], v[42:43] op_sel_hi:[0,1,1]
	v_pk_fma_f32 v[14:15], v[46:47], v[22:23], v[14:15] op_sel_hi:[0,1,1]
	v_pk_fma_f32 v[18:19], v[46:47], v[86:87], v[18:19] op_sel_hi:[0,1,1]
	v_pk_fma_f32 v[16:17], v[46:47], v[24:25], v[16:17] op_sel_hi:[0,1,1]
	v_lshlrev_b32_e32 v76, 16, v30
	v_and_b32_e32 v77, 0xffff0000, v30
	v_lshlrev_b32_e32 v30, 16, v31
	v_and_b32_e32 v31, 0xffff0000, v31
	v_lshlrev_b32_e32 v90, 16, v32
	v_and_b32_e32 v91, 0xffff0000, v32
	v_lshlrev_b32_e32 v32, 16, v33
	v_and_b32_e32 v33, 0xffff0000, v33
	v_pk_fma_f32 v[20:21], v[48:49], v[74:75], v[20:21] op_sel_hi:[0,1,1]
	v_pk_fma_f32 v[14:15], v[48:49], v[26:27], v[14:15] op_sel_hi:[0,1,1]
	v_pk_fma_f32 v[18:19], v[48:49], v[88:89], v[18:19] op_sel_hi:[0,1,1]
	v_pk_fma_f32 v[16:17], v[48:49], v[28:29], v[16:17] op_sel_hi:[0,1,1]
	v_lshlrev_b32_e32 v78, 16, v34
	v_and_b32_e32 v79, 0xffff0000, v34
	v_lshlrev_b32_e32 v34, 16, v35
	v_and_b32_e32 v35, 0xffff0000, v35
	v_lshlrev_b32_e32 v92, 16, v36
	v_and_b32_e32 v93, 0xffff0000, v36
	v_lshlrev_b32_e32 v36, 16, v37
	v_and_b32_e32 v37, 0xffff0000, v37
	v_pk_fma_f32 v[20:21], v[50:51], v[76:77], v[20:21] op_sel_hi:[0,1,1]
	v_pk_fma_f32 v[14:15], v[50:51], v[30:31], v[14:15] op_sel_hi:[0,1,1]
	v_pk_fma_f32 v[18:19], v[50:51], v[90:91], v[18:19] op_sel_hi:[0,1,1]
	v_pk_fma_f32 v[16:17], v[50:51], v[32:33], v[16:17] op_sel_hi:[0,1,1]
	v_lshlrev_b32_e32 v80, 16, v38
	v_and_b32_e32 v81, 0xffff0000, v38
	v_lshlrev_b32_e32 v38, 16, v39
	v_and_b32_e32 v39, 0xffff0000, v39
	v_lshlrev_b32_e32 v94, 16, v40
	v_and_b32_e32 v95, 0xffff0000, v40
	v_lshlrev_b32_e32 v40, 16, v41
	v_and_b32_e32 v41, 0xffff0000, v41
	v_pk_fma_f32 v[20:21], v[52:53], v[78:79], v[20:21] op_sel_hi:[0,1,1]
	v_pk_fma_f32 v[14:15], v[52:53], v[34:35], v[14:15] op_sel_hi:[0,1,1]
	v_pk_fma_f32 v[18:19], v[52:53], v[92:93], v[18:19] op_sel_hi:[0,1,1]
	v_pk_fma_f32 v[16:17], v[52:53], v[36:37], v[16:17] op_sel_hi:[0,1,1]
	v_pk_fma_f32 v[20:21], v[54:55], v[80:81], v[20:21] op_sel_hi:[0,1,1]
	v_pk_fma_f32 v[14:15], v[54:55], v[38:39], v[14:15] op_sel_hi:[0,1,1]
	v_pk_fma_f32 v[18:19], v[54:55], v[94:95], v[18:19] op_sel_hi:[0,1,1]
	v_pk_fma_f32 v[16:17], v[54:55], v[40:41], v[16:17] op_sel_hi:[0,1,1]
	v_pk_fma_f32 v[20:21], v[0:1], v[20:21], v[58:59] op_sel_hi:[0,1,1] neg_lo:[0,0,1] neg_hi:[0,0,1]
	v_pk_fma_f32 v[14:15], v[0:1], v[14:15], v[10:11] op_sel_hi:[0,1,1] neg_lo:[0,0,1] neg_hi:[0,0,1]
	v_pk_fma_f32 v[18:19], v[0:1], v[18:19], v[60:61] op_sel_hi:[0,1,1] neg_lo:[0,0,1] neg_hi:[0,0,1]
	v_pk_fma_f32 v[16:17], v[0:1], v[16:17], v[12:13] op_sel_hi:[0,1,1] neg_lo:[0,0,1] neg_hi:[0,0,1]
	v_cvt_pk_bf16_f32 v10, v20, v21
	v_cvt_pk_bf16_f32 v11, v14, v15
	v_cvt_pk_bf16_f32 v12, v18, v19
	v_cvt_pk_bf16_f32 v13, v16, v17
	global_store_dwordx4 v[56:57], v[10:13], off offset:1024
	s_andn2_b64 exec, exec, s[34:35]
	s_cbranch_execnz .LBB0_114
	s_or_b64 exec, exec, s[34:35]
	s_mov_b64 s[34:35], 0
	s_mov_b64 s[62:63], 0x7ffff
; template <int WIN> DI void pool_mix_group(const bf16_t* U, bf16_t* MIX, int g, size_t first, size_t stride) {
;     ...
;     for (size_t p = first; p < NTOT; p += stride) {
;         const int t = (int)(p >> 5), c0 = g * 256 + (int)(p & 31) * 8, pos = t & (SEQ - 1);
;         const int n = (pos + 1 < WIN) ? pos + 1 : WIN;
;         const bf16_t* src = U + (size_t)t * LDU_E + c0;
;         u32x4 v[WIN];
; #pragma unroll
;         for (int r = 0; r < WIN; ++r) v[r] = *(const u32x4*)(src - (size_t)(r < n ? r : 0) * LDU_E);
;         float a[8] = {0.f, 0.f, 0.f, 0.f, 0.f, 0.f, 0.f, 0.f};
; #pragma unroll
;         for (int r = 0; r < WIN; ++r) { const float m = (r < n) ? 1.f : 0.f;
;             a[0] += m * bflo(v[r].x); a[1] += m * bfhi(v[r].x); a[2] += m * bflo(v[r].y); a[3] += m * bfhi(v[r].y); a[4] += m * bflo(v[r].z); a[5] += m * bfhi(v[r].z); a[6] += m * bflo(v[r].w); a[7] += m * bfhi(v[r].w); }
.LBB0_116:
	v_alignbit_b32 v0, v3, v2, 5
	v_mov_b64_e32 v[6:7], s[20:21]
	v_and_b32_e32 v134, 0x1fff, v0
	v_mad_u64_u32 v[6:7], s[0:1], v0, s86, v[6:7]
	v_lshlrev_b32_e32 v8, 1, v4
	v_cmp_eq_u32_e64 s[0:1], 0, v134
	v_lshrrev_b32_e32 v10, 5, v3
	v_and_b32_e32 v0, 0x1f0, v8
	v_mov_b32_e32 v8, v7
	v_cndmask_b32_e64 v9, -1, 0, s[0:1]
	v_mad_u64_u32 v[10:11], s[12:13], v10, s86, v[8:9]
	v_mov_b32_e32 v7, v10
	v_cmp_gt_u32_e64 s[56:57], 4, v134
	v_cmp_gt_u32_e64 s[50:51], 7, v134
	v_cmp_gt_u32_e64 s[46:47], 9, v134
	v_lshl_add_u64 v[6:7], v[6:7], 0, v[0:1]
	v_cmp_gt_u32_e64 s[60:61], 2, v134
	v_cmp_gt_u32_e64 s[58:59], 3, v134
	v_cmp_gt_u32_e64 s[54:55], 5, v134
	v_cmp_gt_u32_e64 s[52:53], 6, v134
	v_cmp_gt_u32_e64 s[48:49], 8, v134
	v_cmp_gt_u32_e64 s[44:45], 10, v134
	v_cmp_gt_u32_e32 vcc, 11, v134
	v_cmp_gt_u32_e64 s[42:43], 12, v134
	v_cmp_gt_u32_e64 s[40:41], 13, v134
	v_cmp_gt_u32_e64 s[36:37], 15, v134
	v_cmp_gt_u32_e64 s[38:39], 14, v134
	v_cndmask_b32_e64 v19, -1, 0, s[56:57]
	v_cndmask_b32_e64 v25, -1, 0, s[50:51]
	v_cndmask_b32_e64 v29, -1, 0, s[46:47]
	v_cndmask_b32_e64 v18, v235, 0, s[56:57]
	v_cndmask_b32_e64 v24, v238, 0, s[50:51]
	v_cndmask_b32_e64 v28, v214, 0, s[46:47]
	global_load_dwordx4 v[10:13], v[6:7], off offset:1536
	v_cndmask_b32_e64 v15, -1, 0, s[60:61]
	v_cndmask_b32_e64 v17, -1, 0, s[58:59]
	v_cndmask_b32_e64 v21, -1, 0, s[54:55]
	v_cndmask_b32_e64 v23, -1, 0, s[52:53]
	v_cndmask_b32_e64 v27, -1, 0, s[48:49]
	v_cndmask_b32_e64 v31, -1, 0, s[44:45]
	v_cndmask_b32_e64 v33, -1, 0, vcc
	v_cndmask_b32_e64 v8, v232, 0, s[0:1]
	v_cndmask_b32_e64 v14, v233, 0, s[60:61]
	v_cndmask_b32_e64 v16, v234, 0, s[58:59]
	v_cndmask_b32_e64 v20, v236, 0, s[54:55]
	v_cndmask_b32_e64 v22, v237, 0, s[52:53]
	v_cndmask_b32_e64 v26, v213, 0, s[48:49]
	v_cndmask_b32_e64 v30, v215, 0, s[44:45]
	v_cndmask_b32_e64 v32, v216, 0, vcc
	v_cndmask_b32_e64 v35, -1, 0, s[42:43]
	v_cndmask_b32_e64 v34, v217, 0, s[42:43]
	v_cndmask_b32_e64 v37, -1, 0, s[40:41]
	v_cndmask_b32_e64 v36, v230, 0, s[40:41]
	v_cndmask_b32_e64 v39, -1, 0, s[38:39]
	v_cndmask_b32_e64 v38, v239, 0, s[38:39]
	v_cndmask_b32_e64 v41, -1, 0, s[36:37]
	v_cndmask_b32_e64 v40, v246, 0, s[36:37]
	v_lshl_add_u64 v[46:47], v[6:7], 0, v[18:19]
	v_lshl_add_u64 v[18:19], v[6:7], 0, v[24:25]
	v_lshl_add_u64 v[42:43], v[6:7], 0, v[28:29]
	v_lshl_add_u64 v[8:9], v[6:7], 0, v[8:9]
	v_lshl_add_u64 v[14:15], v[6:7], 0, v[14:15]
	v_lshl_add_u64 v[16:17], v[6:7], 0, v[16:17]
	v_lshl_add_u64 v[48:49], v[6:7], 0, v[20:21]
	v_lshl_add_u64 v[22:23], v[6:7], 0, v[22:23]
	v_lshl_add_u64 v[24:25], v[6:7], 0, v[26:27]
	v_lshl_add_u64 v[30:31], v[6:7], 0, v[30:31]
	v_lshl_add_u64 v[32:33], v[6:7], 0, v[32:33]
	v_lshl_add_u64 v[50:51], v[6:7], 0, v[34:35]
	v_lshl_add_u64 v[52:53], v[6:7], 0, v[36:37]
	v_lshl_add_u64 v[38:39], v[6:7], 0, v[38:39]
	v_lshl_add_u64 v[6:7], v[6:7], 0, v[40:41]
	global_load_dwordx4 v[18:21], v[18:19], off offset:1536
	s_nop 0
	global_load_dwordx4 v[26:29], v[24:25], off offset:1536
	global_load_dwordx4 v[34:37], v[42:43], off offset:1536
	s_nop 0
	global_load_dwordx4 v[42:45], v[30:31], off offset:1536
	global_load_dwordx4 v[54:57], v[8:9], off offset:1536
	global_load_dwordx4 v[58:61], v[14:15], off offset:1536
	global_load_dwordx4 v[62:65], v[16:17], off offset:1536
	global_load_dwordx4 v[66:69], v[46:47], off offset:1536
	global_load_dwordx4 v[70:73], v[48:49], off offset:1536
	global_load_dwordx4 v[74:77], v[22:23], off offset:1536
	global_load_dwordx4 v[78:81], v[32:33], off offset:1536
	global_load_dwordx4 v[82:85], v[50:51], off offset:1536
	global_load_dwordx4 v[98:101], v[52:53], off offset:1536
	global_load_dwordx4 v[126:129], v[38:39], off offset:1536
	global_load_dwordx4 v[130:133], v[6:7], off offset:1536
	v_lshl_add_u64 v[4:5], v[4:5], 0, s[64:65]
	s_waitcnt vmcnt(0) lgkmcnt(0)
	v_lshlrev_b32_e32 v6, 16, v10
	v_and_b32_e32 v7, 0xffff0000, v10
	v_lshlrev_b32_e32 v8, 16, v11
	v_and_b32_e32 v9, 0xffff0000, v11
	v_lshlrev_b32_e32 v10, 16, v12
	v_and_b32_e32 v11, 0xffff0000, v12
	v_lshlrev_b32_e32 v12, 16, v13
	v_and_b32_e32 v13, 0xffff0000, v13
	v_lshlrev_b32_e32 v14, 16, v18
	v_and_b32_e32 v15, 0xffff0000, v18
	v_lshlrev_b32_e32 v16, 16, v19
	v_and_b32_e32 v17, 0xffff0000, v19
	v_lshlrev_b32_e32 v136, 16, v54
	v_and_b32_e32 v137, 0xffff0000, v54
	v_lshlrev_b32_e32 v110, 16, v62
	v_and_b32_e32 v111, 0xffff0000, v62
	v_lshlrev_b32_e32 v104, 16, v66
	v_and_b32_e32 v105, 0xffff0000, v66
	v_lshlrev_b32_e32 v46, 16, v78
	v_and_b32_e32 v47, 0xffff0000, v78
	v_lshlrev_b32_e32 v114, 16, v63
	v_and_b32_e32 v115, 0xffff0000, v63
	v_lshlrev_b32_e32 v106, 16, v67
	v_and_b32_e32 v107, 0xffff0000, v67
	v_lshlrev_b32_e32 v140, 16, v56
	v_and_b32_e32 v141, 0xffff0000, v56
	v_lshlrev_b32_e32 v142, 16, v57
	v_and_b32_e32 v143, 0xffff0000, v57
	v_lshlrev_b32_e32 v118, 16, v64
	v_and_b32_e32 v119, 0xffff0000, v64
	v_lshlrev_b32_e32 v112, 16, v65
	v_and_b32_e32 v113, 0xffff0000, v65
	v_lshlrev_b32_e32 v108, 16, v68
	v_and_b32_e32 v109, 0xffff0000, v68
	v_lshlrev_b32_e32 v96, 16, v69
	v_and_b32_e32 v97, 0xffff0000, v69
	v_lshlrev_b32_e32 v56, 16, v79
	v_and_b32_e32 v57, 0xffff0000, v79
	v_lshlrev_b32_e32 v62, 16, v82
	v_and_b32_e32 v63, 0xffff0000, v82
	v_lshlrev_b32_e32 v64, 16, v83
	v_and_b32_e32 v65, 0xffff0000, v83
	v_lshlrev_b32_e32 v66, 16, v84
	v_and_b32_e32 v67, 0xffff0000, v84
	v_lshlrev_b32_e32 v68, 16, v85
	v_and_b32_e32 v69, 0xffff0000, v85
	v_lshlrev_b32_e32 v78, 16, v126
	v_and_b32_e32 v79, 0xffff0000, v126
	v_lshlrev_b32_e32 v82, 16, v128
	v_and_b32_e32 v83, 0xffff0000, v128
	v_lshlrev_b32_e32 v84, 16, v129
	v_and_b32_e32 v85, 0xffff0000, v129
	v_cndmask_b32_e64 v126, 1.0, 0, s[0:1]
; DI unsigned pk2(float lo, float hi) { f32x2_t f = {lo, hi}; bf16x2_t v = __builtin_convertvector(f, bf16x2_t); return __builtin_bit_cast(unsigned, v); }
; template <int WIN> DI void pool_mix_group(const bf16_t* U, bf16_t* MIX, int g, size_t first, size_t stride) {
;     ...
; #pragma unroll
;         for (int r = 0; r < WIN; ++r) { const float m = (r < n) ? 1.f : 0.f;
;             a[0] += m * bflo(v[r].x); a[1] += m * bfhi(v[r].x); a[2] += m * bflo(v[r].y); a[3] += m * bfhi(v[r].y); a[4] += m * bflo(v[r].z); a[5] += m * bfhi(v[r].z); a[6] += m * bflo(v[r].w); a[7] += m * bfhi(v[r].w); }
;         const float inv = 1.f / (float)n;
;         u32x4 w; w.x = pk2(a[0] * inv - bflo(v[0].x), a[1] * inv - bfhi(v[0].x)); w.y = pk2(a[2] * inv - bflo(v[0].y), a[3] * inv - bfhi(v[0].y));
	v_pk_add_f32 v[128:129], v[6:7], 0 op_sel_hi:[1,0]
	v_lshlrev_b32_e32 v48, 16, v74
	v_and_b32_e32 v49, 0xffff0000, v74
	v_lshlrev_b32_e32 v138, 16, v55
	v_and_b32_e32 v139, 0xffff0000, v55
	v_lshlrev_b32_e32 v52, 16, v75
	v_and_b32_e32 v53, 0xffff0000, v75
	v_lshlrev_b32_e32 v86, 16, v76
	v_and_b32_e32 v87, 0xffff0000, v76
	v_lshlrev_b32_e32 v92, 16, v77
	v_and_b32_e32 v93, 0xffff0000, v77
	v_lshlrev_b32_e32 v74, 16, v100
	v_and_b32_e32 v75, 0xffff0000, v100
	v_lshlrev_b32_e32 v76, 16, v101
	v_and_b32_e32 v77, 0xffff0000, v101
	v_lshlrev_b32_e32 v100, 16, v132
	v_and_b32_e32 v101, 0xffff0000, v132
	v_lshlrev_b32_e32 v102, 16, v133
	v_and_b32_e32 v103, 0xffff0000, v133
	v_pk_fma_f32 v[132:133], v[126:127], v[136:137], v[128:129] op_sel_hi:[0,1,1]
	v_pk_add_f32 v[128:129], v[8:9], 0 op_sel_hi:[1,0]
	v_lshlrev_b32_e32 v50, 16, v70
	v_and_b32_e32 v51, 0xffff0000, v70
	v_lshlrev_b32_e32 v54, 16, v71
	v_and_b32_e32 v55, 0xffff0000, v71
	v_lshlrev_b32_e32 v88, 16, v72
	v_and_b32_e32 v89, 0xffff0000, v72
	v_lshlrev_b32_e32 v94, 16, v73
	v_and_b32_e32 v95, 0xffff0000, v73
	v_lshlrev_b32_e32 v70, 16, v98
	v_and_b32_e32 v71, 0xffff0000, v98
	v_lshlrev_b32_e32 v72, 16, v99
	v_and_b32_e32 v73, 0xffff0000, v99
	v_lshlrev_b32_e32 v90, 16, v130
	v_and_b32_e32 v91, 0xffff0000, v130
	v_lshlrev_b32_e32 v98, 16, v131
	v_and_b32_e32 v99, 0xffff0000, v131
	v_pk_fma_f32 v[130:131], v[126:127], v[138:139], v[128:129] op_sel_hi:[0,1,1]
	v_pk_add_f32 v[128:129], v[10:11], 0 op_sel_hi:[1,0]
	v_pk_add_f32 v[136:137], v[12:13], 0 op_sel_hi:[1,0]
	v_lshlrev_b32_e32 v116, 16, v58
	v_and_b32_e32 v117, 0xffff0000, v58
	v_lshlrev_b32_e32 v120, 16, v59
	v_and_b32_e32 v121, 0xffff0000, v59
	v_lshlrev_b32_e32 v124, 16, v60
	v_and_b32_e32 v125, 0xffff0000, v60
	v_lshlrev_b32_e32 v122, 16, v61
	v_and_b32_e32 v123, 0xffff0000, v61
	v_lshlrev_b32_e32 v58, 16, v80
	v_and_b32_e32 v59, 0xffff0000, v80
	v_lshlrev_b32_e32 v60, 16, v81
	v_and_b32_e32 v61, 0xffff0000, v81
	v_lshlrev_b32_e32 v80, 16, v127
	v_and_b32_e32 v81, 0xffff0000, v127
	v_pk_fma_f32 v[128:129], v[126:127], v[140:141], v[128:129] op_sel_hi:[0,1,1]
	v_pk_fma_f32 v[126:127], v[126:127], v[142:143], v[136:137] op_sel_hi:[0,1,1]
	v_lshrrev_b64 v[136:137], 5, v[2:3]
	v_lshlrev_b64 v[136:137], 11, v[136:137]
	v_min_u32_e32 v142, 15, v134
	v_cndmask_b32_e64 v134, 1.0, 0, s[60:61]
	v_lshl_add_u64 v[138:139], s[30:31], 0, v[136:137]
	v_pk_fma_f32 v[132:133], v[134:135], v[116:117], v[132:133] op_sel_hi:[0,1,1]
	v_cndmask_b32_e64 v136, 1.0, 0, s[58:59]
	v_lshl_add_u64 v[2:3], v[2:3], 0, s[90:91]
	v_pk_fma_f32 v[132:133], v[136:137], v[110:111], v[132:133] op_sel_hi:[0,1,1]
	v_add_u32_e32 v111, 1, v142
	v_cmp_lt_u64_e64 s[0:1], s[62:63], v[2:3]
	v_pk_fma_f32 v[130:131], v[134:135], v[120:121], v[130:131] op_sel_hi:[0,1,1]
	v_cvt_f32_ubyte0_e32 v111, v111
	s_or_b64 s[34:35], s[0:1], s[34:35]
	v_pk_fma_f32 v[128:129], v[134:135], v[124:125], v[128:129] op_sel_hi:[0,1,1]
	v_pk_fma_f32 v[126:127], v[134:135], v[122:123], v[126:127] op_sel_hi:[0,1,1]
	v_pk_fma_f32 v[134:135], v[136:137], v[114:115], v[130:131] op_sel_hi:[0,1,1]
	v_div_scale_f32 v115, s[0:1], v111, v111, 1.0
	v_pk_fma_f32 v[140:141], v[136:137], v[118:119], v[128:129] op_sel_hi:[0,1,1]
	v_rcp_f32_e32 v119, v115
	v_div_scale_f32 v117, s[0:1], 1.0, v111, 1.0
	v_cndmask_b32_e64 v120, 1.0, 0, s[56:57]
	v_fma_f32 v121, -v115, v119, 1.0
	v_fmac_f32_e32 v119, v121, v119
	v_mul_f32_e32 v121, v117, v119
	v_fma_f32 v123, -v115, v121, v117
	v_pk_fma_f32 v[112:113], v[136:137], v[112:113], v[126:127] op_sel_hi:[0,1,1]
	v_fmac_f32_e32 v121, v123, v119
	v_cndmask_b32_e64 v124, 1.0, 0, s[54:55]
	v_pk_fma_f32 v[132:133], v[120:121], v[104:105], v[132:133] op_sel_hi:[0,1,1]
	v_pk_fma_f32 v[134:135], v[120:121], v[106:107], v[134:135] op_sel_hi:[0,1,1]
	v_pk_fma_f32 v[136:137], v[120:121], v[108:109], v[140:141] op_sel_hi:[0,1,1]
	v_pk_fma_f32 v[96:97], v[120:121], v[96:97], v[112:113] op_sel_hi:[0,1,1]
	v_cndmask_b32_e64 v122, 1.0, 0, s[52:53]
	v_pk_fma_f32 v[50:51], v[124:125], v[50:51], v[132:133] op_sel_hi:[0,1,1]
	v_pk_fma_f32 v[54:55], v[124:125], v[54:55], v[134:135] op_sel_hi:[0,1,1]
	v_pk_fma_f32 v[88:89], v[124:125], v[88:89], v[136:137] op_sel_hi:[0,1,1]
	v_pk_fma_f32 v[94:95], v[124:125], v[94:95], v[96:97] op_sel_hi:[0,1,1]
	v_lshlrev_b32_e32 v18, 16, v20
	v_and_b32_e32 v19, 0xffff0000, v20
	v_lshlrev_b32_e32 v20, 16, v21
	v_and_b32_e32 v21, 0xffff0000, v21
	v_cndmask_b32_e64 v116, 1.0, 0, s[50:51]
	v_pk_fma_f32 v[48:49], v[122:123], v[48:49], v[50:51] op_sel_hi:[0,1,1]
	v_pk_fma_f32 v[50:51], v[122:123], v[52:53], v[54:55] op_sel_hi:[0,1,1]
	v_pk_fma_f32 v[52:53], v[122:123], v[86:87], v[88:89] op_sel_hi:[0,1,1]
; DI unsigned pk2(float lo, float hi) { f32x2_t f = {lo, hi}; bf16x2_t v = __builtin_convertvector(f, bf16x2_t); return __builtin_bit_cast(unsigned, v); }
; template <int WIN> DI void pool_mix_group(const bf16_t* U, bf16_t* MIX, int g, size_t first, size_t stride) {
;     ...
; #pragma unroll
;         for (int r = 0; r < WIN; ++r) { const float m = (r < n) ? 1.f : 0.f;
;             a[0] += m * bflo(v[r].x); a[1] += m * bfhi(v[r].x); a[2] += m * bflo(v[r].y); a[3] += m * bfhi(v[r].y); a[4] += m * bflo(v[r].z); a[5] += m * bfhi(v[r].z); a[6] += m * bflo(v[r].w); a[7] += m * bfhi(v[r].w); }
;         const float inv = 1.f / (float)n;
;         u32x4 w; w.x = pk2(a[0] * inv - bflo(v[0].x), a[1] * inv - bfhi(v[0].x)); w.y = pk2(a[2] * inv - bflo(v[0].y), a[3] * inv - bfhi(v[0].y));
;         w.z = pk2(a[4] * inv - bflo(v[0].z), a[5] * inv - bfhi(v[0].z)); w.w = pk2(a[6] * inv - bflo(v[0].w), a[7] * inv - bfhi(v[0].w));
;         *(u32x4*)(MIX + (size_t)t * 1024 + c0) = w;
	v_pk_fma_f32 v[54:55], v[122:123], v[92:93], v[94:95] op_sel_hi:[0,1,1]
	v_lshlrev_b32_e32 v22, 16, v26
	v_and_b32_e32 v23, 0xffff0000, v26
	v_lshlrev_b32_e32 v24, 16, v27
	v_and_b32_e32 v25, 0xffff0000, v27
	v_lshlrev_b32_e32 v26, 16, v28
	v_and_b32_e32 v27, 0xffff0000, v28
	v_lshlrev_b32_e32 v28, 16, v29
	v_and_b32_e32 v29, 0xffff0000, v29
	v_cndmask_b32_e64 v110, 1.0, 0, s[48:49]
	v_fma_f32 v115, -v115, v121, v117
	v_cndmask_b32_e64 v126, 1.0, 0, vcc
	s_mov_b64 vcc, s[0:1]
	v_pk_fma_f32 v[14:15], v[116:117], v[14:15], v[48:49] op_sel_hi:[0,1,1]
	v_pk_fma_f32 v[16:17], v[116:117], v[16:17], v[50:51] op_sel_hi:[0,1,1]
	v_pk_fma_f32 v[18:19], v[116:117], v[18:19], v[52:53] op_sel_hi:[0,1,1]
	v_pk_fma_f32 v[20:21], v[116:117], v[20:21], v[54:55] op_sel_hi:[0,1,1]
	v_lshlrev_b32_e32 v30, 16, v34
	v_and_b32_e32 v31, 0xffff0000, v34
	v_lshlrev_b32_e32 v32, 16, v35
	v_and_b32_e32 v33, 0xffff0000, v35
	v_lshlrev_b32_e32 v34, 16, v36
	v_and_b32_e32 v35, 0xffff0000, v36
	v_lshlrev_b32_e32 v36, 16, v37
	v_and_b32_e32 v37, 0xffff0000, v37
	v_cndmask_b32_e64 v114, 1.0, 0, s[46:47]
	v_div_fmas_f32 v115, v115, v119, v121
	v_pk_fma_f32 v[14:15], v[110:111], v[22:23], v[14:15] op_sel_hi:[0,1,1]
	v_pk_fma_f32 v[16:17], v[110:111], v[24:25], v[16:17] op_sel_hi:[0,1,1]
	v_pk_fma_f32 v[18:19], v[110:111], v[26:27], v[18:19] op_sel_hi:[0,1,1]
	v_pk_fma_f32 v[20:21], v[110:111], v[28:29], v[20:21] op_sel_hi:[0,1,1]
	v_lshlrev_b32_e32 v38, 16, v42
	v_and_b32_e32 v39, 0xffff0000, v42
	v_lshlrev_b32_e32 v40, 16, v43
	v_and_b32_e32 v41, 0xffff0000, v43
	v_lshlrev_b32_e32 v42, 16, v44
	v_and_b32_e32 v43, 0xffff0000, v44
	v_lshlrev_b32_e32 v44, 16, v45
	v_and_b32_e32 v45, 0xffff0000, v45
	v_cndmask_b32_e64 v118, 1.0, 0, s[44:45]
	v_pk_fma_f32 v[14:15], v[114:115], v[30:31], v[14:15] op_sel_hi:[0,1,1]
	v_pk_fma_f32 v[16:17], v[114:115], v[32:33], v[16:17] op_sel_hi:[0,1,1]
	v_pk_fma_f32 v[18:19], v[114:115], v[34:35], v[18:19] op_sel_hi:[0,1,1]
	v_pk_fma_f32 v[20:21], v[114:115], v[36:37], v[20:21] op_sel_hi:[0,1,1]
	v_pk_fma_f32 v[14:15], v[118:119], v[38:39], v[14:15] op_sel_hi:[0,1,1]
	v_pk_fma_f32 v[16:17], v[118:119], v[40:41], v[16:17] op_sel_hi:[0,1,1]
	v_pk_fma_f32 v[18:19], v[118:119], v[42:43], v[18:19] op_sel_hi:[0,1,1]
	v_pk_fma_f32 v[20:21], v[118:119], v[44:45], v[20:21] op_sel_hi:[0,1,1]
	v_cndmask_b32_e64 v128, 1.0, 0, s[42:43]
	v_pk_fma_f32 v[14:15], v[126:127], v[46:47], v[14:15] op_sel_hi:[0,1,1]
	v_pk_fma_f32 v[16:17], v[126:127], v[56:57], v[16:17] op_sel_hi:[0,1,1]
	v_pk_fma_f32 v[18:19], v[126:127], v[58:59], v[18:19] op_sel_hi:[0,1,1]
	v_pk_fma_f32 v[20:21], v[126:127], v[60:61], v[20:21] op_sel_hi:[0,1,1]
	v_cndmask_b32_e64 v130, 1.0, 0, s[40:41]
	v_pk_fma_f32 v[14:15], v[128:129], v[62:63], v[14:15] op_sel_hi:[0,1,1]
	v_pk_fma_f32 v[16:17], v[128:129], v[64:65], v[16:17] op_sel_hi:[0,1,1]
	v_pk_fma_f32 v[18:19], v[128:129], v[66:67], v[18:19] op_sel_hi:[0,1,1]
	v_pk_fma_f32 v[20:21], v[128:129], v[68:69], v[20:21] op_sel_hi:[0,1,1]
	v_cndmask_b32_e64 v106, 1.0, 0, s[38:39]
	v_pk_fma_f32 v[14:15], v[130:131], v[70:71], v[14:15] op_sel_hi:[0,1,1]
	v_pk_fma_f32 v[16:17], v[130:131], v[72:73], v[16:17] op_sel_hi:[0,1,1]
	v_pk_fma_f32 v[18:19], v[130:131], v[74:75], v[18:19] op_sel_hi:[0,1,1]
	v_pk_fma_f32 v[20:21], v[130:131], v[76:77], v[20:21] op_sel_hi:[0,1,1]
	v_cndmask_b32_e64 v108, 1.0, 0, s[36:37]
	v_pk_fma_f32 v[14:15], v[106:107], v[78:79], v[14:15] op_sel_hi:[0,1,1]
	v_pk_fma_f32 v[16:17], v[106:107], v[80:81], v[16:17] op_sel_hi:[0,1,1]
	v_pk_fma_f32 v[18:19], v[106:107], v[82:83], v[18:19] op_sel_hi:[0,1,1]
	v_pk_fma_f32 v[20:21], v[106:107], v[84:85], v[20:21] op_sel_hi:[0,1,1]
	v_lshl_add_u64 v[104:105], v[138:139], 0, v[0:1]
	v_div_fixup_f32 v0, v115, v111, 1.0
	v_pk_fma_f32 v[14:15], v[108:109], v[90:91], v[14:15] op_sel_hi:[0,1,1]
	v_pk_fma_f32 v[16:17], v[108:109], v[98:99], v[16:17] op_sel_hi:[0,1,1]
	v_pk_fma_f32 v[18:19], v[108:109], v[100:101], v[18:19] op_sel_hi:[0,1,1]
	v_pk_fma_f32 v[20:21], v[108:109], v[102:103], v[20:21] op_sel_hi:[0,1,1]
	v_pk_fma_f32 v[6:7], v[0:1], v[14:15], v[6:7] op_sel_hi:[0,1,1] neg_lo:[0,0,1] neg_hi:[0,0,1]
	v_pk_fma_f32 v[8:9], v[0:1], v[16:17], v[8:9] op_sel_hi:[0,1,1] neg_lo:[0,0,1] neg_hi:[0,0,1]
	v_pk_fma_f32 v[10:11], v[0:1], v[18:19], v[10:11] op_sel_hi:[0,1,1] neg_lo:[0,0,1] neg_hi:[0,0,1]
	v_pk_fma_f32 v[12:13], v[0:1], v[20:21], v[12:13] op_sel_hi:[0,1,1] neg_lo:[0,0,1] neg_hi:[0,0,1]
	v_cvt_pk_bf16_f32 v6, v6, v7
	v_cvt_pk_bf16_f32 v7, v8, v9
	v_cvt_pk_bf16_f32 v8, v10, v11
	v_cvt_pk_bf16_f32 v9, v12, v13
	global_store_dwordx4 v[104:105], v[6:9], off offset:1536
	s_andn2_b64 exec, exec, s[34:35]
	s_cbranch_execnz .LBB0_116

; DI unsigned pk2(float lo, float hi) { f32x2_t f = {lo, hi}; bf16x2_t v = __builtin_convertvector(f, bf16x2_t); return __builtin_bit_cast(unsigned, v); }
; DI void hgrn_passA(const Params& P, LAS unsigned char* lds, int u, bool skip_gates) {
;     ...
;     for (int r = skip_gates ? 2 : 0; r < 2; ++r) {
;         const int task = tid + NTH * r, ch = task >> 7, d = task & 127, cc = h * 128 + d;
;         const float lbv = 1.f / (1.f + __expf(P.lb[1024 + cc] - P.lb[cc]));
;         bf16_t* pq = U + (size_t)(tok0 + ch * 32) * LDU_E + 2048 + cc; bf16_t* pf = pq + 1024;
;         bf16_t qraw[32], fraw[32];
; #pragma unroll
;         for (int s = 0; s < 32; ++s) { qraw[s] = pq[(size_t)s * LDU_E]; fraw[s] = pf[(size_t)s * LDU_E]; }
;         float bc = 0.f;
; #pragma unroll
;         for (int s = 0; s < 32; ++s) {
;             const float qv = bf2f(qraw[s]), fl = bf2f(fraw[s]);
;             const float ex = __expf(-fl), sg = __builtin_amdgcn_rcpf(1.f + ex), f = lbv + (1.f - lbv) * sg, kk = (1.f - lbv) * (ex * sg);
;             bc += __logf(f);
;             pq[(size_t)s * LDU_E] = (bf16_t)(pk2(qv * __expf(bc), 0.f) & 0xffffu); pf[(size_t)s * LDU_E] = (bf16_t)(pk2(kk * __expf(-bc), 0.f) & 0xffffu);
.LBB0_125:
	v_cndmask_b32_e64 v8, 0, 1, s[0:1]
	v_cmp_ne_u32_e64 s[36:37], 1, v8
	v_add_u32_e32 v8, s22, v82
	v_ashrrev_i32_e32 v74, 7, v8
	global_load_dword v8, v[4:5], off
	global_load_dword v9, v[2:3], off
	v_lshl_add_u32 v11, v74, 5, s7
	s_movk_i32 s22, 0x200
	s_waitcnt vmcnt(0)
	v_sub_f32_e32 v8, v8, v9
	v_mul_f32_e32 v8, 0x3fb8aa3b, v8
	v_exp_f32_e32 v8, v8
	s_nop 0
	v_add_f32_e32 v10, 1.0, v8
	v_mov_b64_e32 v[8:9], s[20:21]
	v_mad_i64_i32 v[8:9], s[0:1], v11, s86, v[8:9]
	v_div_scale_f32 v11, s[0:1], v10, v10, 1.0
	v_rcp_f32_e32 v12, v11
	v_lshl_add_u64 v[8:9], v[8:9], 0, v[0:1]
	v_lshl_add_u64 v[64:65], v[8:9], 0, s[72:73]
	v_fma_f32 v13, -v11, v12, 1.0
	v_fmac_f32_e32 v12, v13, v12
	v_div_scale_f32 v13, vcc, 1.0, v10, 1.0
	v_mul_f32_e32 v14, v13, v12
	v_fma_f32 v15, -v11, v14, v13
	v_fmac_f32_e32 v14, v15, v12
	v_fma_f32 v11, -v11, v14, v13
	v_div_fmas_f32 v11, v11, v12, v14
	v_add_co_u32_e32 v70, vcc, s9, v8
	v_div_fixup_f32 v75, v11, v10, 1.0
	s_nop 0
	v_addc_co_u32_e32 v71, vcc, 0, v9, vcc
	global_load_ushort v10, v[70:71], off
	global_load_ushort v11, v[64:65], off offset:2048
	v_sub_f32_e32 v76, 1.0, v75
	s_waitcnt vmcnt(0) lgkmcnt(0)
	v_lshlrev_b32_e32 v10, 16, v10
	v_lshlrev_b32_e32 v11, 16, v11
	v_mul_f32_e32 v11, 0xbfb8aa3b, v11
	v_exp_f32_e32 v11, v11
	s_nop 0
	v_add_f32_e32 v12, 1.0, v11
	v_rcp_f32_e32 v12, v12
	s_nop 0
	v_fma_f32 v13, v76, v12, v75
	v_mul_f32_e32 v11, v11, v12
	v_cmp_gt_f32_e32 vcc, s33, v13
	v_mul_f32_e32 v120, v76, v11
	s_nop 0
	v_cndmask_b32_e64 v11, 0, 32, vcc
	v_ldexp_f32 v11, v13, v11
	v_log_f32_e32 v11, v11
	s_nop 0
	v_mul_f32_e32 v12, 0x3f317217, v11
	v_fma_f32 v12, v11, s93, -v12
	v_fmac_f32_e32 v12, 0x3377d1cf, v11
	v_fmac_f32_e32 v12, 0x3f317217, v11
	v_cmp_lt_f32_e64 s[0:1], |v11|, s94
	s_nop 1
	v_cndmask_b32_e64 v11, v11, v12, s[0:1]
	v_cndmask_b32_e32 v12, 0, v247, vcc
	v_add_co_u32_e32 v66, vcc, s29, v8
	v_sub_f32_e32 v11, v11, v12
	s_nop 0
	v_addc_co_u32_e32 v67, vcc, 0, v9, vcc
	global_load_ushort v123, v[66:67], off
	global_load_ushort v124, v[66:67], off offset:2048
	v_add_f32_e32 v121, 0, v11
	v_mul_f32_e32 v11, 0x3fb8aa3b, v121
	v_exp_f32_e32 v11, v11
	s_nop 0
	v_mul_f32_e32 v10, v11, v10
	v_cvt_pk_bf16_f32 v122, v10, s0
	s_movk_i32 s0, 0x7000
	v_add_co_u32_e32 v72, vcc, s0, v8
	s_mov_b32 s0, 0xa000
	s_nop 0
	v_addc_co_u32_e32 v73, vcc, 0, v9, vcc
	v_add_co_u32_e32 v68, vcc, s0, v8
	s_mov_b32 s0, 0xd000
	s_nop 0
	v_addc_co_u32_e32 v69, vcc, 0, v9, vcc
	v_add_co_u32_e32 v62, vcc, s0, v8
	s_mov_b32 s0, 0x13000
	s_nop 0
	v_addc_co_u32_e32 v63, vcc, 0, v9, vcc
	v_add_co_u32_e32 v60, vcc, s95, v8
	global_load_ushort v125, v[72:73], off
	global_load_ushort v126, v[72:73], off offset:2048
	v_addc_co_u32_e32 v61, vcc, 0, v9, vcc
	v_add_co_u32_e32 v58, vcc, s0, v8
	s_mov_b32 s0, 0x16000
	s_nop 0
	v_addc_co_u32_e32 v59, vcc, 0, v9, vcc
	v_add_co_u32_e32 v56, vcc, s0, v8
	s_mov_b32 s0, 0x19000
	s_nop 0
	v_addc_co_u32_e32 v57, vcc, 0, v9, vcc
	v_add_co_u32_e32 v54, vcc, s0, v8
	s_mov_b32 s0, 0x1c000
	s_nop 0
	v_addc_co_u32_e32 v55, vcc, 0, v9, vcc
	v_add_co_u32_e32 v52, vcc, s0, v8
	s_mov_b32 s0, 0x1f000
	s_nop 0
	v_addc_co_u32_e32 v53, vcc, 0, v9, vcc
	v_add_co_u32_e32 v50, vcc, s0, v8
	s_mov_b32 s0, 0x22000
	s_nop 0
	v_addc_co_u32_e32 v51, vcc, 0, v9, vcc
	v_add_co_u32_e32 v48, vcc, s0, v8
	s_mov_b32 s0, 0x25000
	s_nop 0
	v_addc_co_u32_e32 v49, vcc, 0, v9, vcc
	v_add_co_u32_e32 v46, vcc, s0, v8
	s_mov_b32 s0, 0x28000
	s_nop 0
	v_addc_co_u32_e32 v47, vcc, 0, v9, vcc
	v_add_co_u32_e32 v44, vcc, s0, v8
	s_mov_b32 s0, 0x2b000
	s_nop 0
	v_addc_co_u32_e32 v45, vcc, 0, v9, vcc
	v_add_co_u32_e32 v42, vcc, s0, v8
	s_mov_b32 s0, 0x2e000
	s_nop 0
	v_addc_co_u32_e32 v43, vcc, 0, v9, vcc
	v_add_co_u32_e32 v40, vcc, s0, v8
	s_mov_b32 s0, 0x31000
	s_nop 0
	v_addc_co_u32_e32 v41, vcc, 0, v9, vcc
	v_add_co_u32_e32 v38, vcc, s0, v8
	s_mov_b32 s0, 0x34000
	s_nop 0
	v_addc_co_u32_e32 v39, vcc, 0, v9, vcc
	v_add_co_u32_e32 v36, vcc, s0, v8
	s_mov_b32 s0, 0x37000
	s_nop 0
	v_addc_co_u32_e32 v37, vcc, 0, v9, vcc
	v_add_co_u32_e32 v34, vcc, s0, v8
	s_mov_b32 s0, 0x3a000
	s_nop 0
	v_addc_co_u32_e32 v35, vcc, 0, v9, vcc
	v_add_co_u32_e32 v32, vcc, s0, v8
	s_mov_b32 s0, 0x3d000
	s_nop 0
	v_addc_co_u32_e32 v33, vcc, 0, v9, vcc
	v_add_co_u32_e32 v30, vcc, s0, v8
	s_mov_b32 s0, 0x40000
	s_nop 0
	v_addc_co_u32_e32 v31, vcc, 0, v9, vcc
	v_add_co_u32_e32 v28, vcc, s0, v8
	s_mov_b32 s0, 0x43000
	s_nop 0
	v_addc_co_u32_e32 v29, vcc, 0, v9, vcc
	v_add_co_u32_e32 v26, vcc, s0, v8
	s_mov_b32 s0, 0x46000
	s_nop 0
	v_addc_co_u32_e32 v27, vcc, 0, v9, vcc
	v_add_co_u32_e32 v24, vcc, s0, v8
	s_mov_b32 s0, 0x49000
	s_nop 0
	v_addc_co_u32_e32 v25, vcc, 0, v9, vcc
	v_add_co_u32_e32 v22, vcc, s0, v8
	s_mov_b32 s0, 0x4c000
	s_nop 0
	v_addc_co_u32_e32 v23, vcc, 0, v9, vcc
	v_add_co_u32_e32 v20, vcc, s0, v8
	s_mov_b32 s0, 0x4f000
	s_nop 0
	v_addc_co_u32_e32 v21, vcc, 0, v9, vcc
	v_add_co_u32_e32 v18, vcc, s0, v8
	s_mov_b32 s0, 0x52000
	s_nop 0
	v_addc_co_u32_e32 v19, vcc, 0, v9, vcc
	v_add_co_u32_e32 v16, vcc, s0, v8
	s_mov_b32 s0, 0x55000
	s_nop 0
	v_addc_co_u32_e32 v17, vcc, 0, v9, vcc
	v_add_co_u32_e32 v14, vcc, s0, v8
	s_mov_b32 s0, 0x58000
	s_nop 0
	v_addc_co_u32_e32 v15, vcc, 0, v9, vcc
	v_add_co_u32_e32 v12, vcc, s0, v8
	s_mov_b32 s0, 0x5b000
	s_nop 0
	v_addc_co_u32_e32 v13, vcc, 0, v9, vcc
	v_add_co_u32_e32 v10, vcc, s0, v8
	s_mov_b32 s0, 0x5e000
	s_nop 0
	v_addc_co_u32_e32 v11, vcc, 0, v9, vcc
	v_add_co_u32_e32 v8, vcc, s0, v8
	global_load_ushort v127, v[68:69], off
	global_load_ushort v128, v[68:69], off offset:2048
	v_addc_co_u32_e32 v9, vcc, 0, v9, vcc
	global_load_ushort v129, v[62:63], off
	global_load_ushort v130, v[62:63], off offset:2048
; DI unsigned pk2(float lo, float hi) { f32x2_t f = {lo, hi}; bf16x2_t v = __builtin_convertvector(f, bf16x2_t); return __builtin_bit_cast(unsigned, v); }
; DI void hgrn_passA(const Params& P, LAS unsigned char* lds, int u, bool skip_gates) {
;     ...
;         for (int s = 0; s < 32; ++s) { qraw[s] = pq[(size_t)s * LDU_E]; fraw[s] = pf[(size_t)s * LDU_E]; }
;         float bc = 0.f;
; #pragma unroll
;         for (int s = 0; s < 32; ++s) {
;             const float qv = bf2f(qraw[s]), fl = bf2f(fraw[s]);
;             const float ex = __expf(-fl), sg = __builtin_amdgcn_rcpf(1.f + ex), f = lbv + (1.f - lbv) * sg, kk = (1.f - lbv) * (ex * sg);
;             bc += __logf(f);
;             pq[(size_t)s * LDU_E] = (bf16_t)(pk2(qv * __expf(bc), 0.f) & 0xffffu); pf[(size_t)s * LDU_E] = (bf16_t)(pk2(kk * __expf(-bc), 0.f) & 0xffffu);
;         }
	global_load_ushort v131, v[60:61], off
	global_load_ushort v132, v[60:61], off offset:2048
	global_load_ushort v133, v[58:59], off
	global_load_ushort v134, v[58:59], off offset:2048
	global_load_ushort v135, v[56:57], off
	global_load_ushort v136, v[56:57], off offset:2048
	global_load_ushort v137, v[54:55], off
	global_load_ushort v138, v[54:55], off offset:2048
	global_load_ushort v139, v[52:53], off
	global_load_ushort v140, v[52:53], off offset:2048
	global_load_ushort v141, v[50:51], off
	global_load_ushort v142, v[50:51], off offset:2048
	global_load_ushort v118, v[48:49], off
	global_load_ushort v119, v[48:49], off offset:2048
	global_load_ushort v116, v[46:47], off
	global_load_ushort v117, v[46:47], off offset:2048
	global_load_ushort v114, v[44:45], off
	global_load_ushort v115, v[44:45], off offset:2048
	global_load_ushort v112, v[42:43], off
	global_load_ushort v113, v[42:43], off offset:2048
	global_load_ushort v110, v[40:41], off
	global_load_ushort v111, v[40:41], off offset:2048
	global_load_ushort v108, v[38:39], off
	global_load_ushort v109, v[38:39], off offset:2048
	global_load_ushort v106, v[36:37], off
	global_load_ushort v107, v[36:37], off offset:2048
	global_load_ushort v104, v[34:35], off
	global_load_ushort v105, v[34:35], off offset:2048
	global_load_ushort v102, v[32:33], off
	global_load_ushort v103, v[32:33], off offset:2048
	global_load_ushort v100, v[30:31], off
	global_load_ushort v101, v[30:31], off offset:2048
	global_load_ushort v98, v[28:29], off
	global_load_ushort v99, v[28:29], off offset:2048
	global_load_ushort v96, v[26:27], off
	global_load_ushort v97, v[26:27], off offset:2048
	global_load_ushort v94, v[24:25], off
	global_load_ushort v95, v[24:25], off offset:2048
	global_load_ushort v92, v[22:23], off
	global_load_ushort v93, v[22:23], off offset:2048
	global_load_ushort v90, v[20:21], off
	global_load_ushort v91, v[20:21], off offset:2048
	global_load_ushort v88, v[18:19], off
	global_load_ushort v89, v[18:19], off offset:2048
	global_load_ushort v86, v[16:17], off
	global_load_ushort v87, v[16:17], off offset:2048
	global_load_ushort v84, v[14:15], off
	global_load_ushort v85, v[14:15], off offset:2048
	global_load_ushort v81, v[12:13], off
	global_load_ushort v83, v[12:13], off offset:2048
	global_load_ushort v79, v[10:11], off
	global_load_ushort v80, v[10:11], off offset:2048
	global_load_ushort v77, v[8:9], off
	global_load_ushort v78, v[8:9], off offset:2048
	s_nop 0
	global_store_short v[70:71], v122, off
	v_mul_f32_e32 v70, 0xbfb8aa3b, v121
	v_exp_f32_e32 v70, v70
	s_nop 0
	v_mul_f32_e32 v70, v120, v70
	v_cvt_pk_bf16_f32 v70, v70, s0
	global_store_short v[64:65], v70, off offset:2048
	s_waitcnt vmcnt(0) lgkmcnt(0)
	v_lshlrev_b32_e32 v65, 16, v124
	v_mul_f32_e32 v65, 0xbfb8aa3b, v65
	v_exp_f32_e32 v65, v65
	v_lshlrev_b32_e32 v64, 16, v123
	v_add_f32_e32 v70, 1.0, v65
	v_rcp_f32_e32 v70, v70
	s_nop 0
	v_fma_f32 v71, v76, v70, v75
	v_cmp_gt_f32_e32 vcc, s33, v71
	v_mul_f32_e32 v65, v65, v70
	v_mul_f32_e32 v65, v76, v65
	v_cndmask_b32_e64 v70, 0, 32, vcc
	v_ldexp_f32 v70, v71, v70
	v_log_f32_e32 v70, v70
	s_nop 0
	v_mul_f32_e32 v71, 0x3f317217, v70
	v_fma_f32 v71, v70, s93, -v71
	v_fmac_f32_e32 v71, 0x3377d1cf, v70
	v_fmac_f32_e32 v71, 0x3f317217, v70
	v_cmp_lt_f32_e64 s[0:1], |v70|, s94
	s_nop 1
	v_cndmask_b32_e64 v70, v70, v71, s[0:1]
	v_cndmask_b32_e32 v71, 0, v247, vcc
	v_sub_f32_e32 v70, v70, v71
	v_add_f32_e32 v70, v121, v70
	v_mul_f32_e32 v71, 0x3fb8aa3b, v70
	v_exp_f32_e32 v71, v71
	s_nop 0
	v_mul_f32_e32 v64, v71, v64
	v_cvt_pk_bf16_f32 v64, v64, s0
	global_store_short v[66:67], v64, off
	v_mul_f32_e32 v64, 0xbfb8aa3b, v70
	v_exp_f32_e32 v64, v64
	s_nop 0
	v_mul_f32_e32 v64, v65, v64
	v_lshlrev_b32_e32 v65, 16, v126
	v_mul_f32_e32 v65, 0xbfb8aa3b, v65
	v_exp_f32_e32 v65, v65
	v_cvt_pk_bf16_f32 v64, v64, s0
	global_store_short v[66:67], v64, off offset:2048
	v_lshlrev_b32_e32 v64, 16, v125
	v_add_f32_e32 v66, 1.0, v65
	v_rcp_f32_e32 v66, v66
	s_nop 0
	v_fma_f32 v67, v76, v66, v75
	v_cmp_gt_f32_e32 vcc, s33, v67
	v_mul_f32_e32 v65, v65, v66
	v_mul_f32_e32 v65, v76, v65
	v_cndmask_b32_e64 v66, 0, 32, vcc
	v_ldexp_f32 v66, v67, v66
	v_log_f32_e32 v66, v66
	s_nop 0
	v_mul_f32_e32 v67, 0x3f317217, v66
	v_fma_f32 v67, v66, s93, -v67
	v_fmac_f32_e32 v67, 0x3377d1cf, v66
	v_fmac_f32_e32 v67, 0x3f317217, v66
	v_cmp_lt_f32_e64 s[0:1], |v66|, s94
	s_nop 1
	v_cndmask_b32_e64 v66, v66, v67, s[0:1]
	v_cndmask_b32_e32 v67, 0, v247, vcc
	v_sub_f32_e32 v66, v66, v67
	v_add_f32_e32 v66, v70, v66
	v_mul_f32_e32 v67, 0x3fb8aa3b, v66
	v_exp_f32_e32 v67, v67
	s_nop 0
	v_mul_f32_e32 v64, v67, v64
	v_cvt_pk_bf16_f32 v64, v64, s0
	global_store_short v[72:73], v64, off
	v_mul_f32_e32 v64, 0xbfb8aa3b, v66
	v_exp_f32_e32 v64, v64
	s_nop 0
	v_mul_f32_e32 v64, v65, v64
	v_lshlrev_b32_e32 v65, 16, v128
	v_mul_f32_e32 v65, 0xbfb8aa3b, v65
	v_exp_f32_e32 v65, v65
	v_cvt_pk_bf16_f32 v64, v64, s0
	global_store_short v[72:73], v64, off offset:2048
	v_lshlrev_b32_e32 v64, 16, v127
	v_add_f32_e32 v67, 1.0, v65
	v_rcp_f32_e32 v67, v67
	s_nop 0
	v_fma_f32 v70, v76, v67, v75
	v_cmp_gt_f32_e32 vcc, s33, v70
	v_mul_f32_e32 v65, v65, v67
	v_mul_f32_e32 v65, v76, v65
	v_cndmask_b32_e64 v67, 0, 32, vcc
	v_ldexp_f32 v67, v70, v67
	v_log_f32_e32 v67, v67
	s_nop 0
	v_mul_f32_e32 v70, 0x3f317217, v67
	v_fma_f32 v70, v67, s93, -v70
	v_fmac_f32_e32 v70, 0x3377d1cf, v67
	v_fmac_f32_e32 v70, 0x3f317217, v67
	v_cmp_lt_f32_e64 s[0:1], |v67|, s94
	s_nop 1
	v_cndmask_b32_e64 v67, v67, v70, s[0:1]
	v_cndmask_b32_e32 v70, 0, v247, vcc
	v_sub_f32_e32 v67, v67, v70
	v_add_f32_e32 v66, v66, v67
	v_mul_f32_e32 v67, 0x3fb8aa3b, v66
; DI unsigned pk2(float lo, float hi) { f32x2_t f = {lo, hi}; bf16x2_t v = __builtin_convertvector(f, bf16x2_t); return __builtin_bit_cast(unsigned, v); }
; DI void hgrn_passA(const Params& P, LAS unsigned char* lds, int u, bool skip_gates) {
;     ...
;         for (int s = 0; s < 32; ++s) {
;             const float qv = bf2f(qraw[s]), fl = bf2f(fraw[s]);
;             const float ex = __expf(-fl), sg = __builtin_amdgcn_rcpf(1.f + ex), f = lbv + (1.f - lbv) * sg, kk = (1.f - lbv) * (ex * sg);
;             bc += __logf(f);
;             pq[(size_t)s * LDU_E] = (bf16_t)(pk2(qv * __expf(bc), 0.f) & 0xffffu); pf[(size_t)s * LDU_E] = (bf16_t)(pk2(kk * __expf(-bc), 0.f) & 0xffffu);
;         }
	v_exp_f32_e32 v67, v67
	s_nop 0
	v_mul_f32_e32 v64, v67, v64
	v_cvt_pk_bf16_f32 v64, v64, s0
	global_store_short v[68:69], v64, off
	v_mul_f32_e32 v64, 0xbfb8aa3b, v66
	v_exp_f32_e32 v64, v64
	s_nop 0
	v_mul_f32_e32 v64, v65, v64
	v_lshlrev_b32_e32 v65, 16, v130
	v_mul_f32_e32 v65, 0xbfb8aa3b, v65
	v_exp_f32_e32 v65, v65
	v_cvt_pk_bf16_f32 v64, v64, s0
	global_store_short v[68:69], v64, off offset:2048
	v_lshlrev_b32_e32 v64, 16, v129
	v_add_f32_e32 v67, 1.0, v65
	v_rcp_f32_e32 v67, v67
	s_nop 0
	v_fma_f32 v68, v76, v67, v75
	v_cmp_gt_f32_e32 vcc, s33, v68
	v_mul_f32_e32 v65, v65, v67
	v_mul_f32_e32 v65, v76, v65
	v_cndmask_b32_e64 v67, 0, 32, vcc
	v_ldexp_f32 v67, v68, v67
	v_log_f32_e32 v67, v67
	s_nop 0
	v_mul_f32_e32 v68, 0x3f317217, v67
	v_fma_f32 v68, v67, s93, -v68
	v_fmac_f32_e32 v68, 0x3377d1cf, v67
	v_fmac_f32_e32 v68, 0x3f317217, v67
	v_cmp_lt_f32_e64 s[0:1], |v67|, s94
	s_nop 1
	v_cndmask_b32_e64 v67, v67, v68, s[0:1]
	v_cndmask_b32_e32 v68, 0, v247, vcc
	v_sub_f32_e32 v67, v67, v68
	v_add_f32_e32 v66, v66, v67
	v_mul_f32_e32 v67, 0x3fb8aa3b, v66
	v_exp_f32_e32 v67, v67
	s_nop 0
	v_mul_f32_e32 v64, v67, v64
	v_cvt_pk_bf16_f32 v64, v64, s0
	global_store_short v[62:63], v64, off
	v_mul_f32_e32 v64, 0xbfb8aa3b, v66
	v_exp_f32_e32 v64, v64
	s_nop 0
	v_mul_f32_e32 v64, v65, v64
	v_cvt_pk_bf16_f32 v64, v64, s0
	global_store_short v[62:63], v64, off offset:2048
	v_lshlrev_b32_e32 v63, 16, v132
	v_mul_f32_e32 v63, 0xbfb8aa3b, v63
	v_exp_f32_e32 v63, v63
	v_lshlrev_b32_e32 v62, 16, v131
	v_add_f32_e32 v64, 1.0, v63
	v_rcp_f32_e32 v64, v64
	s_nop 0
	v_fma_f32 v65, v76, v64, v75
	v_cmp_gt_f32_e32 vcc, s33, v65
	v_mul_f32_e32 v63, v63, v64
	v_mul_f32_e32 v63, v76, v63
	v_cndmask_b32_e64 v64, 0, 32, vcc
	v_ldexp_f32 v64, v65, v64
	v_log_f32_e32 v64, v64
	s_nop 0
	v_mul_f32_e32 v65, 0x3f317217, v64
	v_fma_f32 v65, v64, s93, -v65
	v_fmac_f32_e32 v65, 0x3377d1cf, v64
	v_fmac_f32_e32 v65, 0x3f317217, v64
	v_cmp_lt_f32_e64 s[0:1], |v64|, s94
	s_nop 1
	v_cndmask_b32_e64 v64, v64, v65, s[0:1]
	v_cndmask_b32_e32 v65, 0, v247, vcc
	v_sub_f32_e32 v64, v64, v65
	v_add_f32_e32 v64, v66, v64
	v_mul_f32_e32 v65, 0x3fb8aa3b, v64
	v_exp_f32_e32 v65, v65
	s_nop 0
	v_mul_f32_e32 v62, v65, v62
	v_cvt_pk_bf16_f32 v62, v62, s0
	global_store_short v[60:61], v62, off
	v_mul_f32_e32 v62, 0xbfb8aa3b, v64
	v_exp_f32_e32 v62, v62
	s_nop 0
	v_mul_f32_e32 v62, v63, v62
	v_cvt_pk_bf16_f32 v62, v62, s0
	global_store_short v[60:61], v62, off offset:2048
	v_lshlrev_b32_e32 v61, 16, v134
	v_mul_f32_e32 v61, 0xbfb8aa3b, v61
	v_exp_f32_e32 v61, v61
	v_lshlrev_b32_e32 v60, 16, v133
	v_add_f32_e32 v62, 1.0, v61
	v_rcp_f32_e32 v62, v62
	s_nop 0
	v_fma_f32 v63, v76, v62, v75
	v_cmp_gt_f32_e32 vcc, s33, v63
	v_mul_f32_e32 v61, v61, v62
	v_mul_f32_e32 v61, v76, v61
	v_cndmask_b32_e64 v62, 0, 32, vcc
	v_ldexp_f32 v62, v63, v62
	v_log_f32_e32 v62, v62
	s_nop 0
	v_mul_f32_e32 v63, 0x3f317217, v62
	v_fma_f32 v63, v62, s93, -v63
	v_fmac_f32_e32 v63, 0x3377d1cf, v62
	v_fmac_f32_e32 v63, 0x3f317217, v62
	v_cmp_lt_f32_e64 s[0:1], |v62|, s94
	s_nop 1
	v_cndmask_b32_e64 v62, v62, v63, s[0:1]
	v_cndmask_b32_e32 v63, 0, v247, vcc
	v_sub_f32_e32 v62, v62, v63
	v_add_f32_e32 v62, v64, v62
	v_mul_f32_e32 v63, 0x3fb8aa3b, v62
	v_exp_f32_e32 v63, v63
	s_nop 0
	v_mul_f32_e32 v60, v63, v60
	v_cvt_pk_bf16_f32 v60, v60, s0
	global_store_short v[58:59], v60, off
	v_mul_f32_e32 v60, 0xbfb8aa3b, v62
	v_exp_f32_e32 v60, v60
	s_nop 0
	v_mul_f32_e32 v60, v61, v60
	v_cvt_pk_bf16_f32 v60, v60, s0
	global_store_short v[58:59], v60, off offset:2048
	v_lshlrev_b32_e32 v59, 16, v136
	v_mul_f32_e32 v59, 0xbfb8aa3b, v59
	v_exp_f32_e32 v59, v59
	v_lshlrev_b32_e32 v58, 16, v135
	v_add_f32_e32 v60, 1.0, v59
	v_rcp_f32_e32 v60, v60
	s_nop 0
	v_fma_f32 v61, v76, v60, v75
	v_cmp_gt_f32_e32 vcc, s33, v61
	v_mul_f32_e32 v59, v59, v60
	v_mul_f32_e32 v59, v76, v59
	v_cndmask_b32_e64 v60, 0, 32, vcc
	v_ldexp_f32 v60, v61, v60
	v_log_f32_e32 v60, v60
	s_nop 0
	v_mul_f32_e32 v61, 0x3f317217, v60
	v_fma_f32 v61, v60, s93, -v61
	v_fmac_f32_e32 v61, 0x3377d1cf, v60
	v_fmac_f32_e32 v61, 0x3f317217, v60
	v_cmp_lt_f32_e64 s[0:1], |v60|, s94
	s_nop 1
	v_cndmask_b32_e64 v60, v60, v61, s[0:1]
	v_cndmask_b32_e32 v61, 0, v247, vcc
	v_sub_f32_e32 v60, v60, v61
	v_add_f32_e32 v60, v62, v60
	v_mul_f32_e32 v61, 0x3fb8aa3b, v60
	v_exp_f32_e32 v61, v61
	s_nop 0
	v_mul_f32_e32 v58, v61, v58
	v_cvt_pk_bf16_f32 v58, v58, s0
	global_store_short v[56:57], v58, off
	v_mul_f32_e32 v58, 0xbfb8aa3b, v60
	v_exp_f32_e32 v58, v58
	s_nop 0
	v_mul_f32_e32 v58, v59, v58
	v_cvt_pk_bf16_f32 v58, v58, s0
	global_store_short v[56:57], v58, off offset:2048
	v_lshlrev_b32_e32 v57, 16, v138
	v_mul_f32_e32 v57, 0xbfb8aa3b, v57
	v_exp_f32_e32 v57, v57
	v_lshlrev_b32_e32 v56, 16, v137
	v_add_f32_e32 v58, 1.0, v57
	v_rcp_f32_e32 v58, v58
	s_nop 0
	v_fma_f32 v59, v76, v58, v75
	v_cmp_gt_f32_e32 vcc, s33, v59
	v_mul_f32_e32 v57, v57, v58
	v_mul_f32_e32 v57, v76, v57
	v_cndmask_b32_e64 v58, 0, 32, vcc
	v_ldexp_f32 v58, v59, v58
	v_log_f32_e32 v58, v58
	s_nop 0
	v_mul_f32_e32 v59, 0x3f317217, v58
	v_fma_f32 v59, v58, s93, -v59
	v_fmac_f32_e32 v59, 0x3377d1cf, v58
	v_fmac_f32_e32 v59, 0x3f317217, v58
	v_cmp_lt_f32_e64 s[0:1], |v58|, s94
	s_nop 1
	v_cndmask_b32_e64 v58, v58, v59, s[0:1]
	v_cndmask_b32_e32 v59, 0, v247, vcc
	v_sub_f32_e32 v58, v58, v59
	v_add_f32_e32 v58, v60, v58
	v_mul_f32_e32 v59, 0x3fb8aa3b, v58
	v_exp_f32_e32 v59, v59
	s_nop 0
	v_mul_f32_e32 v56, v59, v56
	v_cvt_pk_bf16_f32 v56, v56, s0
	global_store_short v[54:55], v56, off
	v_mul_f32_e32 v56, 0xbfb8aa3b, v58
	v_exp_f32_e32 v56, v56
	s_nop 0
	v_mul_f32_e32 v56, v57, v56
	v_cvt_pk_bf16_f32 v56, v56, s0
; DI unsigned pk2(float lo, float hi) { f32x2_t f = {lo, hi}; bf16x2_t v = __builtin_convertvector(f, bf16x2_t); return __builtin_bit_cast(unsigned, v); }
; DI void hgrn_passA(const Params& P, LAS unsigned char* lds, int u, bool skip_gates) {
;     ...
;         for (int s = 0; s < 32; ++s) {
;             const float qv = bf2f(qraw[s]), fl = bf2f(fraw[s]);
;             const float ex = __expf(-fl), sg = __builtin_amdgcn_rcpf(1.f + ex), f = lbv + (1.f - lbv) * sg, kk = (1.f - lbv) * (ex * sg);
;             bc += __logf(f);
;             pq[(size_t)s * LDU_E] = (bf16_t)(pk2(qv * __expf(bc), 0.f) & 0xffffu); pf[(size_t)s * LDU_E] = (bf16_t)(pk2(kk * __expf(-bc), 0.f) & 0xffffu);
;         }
	global_store_short v[54:55], v56, off offset:2048
	v_lshlrev_b32_e32 v55, 16, v140
	v_mul_f32_e32 v55, 0xbfb8aa3b, v55
	v_exp_f32_e32 v55, v55
	v_lshlrev_b32_e32 v54, 16, v139
	v_add_f32_e32 v56, 1.0, v55
	v_rcp_f32_e32 v56, v56
	s_nop 0
	v_fma_f32 v57, v76, v56, v75
	v_cmp_gt_f32_e32 vcc, s33, v57
	v_mul_f32_e32 v55, v55, v56
	v_mul_f32_e32 v55, v76, v55
	v_cndmask_b32_e64 v56, 0, 32, vcc
	v_ldexp_f32 v56, v57, v56
	v_log_f32_e32 v56, v56
	s_nop 0
	v_mul_f32_e32 v57, 0x3f317217, v56
	v_fma_f32 v57, v56, s93, -v57
	v_fmac_f32_e32 v57, 0x3377d1cf, v56
	v_fmac_f32_e32 v57, 0x3f317217, v56
	v_cmp_lt_f32_e64 s[0:1], |v56|, s94
	s_nop 1
	v_cndmask_b32_e64 v56, v56, v57, s[0:1]
	v_cndmask_b32_e32 v57, 0, v247, vcc
	v_sub_f32_e32 v56, v56, v57
	v_add_f32_e32 v56, v58, v56
	v_mul_f32_e32 v57, 0x3fb8aa3b, v56
	v_exp_f32_e32 v57, v57
	s_nop 0
	v_mul_f32_e32 v54, v57, v54
	v_cvt_pk_bf16_f32 v54, v54, s0
	global_store_short v[52:53], v54, off
	v_mul_f32_e32 v54, 0xbfb8aa3b, v56
	v_exp_f32_e32 v54, v54
	s_nop 0
	v_mul_f32_e32 v54, v55, v54
	v_cvt_pk_bf16_f32 v54, v54, s0
	global_store_short v[52:53], v54, off offset:2048
	v_lshlrev_b32_e32 v53, 16, v142
	v_mul_f32_e32 v53, 0xbfb8aa3b, v53
	v_exp_f32_e32 v53, v53
	v_lshlrev_b32_e32 v52, 16, v141
	v_add_f32_e32 v54, 1.0, v53
	v_rcp_f32_e32 v54, v54
	s_nop 0
	v_fma_f32 v55, v76, v54, v75
	v_cmp_gt_f32_e32 vcc, s33, v55
	v_mul_f32_e32 v53, v53, v54
	v_mul_f32_e32 v53, v76, v53
	v_cndmask_b32_e64 v54, 0, 32, vcc
	v_ldexp_f32 v54, v55, v54
	v_log_f32_e32 v54, v54
	s_nop 0
	v_mul_f32_e32 v55, 0x3f317217, v54
	v_fma_f32 v55, v54, s93, -v55
	v_fmac_f32_e32 v55, 0x3377d1cf, v54
	v_fmac_f32_e32 v55, 0x3f317217, v54
	v_cmp_lt_f32_e64 s[0:1], |v54|, s94
	s_nop 1
	v_cndmask_b32_e64 v54, v54, v55, s[0:1]
	v_cndmask_b32_e32 v55, 0, v247, vcc
	v_sub_f32_e32 v54, v54, v55
	v_add_f32_e32 v54, v56, v54
	v_mul_f32_e32 v55, 0x3fb8aa3b, v54
	v_exp_f32_e32 v55, v55
	s_nop 0
	v_mul_f32_e32 v52, v55, v52
	v_cvt_pk_bf16_f32 v52, v52, s0
	global_store_short v[50:51], v52, off
	v_mul_f32_e32 v52, 0xbfb8aa3b, v54
	v_exp_f32_e32 v52, v52
	s_nop 0
	v_mul_f32_e32 v52, v53, v52
	v_cvt_pk_bf16_f32 v52, v52, s0
	global_store_short v[50:51], v52, off offset:2048
	v_lshlrev_b32_e32 v51, 16, v119
	v_mul_f32_e32 v51, 0xbfb8aa3b, v51
	v_exp_f32_e32 v51, v51
	v_lshlrev_b32_e32 v50, 16, v118
	v_add_f32_e32 v52, 1.0, v51
	v_rcp_f32_e32 v52, v52
	s_nop 0
	v_fma_f32 v53, v76, v52, v75
	v_cmp_gt_f32_e32 vcc, s33, v53
	v_mul_f32_e32 v51, v51, v52
	v_mul_f32_e32 v51, v76, v51
	v_cndmask_b32_e64 v52, 0, 32, vcc
	v_ldexp_f32 v52, v53, v52
	v_log_f32_e32 v52, v52
	s_nop 0
	v_mul_f32_e32 v53, 0x3f317217, v52
	v_fma_f32 v53, v52, s93, -v53
	v_fmac_f32_e32 v53, 0x3377d1cf, v52
	v_fmac_f32_e32 v53, 0x3f317217, v52
	v_cmp_lt_f32_e64 s[0:1], |v52|, s94
	s_nop 1
	v_cndmask_b32_e64 v52, v52, v53, s[0:1]
	v_cndmask_b32_e32 v53, 0, v247, vcc
	v_sub_f32_e32 v52, v52, v53
	v_add_f32_e32 v52, v54, v52
	v_mul_f32_e32 v53, 0x3fb8aa3b, v52
	v_exp_f32_e32 v53, v53
	s_nop 0
	v_mul_f32_e32 v50, v53, v50
	v_cvt_pk_bf16_f32 v50, v50, s0
	global_store_short v[48:49], v50, off
	v_mul_f32_e32 v50, 0xbfb8aa3b, v52
	v_exp_f32_e32 v50, v50
	s_nop 0
	v_mul_f32_e32 v50, v51, v50
	v_cvt_pk_bf16_f32 v50, v50, s0
	global_store_short v[48:49], v50, off offset:2048
	v_lshlrev_b32_e32 v49, 16, v117
	v_mul_f32_e32 v49, 0xbfb8aa3b, v49
	v_exp_f32_e32 v49, v49
	v_lshlrev_b32_e32 v48, 16, v116
	v_add_f32_e32 v50, 1.0, v49
	v_rcp_f32_e32 v50, v50
	s_nop 0
	v_fma_f32 v51, v76, v50, v75
	v_cmp_gt_f32_e32 vcc, s33, v51
	v_mul_f32_e32 v49, v49, v50
	v_mul_f32_e32 v49, v76, v49
	v_cndmask_b32_e64 v50, 0, 32, vcc
	v_ldexp_f32 v50, v51, v50
	v_log_f32_e32 v50, v50
	s_nop 0
	v_mul_f32_e32 v51, 0x3f317217, v50
	v_fma_f32 v51, v50, s93, -v51
	v_fmac_f32_e32 v51, 0x3377d1cf, v50
	v_fmac_f32_e32 v51, 0x3f317217, v50
	v_cmp_lt_f32_e64 s[0:1], |v50|, s94
	s_nop 1
	v_cndmask_b32_e64 v50, v50, v51, s[0:1]
	v_cndmask_b32_e32 v51, 0, v247, vcc
	v_sub_f32_e32 v50, v50, v51
	v_add_f32_e32 v50, v52, v50
	v_mul_f32_e32 v51, 0x3fb8aa3b, v50
	v_exp_f32_e32 v51, v51
	s_nop 0
	v_mul_f32_e32 v48, v51, v48
	v_cvt_pk_bf16_f32 v48, v48, s0
	global_store_short v[46:47], v48, off
	v_mul_f32_e32 v48, 0xbfb8aa3b, v50
	v_exp_f32_e32 v48, v48
	s_nop 0
	v_mul_f32_e32 v48, v49, v48
	v_cvt_pk_bf16_f32 v48, v48, s0
	global_store_short v[46:47], v48, off offset:2048
	v_lshlrev_b32_e32 v47, 16, v115
	v_mul_f32_e32 v47, 0xbfb8aa3b, v47
	v_exp_f32_e32 v47, v47
	v_lshlrev_b32_e32 v46, 16, v114
	v_add_f32_e32 v48, 1.0, v47
	v_rcp_f32_e32 v48, v48
	s_nop 0
	v_fma_f32 v49, v76, v48, v75
	v_cmp_gt_f32_e32 vcc, s33, v49
	v_mul_f32_e32 v47, v47, v48
	v_mul_f32_e32 v47, v76, v47
	v_cndmask_b32_e64 v48, 0, 32, vcc
	v_ldexp_f32 v48, v49, v48
	v_log_f32_e32 v48, v48
	s_nop 0
	v_mul_f32_e32 v49, 0x3f317217, v48
	v_fma_f32 v49, v48, s93, -v49
	v_fmac_f32_e32 v49, 0x3377d1cf, v48
	v_fmac_f32_e32 v49, 0x3f317217, v48
	v_cmp_lt_f32_e64 s[0:1], |v48|, s94
	s_nop 1
	v_cndmask_b32_e64 v48, v48, v49, s[0:1]
	v_cndmask_b32_e32 v49, 0, v247, vcc
	v_sub_f32_e32 v48, v48, v49
	v_add_f32_e32 v48, v50, v48
	v_mul_f32_e32 v49, 0x3fb8aa3b, v48
	v_exp_f32_e32 v49, v49
	s_nop 0
	v_mul_f32_e32 v46, v49, v46
	v_cvt_pk_bf16_f32 v46, v46, s0
	global_store_short v[44:45], v46, off
	v_mul_f32_e32 v46, 0xbfb8aa3b, v48
	v_exp_f32_e32 v46, v46
	s_nop 0
	v_mul_f32_e32 v46, v47, v46
	v_cvt_pk_bf16_f32 v46, v46, s0
	global_store_short v[44:45], v46, off offset:2048
	v_lshlrev_b32_e32 v45, 16, v113
	v_mul_f32_e32 v45, 0xbfb8aa3b, v45
	v_exp_f32_e32 v45, v45
	v_lshlrev_b32_e32 v44, 16, v112
	v_add_f32_e32 v46, 1.0, v45
	v_rcp_f32_e32 v46, v46
	s_nop 0
	v_fma_f32 v47, v76, v46, v75
; DI unsigned pk2(float lo, float hi) { f32x2_t f = {lo, hi}; bf16x2_t v = __builtin_convertvector(f, bf16x2_t); return __builtin_bit_cast(unsigned, v); }
; DI void hgrn_passA(const Params& P, LAS unsigned char* lds, int u, bool skip_gates) {
;     ...
;         for (int s = 0; s < 32; ++s) {
;             const float qv = bf2f(qraw[s]), fl = bf2f(fraw[s]);
;             const float ex = __expf(-fl), sg = __builtin_amdgcn_rcpf(1.f + ex), f = lbv + (1.f - lbv) * sg, kk = (1.f - lbv) * (ex * sg);
;             bc += __logf(f);
;             pq[(size_t)s * LDU_E] = (bf16_t)(pk2(qv * __expf(bc), 0.f) & 0xffffu); pf[(size_t)s * LDU_E] = (bf16_t)(pk2(kk * __expf(-bc), 0.f) & 0xffffu);
;         }
	v_cmp_gt_f32_e32 vcc, s33, v47
	v_mul_f32_e32 v45, v45, v46
	v_mul_f32_e32 v45, v76, v45
	v_cndmask_b32_e64 v46, 0, 32, vcc
	v_ldexp_f32 v46, v47, v46
	v_log_f32_e32 v46, v46
	s_nop 0
	v_mul_f32_e32 v47, 0x3f317217, v46
	v_fma_f32 v47, v46, s93, -v47
	v_fmac_f32_e32 v47, 0x3377d1cf, v46
	v_fmac_f32_e32 v47, 0x3f317217, v46
	v_cmp_lt_f32_e64 s[0:1], |v46|, s94
	s_nop 1
	v_cndmask_b32_e64 v46, v46, v47, s[0:1]
	v_cndmask_b32_e32 v47, 0, v247, vcc
	v_sub_f32_e32 v46, v46, v47
	v_add_f32_e32 v46, v48, v46
	v_mul_f32_e32 v47, 0x3fb8aa3b, v46
	v_exp_f32_e32 v47, v47
	s_nop 0
	v_mul_f32_e32 v44, v47, v44
	v_cvt_pk_bf16_f32 v44, v44, s0
	global_store_short v[42:43], v44, off
	v_mul_f32_e32 v44, 0xbfb8aa3b, v46
	v_exp_f32_e32 v44, v44
	s_nop 0
	v_mul_f32_e32 v44, v45, v44
	v_cvt_pk_bf16_f32 v44, v44, s0
	global_store_short v[42:43], v44, off offset:2048
	v_lshlrev_b32_e32 v43, 16, v111
	v_mul_f32_e32 v43, 0xbfb8aa3b, v43
	v_exp_f32_e32 v43, v43
	v_lshlrev_b32_e32 v42, 16, v110
	v_add_f32_e32 v44, 1.0, v43
	v_rcp_f32_e32 v44, v44
	s_nop 0
	v_fma_f32 v45, v76, v44, v75
	v_cmp_gt_f32_e32 vcc, s33, v45
	v_mul_f32_e32 v43, v43, v44
	v_mul_f32_e32 v43, v76, v43
	v_cndmask_b32_e64 v44, 0, 32, vcc
	v_ldexp_f32 v44, v45, v44
	v_log_f32_e32 v44, v44
	s_nop 0
	v_mul_f32_e32 v45, 0x3f317217, v44
	v_fma_f32 v45, v44, s93, -v45
	v_fmac_f32_e32 v45, 0x3377d1cf, v44
	v_fmac_f32_e32 v45, 0x3f317217, v44
	v_cmp_lt_f32_e64 s[0:1], |v44|, s94
	s_nop 1
	v_cndmask_b32_e64 v44, v44, v45, s[0:1]
	v_cndmask_b32_e32 v45, 0, v247, vcc
	v_sub_f32_e32 v44, v44, v45
	v_add_f32_e32 v44, v46, v44
	v_mul_f32_e32 v45, 0x3fb8aa3b, v44
	v_exp_f32_e32 v45, v45
	s_nop 0
	v_mul_f32_e32 v42, v45, v42
	v_cvt_pk_bf16_f32 v42, v42, s0
	global_store_short v[40:41], v42, off
	v_mul_f32_e32 v42, 0xbfb8aa3b, v44
	v_exp_f32_e32 v42, v42
	s_nop 0
	v_mul_f32_e32 v42, v43, v42
	v_cvt_pk_bf16_f32 v42, v42, s0
	global_store_short v[40:41], v42, off offset:2048
	v_lshlrev_b32_e32 v41, 16, v109
	v_mul_f32_e32 v41, 0xbfb8aa3b, v41
	v_exp_f32_e32 v41, v41
	v_lshlrev_b32_e32 v40, 16, v108
	v_add_f32_e32 v42, 1.0, v41
	v_rcp_f32_e32 v42, v42
	s_nop 0
	v_fma_f32 v43, v76, v42, v75
	v_cmp_gt_f32_e32 vcc, s33, v43
	v_mul_f32_e32 v41, v41, v42
	v_mul_f32_e32 v41, v76, v41
	v_cndmask_b32_e64 v42, 0, 32, vcc
	v_ldexp_f32 v42, v43, v42
	v_log_f32_e32 v42, v42
	s_nop 0
	v_mul_f32_e32 v43, 0x3f317217, v42
	v_fma_f32 v43, v42, s93, -v43
	v_fmac_f32_e32 v43, 0x3377d1cf, v42
	v_fmac_f32_e32 v43, 0x3f317217, v42
	v_cmp_lt_f32_e64 s[0:1], |v42|, s94
	s_nop 1
	v_cndmask_b32_e64 v42, v42, v43, s[0:1]
	v_cndmask_b32_e32 v43, 0, v247, vcc
	v_sub_f32_e32 v42, v42, v43
	v_add_f32_e32 v42, v44, v42
	v_mul_f32_e32 v43, 0x3fb8aa3b, v42
	v_exp_f32_e32 v43, v43
	s_nop 0
	v_mul_f32_e32 v40, v43, v40
	v_cvt_pk_bf16_f32 v40, v40, s0
	global_store_short v[38:39], v40, off
	v_mul_f32_e32 v40, 0xbfb8aa3b, v42
	v_exp_f32_e32 v40, v40
	s_nop 0
	v_mul_f32_e32 v40, v41, v40
	v_cvt_pk_bf16_f32 v40, v40, s0
	global_store_short v[38:39], v40, off offset:2048
	v_lshlrev_b32_e32 v39, 16, v107
	v_mul_f32_e32 v39, 0xbfb8aa3b, v39
	v_exp_f32_e32 v39, v39
	v_lshlrev_b32_e32 v38, 16, v106
	v_add_f32_e32 v40, 1.0, v39
	v_rcp_f32_e32 v40, v40
	s_nop 0
	v_fma_f32 v41, v76, v40, v75
	v_cmp_gt_f32_e32 vcc, s33, v41
	v_mul_f32_e32 v39, v39, v40
	v_mul_f32_e32 v39, v76, v39
	v_cndmask_b32_e64 v40, 0, 32, vcc
	v_ldexp_f32 v40, v41, v40
	v_log_f32_e32 v40, v40
	s_nop 0
	v_mul_f32_e32 v41, 0x3f317217, v40
	v_fma_f32 v41, v40, s93, -v41
	v_fmac_f32_e32 v41, 0x3377d1cf, v40
	v_fmac_f32_e32 v41, 0x3f317217, v40
	v_cmp_lt_f32_e64 s[0:1], |v40|, s94
	s_nop 1
	v_cndmask_b32_e64 v40, v40, v41, s[0:1]
	v_cndmask_b32_e32 v41, 0, v247, vcc
	v_sub_f32_e32 v40, v40, v41
	v_add_f32_e32 v40, v42, v40
	v_mul_f32_e32 v41, 0x3fb8aa3b, v40
	v_exp_f32_e32 v41, v41
	s_nop 0
	v_mul_f32_e32 v38, v41, v38
	v_cvt_pk_bf16_f32 v38, v38, s0
	global_store_short v[36:37], v38, off
	v_mul_f32_e32 v38, 0xbfb8aa3b, v40
	v_exp_f32_e32 v38, v38
	s_nop 0
	v_mul_f32_e32 v38, v39, v38
	v_cvt_pk_bf16_f32 v38, v38, s0
	global_store_short v[36:37], v38, off offset:2048
	v_lshlrev_b32_e32 v37, 16, v105
	v_mul_f32_e32 v37, 0xbfb8aa3b, v37
	v_exp_f32_e32 v37, v37
	v_lshlrev_b32_e32 v36, 16, v104
	v_add_f32_e32 v38, 1.0, v37
	v_rcp_f32_e32 v38, v38
	s_nop 0
	v_fma_f32 v39, v76, v38, v75
	v_cmp_gt_f32_e32 vcc, s33, v39
	v_mul_f32_e32 v37, v37, v38
	v_mul_f32_e32 v37, v76, v37
	v_cndmask_b32_e64 v38, 0, 32, vcc
	v_ldexp_f32 v38, v39, v38
	v_log_f32_e32 v38, v38
	s_nop 0
	v_mul_f32_e32 v39, 0x3f317217, v38
	v_fma_f32 v39, v38, s93, -v39
	v_fmac_f32_e32 v39, 0x3377d1cf, v38
	v_fmac_f32_e32 v39, 0x3f317217, v38
	v_cmp_lt_f32_e64 s[0:1], |v38|, s94
	s_nop 1
	v_cndmask_b32_e64 v38, v38, v39, s[0:1]
	v_cndmask_b32_e32 v39, 0, v247, vcc
	v_sub_f32_e32 v38, v38, v39
	v_add_f32_e32 v38, v40, v38
	v_mul_f32_e32 v39, 0x3fb8aa3b, v38
	v_exp_f32_e32 v39, v39
	s_nop 0
	v_mul_f32_e32 v36, v39, v36
	v_cvt_pk_bf16_f32 v36, v36, s0
	global_store_short v[34:35], v36, off
	v_mul_f32_e32 v36, 0xbfb8aa3b, v38
	v_exp_f32_e32 v36, v36
	s_nop 0
	v_mul_f32_e32 v36, v37, v36
	v_cvt_pk_bf16_f32 v36, v36, s0
	global_store_short v[34:35], v36, off offset:2048
	v_lshlrev_b32_e32 v35, 16, v103
	v_mul_f32_e32 v35, 0xbfb8aa3b, v35
	v_exp_f32_e32 v35, v35
	v_lshlrev_b32_e32 v34, 16, v102
	v_add_f32_e32 v36, 1.0, v35
	v_rcp_f32_e32 v36, v36
	s_nop 0
	v_fma_f32 v37, v76, v36, v75
	v_cmp_gt_f32_e32 vcc, s33, v37
	v_mul_f32_e32 v35, v35, v36
	v_mul_f32_e32 v35, v76, v35
	v_cndmask_b32_e64 v36, 0, 32, vcc
	v_ldexp_f32 v36, v37, v36
	v_log_f32_e32 v36, v36
	s_nop 0
	v_mul_f32_e32 v37, 0x3f317217, v36
	v_fma_f32 v37, v36, s93, -v37
; DI unsigned pk2(float lo, float hi) { f32x2_t f = {lo, hi}; bf16x2_t v = __builtin_convertvector(f, bf16x2_t); return __builtin_bit_cast(unsigned, v); }
; DI void hgrn_passA(const Params& P, LAS unsigned char* lds, int u, bool skip_gates) {
;     ...
;         for (int s = 0; s < 32; ++s) {
;             const float qv = bf2f(qraw[s]), fl = bf2f(fraw[s]);
;             const float ex = __expf(-fl), sg = __builtin_amdgcn_rcpf(1.f + ex), f = lbv + (1.f - lbv) * sg, kk = (1.f - lbv) * (ex * sg);
;             bc += __logf(f);
;             pq[(size_t)s * LDU_E] = (bf16_t)(pk2(qv * __expf(bc), 0.f) & 0xffffu); pf[(size_t)s * LDU_E] = (bf16_t)(pk2(kk * __expf(-bc), 0.f) & 0xffffu);
;         }
	v_fmac_f32_e32 v37, 0x3377d1cf, v36
	v_fmac_f32_e32 v37, 0x3f317217, v36
	v_cmp_lt_f32_e64 s[0:1], |v36|, s94
	s_nop 1
	v_cndmask_b32_e64 v36, v36, v37, s[0:1]
	v_cndmask_b32_e32 v37, 0, v247, vcc
	v_sub_f32_e32 v36, v36, v37
	v_add_f32_e32 v36, v38, v36
	v_mul_f32_e32 v37, 0x3fb8aa3b, v36
	v_exp_f32_e32 v37, v37
	s_nop 0
	v_mul_f32_e32 v34, v37, v34
	v_cvt_pk_bf16_f32 v34, v34, s0
	global_store_short v[32:33], v34, off
	v_mul_f32_e32 v34, 0xbfb8aa3b, v36
	v_exp_f32_e32 v34, v34
	s_nop 0
	v_mul_f32_e32 v34, v35, v34
	v_cvt_pk_bf16_f32 v34, v34, s0
	global_store_short v[32:33], v34, off offset:2048
	v_lshlrev_b32_e32 v33, 16, v101
	v_mul_f32_e32 v33, 0xbfb8aa3b, v33
	v_exp_f32_e32 v33, v33
	v_lshlrev_b32_e32 v32, 16, v100
	v_add_f32_e32 v34, 1.0, v33
	v_rcp_f32_e32 v34, v34
	s_nop 0
	v_fma_f32 v35, v76, v34, v75
	v_cmp_gt_f32_e32 vcc, s33, v35
	v_mul_f32_e32 v33, v33, v34
	v_mul_f32_e32 v33, v76, v33
	v_cndmask_b32_e64 v34, 0, 32, vcc
	v_ldexp_f32 v34, v35, v34
	v_log_f32_e32 v34, v34
	s_nop 0
	v_mul_f32_e32 v35, 0x3f317217, v34
	v_fma_f32 v35, v34, s93, -v35
	v_fmac_f32_e32 v35, 0x3377d1cf, v34
	v_fmac_f32_e32 v35, 0x3f317217, v34
	v_cmp_lt_f32_e64 s[0:1], |v34|, s94
	s_nop 1
	v_cndmask_b32_e64 v34, v34, v35, s[0:1]
	v_cndmask_b32_e32 v35, 0, v247, vcc
	v_sub_f32_e32 v34, v34, v35
	v_add_f32_e32 v34, v36, v34
	v_mul_f32_e32 v35, 0x3fb8aa3b, v34
	v_exp_f32_e32 v35, v35
	s_nop 0
	v_mul_f32_e32 v32, v35, v32
	v_cvt_pk_bf16_f32 v32, v32, s0
	global_store_short v[30:31], v32, off
	v_mul_f32_e32 v32, 0xbfb8aa3b, v34
	v_exp_f32_e32 v32, v32
	s_nop 0
	v_mul_f32_e32 v32, v33, v32
	v_cvt_pk_bf16_f32 v32, v32, s0
	global_store_short v[30:31], v32, off offset:2048
	v_lshlrev_b32_e32 v31, 16, v99
	v_mul_f32_e32 v31, 0xbfb8aa3b, v31
	v_exp_f32_e32 v31, v31
	v_lshlrev_b32_e32 v30, 16, v98
	v_add_f32_e32 v32, 1.0, v31
	v_rcp_f32_e32 v32, v32
	s_nop 0
	v_fma_f32 v33, v76, v32, v75
	v_cmp_gt_f32_e32 vcc, s33, v33
	v_mul_f32_e32 v31, v31, v32
	v_mul_f32_e32 v31, v76, v31
	v_cndmask_b32_e64 v32, 0, 32, vcc
	v_ldexp_f32 v32, v33, v32
	v_log_f32_e32 v32, v32
	s_nop 0
	v_mul_f32_e32 v33, 0x3f317217, v32
	v_fma_f32 v33, v32, s93, -v33
	v_fmac_f32_e32 v33, 0x3377d1cf, v32
	v_fmac_f32_e32 v33, 0x3f317217, v32
	v_cmp_lt_f32_e64 s[0:1], |v32|, s94
	s_nop 1
	v_cndmask_b32_e64 v32, v32, v33, s[0:1]
	v_cndmask_b32_e32 v33, 0, v247, vcc
	v_sub_f32_e32 v32, v32, v33
	v_add_f32_e32 v32, v34, v32
	v_mul_f32_e32 v33, 0x3fb8aa3b, v32
	v_exp_f32_e32 v33, v33
	s_nop 0
	v_mul_f32_e32 v30, v33, v30
	v_cvt_pk_bf16_f32 v30, v30, s0
	global_store_short v[28:29], v30, off
	v_mul_f32_e32 v30, 0xbfb8aa3b, v32
	v_exp_f32_e32 v30, v30
	s_nop 0
	v_mul_f32_e32 v30, v31, v30
	v_cvt_pk_bf16_f32 v30, v30, s0
	global_store_short v[28:29], v30, off offset:2048
	v_lshlrev_b32_e32 v29, 16, v97
	v_mul_f32_e32 v29, 0xbfb8aa3b, v29
	v_exp_f32_e32 v29, v29
	v_lshlrev_b32_e32 v28, 16, v96
	v_add_f32_e32 v30, 1.0, v29
	v_rcp_f32_e32 v30, v30
	s_nop 0
	v_fma_f32 v31, v76, v30, v75
	v_cmp_gt_f32_e32 vcc, s33, v31
	v_mul_f32_e32 v29, v29, v30
	v_mul_f32_e32 v29, v76, v29
	v_cndmask_b32_e64 v30, 0, 32, vcc
	v_ldexp_f32 v30, v31, v30
	v_log_f32_e32 v30, v30
	s_nop 0
	v_mul_f32_e32 v31, 0x3f317217, v30
	v_fma_f32 v31, v30, s93, -v31
	v_fmac_f32_e32 v31, 0x3377d1cf, v30
	v_fmac_f32_e32 v31, 0x3f317217, v30
	v_cmp_lt_f32_e64 s[0:1], |v30|, s94
	s_nop 1
	v_cndmask_b32_e64 v30, v30, v31, s[0:1]
	v_cndmask_b32_e32 v31, 0, v247, vcc
	v_sub_f32_e32 v30, v30, v31
	v_add_f32_e32 v30, v32, v30
	v_mul_f32_e32 v31, 0x3fb8aa3b, v30
	v_exp_f32_e32 v31, v31
	s_nop 0
	v_mul_f32_e32 v28, v31, v28
	v_cvt_pk_bf16_f32 v28, v28, s0
	global_store_short v[26:27], v28, off
	v_mul_f32_e32 v28, 0xbfb8aa3b, v30
	v_exp_f32_e32 v28, v28
	s_nop 0
	v_mul_f32_e32 v28, v29, v28
	v_cvt_pk_bf16_f32 v28, v28, s0
	global_store_short v[26:27], v28, off offset:2048
	v_lshlrev_b32_e32 v27, 16, v95
	v_mul_f32_e32 v27, 0xbfb8aa3b, v27
	v_exp_f32_e32 v27, v27
	v_lshlrev_b32_e32 v26, 16, v94
	v_add_f32_e32 v28, 1.0, v27
	v_rcp_f32_e32 v28, v28
	s_nop 0
	v_fma_f32 v29, v76, v28, v75
	v_cmp_gt_f32_e32 vcc, s33, v29
	v_mul_f32_e32 v27, v27, v28
	v_mul_f32_e32 v27, v76, v27
	v_cndmask_b32_e64 v28, 0, 32, vcc
	v_ldexp_f32 v28, v29, v28
	v_log_f32_e32 v28, v28
	s_nop 0
	v_mul_f32_e32 v29, 0x3f317217, v28
	v_fma_f32 v29, v28, s93, -v29
	v_fmac_f32_e32 v29, 0x3377d1cf, v28
	v_fmac_f32_e32 v29, 0x3f317217, v28
	v_cmp_lt_f32_e64 s[0:1], |v28|, s94
	s_nop 1
	v_cndmask_b32_e64 v28, v28, v29, s[0:1]
	v_cndmask_b32_e32 v29, 0, v247, vcc
	v_sub_f32_e32 v28, v28, v29
	v_add_f32_e32 v28, v30, v28
	v_mul_f32_e32 v29, 0x3fb8aa3b, v28
	v_exp_f32_e32 v29, v29
	s_nop 0
	v_mul_f32_e32 v26, v29, v26
	v_cvt_pk_bf16_f32 v26, v26, s0
	global_store_short v[24:25], v26, off
	v_mul_f32_e32 v26, 0xbfb8aa3b, v28
	v_exp_f32_e32 v26, v26
	s_nop 0
	v_mul_f32_e32 v26, v27, v26
	v_cvt_pk_bf16_f32 v26, v26, s0
	global_store_short v[24:25], v26, off offset:2048
	v_lshlrev_b32_e32 v25, 16, v93
	v_mul_f32_e32 v25, 0xbfb8aa3b, v25
	v_exp_f32_e32 v25, v25
	v_lshlrev_b32_e32 v24, 16, v92
	v_add_f32_e32 v26, 1.0, v25
	v_rcp_f32_e32 v26, v26
	s_nop 0
	v_fma_f32 v27, v76, v26, v75
	v_cmp_gt_f32_e32 vcc, s33, v27
	v_mul_f32_e32 v25, v25, v26
	v_mul_f32_e32 v25, v76, v25
	v_cndmask_b32_e64 v26, 0, 32, vcc
	v_ldexp_f32 v26, v27, v26
	v_log_f32_e32 v26, v26
	s_nop 0
	v_mul_f32_e32 v27, 0x3f317217, v26
	v_fma_f32 v27, v26, s93, -v27
	v_fmac_f32_e32 v27, 0x3377d1cf, v26
	v_fmac_f32_e32 v27, 0x3f317217, v26
	v_cmp_lt_f32_e64 s[0:1], |v26|, s94
	s_nop 1
	v_cndmask_b32_e64 v26, v26, v27, s[0:1]
	v_cndmask_b32_e32 v27, 0, v247, vcc
	v_sub_f32_e32 v26, v26, v27
	v_add_f32_e32 v26, v28, v26
; DI unsigned pk2(float lo, float hi) { f32x2_t f = {lo, hi}; bf16x2_t v = __builtin_convertvector(f, bf16x2_t); return __builtin_bit_cast(unsigned, v); }
; DI void hgrn_passA(const Params& P, LAS unsigned char* lds, int u, bool skip_gates) {
;     ...
;         for (int s = 0; s < 32; ++s) {
;             const float qv = bf2f(qraw[s]), fl = bf2f(fraw[s]);
;             const float ex = __expf(-fl), sg = __builtin_amdgcn_rcpf(1.f + ex), f = lbv + (1.f - lbv) * sg, kk = (1.f - lbv) * (ex * sg);
;             bc += __logf(f);
;             pq[(size_t)s * LDU_E] = (bf16_t)(pk2(qv * __expf(bc), 0.f) & 0xffffu); pf[(size_t)s * LDU_E] = (bf16_t)(pk2(kk * __expf(-bc), 0.f) & 0xffffu);
;         }
	v_mul_f32_e32 v27, 0x3fb8aa3b, v26
	v_exp_f32_e32 v27, v27
	s_nop 0
	v_mul_f32_e32 v24, v27, v24
	v_cvt_pk_bf16_f32 v24, v24, s0
	global_store_short v[22:23], v24, off
	v_mul_f32_e32 v24, 0xbfb8aa3b, v26
	v_exp_f32_e32 v24, v24
	s_nop 0
	v_mul_f32_e32 v24, v25, v24
	v_cvt_pk_bf16_f32 v24, v24, s0
	global_store_short v[22:23], v24, off offset:2048
	v_lshlrev_b32_e32 v23, 16, v91
	v_mul_f32_e32 v23, 0xbfb8aa3b, v23
	v_exp_f32_e32 v23, v23
	v_lshlrev_b32_e32 v22, 16, v90
	v_add_f32_e32 v24, 1.0, v23
	v_rcp_f32_e32 v24, v24
	s_nop 0
	v_fma_f32 v25, v76, v24, v75
	v_cmp_gt_f32_e32 vcc, s33, v25
	v_mul_f32_e32 v23, v23, v24
	v_mul_f32_e32 v23, v76, v23
	v_cndmask_b32_e64 v24, 0, 32, vcc
	v_ldexp_f32 v24, v25, v24
	v_log_f32_e32 v24, v24
	s_nop 0
	v_mul_f32_e32 v25, 0x3f317217, v24
	v_fma_f32 v25, v24, s93, -v25
	v_fmac_f32_e32 v25, 0x3377d1cf, v24
	v_fmac_f32_e32 v25, 0x3f317217, v24
	v_cmp_lt_f32_e64 s[0:1], |v24|, s94
	s_nop 1
	v_cndmask_b32_e64 v24, v24, v25, s[0:1]
	v_cndmask_b32_e32 v25, 0, v247, vcc
	v_sub_f32_e32 v24, v24, v25
	v_add_f32_e32 v24, v26, v24
	v_mul_f32_e32 v25, 0x3fb8aa3b, v24
	v_exp_f32_e32 v25, v25
	s_nop 0
	v_mul_f32_e32 v22, v25, v22
	v_cvt_pk_bf16_f32 v22, v22, s0
	global_store_short v[20:21], v22, off
	v_mul_f32_e32 v22, 0xbfb8aa3b, v24
	v_exp_f32_e32 v22, v22
	s_nop 0
	v_mul_f32_e32 v22, v23, v22
	v_cvt_pk_bf16_f32 v22, v22, s0
	global_store_short v[20:21], v22, off offset:2048
	v_lshlrev_b32_e32 v21, 16, v89
	v_mul_f32_e32 v21, 0xbfb8aa3b, v21
	v_exp_f32_e32 v21, v21
	v_lshlrev_b32_e32 v20, 16, v88
	v_add_f32_e32 v22, 1.0, v21
	v_rcp_f32_e32 v22, v22
	s_nop 0
	v_fma_f32 v23, v76, v22, v75
	v_cmp_gt_f32_e32 vcc, s33, v23
	v_mul_f32_e32 v21, v21, v22
	v_mul_f32_e32 v21, v76, v21
	v_cndmask_b32_e64 v22, 0, 32, vcc
	v_ldexp_f32 v22, v23, v22
	v_log_f32_e32 v22, v22
	s_nop 0
	v_mul_f32_e32 v23, 0x3f317217, v22
	v_fma_f32 v23, v22, s93, -v23
	v_fmac_f32_e32 v23, 0x3377d1cf, v22
	v_fmac_f32_e32 v23, 0x3f317217, v22
	v_cmp_lt_f32_e64 s[0:1], |v22|, s94
	s_nop 1
	v_cndmask_b32_e64 v22, v22, v23, s[0:1]
	v_cndmask_b32_e32 v23, 0, v247, vcc
	v_sub_f32_e32 v22, v22, v23
	v_add_f32_e32 v22, v24, v22
	v_mul_f32_e32 v23, 0x3fb8aa3b, v22
	v_exp_f32_e32 v23, v23
	s_nop 0
	v_mul_f32_e32 v20, v23, v20
	v_cvt_pk_bf16_f32 v20, v20, s0
	global_store_short v[18:19], v20, off
	v_mul_f32_e32 v20, 0xbfb8aa3b, v22
	v_exp_f32_e32 v20, v20
	s_nop 0
	v_mul_f32_e32 v20, v21, v20
	v_cvt_pk_bf16_f32 v20, v20, s0
	global_store_short v[18:19], v20, off offset:2048
	v_lshlrev_b32_e32 v19, 16, v87
	v_mul_f32_e32 v19, 0xbfb8aa3b, v19
	v_exp_f32_e32 v19, v19
	v_lshlrev_b32_e32 v18, 16, v86
	v_add_f32_e32 v20, 1.0, v19
	v_rcp_f32_e32 v20, v20
	s_nop 0
	v_fma_f32 v21, v76, v20, v75
	v_cmp_gt_f32_e32 vcc, s33, v21
	v_mul_f32_e32 v19, v19, v20
	v_mul_f32_e32 v19, v76, v19
	v_cndmask_b32_e64 v20, 0, 32, vcc
	v_ldexp_f32 v20, v21, v20
	v_log_f32_e32 v20, v20
	s_nop 0
	v_mul_f32_e32 v21, 0x3f317217, v20
	v_fma_f32 v21, v20, s93, -v21
	v_fmac_f32_e32 v21, 0x3377d1cf, v20
	v_fmac_f32_e32 v21, 0x3f317217, v20
	v_cmp_lt_f32_e64 s[0:1], |v20|, s94
	s_nop 1
	v_cndmask_b32_e64 v20, v20, v21, s[0:1]
	v_cndmask_b32_e32 v21, 0, v247, vcc
	v_sub_f32_e32 v20, v20, v21
	v_add_f32_e32 v20, v22, v20
	v_mul_f32_e32 v21, 0x3fb8aa3b, v20
	v_exp_f32_e32 v21, v21
	s_nop 0
	v_mul_f32_e32 v18, v21, v18
	v_cvt_pk_bf16_f32 v18, v18, s0
	global_store_short v[16:17], v18, off
	v_mul_f32_e32 v18, 0xbfb8aa3b, v20
	v_exp_f32_e32 v18, v18
	s_nop 0
	v_mul_f32_e32 v18, v19, v18
	v_cvt_pk_bf16_f32 v18, v18, s0
	global_store_short v[16:17], v18, off offset:2048
	v_lshlrev_b32_e32 v17, 16, v85
	v_mul_f32_e32 v17, 0xbfb8aa3b, v17
	v_exp_f32_e32 v17, v17
	v_lshlrev_b32_e32 v16, 16, v84
	v_add_f32_e32 v18, 1.0, v17
	v_rcp_f32_e32 v18, v18
	s_nop 0
	v_fma_f32 v19, v76, v18, v75
	v_cmp_gt_f32_e32 vcc, s33, v19
	v_mul_f32_e32 v17, v17, v18
	v_mul_f32_e32 v17, v76, v17
	v_cndmask_b32_e64 v18, 0, 32, vcc
	v_ldexp_f32 v18, v19, v18
	v_log_f32_e32 v18, v18
	s_nop 0
	v_mul_f32_e32 v19, 0x3f317217, v18
	v_fma_f32 v19, v18, s93, -v19
	v_fmac_f32_e32 v19, 0x3377d1cf, v18
	v_fmac_f32_e32 v19, 0x3f317217, v18
	v_cmp_lt_f32_e64 s[0:1], |v18|, s94
	s_nop 1
	v_cndmask_b32_e64 v18, v18, v19, s[0:1]
	v_cndmask_b32_e32 v19, 0, v247, vcc
	v_sub_f32_e32 v18, v18, v19
	v_add_f32_e32 v18, v20, v18
	v_mul_f32_e32 v19, 0x3fb8aa3b, v18
	v_exp_f32_e32 v19, v19
	s_nop 0
	v_mul_f32_e32 v16, v19, v16
	v_cvt_pk_bf16_f32 v16, v16, s0
	global_store_short v[14:15], v16, off
	v_mul_f32_e32 v16, 0xbfb8aa3b, v18
	v_exp_f32_e32 v16, v16
	s_nop 0
	v_mul_f32_e32 v16, v17, v16
	v_cvt_pk_bf16_f32 v16, v16, s0
	global_store_short v[14:15], v16, off offset:2048
	v_lshlrev_b32_e32 v15, 16, v83
	v_mul_f32_e32 v15, 0xbfb8aa3b, v15
	v_exp_f32_e32 v15, v15
	v_lshlrev_b32_e32 v14, 16, v81
	v_add_f32_e32 v16, 1.0, v15
	v_rcp_f32_e32 v16, v16
	s_nop 0
	v_fma_f32 v17, v76, v16, v75
	v_cmp_gt_f32_e32 vcc, s33, v17
	v_mul_f32_e32 v15, v15, v16
	v_mul_f32_e32 v15, v76, v15
	v_cndmask_b32_e64 v16, 0, 32, vcc
	v_ldexp_f32 v16, v17, v16
	v_log_f32_e32 v16, v16
	s_nop 0
	v_mul_f32_e32 v17, 0x3f317217, v16
	v_fma_f32 v17, v16, s93, -v17
	v_fmac_f32_e32 v17, 0x3377d1cf, v16
	v_fmac_f32_e32 v17, 0x3f317217, v16
	v_cmp_lt_f32_e64 s[0:1], |v16|, s94
	s_nop 1
	v_cndmask_b32_e64 v16, v16, v17, s[0:1]
	v_cndmask_b32_e32 v17, 0, v247, vcc
	v_sub_f32_e32 v16, v16, v17
	v_add_f32_e32 v16, v18, v16
	v_mul_f32_e32 v17, 0x3fb8aa3b, v16
	v_exp_f32_e32 v17, v17
	s_nop 0
	v_mul_f32_e32 v14, v17, v14
	v_cvt_pk_bf16_f32 v14, v14, s0
	global_store_short v[12:13], v14, off
	v_mul_f32_e32 v14, 0xbfb8aa3b, v16
	v_exp_f32_e32 v14, v14
	s_nop 0
	v_mul_f32_e32 v14, v15, v14
; #define LAS __attribute__((address_space(3)))
; DI unsigned pk2(float lo, float hi) { f32x2_t f = {lo, hi}; bf16x2_t v = __builtin_convertvector(f, bf16x2_t); return __builtin_bit_cast(unsigned, v); }
; DI void hgrn_passA(const Params& P, LAS unsigned char* lds, int u, bool skip_gates) {
;     ...
;         for (int s = 0; s < 32; ++s) {
;             const float qv = bf2f(qraw[s]), fl = bf2f(fraw[s]);
;             const float ex = __expf(-fl), sg = __builtin_amdgcn_rcpf(1.f + ex), f = lbv + (1.f - lbv) * sg, kk = (1.f - lbv) * (ex * sg);
;             bc += __logf(f);
;             pq[(size_t)s * LDU_E] = (bf16_t)(pk2(qv * __expf(bc), 0.f) & 0xffffu); pf[(size_t)s * LDU_E] = (bf16_t)(pk2(kk * __expf(-bc), 0.f) & 0xffffu);
;         }
;         DEC[(size_t)(chunk0 + ch) * 1024 + cc] = __expf(bc);
;     }
;     __syncthreads();
;     f32x4 acc[8];
; #pragma unroll
;     for (int dt = 0; dt < 8; ++dt) acc[dt] = (f32x4){0.f, 0.f, 0.f, 0.f};
;     const int row = tid & 31, seg = tid >> 5;
;     const bf16_t* src = U + (size_t)(tok0 + row) * LDU_E + h * 128 + seg * 8;
;     u32x4 rk = *(const u32x4*)(src + 3072), ri = *(const u32x4*)(src + 4096);
;     float rdec = (tid < 128) ? DEC[(size_t)chunk0 * 1024 + h * 128 + tid] : 1.f, dtot = 1.f;
;     LAS unsigned char* KT = lds; LAS unsigned char* IT = lds + 10240; LAS float* dec = (LAS float*)(lds + 20480);
;     for (int ch = 0; ch < 8; ++ch) {
;         tr_write8(KT, 80, row * 2, seg * 8, rk); tr_write8(IT, 80, row * 2, seg * 8, ri);
;         if (tid < 128) { dec[tid] = rdec; dtot *= rdec; }
;         if (ch < 7) { const bf16_t* s2 = src + (size_t)(ch + 1) * 32 * LDU_E; rk = *(const u32x4*)(s2 + 3072); ri = *(const u32x4*)(s2 + 4096);
;             if (tid < 128) rdec = DEC[(size_t)(chunk0 + ch + 1) * 1024 + h * 128 + tid]; }
	v_cvt_pk_bf16_f32 v14, v14, s0
	global_store_short v[12:13], v14, off offset:2048
	v_lshlrev_b32_e32 v13, 16, v80
	v_mul_f32_e32 v13, 0xbfb8aa3b, v13
	v_exp_f32_e32 v13, v13
	v_lshlrev_b32_e32 v12, 16, v79
	v_add_f32_e32 v14, 1.0, v13
	v_rcp_f32_e32 v14, v14
	s_nop 0
	v_fma_f32 v15, v76, v14, v75
	v_cmp_gt_f32_e32 vcc, s33, v15
	v_mul_f32_e32 v13, v13, v14
	v_mul_f32_e32 v13, v76, v13
	v_cndmask_b32_e64 v14, 0, 32, vcc
	v_ldexp_f32 v14, v15, v14
	v_log_f32_e32 v14, v14
	s_nop 0
	v_mul_f32_e32 v15, 0x3f317217, v14
	v_fma_f32 v15, v14, s93, -v15
	v_fmac_f32_e32 v15, 0x3377d1cf, v14
	v_fmac_f32_e32 v15, 0x3f317217, v14
	v_cmp_lt_f32_e64 s[0:1], |v14|, s94
	s_nop 1
	v_cndmask_b32_e64 v14, v14, v15, s[0:1]
	v_cndmask_b32_e32 v15, 0, v247, vcc
	v_sub_f32_e32 v14, v14, v15
	v_add_f32_e32 v14, v16, v14
	v_mul_f32_e32 v15, 0x3fb8aa3b, v14
	v_exp_f32_e32 v15, v15
	s_nop 0
	v_mul_f32_e32 v12, v15, v12
	v_cvt_pk_bf16_f32 v12, v12, s0
	global_store_short v[10:11], v12, off
	v_mul_f32_e32 v12, 0xbfb8aa3b, v14
	v_exp_f32_e32 v12, v12
	s_nop 0
	v_mul_f32_e32 v12, v13, v12
	v_cvt_pk_bf16_f32 v12, v12, s0
	global_store_short v[10:11], v12, off offset:2048
	v_lshlrev_b32_e32 v11, 16, v78
	v_mul_f32_e32 v11, 0xbfb8aa3b, v11
	v_exp_f32_e32 v11, v11
	v_lshlrev_b32_e32 v10, 16, v77
	v_add_f32_e32 v12, 1.0, v11
	v_rcp_f32_e32 v12, v12
	s_nop 0
	v_fmac_f32_e32 v75, v76, v12
	v_cmp_gt_f32_e32 vcc, s33, v75
	v_mul_f32_e32 v11, v11, v12
	v_mul_f32_e32 v11, v76, v11
	v_cndmask_b32_e64 v12, 0, 32, vcc
	v_ldexp_f32 v12, v75, v12
	v_log_f32_e32 v12, v12
	s_nop 0
	v_mul_f32_e32 v13, 0x3f317217, v12
	v_fma_f32 v13, v12, s93, -v13
	v_fmac_f32_e32 v13, 0x3377d1cf, v12
	v_fmac_f32_e32 v13, 0x3f317217, v12
	v_cmp_lt_f32_e64 s[0:1], |v12|, s94
	s_nop 1
	v_cndmask_b32_e64 v12, v12, v13, s[0:1]
	v_cndmask_b32_e32 v13, 0, v247, vcc
	v_sub_f32_e32 v12, v12, v13
	v_add_f32_e32 v12, v14, v12
	v_mul_f32_e32 v13, 0x3fb8aa3b, v12
	v_exp_f32_e32 v13, v13
	s_and_b64 vcc, exec, s[36:37]
	v_mul_f32_e32 v10, v13, v10
	v_cvt_pk_bf16_f32 v10, v10, s0
	global_store_short v[8:9], v10, off
	v_mul_f32_e32 v10, 0xbfb8aa3b, v12
	v_exp_f32_e32 v10, v10
	s_nop 0
	v_mul_f32_e32 v10, v11, v10
	v_cvt_pk_bf16_f32 v10, v10, s0
	global_store_short v[8:9], v10, off offset:2048
	v_add_u32_e32 v8, s6, v74
	v_ashrrev_i32_e32 v9, 31, v8
	v_lshlrev_b64 v[8:9], 12, v[8:9]
	v_lshl_add_u64 v[8:9], v[6:7], 0, v[8:9]
	s_mov_b64 s[0:1], 0
	global_store_dword v[8:9], v13, off
	s_cbranch_vccz .LBB0_125
	v_and_b32_e32 v13, 31, v82
	v_or_b32_e32 v0, s7, v13
	v_mov_b64_e32 v[2:3], s[20:21]
	v_ashrrev_i32_e32 v12, 2, v82
	v_mad_i64_i32 v[2:3], s[0:1], v0, s86, v[2:3]
	s_lshl_b32 s10, s17, 1
	v_and_b32_e32 v10, -8, v12
	v_lshl_add_u64 v[2:3], v[2:3], 0, s[10:11]
	v_ashrrev_i32_e32 v11, 31, v10
	v_lshl_add_u64 v[84:85], v[10:11], 1, v[2:3]
	v_add_co_u32_e32 v2, vcc, 0x1000, v84
	s_waitcnt lgkmcnt(0)
	s_nop 0
	v_addc_co_u32_e32 v3, vcc, 0, v85, vcc
	v_add_co_u32_e32 v4, vcc, 0x2000, v84
	s_barrier
	s_nop 0
	v_addc_co_u32_e32 v5, vcc, 0, v85, vcc
	global_load_dwordx4 v[6:9], v[2:3], off offset:2048
	s_nop 0
	global_load_dwordx4 v[2:5], v[4:5], off
	v_cmp_gt_i32_e64 s[36:37], s84, v82
	v_cmp_lt_i32_e32 vcc, s68, v82
	s_and_saveexec_b64 s[0:1], vcc
	s_xor_b64 s[0:1], exec, s[0:1]
	v_mov_b32_e32 v83, v1
	s_or_saveexec_b64 s[0:1], s[0:1]
	v_mov_b32_e32 v0, 1.0
	v_mov_b32_e32 v93, 1.0
	s_xor_b64 exec, exec, s[0:1]
	s_cbranch_execz .LBB0_130
	s_ashr_i32 s7, s6, 31
	s_lshl_b64 s[12:13], s[6:7], 12
	s_add_u32 s7, s18, s12
	s_addc_u32 s8, s19, s13
	s_lshl_b32 s12, s17, 2
	s_add_u32 s12, s7, s12
	s_addc_u32 s13, s8, 0
	v_ashrrev_i32_e32 v83, 31, v82
	v_lshl_add_u64 v[14:15], v[82:83], 2, s[12:13]
	global_load_dword v93, v[14:15], off
.LBB0_130:
	s_or_b64 exec, exec, s[0:1]
	v_lshlrev_b32_e32 v11, 1, v13
	v_mul_lo_u32 v10, v10, s96
	v_add3_u32 v92, 0, v10, v11
	v_lshl_add_u32 v90, v82, 2, 0
	s_waitcnt vmcnt(0) lgkmcnt(0)
	ds_write_b16 v92, v6
	ds_write_b16_d16_hi v92, v6 offset:80
	ds_write_b16 v92, v7 offset:160
	ds_write_b16_d16_hi v92, v7 offset:240
	ds_write_b16 v92, v8 offset:320
	ds_write_b16_d16_hi v92, v8 offset:400
	ds_write_b16 v92, v9 offset:480
	ds_write_b16_d16_hi v92, v9 offset:560
	ds_write_b16 v92, v2 offset:10240
	ds_write_b16_d16_hi v92, v2 offset:10320
	ds_write_b16 v92, v3 offset:10400
	ds_write_b16_d16_hi v92, v3 offset:10480
	ds_write_b16 v92, v4 offset:10560
	ds_write_b16_d16_hi v92, v4 offset:10640
	ds_write_b16 v92, v5 offset:10720
	ds_write_b16_d16_hi v92, v5 offset:10800
	s_and_saveexec_b64 s[0:1], s[36:37]
	v_mov_b32_e32 v0, v93
	ds_write_b32 v90, v93 offset:20480
	s_or_b64 exec, exec, s[0:1]
	v_add_co_u32_e32 v2, vcc, 0x61000, v84
	s_lshl_b32 s0, s17, 2
	s_nop 0
	v_addc_co_u32_e32 v3, vcc, 0, v85, vcc
	v_add_co_u32_e32 v4, vcc, 0x62000, v84
	s_add_u32 s0, s18, s0
	s_nop 0
	v_addc_co_u32_e32 v5, vcc, 0, v85, vcc
	global_load_dwordx4 v[66:69], v[2:3], off offset:2048
	global_load_dwordx4 v[58:61], v[4:5], off
	s_addc_u32 s1, s19, 0
	v_lshl_add_u64 v[86:87], v[82:83], 2, s[0:1]
	s_and_saveexec_b64 s[0:1], s[36:37]
	s_cbranch_execz .LBB0_134
	s_or_b32 s12, s6, 1
	s_ashr_i32 s13, s12, 31
	s_lshl_b64 s[12:13], s[12:13], 12
	v_lshl_add_u64 v[2:3], v[86:87], 0, s[12:13]
	global_load_dword v93, v[2:3], off
; #define LAS __attribute__((address_space(3)))
; DI f32x4 mfma16(bf16x8 a, bf16x8 b, f32x4 c) { return __builtin_amdgcn_mfma_f32_16x16x32_bf16(a, b, c, 0, 0, 0); }
; DI void hgrn_passA(const Params& P, LAS unsigned char* lds, int u, bool skip_gates) {
;     ...
;     for (int ch = 0; ch < 8; ++ch) {
;         tr_write8(KT, 80, row * 2, seg * 8, rk); tr_write8(IT, 80, row * 2, seg * 8, ri);
;         if (tid < 128) { dec[tid] = rdec; dtot *= rdec; }
;         if (ch < 7) { const bf16_t* s2 = src + (size_t)(ch + 1) * 32 * LDU_E; rk = *(const u32x4*)(s2 + 3072); ri = *(const u32x4*)(s2 + 4096);
;             if (tid < 128) rdec = DEC[(size_t)(chunk0 + ch + 1) * 1024 + h * 128 + tid]; }
;         __syncthreads();
;         const bf16x8 bi = *(const LAS bf16x8*)(IT + (16 * w + r16) * 80 + g * 16);
; #pragma unroll
;         for (int dt = 0; dt < 8; ++dt) {
;             const bf16x8 a = *(const LAS bf16x8*)(KT + (16 * dt + r16) * 80 + g * 16);
;             acc[dt] = mfma16(a, bi, acc[dt]);
;             const f32x4 dv = *(const LAS f32x4*)(dec + 16 * dt + 4 * g);
;             acc[dt] *= dv;
;         }
;         __syncthreads();
;     }
.LBB0_134:
	s_or_b64 exec, exec, s[0:1]
	v_bfe_u32 v83, v82, 4, 2
	v_bfi_b32 v88, -16, v12, v82
	v_lshlrev_b32_e32 v6, 4, v83
	v_mul_lo_u32 v7, v88, s96
	v_and_b32_e32 v74, 15, v82
	v_add_u32_e32 v89, 0, v6
	v_add_u32_e32 v7, 0, v7
	v_mad_u32_u24 v34, v74, s96, v89
	v_add_u32_e32 v91, v7, v6
	s_waitcnt lgkmcnt(0)
	s_barrier
	ds_read_b128 v[2:5], v34
	ds_read_b128 v[22:25], v91 offset:10240
	ds_read_b128 v[6:9], v34 offset:1280
	ds_read_b128 v[10:13], v34 offset:2560
	ds_read_b128 v[14:17], v34 offset:3840
	ds_read_b128 v[18:21], v34 offset:5120
	ds_read_b128 v[26:29], v34 offset:6400
	ds_read_b128 v[30:33], v34 offset:7680
	ds_read_b128 v[34:37], v34 offset:8960
	ds_read_b128 v[70:73], v89 offset:20480
	ds_read_b128 v[62:65], v89 offset:20544
	ds_read_b128 v[54:57], v89 offset:20608
	ds_read_b128 v[50:53], v89 offset:20672
	ds_read_b128 v[46:49], v89 offset:20736
	ds_read_b128 v[42:45], v89 offset:20800
	s_waitcnt lgkmcnt(0)
	v_mfma_f32_16x16x32_bf16 v[2:5], v[2:5], v[22:25], 0
	v_mfma_f32_16x16x32_bf16 v[6:9], v[6:9], v[22:25], 0
	v_mfma_f32_16x16x32_bf16 v[10:13], v[10:13], v[22:25], 0
	v_mfma_f32_16x16x32_bf16 v[14:17], v[14:17], v[22:25], 0
	v_mfma_f32_16x16x32_bf16 v[18:21], v[18:21], v[22:25], 0
	v_mfma_f32_16x16x32_bf16 v[26:29], v[26:29], v[22:25], 0
	v_mfma_f32_16x16x32_bf16 v[30:33], v[30:33], v[22:25], 0
	v_mfma_f32_16x16x32_bf16 v[22:25], v[34:37], v[22:25], 0
	ds_read_b128 v[38:41], v89 offset:20864
	ds_read_b128 v[34:37], v89 offset:20928
	s_waitcnt lgkmcnt(0)
	s_barrier
	s_waitcnt vmcnt(0)
	ds_write_b16 v92, v66
	ds_write_b16_d16_hi v92, v66 offset:80
	ds_write_b16 v92, v67 offset:160
	ds_write_b16_d16_hi v92, v67 offset:240
	ds_write_b16 v92, v68 offset:320
	ds_write_b16_d16_hi v92, v68 offset:400
	ds_write_b16 v92, v69 offset:480
	ds_write_b16_d16_hi v92, v69 offset:560
	ds_write_b16 v92, v58 offset:10240
	ds_write_b16_d16_hi v92, v58 offset:10320
	ds_write_b16 v92, v59 offset:10400
	ds_write_b16_d16_hi v92, v59 offset:10480
	ds_write_b16 v92, v60 offset:10560
	ds_write_b16_d16_hi v92, v60 offset:10640
	ds_write_b16 v92, v61 offset:10720
	ds_write_b16_d16_hi v92, v61 offset:10800
	s_and_saveexec_b64 s[0:1], s[36:37]
	v_mul_f32_e32 v0, v0, v93
	ds_write_b32 v90, v93 offset:20480
	s_or_b64 exec, exec, s[0:1]
	v_add_co_u32_e32 v58, vcc, 0xc1000, v84
	s_nop 1
	v_addc_co_u32_e32 v59, vcc, 0, v85, vcc
	v_add_co_u32_e32 v60, vcc, 0xc2000, v84
	s_nop 1
	v_addc_co_u32_e32 v61, vcc, 0, v85, vcc
	global_load_dwordx4 v[66:69], v[58:59], off offset:2048
	s_nop 0
	global_load_dwordx4 v[58:61], v[60:61], off
	s_and_saveexec_b64 s[0:1], s[36:37]
	s_cbranch_execz .LBB0_138
	s_or_b32 s12, s6, 2
	s_ashr_i32 s13, s12, 31
	s_lshl_b64 s[12:13], s[12:13], 12
	v_lshl_add_u64 v[76:77], v[86:87], 0, s[12:13]
	global_load_dword v93, v[76:77], off
.LBB0_138:
	s_or_b64 exec, exec, s[0:1]
	v_mul_u32_u24_e32 v74, 0x50, v74
	v_add_u32_e32 v94, v89, v74
	s_waitcnt lgkmcnt(0)
	s_barrier
	ds_read_b128 v[74:77], v94
	ds_read_b128 v[96:99], v91 offset:10240
	ds_read_b128 v[78:81], v94 offset:1280
	v_pk_mul_f32 v[4:5], v[4:5], v[72:73]
	v_pk_mul_f32 v[2:3], v[2:3], v[70:71]
	ds_read_b128 v[70:73], v94 offset:2560
	v_pk_mul_f32 v[8:9], v[8:9], v[64:65]
	v_pk_mul_f32 v[6:7], v[6:7], v[62:63]
	ds_read_b128 v[62:65], v94 offset:3840
	v_pk_mul_f32 v[12:13], v[12:13], v[56:57]
	v_pk_mul_f32 v[10:11], v[10:11], v[54:55]
	ds_read_b128 v[54:57], v94 offset:5120
	v_pk_mul_f32 v[14:15], v[14:15], v[50:51]
	v_pk_mul_f32 v[20:21], v[20:21], v[48:49]
	ds_read_b128 v[48:51], v94 offset:6400
	v_pk_mul_f32 v[28:29], v[28:29], v[44:45]
	v_pk_mul_f32 v[26:27], v[26:27], v[42:43]
	ds_read_b128 v[42:45], v94 offset:7680
	s_waitcnt lgkmcnt(0)
	v_mfma_f32_16x16x32_bf16 v[2:5], v[74:77], v[96:99], v[2:5]
	ds_read_b128 v[74:77], v94 offset:8960
	v_pk_mul_f32 v[16:17], v[16:17], v[52:53]
	v_pk_mul_f32 v[18:19], v[18:19], v[46:47]
	v_pk_mul_f32 v[32:33], v[32:33], v[40:41]
	v_pk_mul_f32 v[30:31], v[30:31], v[38:39]
	v_mfma_f32_16x16x32_bf16 v[6:9], v[78:81], v[96:99], v[6:9]
	v_mul_f32_e64 v38, v24, v36
	v_mul_f32_e64 v39, v25, v37
	v_pk_mul_f32 v[36:37], v[22:23], v[34:35]
	v_mfma_f32_16x16x32_bf16 v[10:13], v[70:73], v[96:99], v[10:13]
	ds_read_b128 v[78:81], v89 offset:20480
	ds_read_b128 v[70:73], v89 offset:20544
	v_mfma_f32_16x16x32_bf16 v[14:17], v[62:65], v[96:99], v[14:17]
	v_mfma_f32_16x16x32_bf16 v[18:21], v[54:57], v[96:99], v[18:21]
	v_mfma_f32_16x16x32_bf16 v[24:27], v[48:51], v[96:99], v[26:29]
	v_mfma_f32_16x16x32_bf16 v[32:35], v[42:45], v[96:99], v[30:33]
	ds_read_b128 v[62:65], v89 offset:20608
	ds_read_b128 v[52:55], v89 offset:20672
	ds_read_b128 v[48:51], v89 offset:20736
	ds_read_b128 v[44:47], v89 offset:20800
	s_waitcnt lgkmcnt(0)
	v_mfma_f32_16x16x32_bf16 v[28:31], v[74:77], v[96:99], v[36:39]
	ds_read_b128 v[40:43], v89 offset:20864
	s_nop 1
	ds_read_b128 v[36:39], v89 offset:20928
	s_waitcnt lgkmcnt(0)
	s_barrier
	s_waitcnt vmcnt(0)
	ds_write_b16 v92, v66
	ds_write_b16_d16_hi v92, v66 offset:80
	ds_write_b16 v92, v67 offset:160
	ds_write_b16_d16_hi v92, v67 offset:240
	ds_write_b16 v92, v68 offset:320
	ds_write_b16_d16_hi v92, v68 offset:400
	ds_write_b16 v92, v69 offset:480
	ds_write_b16_d16_hi v92, v69 offset:560
	ds_write_b16 v92, v58 offset:10240
	ds_write_b16_d16_hi v92, v58 offset:10320
	ds_write_b16 v92, v59 offset:10400
	ds_write_b16_d16_hi v92, v59 offset:10480
	ds_write_b16 v92, v60 offset:10560
	ds_write_b16_d16_hi v92, v60 offset:10640
	ds_write_b16 v92, v61 offset:10720
	ds_write_b16_d16_hi v92, v61 offset:10800
	s_and_saveexec_b64 s[0:1], s[36:37]
	v_mul_f32_e32 v0, v0, v93
	ds_write_b32 v90, v93 offset:20480
	s_or_b64 exec, exec, s[0:1]
	v_add_co_u32_e32 v22, vcc, 0x121000, v84
	s_nop 1
	v_addc_co_u32_e32 v23, vcc, 0, v85, vcc
	v_add_co_u32_e32 v56, vcc, 0x122000, v84
	s_nop 1
	v_addc_co_u32_e32 v57, vcc, 0, v85, vcc
	global_load_dwordx4 v[74:77], v[22:23], off offset:2048
	s_nop 0
	global_load_dwordx4 v[56:59], v[56:57], off
	s_and_saveexec_b64 s[0:1], s[36:37]
	s_cbranch_execz .LBB0_142
	s_or_b32 s12, s6, 3
	s_ashr_i32 s13, s12, 31
	s_lshl_b64 s[12:13], s[12:13], 12
	v_lshl_add_u64 v[22:23], v[86:87], 0, s[12:13]
	global_load_dword v93, v[22:23], off
; #define LAS __attribute__((address_space(3)))
; DI f32x4 mfma16(bf16x8 a, bf16x8 b, f32x4 c) { return __builtin_amdgcn_mfma_f32_16x16x32_bf16(a, b, c, 0, 0, 0); }
; DI void hgrn_passA(const Params& P, LAS unsigned char* lds, int u, bool skip_gates) {
;     ...
;     for (int ch = 0; ch < 8; ++ch) {
;         tr_write8(KT, 80, row * 2, seg * 8, rk); tr_write8(IT, 80, row * 2, seg * 8, ri);
;         if (tid < 128) { dec[tid] = rdec; dtot *= rdec; }
;         if (ch < 7) { const bf16_t* s2 = src + (size_t)(ch + 1) * 32 * LDU_E; rk = *(const u32x4*)(s2 + 3072); ri = *(const u32x4*)(s2 + 4096);
;             if (tid < 128) rdec = DEC[(size_t)(chunk0 + ch + 1) * 1024 + h * 128 + tid]; }
;         __syncthreads();
;         const bf16x8 bi = *(const LAS bf16x8*)(IT + (16 * w + r16) * 80 + g * 16);
; #pragma unroll
;         for (int dt = 0; dt < 8; ++dt) {
;             const bf16x8 a = *(const LAS bf16x8*)(KT + (16 * dt + r16) * 80 + g * 16);
;             acc[dt] = mfma16(a, bi, acc[dt]);
;             const f32x4 dv = *(const LAS f32x4*)(dec + 16 * dt + 4 * g);
;             acc[dt] *= dv;
;         }
;         __syncthreads();
;     }
.LBB0_142:
	s_or_b64 exec, exec, s[0:1]
	s_waitcnt lgkmcnt(0)
	s_barrier
	ds_read_b128 v[66:69], v94
	ds_read_b128 v[96:99], v91 offset:10240
	ds_read_b128 v[100:103], v94 offset:1280
	v_pk_mul_f32 v[4:5], v[4:5], v[80:81]
	v_pk_mul_f32 v[2:3], v[2:3], v[78:79]
	v_pk_mul_f32 v[8:9], v[8:9], v[72:73]
	v_pk_mul_f32 v[6:7], v[6:7], v[70:71]
	s_waitcnt lgkmcnt(0)
	v_mfma_f32_16x16x32_bf16 v[2:5], v[66:69], v[96:99], v[2:5]
	ds_read_b128 v[66:69], v94 offset:2560
	ds_read_b128 v[70:73], v94 offset:3840
	v_pk_mul_f32 v[10:11], v[10:11], v[62:63]
	ds_read_b128 v[60:63], v94 offset:5120
	v_pk_mul_f32 v[14:15], v[14:15], v[52:53]
	v_pk_mul_f32 v[20:21], v[20:21], v[50:51]
	ds_read_b128 v[50:53], v94 offset:6400
	v_pk_mul_f32 v[26:27], v[26:27], v[46:47]
	v_pk_mul_f32 v[24:25], v[24:25], v[44:45]
	ds_read_b128 v[44:47], v94 offset:7680
	v_pk_mul_f32 v[12:13], v[12:13], v[64:65]
	v_pk_mul_f32 v[16:17], v[16:17], v[54:55]
	v_pk_mul_f32 v[18:19], v[18:19], v[48:49]
	s_waitcnt lgkmcnt(0)
	v_mfma_f32_16x16x32_bf16 v[10:13], v[66:69], v[96:99], v[10:13]
	v_mul_f32_e64 v34, v34, v42
	v_mul_f32_e64 v35, v35, v43
	v_pk_mul_f32 v[32:33], v[32:33], v[40:41]
	v_pk_mul_f32 v[38:39], v[30:31], v[38:39]
	v_mfma_f32_16x16x32_bf16 v[14:17], v[70:73], v[96:99], v[14:17]
	ds_read_b128 v[68:71], v94 offset:8960
	ds_read_b128 v[78:81], v89 offset:20480
	ds_read_b128 v[64:67], v89 offset:20544
	v_pk_mul_f32 v[36:37], v[28:29], v[36:37]
	v_mfma_f32_16x16x32_bf16 v[18:21], v[60:63], v[96:99], v[18:21]
	v_mfma_f32_16x16x32_bf16 v[22:25], v[50:53], v[96:99], v[24:27]
	v_mfma_f32_16x16x32_bf16 v[30:33], v[44:47], v[96:99], v[32:35]
	ds_read_b128 v[60:63], v89 offset:20608
	ds_read_b128 v[50:53], v89 offset:20672
	ds_read_b128 v[46:49], v89 offset:20736
	ds_read_b128 v[42:45], v89 offset:20800
	s_waitcnt lgkmcnt(0)
	v_mfma_f32_16x16x32_bf16 v[26:29], v[68:71], v[96:99], v[36:39]
	s_nop 2
	ds_read_b128 v[38:41], v89 offset:20864
	ds_read_b128 v[34:37], v89 offset:20928
	s_waitcnt lgkmcnt(0)
	s_barrier
	v_mfma_f32_16x16x32_bf16 v[6:9], v[100:103], v[96:99], v[6:9]
	s_waitcnt vmcnt(0)
	ds_write_b16 v92, v74
	ds_write_b16_d16_hi v92, v74 offset:80
	ds_write_b16 v92, v75 offset:160
	ds_write_b16_d16_hi v92, v75 offset:240
	ds_write_b16 v92, v76 offset:320
	ds_write_b16_d16_hi v92, v76 offset:400
	ds_write_b16 v92, v77 offset:480
	ds_write_b16_d16_hi v92, v77 offset:560
	ds_write_b16 v92, v56 offset:10240
	ds_write_b16_d16_hi v92, v56 offset:10320
	ds_write_b16 v92, v57 offset:10400
	ds_write_b16_d16_hi v92, v57 offset:10480
	ds_write_b16 v92, v58 offset:10560
	ds_write_b16_d16_hi v92, v58 offset:10640
	ds_write_b16 v92, v59 offset:10720
	ds_write_b16_d16_hi v92, v59 offset:10800
	s_and_saveexec_b64 s[0:1], s[36:37]
	v_mul_f32_e32 v0, v0, v93
	ds_write_b32 v90, v93 offset:20480
	s_or_b64 exec, exec, s[0:1]
	v_add_co_u32_e32 v54, vcc, 0x181000, v84
	s_nop 1
	v_addc_co_u32_e32 v55, vcc, 0, v85, vcc
	v_add_co_u32_e32 v56, vcc, 0x182000, v84
	s_nop 1
	v_addc_co_u32_e32 v57, vcc, 0, v85, vcc
	global_load_dwordx4 v[68:71], v[54:55], off offset:2048
	s_nop 0
	global_load_dwordx4 v[54:57], v[56:57], off
	s_and_saveexec_b64 s[0:1], s[36:37]
	s_cbranch_execz .LBB0_146
	s_or_b32 s12, s6, 4
	s_ashr_i32 s13, s12, 31
	s_lshl_b64 s[12:13], s[12:13], 12
	v_lshl_add_u64 v[58:59], v[86:87], 0, s[12:13]
	global_load_dword v93, v[58:59], off
.LBB0_146:
	s_or_b64 exec, exec, s[0:1]
	s_waitcnt lgkmcnt(0)
	s_barrier
	ds_read_b128 v[72:75], v94
	ds_read_b128 v[96:99], v91 offset:10240
	ds_read_b128 v[100:103], v94 offset:1280
	v_pk_mul_f32 v[4:5], v[4:5], v[80:81]
	v_pk_mul_f32 v[2:3], v[2:3], v[78:79]
	v_pk_mul_f32 v[8:9], v[8:9], v[66:67]
	v_pk_mul_f32 v[6:7], v[6:7], v[64:65]
	s_waitcnt lgkmcnt(0)
	v_mfma_f32_16x16x32_bf16 v[2:5], v[72:75], v[96:99], v[2:5]
	ds_read_b128 v[72:75], v94 offset:2560
	ds_read_b128 v[64:67], v94 offset:3840
	v_pk_mul_f32 v[10:11], v[10:11], v[60:61]
	ds_read_b128 v[58:61], v94 offset:5120
	v_pk_mul_f32 v[14:15], v[14:15], v[50:51]
	v_pk_mul_f32 v[20:21], v[20:21], v[48:49]
	ds_read_b128 v[48:51], v94 offset:6400
	v_pk_mul_f32 v[24:25], v[24:25], v[44:45]
	v_pk_mul_f32 v[22:23], v[22:23], v[42:43]
	ds_read_b128 v[42:45], v94 offset:7680
	v_pk_mul_f32 v[30:31], v[30:31], v[38:39]
	v_pk_mul_f32 v[28:29], v[28:29], v[36:37]
	ds_read_b128 v[36:39], v94 offset:8960
	v_pk_mul_f32 v[12:13], v[12:13], v[62:63]
	v_pk_mul_f32 v[16:17], v[16:17], v[52:53]
	v_pk_mul_f32 v[18:19], v[18:19], v[46:47]
	v_pk_mul_f32 v[32:33], v[32:33], v[40:41]
	s_waitcnt lgkmcnt(0)
	v_mfma_f32_16x16x32_bf16 v[10:13], v[72:75], v[96:99], v[10:13]
	v_mul_f32_e64 v26, v26, v34
	v_mul_f32_e64 v27, v27, v35
	v_mfma_f32_16x16x32_bf16 v[14:17], v[64:67], v[96:99], v[14:17]
	ds_read_b128 v[72:75], v89 offset:20480
	ds_read_b128 v[62:65], v89 offset:20544
	v_mfma_f32_16x16x32_bf16 v[18:21], v[58:61], v[96:99], v[18:21]
	v_mfma_f32_16x16x32_bf16 v[22:25], v[48:51], v[96:99], v[22:25]
	v_mfma_f32_16x16x32_bf16 v[30:33], v[42:45], v[96:99], v[30:33]
	ds_read_b128 v[58:61], v89 offset:20608
	ds_read_b128 v[50:53], v89 offset:20672
	ds_read_b128 v[46:49], v89 offset:20736
	ds_read_b128 v[42:45], v89 offset:20800
	v_mfma_f32_16x16x32_bf16 v[26:29], v[36:39], v[96:99], v[26:29]
	ds_read_b128 v[38:41], v89 offset:20864
	ds_read_b128 v[34:37], v89 offset:20928
	s_waitcnt lgkmcnt(0)
	s_barrier
	v_mfma_f32_16x16x32_bf16 v[6:9], v[100:103], v[96:99], v[6:9]
	s_waitcnt vmcnt(0)
	ds_write_b16 v92, v68
	ds_write_b16_d16_hi v92, v68 offset:80
	ds_write_b16 v92, v69 offset:160
	ds_write_b16_d16_hi v92, v69 offset:240
	ds_write_b16 v92, v70 offset:320
	ds_write_b16_d16_hi v92, v70 offset:400
	ds_write_b16 v92, v71 offset:480
	ds_write_b16_d16_hi v92, v71 offset:560
	ds_write_b16 v92, v54 offset:10240
	ds_write_b16_d16_hi v92, v54 offset:10320
	ds_write_b16 v92, v55 offset:10400
	ds_write_b16_d16_hi v92, v55 offset:10480
	ds_write_b16 v92, v56 offset:10560
	ds_write_b16_d16_hi v92, v56 offset:10640
	ds_write_b16 v92, v57 offset:10720
	ds_write_b16_d16_hi v92, v57 offset:10800
	s_and_saveexec_b64 s[0:1], s[36:37]
	v_mul_f32_e32 v0, v0, v93
	ds_write_b32 v90, v93 offset:20480
	s_or_b64 exec, exec, s[0:1]
	v_add_co_u32_e32 v54, vcc, 0x1e1000, v84
	s_nop 1
	v_addc_co_u32_e32 v55, vcc, 0, v85, vcc
	v_add_co_u32_e32 v56, vcc, 0x1e2000, v84
	s_nop 1
	v_addc_co_u32_e32 v57, vcc, 0, v85, vcc
	global_load_dwordx4 v[66:69], v[54:55], off offset:2048
	s_nop 0
	global_load_dwordx4 v[54:57], v[56:57], off
	s_and_saveexec_b64 s[0:1], s[36:37]
	s_cbranch_execz .LBB0_150
	s_or_b32 s12, s6, 5
	s_ashr_i32 s13, s12, 31
	s_lshl_b64 s[12:13], s[12:13], 12
	v_lshl_add_u64 v[70:71], v[86:87], 0, s[12:13]
	global_load_dword v93, v[70:71], off
; #define LAS __attribute__((address_space(3)))
; DI f32x4 mfma16(bf16x8 a, bf16x8 b, f32x4 c) { return __builtin_amdgcn_mfma_f32_16x16x32_bf16(a, b, c, 0, 0, 0); }
; DI void hgrn_passA(const Params& P, LAS unsigned char* lds, int u, bool skip_gates) {
;     ...
;     for (int ch = 0; ch < 8; ++ch) {
;         tr_write8(KT, 80, row * 2, seg * 8, rk); tr_write8(IT, 80, row * 2, seg * 8, ri);
;         if (tid < 128) { dec[tid] = rdec; dtot *= rdec; }
;         if (ch < 7) { const bf16_t* s2 = src + (size_t)(ch + 1) * 32 * LDU_E; rk = *(const u32x4*)(s2 + 3072); ri = *(const u32x4*)(s2 + 4096);
;             if (tid < 128) rdec = DEC[(size_t)(chunk0 + ch + 1) * 1024 + h * 128 + tid]; }
;         __syncthreads();
;         const bf16x8 bi = *(const LAS bf16x8*)(IT + (16 * w + r16) * 80 + g * 16);
; #pragma unroll
;         for (int dt = 0; dt < 8; ++dt) {
;             const bf16x8 a = *(const LAS bf16x8*)(KT + (16 * dt + r16) * 80 + g * 16);
;             acc[dt] = mfma16(a, bi, acc[dt]);
;             const f32x4 dv = *(const LAS f32x4*)(dec + 16 * dt + 4 * g);
;             acc[dt] *= dv;
;         }
;         __syncthreads();
;     }
.LBB0_150:
	s_or_b64 exec, exec, s[0:1]
	s_waitcnt lgkmcnt(0)
	s_barrier
	ds_read_b128 v[76:79], v94
	ds_read_b128 v[96:99], v91 offset:10240
	ds_read_b128 v[100:103], v94 offset:1280
	v_pk_mul_f32 v[2:3], v[2:3], v[72:73]
	ds_read_b128 v[70:73], v94 offset:2560
	v_pk_mul_f32 v[8:9], v[8:9], v[64:65]
	v_pk_mul_f32 v[6:7], v[6:7], v[62:63]
	ds_read_b128 v[62:65], v94 offset:3840
	v_pk_mul_f32 v[12:13], v[12:13], v[60:61]
	v_pk_mul_f32 v[10:11], v[10:11], v[58:59]
	ds_read_b128 v[58:61], v94 offset:5120
	v_pk_mul_f32 v[14:15], v[14:15], v[50:51]
	v_pk_mul_f32 v[20:21], v[20:21], v[48:49]
	ds_read_b128 v[48:51], v94 offset:6400
	v_pk_mul_f32 v[24:25], v[24:25], v[44:45]
	v_pk_mul_f32 v[22:23], v[22:23], v[42:43]
	ds_read_b128 v[42:45], v94 offset:7680
	v_pk_mul_f32 v[30:31], v[30:31], v[38:39]
	v_pk_mul_f32 v[28:29], v[28:29], v[36:37]
	ds_read_b128 v[36:39], v94 offset:8960
	v_pk_mul_f32 v[16:17], v[16:17], v[52:53]
	v_pk_mul_f32 v[18:19], v[18:19], v[46:47]
	v_pk_mul_f32 v[32:33], v[32:33], v[40:41]
	s_waitcnt lgkmcnt(0)
	v_mfma_f32_16x16x32_bf16 v[10:13], v[70:73], v[96:99], v[10:13]
	v_mul_f32_e64 v26, v26, v34
	v_mul_f32_e64 v27, v27, v35
	v_pk_mul_f32 v[4:5], v[4:5], v[74:75]
	v_mfma_f32_16x16x32_bf16 v[14:17], v[62:65], v[96:99], v[14:17]
	ds_read_b128 v[70:73], v89 offset:20480
	ds_read_b128 v[62:65], v89 offset:20544
	v_mfma_f32_16x16x32_bf16 v[18:21], v[58:61], v[96:99], v[18:21]
	v_mfma_f32_16x16x32_bf16 v[22:25], v[48:51], v[96:99], v[22:25]
	v_mfma_f32_16x16x32_bf16 v[30:33], v[42:45], v[96:99], v[30:33]
	ds_read_b128 v[58:61], v89 offset:20608
	ds_read_b128 v[50:53], v89 offset:20672
	ds_read_b128 v[46:49], v89 offset:20736
	ds_read_b128 v[42:45], v89 offset:20800
	v_mfma_f32_16x16x32_bf16 v[26:29], v[36:39], v[96:99], v[26:29]
	ds_read_b128 v[38:41], v89 offset:20864
	ds_read_b128 v[34:37], v89 offset:20928
	s_waitcnt lgkmcnt(0)
	s_barrier
	v_mfma_f32_16x16x32_bf16 v[2:5], v[76:79], v[96:99], v[2:5]
	s_waitcnt vmcnt(0)
	ds_write_b16 v92, v66
	ds_write_b16_d16_hi v92, v66 offset:80
	ds_write_b16 v92, v67 offset:160
	ds_write_b16_d16_hi v92, v67 offset:240
	ds_write_b16 v92, v68 offset:320
	ds_write_b16_d16_hi v92, v68 offset:400
	ds_write_b16 v92, v69 offset:480
	ds_write_b16_d16_hi v92, v69 offset:560
	ds_write_b16 v92, v54 offset:10240
	ds_write_b16_d16_hi v92, v54 offset:10320
	ds_write_b16 v92, v55 offset:10400
	ds_write_b16_d16_hi v92, v55 offset:10480
	ds_write_b16 v92, v56 offset:10560
	ds_write_b16_d16_hi v92, v56 offset:10640
	ds_write_b16 v92, v57 offset:10720
	ds_write_b16_d16_hi v92, v57 offset:10800
	v_mfma_f32_16x16x32_bf16 v[6:9], v[100:103], v[96:99], v[6:9]
	s_and_saveexec_b64 s[0:1], s[36:37]
	v_mul_f32_e32 v0, v0, v93
	ds_write_b32 v90, v93 offset:20480
	s_or_b64 exec, exec, s[0:1]
	v_add_co_u32_e32 v54, vcc, 0x241000, v84
	s_nop 1
	v_addc_co_u32_e32 v55, vcc, 0, v85, vcc
	v_add_co_u32_e32 v56, vcc, 0x242000, v84
	s_nop 1
	v_addc_co_u32_e32 v57, vcc, 0, v85, vcc
	global_load_dwordx4 v[66:69], v[54:55], off offset:2048
	s_nop 0
	global_load_dwordx4 v[54:57], v[56:57], off
	s_and_saveexec_b64 s[0:1], s[36:37]
	s_cbranch_execz .LBB0_154
	s_or_b32 s12, s6, 6
	s_ashr_i32 s13, s12, 31
	s_lshl_b64 s[12:13], s[12:13], 12
	v_lshl_add_u64 v[74:75], v[86:87], 0, s[12:13]
	global_load_dword v93, v[74:75], off
.LBB0_154:
	s_or_b64 exec, exec, s[0:1]
	s_waitcnt lgkmcnt(0)
	s_barrier
	ds_read_b128 v[74:77], v94
	ds_read_b128 v[78:81], v91 offset:10240
	ds_read_b128 v[96:99], v94 offset:1280
	v_pk_mul_f32 v[4:5], v[4:5], v[72:73]
	v_pk_mul_f32 v[2:3], v[2:3], v[70:71]
	ds_read_b128 v[70:73], v94 offset:2560
	v_pk_mul_f32 v[8:9], v[8:9], v[64:65]
	v_pk_mul_f32 v[6:7], v[6:7], v[62:63]
	ds_read_b128 v[62:65], v94 offset:3840
	v_pk_mul_f32 v[12:13], v[12:13], v[60:61]
	v_pk_mul_f32 v[10:11], v[10:11], v[58:59]
	ds_read_b128 v[58:61], v94 offset:5120
	v_pk_mul_f32 v[14:15], v[14:15], v[50:51]
	v_pk_mul_f32 v[20:21], v[20:21], v[48:49]
	ds_read_b128 v[48:51], v94 offset:6400
	v_pk_mul_f32 v[24:25], v[24:25], v[44:45]
	v_pk_mul_f32 v[22:23], v[22:23], v[42:43]
	ds_read_b128 v[42:45], v94 offset:7680
	v_pk_mul_f32 v[30:31], v[30:31], v[38:39]
	v_pk_mul_f32 v[28:29], v[28:29], v[36:37]
	ds_read_b128 v[36:39], v94 offset:8960
	v_pk_mul_f32 v[16:17], v[16:17], v[52:53]
	v_pk_mul_f32 v[18:19], v[18:19], v[46:47]
	v_pk_mul_f32 v[32:33], v[32:33], v[40:41]
	s_waitcnt lgkmcnt(0)
	v_mfma_f32_16x16x32_bf16 v[10:13], v[70:73], v[78:81], v[10:13]
	v_mul_f32_e64 v26, v26, v34
	v_mul_f32_e64 v27, v27, v35
	v_mfma_f32_16x16x32_bf16 v[14:17], v[62:65], v[78:81], v[14:17]
	ds_read_b128 v[70:73], v89 offset:20480
	ds_read_b128 v[62:65], v89 offset:20544
	v_mfma_f32_16x16x32_bf16 v[18:21], v[58:61], v[78:81], v[18:21]
	v_mfma_f32_16x16x32_bf16 v[22:25], v[48:51], v[78:81], v[22:25]
	v_mfma_f32_16x16x32_bf16 v[30:33], v[42:45], v[78:81], v[30:33]
	ds_read_b128 v[58:61], v89 offset:20608
	ds_read_b128 v[50:53], v89 offset:20672
	ds_read_b128 v[46:49], v89 offset:20736
	ds_read_b128 v[42:45], v89 offset:20800
	v_mfma_f32_16x16x32_bf16 v[26:29], v[36:39], v[78:81], v[26:29]
	ds_read_b128 v[38:41], v89 offset:20864
	ds_read_b128 v[34:37], v89 offset:20928
	s_waitcnt lgkmcnt(0)
	s_barrier
	v_mfma_f32_16x16x32_bf16 v[2:5], v[74:77], v[78:81], v[2:5]
	s_waitcnt vmcnt(0)
	ds_write_b16 v92, v66
	ds_write_b16_d16_hi v92, v66 offset:80
	ds_write_b16 v92, v67 offset:160
	ds_write_b16_d16_hi v92, v67 offset:240
	ds_write_b16 v92, v68 offset:320
	ds_write_b16_d16_hi v92, v68 offset:400
	ds_write_b16 v92, v69 offset:480
	ds_write_b16_d16_hi v92, v69 offset:560
	ds_write_b16 v92, v54 offset:10240
	ds_write_b16_d16_hi v92, v54 offset:10320
	ds_write_b16 v92, v55 offset:10400
	ds_write_b16_d16_hi v92, v55 offset:10480
	ds_write_b16 v92, v56 offset:10560
	ds_write_b16_d16_hi v92, v56 offset:10640
	ds_write_b16 v92, v57 offset:10720
	ds_write_b16_d16_hi v92, v57 offset:10800
	v_mfma_f32_16x16x32_bf16 v[6:9], v[96:99], v[78:81], v[6:9]
	s_and_saveexec_b64 s[0:1], s[36:37]
	v_mul_f32_e32 v0, v0, v93
	ds_write_b32 v90, v93 offset:20480
	s_or_b64 exec, exec, s[0:1]
	v_add_co_u32_e32 v54, vcc, 0x2a1000, v84
	s_nop 1
	v_addc_co_u32_e32 v55, vcc, 0, v85, vcc
	v_add_co_u32_e32 v56, vcc, 0x2a2000, v84
	s_nop 1
	v_addc_co_u32_e32 v57, vcc, 0, v85, vcc
	global_load_dwordx4 v[66:69], v[54:55], off offset:2048
	s_nop 0
	global_load_dwordx4 v[54:57], v[56:57], off
	s_and_saveexec_b64 s[0:1], s[36:37]
	s_cbranch_execz .LBB0_158
	s_or_b32 s6, s6, 7
	s_ashr_i32 s7, s6, 31
	s_lshl_b64 s[6:7], s[6:7], 12
	v_lshl_add_u64 v[74:75], v[86:87], 0, s[6:7]
	global_load_dword v93, v[74:75], off
; #define LAS __attribute__((address_space(3)))
; DI f32x4 mfma16(bf16x8 a, bf16x8 b, f32x4 c) { return __builtin_amdgcn_mfma_f32_16x16x32_bf16(a, b, c, 0, 0, 0); }
; DI void hgrn_passA(const Params& P, LAS unsigned char* lds, int u, bool skip_gates) {
;     ...
;         __syncthreads();
;         const bf16x8 bi = *(const LAS bf16x8*)(IT + (16 * w + r16) * 80 + g * 16);
; #pragma unroll
;         for (int dt = 0; dt < 8; ++dt) {
;             const bf16x8 a = *(const LAS bf16x8*)(KT + (16 * dt + r16) * 80 + g * 16);
;             acc[dt] = mfma16(a, bi, acc[dt]);
;             const f32x4 dv = *(const LAS f32x4*)(dec + 16 * dt + 4 * g);
;             acc[dt] *= dv;
;         }
;         __syncthreads();
;     }
.LBB0_158:
	s_or_b64 exec, exec, s[0:1]
	s_waitcnt lgkmcnt(0)
	s_barrier
	ds_read_b128 v[74:77], v94
	ds_read_b128 v[78:81], v91 offset:10240
	ds_read_b128 v[84:87], v94 offset:1280
	v_pk_mul_f32 v[4:5], v[4:5], v[72:73]
	v_pk_mul_f32 v[2:3], v[2:3], v[70:71]
	v_pk_mul_f32 v[8:9], v[8:9], v[64:65]
	v_pk_mul_f32 v[6:7], v[6:7], v[62:63]
	s_waitcnt lgkmcnt(0)
	v_mfma_f32_16x16x32_bf16 v[70:73], v[74:77], v[78:81], v[2:5]
	v_mul_f32_e64 v12, v12, v60
	v_mul_f32_e64 v13, v13, v61
	v_pk_mul_f32 v[10:11], v[10:11], v[58:59]
	ds_read_b128 v[2:5], v94 offset:2560
	v_mfma_f32_16x16x32_bf16 v[62:65], v[84:87], v[78:81], v[6:9]
	v_mul_f32_e64 v86, v28, v36
	v_mul_f32_e64 v87, v29, v37
	v_pk_mul_f32 v[84:85], v[26:27], v[34:35]
	ds_read_b128 v[6:9], v94 offset:3840
	s_waitcnt lgkmcnt(0)
	v_mfma_f32_16x16x32_bf16 v[58:61], v[2:5], v[78:81], v[10:13]
	ds_read_b128 v[2:5], v94 offset:5120
	s_nop 1
	v_pk_mul_f32 v[12:13], v[16:17], v[52:53]
	v_pk_mul_f32 v[10:11], v[14:15], v[50:51]
	v_pk_mul_f32 v[14:15], v[20:21], v[48:49]
	v_pk_mul_f32 v[16:17], v[22:23], v[42:43]
	v_mfma_f32_16x16x32_bf16 v[48:51], v[6:9], v[78:81], v[10:13]
	ds_read_b128 v[6:9], v94 offset:6400
	v_pk_mul_f32 v[22:23], v[32:33], v[40:41]
	v_pk_mul_f32 v[20:21], v[30:31], v[38:39]
	v_pk_mul_f32 v[12:13], v[18:19], v[46:47]
	v_pk_mul_f32 v[18:19], v[24:25], v[44:45]
	s_waitcnt lgkmcnt(0)
	v_mfma_f32_16x16x32_bf16 v[42:45], v[2:5], v[78:81], v[12:15]
	s_nop 2
	ds_read_b128 v[10:13], v94 offset:7680
	v_mfma_f32_16x16x32_bf16 v[2:5], v[6:9], v[78:81], v[16:19]
	s_nop 2
	ds_read_b128 v[14:17], v94 offset:8960
	ds_read_b128 v[74:77], v89 offset:20480
	ds_read_b128 v[38:41], v89 offset:20544
	s_waitcnt lgkmcnt(0)
	v_mfma_f32_16x16x32_bf16 v[6:9], v[10:13], v[78:81], v[20:23]
	ds_read_b128 v[34:37], v89 offset:20608
	ds_read_b128 v[30:33], v89 offset:20672
	ds_read_b128 v[26:29], v89 offset:20736
	ds_read_b128 v[18:21], v89 offset:20800
	v_mfma_f32_16x16x32_bf16 v[10:13], v[14:17], v[78:81], v[84:87]
	ds_read_b128 v[22:25], v89 offset:20864
	ds_read_b128 v[14:17], v89 offset:20928
	s_waitcnt lgkmcnt(0)
	s_barrier
	s_waitcnt vmcnt(0)
	ds_write_b16 v92, v66
	ds_write_b16_d16_hi v92, v66 offset:80
	ds_write_b16 v92, v67 offset:160
	ds_write_b16_d16_hi v92, v67 offset:240
	ds_write_b16 v92, v68 offset:320
	ds_write_b16_d16_hi v92, v68 offset:400
	ds_write_b16 v92, v69 offset:480
	ds_write_b16_d16_hi v92, v69 offset:560
	ds_write_b16 v92, v54 offset:10240
	ds_write_b16_d16_hi v92, v54 offset:10320
	ds_write_b16 v92, v55 offset:10400
	ds_write_b16_d16_hi v92, v55 offset:10480
	ds_write_b16 v92, v56 offset:10560
	ds_write_b16_d16_hi v92, v56 offset:10640
	ds_write_b16 v92, v57 offset:10720
	ds_write_b16_d16_hi v92, v57 offset:10800
	s_and_saveexec_b64 s[0:1], s[36:37]
	v_mul_f32_e32 v0, v0, v93
	ds_write_b32 v90, v93 offset:20480
	s_or_b64 exec, exec, s[0:1]
	v_pk_mul_f32 v[30:31], v[48:49], v[30:31]
	v_pk_mul_f32 v[28:29], v[44:45], v[28:29]
	v_pk_mul_f32 v[26:27], v[42:43], v[26:27]
	s_waitcnt lgkmcnt(0)
	s_barrier
	ds_read_b128 v[42:45], v91 offset:10240
	ds_read_b128 v[46:49], v94
	v_pk_mul_f32 v[54:55], v[72:73], v[76:77]
	v_pk_mul_f32 v[52:53], v[70:71], v[74:75]
	v_pk_mul_f32 v[4:5], v[4:5], v[20:21]
	v_pk_mul_f32 v[2:3], v[2:3], v[18:19]
	v_pk_mul_f32 v[12:13], v[12:13], v[16:17]
	v_pk_mul_f32 v[10:11], v[10:11], v[14:15]
	ds_read_b128 v[14:17], v94 offset:1280
	ds_read_b128 v[18:21], v89 offset:20480
	v_pk_mul_f32 v[8:9], v[8:9], v[24:25]
	v_pk_mul_f32 v[6:7], v[6:7], v[22:23]
	s_waitcnt lgkmcnt(2)
	v_mfma_f32_16x16x32_bf16 v[22:25], v[46:49], v[42:45], v[52:55]
	v_mul_f32_e64 v32, v50, v32
	v_mul_f32_e64 v33, v51, v33
	ds_read_b128 v[46:49], v89 offset:20544
	v_pk_mul_f32 v[40:41], v[64:65], v[40:41]
	v_pk_mul_f32 v[38:39], v[62:63], v[38:39]
	v_pk_mul_f32 v[36:37], v[60:61], v[36:37]
	s_waitcnt lgkmcnt(1)
	s_nop 0
	v_pk_mul_f32 v[50:51], v[24:25], v[20:21]
	v_pk_mul_f32 v[52:53], v[22:23], v[18:19]
	ds_read_b128 v[18:21], v94 offset:2560
	v_mfma_f32_16x16x32_bf16 v[14:17], v[14:17], v[42:45], v[38:41]
	v_mul_f32_e64 v34, v58, v34
	v_mul_f32_e64 v35, v59, v35
	s_ashr_i32 s17, s16, 31
	s_lshl_b64 s[0:1], s[16:17], 16
	s_waitcnt lgkmcnt(0)
	v_mfma_f32_16x16x32_bf16 v[18:21], v[18:21], v[42:45], v[34:37]
	s_nop 1
	v_mul_f32_e64 v38, v16, v48
	v_mul_f32_e64 v39, v17, v49
	v_pk_mul_f32 v[40:41], v[14:15], v[46:47]
	ds_read_b128 v[14:17], v94 offset:3840
	ds_read_b128 v[22:25], v89 offset:20608
	ds_read_b128 v[34:37], v89 offset:20672
	s_waitcnt lgkmcnt(2)
	v_mfma_f32_16x16x32_bf16 v[14:17], v[14:17], v[42:45], v[30:33]
	s_waitcnt lgkmcnt(1)
	v_pk_mul_f32 v[46:47], v[20:21], v[24:25]
	v_pk_mul_f32 v[48:49], v[18:19], v[22:23]
	ds_read_b128 v[18:21], v94 offset:5120
	s_waitcnt lgkmcnt(1)
	s_nop 2
	v_pk_mul_f32 v[30:31], v[16:17], v[36:37]
	v_pk_mul_f32 v[32:33], v[14:15], v[34:35]
	ds_read_b128 v[14:17], v94 offset:6400
	ds_read_b128 v[22:25], v89 offset:20736
	s_waitcnt lgkmcnt(2)
	v_mfma_f32_16x16x32_bf16 v[18:21], v[18:21], v[42:45], v[26:29]
	s_nop 2
	ds_read_b128 v[26:29], v89 offset:20800
	s_add_u32 s0, s98, s0
	s_addc_u32 s1, s99, s1
	s_waitcnt lgkmcnt(1)
	s_nop 0
	v_pk_mul_f32 v[24:25], v[20:21], v[24:25]
	v_pk_mul_f32 v[22:23], v[18:19], v[22:23]
	ds_read_b128 v[18:21], v94 offset:7680
	v_mfma_f32_16x16x32_bf16 v[2:5], v[14:17], v[42:45], v[2:5]
	ds_read_b128 v[14:17], v94 offset:8960
	s_waitcnt lgkmcnt(1)
	v_mfma_f32_16x16x32_bf16 v[6:9], v[18:21], v[42:45], v[6:9]
	ds_read_b128 v[18:21], v89 offset:20928
	s_nop 3
	v_pk_mul_f32 v[28:29], v[4:5], v[28:29]
	v_pk_mul_f32 v[26:27], v[2:3], v[26:27]
	ds_read_b128 v[2:5], v89 offset:20864
	s_waitcnt lgkmcnt(0)
	s_barrier
; DI void hgrn_passA(const Params& P, LAS unsigned char* lds, int u, bool skip_gates) {
;     ...
;     float* SE = (float*)(P.ws + WS_SE) + (size_t)u * 16384;
; #pragma unroll
;     for (int dt = 0; dt < 8; ++dt)
; #pragma unroll
;         for (int j = 0; j < 4; ++j) SE[(16 * dt + 4 * g + j) * 128 + 16 * w + r16] = acc[dt][j];
;     if (tid < 128) ((float*)(P.ws + WS_DT))[u * 128 + tid] = dtot;
	v_pk_mul_f32 v[8:9], v[8:9], v[4:5]
	v_pk_mul_f32 v[6:7], v[6:7], v[2:3]
	v_mfma_f32_16x16x32_bf16 v[2:5], v[14:17], v[42:45], v[10:13]
	s_nop 2
	v_lshl_add_u32 v10, v83, 9, v88
	v_ashrrev_i32_e32 v11, 31, v10
	v_lshl_add_u64 v[12:13], v[10:11], 2, s[0:1]
	global_store_dword v[12:13], v52, off
	global_store_dword v[12:13], v53, off offset:512
	global_store_dword v[12:13], v50, off offset:1024
	global_store_dword v[12:13], v51, off offset:1536
	v_add_u32_e32 v12, 0x800, v10
	v_ashrrev_i32_e32 v13, 31, v12
	v_lshl_add_u64 v[12:13], v[12:13], 2, s[0:1]
	global_store_dword v[12:13], v40, off
	v_add_u32_e32 v12, 0x880, v10
	v_ashrrev_i32_e32 v13, 31, v12
	v_lshl_add_u64 v[12:13], v[12:13], 2, s[0:1]
	global_store_dword v[12:13], v41, off
	v_add_u32_e32 v12, 0x900, v10
	v_ashrrev_i32_e32 v13, 31, v12
	v_lshl_add_u64 v[12:13], v[12:13], 2, s[0:1]
	global_store_dword v[12:13], v38, off
	v_add_u32_e32 v12, 0x980, v10
	v_ashrrev_i32_e32 v13, 31, v12
	v_lshl_add_u64 v[12:13], v[12:13], 2, s[0:1]
	global_store_dword v[12:13], v39, off
	v_add_u32_e32 v12, 0x1000, v10
	v_ashrrev_i32_e32 v13, 31, v12
	v_lshl_add_u64 v[12:13], v[12:13], 2, s[0:1]
	global_store_dword v[12:13], v48, off
	v_add_u32_e32 v12, 0x1080, v10
	v_ashrrev_i32_e32 v13, 31, v12
	v_lshl_add_u64 v[12:13], v[12:13], 2, s[0:1]
	global_store_dword v[12:13], v49, off
	v_add_u32_e32 v12, 0x1100, v10
	v_ashrrev_i32_e32 v13, 31, v12
	v_lshl_add_u64 v[12:13], v[12:13], 2, s[0:1]
	global_store_dword v[12:13], v46, off
	v_add_u32_e32 v12, 0x1180, v10
	v_ashrrev_i32_e32 v13, 31, v12
	v_lshl_add_u64 v[12:13], v[12:13], 2, s[0:1]
	global_store_dword v[12:13], v47, off
	v_add_u32_e32 v12, 0x1800, v10
	v_ashrrev_i32_e32 v13, 31, v12
	v_lshl_add_u64 v[12:13], v[12:13], 2, s[0:1]
	global_store_dword v[12:13], v32, off
	v_add_u32_e32 v12, 0x1880, v10
	v_ashrrev_i32_e32 v13, 31, v12
	v_lshl_add_u64 v[12:13], v[12:13], 2, s[0:1]
	global_store_dword v[12:13], v33, off
	v_add_u32_e32 v12, 0x1900, v10
	v_ashrrev_i32_e32 v13, 31, v12
	v_lshl_add_u64 v[12:13], v[12:13], 2, s[0:1]
	global_store_dword v[12:13], v30, off
	v_add_u32_e32 v12, 0x1980, v10
	v_ashrrev_i32_e32 v13, 31, v12
	v_lshl_add_u64 v[12:13], v[12:13], 2, s[0:1]
	global_store_dword v[12:13], v31, off
	v_add_u32_e32 v12, 0x2000, v10
	v_ashrrev_i32_e32 v13, 31, v12
	v_lshl_add_u64 v[12:13], v[12:13], 2, s[0:1]
	global_store_dword v[12:13], v22, off
	v_add_u32_e32 v12, 0x2080, v10
	v_ashrrev_i32_e32 v13, 31, v12
	v_lshl_add_u64 v[12:13], v[12:13], 2, s[0:1]
	global_store_dword v[12:13], v23, off
	v_add_u32_e32 v12, 0x2100, v10
	v_ashrrev_i32_e32 v13, 31, v12
	v_lshl_add_u64 v[12:13], v[12:13], 2, s[0:1]
	global_store_dword v[12:13], v24, off
	v_add_u32_e32 v12, 0x2180, v10
	v_ashrrev_i32_e32 v13, 31, v12
	v_lshl_add_u64 v[12:13], v[12:13], 2, s[0:1]
	global_store_dword v[12:13], v25, off
	v_add_u32_e32 v12, 0x2800, v10
	v_ashrrev_i32_e32 v13, 31, v12
	v_lshl_add_u64 v[12:13], v[12:13], 2, s[0:1]
	global_store_dword v[12:13], v26, off
	v_add_u32_e32 v12, 0x2880, v10
	v_ashrrev_i32_e32 v13, 31, v12
	v_lshl_add_u64 v[12:13], v[12:13], 2, s[0:1]
	global_store_dword v[12:13], v27, off
	v_add_u32_e32 v12, 0x2900, v10
	v_ashrrev_i32_e32 v13, 31, v12
	v_lshl_add_u64 v[12:13], v[12:13], 2, s[0:1]
	global_store_dword v[12:13], v28, off
	v_add_u32_e32 v12, 0x2980, v10
	v_ashrrev_i32_e32 v13, 31, v12
	v_lshl_add_u64 v[12:13], v[12:13], 2, s[0:1]
	global_store_dword v[12:13], v29, off
	v_add_u32_e32 v12, 0x3000, v10
	v_ashrrev_i32_e32 v13, 31, v12
	v_lshl_add_u64 v[12:13], v[12:13], 2, s[0:1]
	global_store_dword v[12:13], v6, off
	v_add_u32_e32 v12, 0x3080, v10
	v_ashrrev_i32_e32 v13, 31, v12
	v_lshl_add_u64 v[12:13], v[12:13], 2, s[0:1]
	v_add_u32_e32 v6, 0x3100, v10
	global_store_dword v[12:13], v7, off
	v_ashrrev_i32_e32 v7, 31, v6
	v_lshl_add_u64 v[6:7], v[6:7], 2, s[0:1]
	global_store_dword v[6:7], v8, off
	v_add_u32_e32 v6, 0x3180, v10
	v_ashrrev_i32_e32 v7, 31, v6
	v_lshl_add_u64 v[6:7], v[6:7], 2, s[0:1]
	global_store_dword v[6:7], v9, off
	v_add_u32_e32 v6, 0x3800, v10
	v_ashrrev_i32_e32 v7, 31, v6
	v_pk_mul_f32 v[2:3], v[2:3], v[18:19]
	v_lshl_add_u64 v[6:7], v[6:7], 2, s[0:1]
	global_store_dword v[6:7], v2, off
	v_add_u32_e32 v6, 0x3880, v10
	v_ashrrev_i32_e32 v7, 31, v6
	v_lshl_add_u64 v[6:7], v[6:7], 2, s[0:1]
	v_add_u32_e32 v2, 0x3900, v10
	global_store_dword v[6:7], v3, off
	v_ashrrev_i32_e32 v3, 31, v2
	v_pk_mul_f32 v[4:5], v[4:5], v[20:21]
	v_lshl_add_u64 v[2:3], v[2:3], 2, s[0:1]
	global_store_dword v[2:3], v4, off
	v_add_u32_e32 v2, 0x3980, v10
	v_ashrrev_i32_e32 v3, 31, v2
	v_lshl_add_u64 v[2:3], v[2:3], 2, s[0:1]
	global_store_dword v[2:3], v5, off
	s_and_saveexec_b64 s[0:1], s[36:37]
	s_cbranch_execz .LBB0_123
	v_lshl_add_u32 v2, s16, 7, v82
	v_ashrrev_i32_e32 v3, 31, v2
	v_lshl_add_u64 v[2:3], v[2:3], 2, s[24:25]
	global_store_dword v[2:3], v0, off
	s_branch .LBB0_123

; #define LAS __attribute__((address_space(3)))
; DI unsigned pk2(float lo, float hi) { f32x2_t f = {lo, hi}; bf16x2_t v = __builtin_convertvector(f, bf16x2_t); return __builtin_bit_cast(unsigned, v); }
; DI void transpose_item(const float* W, int K, int N, bf16_t* WT, LAS float* scr, int item, int lane, const float* gk = nullptr) {
;     const int nblk = N / 32, kb = item / nblk, nb = item % nblk, k0 = 64 * kb, n0 = 32 * nb;
; #pragma unroll 8
;     for (int i = 0; i < 32; ++i) { const int kk = 2 * i + (lane >> 5); scr[kk * 33 + (lane & 31)] = __builtin_nontemporal_load(W + (size_t)(k0 + kk) * N + n0 + (lane & 31)) * (gk ? gk[k0 + kk] : 1.f); }
;     asm volatile("s_waitcnt lgkmcnt(0)" ::: "memory");
;     const int c = lane & 7;
; #pragma unroll
;     for (int j = 0; j < 4; ++j) { const int n = (lane >> 3) + 8 * j; const LAS float* s = scr + (8 * c) * 33 + n;
;         u32x4 o; o.x = pk2(s[0 * 33], s[1 * 33]); o.y = pk2(s[2 * 33], s[3 * 33]); o.z = pk2(s[4 * 33], s[5 * 33]); o.w = pk2(s[6 * 33], s[7 * 33]);
;         *(u32x4*)(WT + (size_t)(n0 + n) * K + k0 + 8 * c) = o; }
;     asm volatile("s_waitcnt lgkmcnt(0)" ::: "memory");
; }
.LBB0_170:
	v_lshl_add_u64 v[44:45], v[42:43], 0, s[38:39]
	v_lshl_add_u64 v[46:47], v[40:41], 0, s[38:39]
	v_lshl_add_u64 v[48:49], v[38:39], 0, s[38:39]
	v_lshl_add_u64 v[50:51], v[36:37], 0, s[38:39]
	v_lshl_add_u64 v[52:53], v[34:35], 0, s[38:39]
	v_lshl_add_u64 v[54:55], v[32:33], 0, s[38:39]
	v_lshl_add_u64 v[56:57], v[30:31], 0, s[38:39]
	v_lshl_add_u64 v[58:59], v[28:29], 0, s[38:39]
	global_load_dword v44, v[44:45], off nt
	s_nop 0
	global_load_dword v45, v[46:47], off nt
	s_nop 0
	global_load_dword v46, v[48:49], off nt
	global_load_dword v47, v[50:51], off nt
	s_nop 0
	global_load_dword v48, v[52:53], off nt
	global_load_dword v49, v[54:55], off nt
	global_load_dword v50, v[56:57], off nt
	global_load_dword v51, v[58:59], off nt
	s_add_u32 s38, s38, 0x4000
	s_addc_u32 s39, s39, 0
	v_add_u32_e32 v52, 0x400, v0
	s_cmp_lg_u32 s38, 0x10000
	s_waitcnt vmcnt(0)
	ds_write2_b32 v0, v44, v45 offset1:66
	ds_write2_b32 v0, v46, v47 offset0:132 offset1:198
	ds_write2_b32 v52, v48, v49 offset0:8 offset1:74
	ds_write2_b32 v52, v50, v51 offset0:140 offset1:206
	v_add_u32_e32 v0, 0x840, v0
	s_cbranch_scc1 .LBB0_170
	v_add_u32_e32 v0, 0xffff8800, v82
	v_lshrrev_b32_e32 v0, 5, v0
	v_lshlrev_b32_e32 v28, 5, v82
	v_readlane_b32 s12, v254, 60
	s_waitcnt lgkmcnt(0)
	v_and_b32_e32 v36, 0xe0, v28
	v_lshlrev_b64 v[28:29], 17, v[0:1]
	v_readlane_b32 s13, v254, 61
	v_lshlrev_b32_e32 v0, 4, v82
	ds_read_b32 v30, v63
	ds_read_b32 v31, v63 offset:132
	ds_read_b32 v34, v63 offset:264
	ds_read_b32 v35, v63 offset:396
	ds_read_b32 v37, v63 offset:528
	ds_read_b32 v38, v63 offset:660
	ds_read_b32 v39, v63 offset:792
	ds_read_b32 v40, v63 offset:924
	v_lshl_add_u64 v[28:29], s[12:13], 0, v[28:29]
	v_and_b32_e32 v0, 0x180, v0
	v_lshl_add_u64 v[28:29], v[28:29], 0, v[0:1]
	v_lshlrev_b32_e32 v0, 1, v2
	v_lshl_add_u64 v[32:33], v[28:29], 0, v[0:1]
	v_or_b32_e32 v0, v36, v62
	v_lshlrev_b32_e32 v0, 9, v0
	s_waitcnt lgkmcnt(0)
	v_cvt_pk_bf16_f32 v28, v30, v31
	v_cvt_pk_bf16_f32 v29, v34, v35
	v_cvt_pk_bf16_f32 v30, v37, v38
	v_cvt_pk_bf16_f32 v31, v39, v40
	v_lshl_add_u64 v[34:35], v[32:33], 0, v[0:1]
	global_store_dwordx4 v[34:35], v[28:31], off
	ds_read_b32 v0, v63 offset:32
	ds_read_b32 v28, v63 offset:164
	ds_read_b32 v29, v63 offset:296
	ds_read_b32 v30, v63 offset:428
	ds_read_b32 v31, v63 offset:560
	ds_read_b32 v34, v63 offset:692
	ds_read_b32 v35, v63 offset:824
	ds_read_b32 v37, v63 offset:956
	s_waitcnt lgkmcnt(0)
	v_cvt_pk_bf16_f32 v28, v0, v28
	v_or_b32_e32 v0, v36, v64
	v_lshlrev_b32_e32 v0, 9, v0
	v_cvt_pk_bf16_f32 v29, v29, v30
	v_cvt_pk_bf16_f32 v30, v31, v34
	v_cvt_pk_bf16_f32 v31, v35, v37
	v_lshl_add_u64 v[34:35], v[32:33], 0, v[0:1]
	global_store_dwordx4 v[34:35], v[28:31], off
	ds_read_b32 v0, v63 offset:64
	ds_read_b32 v28, v63 offset:196
	ds_read_b32 v29, v63 offset:328
	ds_read_b32 v30, v63 offset:460
	ds_read_b32 v31, v63 offset:592
	ds_read_b32 v34, v63 offset:724
	ds_read_b32 v35, v63 offset:856
	ds_read_b32 v37, v63 offset:988
	s_waitcnt lgkmcnt(0)
	v_cvt_pk_bf16_f32 v28, v0, v28
	v_or_b32_e32 v0, v36, v65
	v_lshlrev_b32_e32 v0, 9, v0
	v_cvt_pk_bf16_f32 v29, v29, v30
	v_cvt_pk_bf16_f32 v30, v31, v34
	v_cvt_pk_bf16_f32 v31, v35, v37
	v_lshl_add_u64 v[34:35], v[32:33], 0, v[0:1]
	global_store_dwordx4 v[34:35], v[28:31], off
	ds_read_b32 v0, v63 offset:96
	ds_read_b32 v28, v63 offset:228
	ds_read_b32 v29, v63 offset:360
	ds_read_b32 v30, v63 offset:492
	ds_read_b32 v31, v63 offset:624
	ds_read_b32 v34, v63 offset:756
	ds_read_b32 v35, v63 offset:888
	ds_read_b32 v37, v63 offset:1020
	s_waitcnt lgkmcnt(0)
	v_cvt_pk_bf16_f32 v28, v0, v28
	v_or_b32_e32 v0, v36, v66
	v_lshlrev_b32_e32 v0, 9, v0
	v_cvt_pk_bf16_f32 v29, v29, v30
	v_cvt_pk_bf16_f32 v30, v31, v34
	v_cvt_pk_bf16_f32 v31, v35, v37
	v_lshl_add_u64 v[32:33], v[32:33], 0, v[0:1]
	global_store_dwordx4 v[32:33], v[28:31], off
	s_waitcnt lgkmcnt(0)

; #define LAS __attribute__((address_space(3)))
; DI unsigned pk2(float lo, float hi) { f32x2_t f = {lo, hi}; bf16x2_t v = __builtin_convertvector(f, bf16x2_t); return __builtin_bit_cast(unsigned, v); }
; DI void transpose_item(const float* W, int K, int N, bf16_t* WT, LAS float* scr, int item, int lane, const float* gk = nullptr) {
;     const int nblk = N / 32, kb = item / nblk, nb = item % nblk, k0 = 64 * kb, n0 = 32 * nb;
; #pragma unroll 8
;     for (int i = 0; i < 32; ++i) { const int kk = 2 * i + (lane >> 5); scr[kk * 33 + (lane & 31)] = __builtin_nontemporal_load(W + (size_t)(k0 + kk) * N + n0 + (lane & 31)) * (gk ? gk[k0 + kk] : 1.f); }
;     asm volatile("s_waitcnt lgkmcnt(0)" ::: "memory");
;     const int c = lane & 7;
; #pragma unroll
;     for (int j = 0; j < 4; ++j) { const int n = (lane >> 3) + 8 * j; const LAS float* s = scr + (8 * c) * 33 + n;
;         u32x4 o; o.x = pk2(s[0 * 33], s[1 * 33]); o.y = pk2(s[2 * 33], s[3 * 33]); o.z = pk2(s[4 * 33], s[5 * 33]); o.w = pk2(s[6 * 33], s[7 * 33]);
;         *(u32x4*)(WT + (size_t)(n0 + n) * K + k0 + 8 * c) = o; }
;     asm volatile("s_waitcnt lgkmcnt(0)" ::: "memory");
; }
.LBB0_174:
	v_lshl_add_u64 v[46:47], v[42:43], 0, s[38:39]
	v_lshl_add_u64 v[48:49], v[40:41], 0, s[38:39]
	v_lshl_add_u64 v[50:51], v[38:39], 0, s[38:39]
	v_lshl_add_u64 v[52:53], v[36:37], 0, s[38:39]
	v_lshl_add_u64 v[54:55], v[34:35], 0, s[38:39]
	v_lshl_add_u64 v[56:57], v[32:33], 0, s[38:39]
	v_lshl_add_u64 v[58:59], v[30:31], 0, s[38:39]
	v_lshl_add_u64 v[84:85], v[28:29], 0, s[38:39]
	global_load_dword v46, v[46:47], off nt
	s_nop 0
	global_load_dword v47, v[48:49], off nt
	s_nop 0
	global_load_dword v48, v[50:51], off nt
	global_load_dword v49, v[52:53], off nt
	s_nop 0
	global_load_dword v50, v[54:55], off nt
	global_load_dword v51, v[56:57], off nt
	global_load_dword v52, v[58:59], off nt
	global_load_dword v53, v[84:85], off nt
	s_add_u32 s38, s38, 0x20000
	s_addc_u32 s39, s39, 0
	v_add_u32_e32 v54, 0x400, v45
	s_cmp_lg_u32 s38, 0x80000
	s_waitcnt vmcnt(0)
	ds_write2_b32 v45, v46, v47 offset1:66
	ds_write2_b32 v45, v48, v49 offset0:132 offset1:198
	ds_write2_b32 v54, v50, v51 offset0:8 offset1:74
	ds_write2_b32 v54, v52, v53 offset0:140 offset1:206
	v_add_u32_e32 v45, 0x840, v45
	s_cbranch_scc1 .LBB0_174
	v_lshlrev_b32_e32 v28, 5, v82
	v_readlane_b32 s12, v254, 62
	s_waitcnt lgkmcnt(0)
	v_and_b32_e32 v36, 0x7e0, v28
	v_lshlrev_b64 v[28:29], 12, v[0:1]
	v_readlane_b32 s13, v254, 63
	ds_read_b32 v30, v63
	ds_read_b32 v31, v63 offset:132
	ds_read_b32 v34, v63 offset:264
	ds_read_b32 v35, v63 offset:396
	ds_read_b32 v37, v63 offset:528
	ds_read_b32 v38, v63 offset:660
	ds_read_b32 v39, v63 offset:792
	ds_read_b32 v40, v63 offset:924
	v_lshl_add_u64 v[28:29], s[12:13], 0, v[28:29]
	v_lshlrev_b32_e32 v0, 1, v44
	v_lshl_add_u64 v[28:29], v[28:29], 0, v[0:1]
	v_lshlrev_b32_e32 v0, 1, v2
	v_lshl_add_u64 v[32:33], v[28:29], 0, v[0:1]
	v_or_b32_e32 v0, v36, v62
	v_lshlrev_b32_e32 v0, 12, v0
	s_waitcnt lgkmcnt(0)
	v_cvt_pk_bf16_f32 v28, v30, v31
	v_cvt_pk_bf16_f32 v29, v34, v35
	v_cvt_pk_bf16_f32 v30, v37, v38
	v_cvt_pk_bf16_f32 v31, v39, v40
	v_lshl_add_u64 v[34:35], v[32:33], 0, v[0:1]
	global_store_dwordx4 v[34:35], v[28:31], off
	ds_read_b32 v0, v63 offset:32
	ds_read_b32 v28, v63 offset:164
	ds_read_b32 v29, v63 offset:296
	ds_read_b32 v30, v63 offset:428
	ds_read_b32 v31, v63 offset:560
	ds_read_b32 v34, v63 offset:692
	ds_read_b32 v35, v63 offset:824
	ds_read_b32 v37, v63 offset:956
	s_waitcnt lgkmcnt(0)
	v_cvt_pk_bf16_f32 v28, v0, v28
	v_or_b32_e32 v0, v36, v64
	v_lshlrev_b32_e32 v0, 12, v0
	v_cvt_pk_bf16_f32 v29, v29, v30
	v_cvt_pk_bf16_f32 v30, v31, v34
	v_cvt_pk_bf16_f32 v31, v35, v37
	v_lshl_add_u64 v[34:35], v[32:33], 0, v[0:1]
	global_store_dwordx4 v[34:35], v[28:31], off
	ds_read_b32 v0, v63 offset:64
	ds_read_b32 v28, v63 offset:196
	ds_read_b32 v29, v63 offset:328
	ds_read_b32 v30, v63 offset:460
	ds_read_b32 v31, v63 offset:592
	ds_read_b32 v34, v63 offset:724
	ds_read_b32 v35, v63 offset:856
	ds_read_b32 v37, v63 offset:988
	s_waitcnt lgkmcnt(0)
	v_cvt_pk_bf16_f32 v28, v0, v28
	v_or_b32_e32 v0, v36, v65
	v_lshlrev_b32_e32 v0, 12, v0
	v_cvt_pk_bf16_f32 v29, v29, v30
	v_cvt_pk_bf16_f32 v30, v31, v34
	v_cvt_pk_bf16_f32 v31, v35, v37
	v_lshl_add_u64 v[34:35], v[32:33], 0, v[0:1]
	global_store_dwordx4 v[34:35], v[28:31], off
	ds_read_b32 v0, v63 offset:96
	ds_read_b32 v28, v63 offset:228
	ds_read_b32 v29, v63 offset:360
	ds_read_b32 v30, v63 offset:492
	ds_read_b32 v31, v63 offset:624
	ds_read_b32 v34, v63 offset:756
	ds_read_b32 v35, v63 offset:888
	ds_read_b32 v37, v63 offset:1020
	s_waitcnt lgkmcnt(0)
	v_cvt_pk_bf16_f32 v28, v0, v28
	v_or_b32_e32 v0, v36, v66
	v_lshlrev_b32_e32 v0, 12, v0
	v_cvt_pk_bf16_f32 v29, v29, v30
	v_cvt_pk_bf16_f32 v30, v31, v34
	v_cvt_pk_bf16_f32 v31, v35, v37
	v_lshl_add_u64 v[32:33], v[32:33], 0, v[0:1]
	global_store_dwordx4 v[32:33], v[28:31], off
	s_waitcnt lgkmcnt(0)

; #define LAS __attribute__((address_space(3)))
; DI unsigned pk2(float lo, float hi) { f32x2_t f = {lo, hi}; bf16x2_t v = __builtin_convertvector(f, bf16x2_t); return __builtin_bit_cast(unsigned, v); }
; DI void transpose_item(const float* W, int K, int N, bf16_t* WT, LAS float* scr, int item, int lane, const float* gk = nullptr) {
;     const int nblk = N / 32, kb = item / nblk, nb = item % nblk, k0 = 64 * kb, n0 = 32 * nb;
; #pragma unroll 8
;     for (int i = 0; i < 32; ++i) { const int kk = 2 * i + (lane >> 5); scr[kk * 33 + (lane & 31)] = __builtin_nontemporal_load(W + (size_t)(k0 + kk) * N + n0 + (lane & 31)) * (gk ? gk[k0 + kk] : 1.f); }
;     asm volatile("s_waitcnt lgkmcnt(0)" ::: "memory");
;     const int c = lane & 7;
; #pragma unroll
;     for (int j = 0; j < 4; ++j) { const int n = (lane >> 3) + 8 * j; const LAS float* s = scr + (8 * c) * 33 + n;
;         u32x4 o; o.x = pk2(s[0 * 33], s[1 * 33]); o.y = pk2(s[2 * 33], s[3 * 33]); o.z = pk2(s[4 * 33], s[5 * 33]); o.w = pk2(s[6 * 33], s[7 * 33]);
;         *(u32x4*)(WT + (size_t)(n0 + n) * K + k0 + 8 * c) = o; }
;     asm volatile("s_waitcnt lgkmcnt(0)" ::: "memory");
; }
.LBB0_179:
	v_lshl_add_u64 v[44:45], v[42:43], 0, s[36:37]
	v_lshl_add_u64 v[46:47], v[40:41], 0, s[36:37]
	v_lshl_add_u64 v[48:49], v[38:39], 0, s[36:37]
	v_lshl_add_u64 v[50:51], v[36:37], 0, s[36:37]
	v_lshl_add_u64 v[52:53], v[34:35], 0, s[36:37]
	v_lshl_add_u64 v[54:55], v[32:33], 0, s[36:37]
	v_lshl_add_u64 v[56:57], v[30:31], 0, s[36:37]
	v_lshl_add_u64 v[58:59], v[28:29], 0, s[36:37]
	global_load_dword v44, v[44:45], off nt
	s_nop 0
	global_load_dword v45, v[46:47], off nt
	s_nop 0
	global_load_dword v46, v[48:49], off nt
	global_load_dword v47, v[50:51], off nt
	s_nop 0
	global_load_dword v48, v[52:53], off nt
	global_load_dword v49, v[54:55], off nt
	global_load_dword v50, v[56:57], off nt
	global_load_dword v51, v[58:59], off nt
	s_add_u32 s36, s36, 0x40000
	s_addc_u32 s37, s37, 0
	v_add_u32_e32 v52, 0x400, v0
	s_cmp_lg_u32 s36, 0x100000
	s_waitcnt vmcnt(0)
	ds_write2_b32 v0, v44, v45 offset1:66
	ds_write2_b32 v0, v46, v47 offset0:132 offset1:198
	ds_write2_b32 v52, v48, v49 offset0:8 offset1:74
	ds_write2_b32 v52, v50, v51 offset0:140 offset1:206
	v_add_u32_e32 v0, 0x840, v0
	s_cbranch_scc1 .LBB0_179
	v_add_u32_e32 v30, 0xffffb800, v82
	v_lshrrev_b32_e32 v0, 1, v30
	v_and_b32_e32 v0, 0x7ffff800, v0
	v_lshlrev_b32_e32 v28, 5, v82
	v_readlane_b32 s12, v255, 0
	s_waitcnt lgkmcnt(0)
	v_and_b32_e32 v36, 0xfe0, v28
	v_lshlrev_b64 v[28:29], 13, v[0:1]
	v_readlane_b32 s13, v255, 1
	v_and_b32_e32 v0, 0xf80, v30
	ds_read_b32 v30, v63
	ds_read_b32 v31, v63 offset:132
	ds_read_b32 v34, v63 offset:264
	ds_read_b32 v35, v63 offset:396
	ds_read_b32 v37, v63 offset:528
	ds_read_b32 v38, v63 offset:660
	ds_read_b32 v39, v63 offset:792
	ds_read_b32 v40, v63 offset:924
	v_lshl_add_u64 v[28:29], s[12:13], 0, v[28:29]
	v_lshl_add_u64 v[28:29], v[28:29], 0, v[0:1]
	v_lshlrev_b32_e32 v0, 1, v2
	v_lshl_add_u64 v[32:33], v[28:29], 0, v[0:1]
	v_or_b32_e32 v0, v36, v62
	v_lshlrev_b32_e32 v0, 12, v0
	s_waitcnt lgkmcnt(0)
	v_cvt_pk_bf16_f32 v28, v30, v31
	v_cvt_pk_bf16_f32 v29, v34, v35
	v_cvt_pk_bf16_f32 v30, v37, v38
	v_cvt_pk_bf16_f32 v31, v39, v40
	v_lshl_add_u64 v[34:35], v[32:33], 0, v[0:1]
	global_store_dwordx4 v[34:35], v[28:31], off
	ds_read_b32 v0, v63 offset:32
	ds_read_b32 v28, v63 offset:164
	ds_read_b32 v29, v63 offset:296
	ds_read_b32 v30, v63 offset:428
	ds_read_b32 v31, v63 offset:560
	ds_read_b32 v34, v63 offset:692
	ds_read_b32 v35, v63 offset:824
	ds_read_b32 v37, v63 offset:956
	s_waitcnt lgkmcnt(0)
	v_cvt_pk_bf16_f32 v28, v0, v28
	v_or_b32_e32 v0, v36, v64
	v_lshlrev_b32_e32 v0, 12, v0
	v_cvt_pk_bf16_f32 v29, v29, v30
	v_cvt_pk_bf16_f32 v30, v31, v34
	v_cvt_pk_bf16_f32 v31, v35, v37
	v_lshl_add_u64 v[34:35], v[32:33], 0, v[0:1]
	global_store_dwordx4 v[34:35], v[28:31], off
	ds_read_b32 v0, v63 offset:64
	ds_read_b32 v28, v63 offset:196
	ds_read_b32 v29, v63 offset:328
	ds_read_b32 v30, v63 offset:460
	ds_read_b32 v31, v63 offset:592
	ds_read_b32 v34, v63 offset:724
	ds_read_b32 v35, v63 offset:856
	ds_read_b32 v37, v63 offset:988
	s_waitcnt lgkmcnt(0)
	v_cvt_pk_bf16_f32 v28, v0, v28
	v_or_b32_e32 v0, v36, v65
	v_lshlrev_b32_e32 v0, 12, v0
	v_cvt_pk_bf16_f32 v29, v29, v30
	v_cvt_pk_bf16_f32 v30, v31, v34
	v_cvt_pk_bf16_f32 v31, v35, v37
	v_lshl_add_u64 v[34:35], v[32:33], 0, v[0:1]
	global_store_dwordx4 v[34:35], v[28:31], off
	ds_read_b32 v0, v63 offset:96
	ds_read_b32 v28, v63 offset:228
	ds_read_b32 v29, v63 offset:360
	ds_read_b32 v30, v63 offset:492
	ds_read_b32 v31, v63 offset:624
	ds_read_b32 v34, v63 offset:756
	ds_read_b32 v35, v63 offset:888
	ds_read_b32 v37, v63 offset:1020
	s_waitcnt lgkmcnt(0)
	v_cvt_pk_bf16_f32 v28, v0, v28
	v_or_b32_e32 v0, v36, v66
	v_lshlrev_b32_e32 v0, 12, v0
	v_cvt_pk_bf16_f32 v29, v29, v30
	v_cvt_pk_bf16_f32 v30, v31, v34
	v_cvt_pk_bf16_f32 v31, v35, v37
	v_lshl_add_u64 v[32:33], v[32:33], 0, v[0:1]
	global_store_dwordx4 v[32:33], v[28:31], off
	s_waitcnt lgkmcnt(0)

; #define LAS __attribute__((address_space(3)))
; DI unsigned pk2(float lo, float hi) { f32x2_t f = {lo, hi}; bf16x2_t v = __builtin_convertvector(f, bf16x2_t); return __builtin_bit_cast(unsigned, v); }
; DI void transpose_item(const float* W, int K, int N, bf16_t* WT, LAS float* scr, int item, int lane, const float* gk = nullptr) {
;     ...
;     for (int i = 0; i < 32; ++i) { const int kk = 2 * i + (lane >> 5); scr[kk * 33 + (lane & 31)] = __builtin_nontemporal_load(W + (size_t)(k0 + kk) * N + n0 + (lane & 31)) * (gk ? gk[k0 + kk] : 1.f); }
;     asm volatile("s_waitcnt lgkmcnt(0)" ::: "memory");
;     const int c = lane & 7;
; #pragma unroll
;     for (int j = 0; j < 4; ++j) { const int n = (lane >> 3) + 8 * j; const LAS float* s = scr + (8 * c) * 33 + n;
;         u32x4 o; o.x = pk2(s[0 * 33], s[1 * 33]); o.y = pk2(s[2 * 33], s[3 * 33]); o.z = pk2(s[4 * 33], s[5 * 33]); o.w = pk2(s[6 * 33], s[7 * 33]);
;         *(u32x4*)(WT + (size_t)(n0 + n) * K + k0 + 8 * c) = o; }
.LBB0_184:
	v_lshl_add_u64 v[44:45], v[42:43], 0, s[34:35]
	v_lshl_add_u64 v[46:47], v[40:41], 0, s[34:35]
	v_lshl_add_u64 v[48:49], v[38:39], 0, s[34:35]
	v_lshl_add_u64 v[50:51], v[36:37], 0, s[34:35]
	v_lshl_add_u64 v[52:53], v[34:35], 0, s[34:35]
	v_lshl_add_u64 v[54:55], v[32:33], 0, s[34:35]
	v_lshl_add_u64 v[56:57], v[30:31], 0, s[34:35]
	v_lshl_add_u64 v[58:59], v[28:29], 0, s[34:35]
	global_load_dword v44, v[44:45], off nt
	s_nop 0
	global_load_dword v45, v[46:47], off nt
	s_nop 0
	global_load_dword v46, v[48:49], off nt
	global_load_dword v47, v[50:51], off nt
	s_nop 0
	global_load_dword v48, v[52:53], off nt
	global_load_dword v49, v[54:55], off nt
	global_load_dword v50, v[56:57], off nt
	global_load_dword v51, v[58:59], off nt
	s_add_u32 s34, s34, 0x20000
	s_addc_u32 s35, s35, 0
	v_add_u32_e32 v52, 0x400, v0
	s_cmp_lg_u32 s34, 0x80000
	s_waitcnt vmcnt(0)
	ds_write2_b32 v0, v44, v45 offset1:66
	ds_write2_b32 v0, v46, v47 offset0:132 offset1:198
	ds_write2_b32 v52, v48, v49 offset0:8 offset1:74
	ds_write2_b32 v52, v50, v51 offset0:140 offset1:206
	v_add_u32_e32 v0, 0x840, v0
	s_cbranch_scc1 .LBB0_184
	v_lshlrev_b32_e32 v28, 5, v82
	s_waitcnt lgkmcnt(0)
	v_add_u32_e32 v0, 0xc000, v82
	v_and_b32_e32 v36, 0x7e0, v28
	ds_read_b32 v28, v63
	ds_read_b32 v29, v63 offset:132
	ds_read_b32 v30, v63 offset:264
	ds_read_b32 v31, v63 offset:396
	ds_read_b32 v34, v63 offset:528
	ds_read_b32 v35, v63 offset:660
	ds_read_b32 v37, v63 offset:792
	ds_read_b32 v38, v63 offset:924
	v_and_b32_e32 v0, 0xffc0, v0
	v_lshlrev_b32_e32 v0, 1, v0
	v_lshl_add_u64 v[32:33], v[4:5], 0, v[0:1]
	v_or_b32_e32 v0, v36, v62
	v_lshlrev_b32_e32 v0, 12, v0
	s_waitcnt lgkmcnt(0)
	v_cvt_pk_bf16_f32 v28, v28, v29
	v_cvt_pk_bf16_f32 v29, v30, v31
	v_cvt_pk_bf16_f32 v30, v34, v35
	v_cvt_pk_bf16_f32 v31, v37, v38
	v_lshl_add_u64 v[34:35], v[32:33], 0, v[0:1]
	global_store_dwordx4 v[34:35], v[28:31], off
	ds_read_b32 v0, v63 offset:32
	ds_read_b32 v28, v63 offset:164
	ds_read_b32 v29, v63 offset:296
	ds_read_b32 v30, v63 offset:428
	ds_read_b32 v31, v63 offset:560
	ds_read_b32 v34, v63 offset:692
	ds_read_b32 v35, v63 offset:824
	ds_read_b32 v37, v63 offset:956
	s_waitcnt lgkmcnt(0)
	v_cvt_pk_bf16_f32 v28, v0, v28
	v_or_b32_e32 v0, v36, v64
	v_lshlrev_b32_e32 v0, 12, v0
	v_cvt_pk_bf16_f32 v29, v29, v30
	v_cvt_pk_bf16_f32 v30, v31, v34
	v_cvt_pk_bf16_f32 v31, v35, v37
	v_lshl_add_u64 v[34:35], v[32:33], 0, v[0:1]
	global_store_dwordx4 v[34:35], v[28:31], off
	ds_read_b32 v0, v63 offset:64
	ds_read_b32 v28, v63 offset:196
	ds_read_b32 v29, v63 offset:328
	ds_read_b32 v30, v63 offset:460
	ds_read_b32 v31, v63 offset:592
	ds_read_b32 v34, v63 offset:724
	ds_read_b32 v35, v63 offset:856
	ds_read_b32 v37, v63 offset:988
	s_waitcnt lgkmcnt(0)
	v_cvt_pk_bf16_f32 v28, v0, v28
	v_or_b32_e32 v0, v36, v65
	v_lshlrev_b32_e32 v0, 12, v0
	v_cvt_pk_bf16_f32 v29, v29, v30
	v_cvt_pk_bf16_f32 v30, v31, v34
	v_cvt_pk_bf16_f32 v31, v35, v37
	v_lshl_add_u64 v[34:35], v[32:33], 0, v[0:1]
	global_store_dwordx4 v[34:35], v[28:31], off
	ds_read_b32 v0, v63 offset:96
	ds_read_b32 v28, v63 offset:228
	ds_read_b32 v29, v63 offset:360
	ds_read_b32 v30, v63 offset:492
	ds_read_b32 v31, v63 offset:624
	ds_read_b32 v34, v63 offset:756
	ds_read_b32 v35, v63 offset:888
	ds_read_b32 v37, v63 offset:1020
	s_waitcnt lgkmcnt(0)
	v_cvt_pk_bf16_f32 v28, v0, v28
	v_or_b32_e32 v0, v36, v66
	v_lshlrev_b32_e32 v0, 12, v0
	v_cvt_pk_bf16_f32 v29, v29, v30
	v_cvt_pk_bf16_f32 v30, v31, v34
	v_cvt_pk_bf16_f32 v31, v35, v37
	v_lshl_add_u64 v[32:33], v[32:33], 0, v[0:1]
	global_store_dwordx4 v[32:33], v[28:31], off
	s_waitcnt lgkmcnt(0)

; #define LAS __attribute__((address_space(3)))
; DI unsigned pk2(float lo, float hi) { f32x2_t f = {lo, hi}; bf16x2_t v = __builtin_convertvector(f, bf16x2_t); return __builtin_bit_cast(unsigned, v); }
; DI void transpose_item(const float* W, int K, int N, bf16_t* WT, LAS float* scr, int item, int lane, const float* gk = nullptr) {
;     ...
;     for (int i = 0; i < 32; ++i) { const int kk = 2 * i + (lane >> 5); scr[kk * 33 + (lane & 31)] = __builtin_nontemporal_load(W + (size_t)(k0 + kk) * N + n0 + (lane & 31)) * (gk ? gk[k0 + kk] : 1.f); }
;     asm volatile("s_waitcnt lgkmcnt(0)" ::: "memory");
;     const int c = lane & 7;
; #pragma unroll
;     for (int j = 0; j < 4; ++j) { const int n = (lane >> 3) + 8 * j; const LAS float* s = scr + (8 * c) * 33 + n;
;         u32x4 o; o.x = pk2(s[0 * 33], s[1 * 33]); o.y = pk2(s[2 * 33], s[3 * 33]); o.z = pk2(s[4 * 33], s[5 * 33]); o.w = pk2(s[6 * 33], s[7 * 33]);
;         *(u32x4*)(WT + (size_t)(n0 + n) * K + k0 + 8 * c) = o; }
.LBB0_189:
	v_lshl_add_u64 v[84:85], v[30:31], 0, v[58:59]
	v_lshl_add_u64 v[86:87], v[56:57], 0, s[22:23]
	v_lshl_add_u64 v[88:89], v[30:31], 0, v[54:55]
	v_lshl_add_u64 v[90:91], v[52:53], 0, s[22:23]
	v_lshl_add_u64 v[92:93], v[30:31], 0, v[50:51]
	v_lshl_add_u64 v[94:95], v[48:49], 0, s[22:23]
	v_lshl_add_u64 v[96:97], v[30:31], 0, v[46:47]
	v_lshl_add_u64 v[98:99], v[44:45], 0, s[22:23]
	v_lshl_add_u64 v[100:101], v[30:31], 0, v[42:43]
	v_lshl_add_u64 v[102:103], v[40:41], 0, s[22:23]
	v_lshl_add_u64 v[104:105], v[30:31], 0, v[38:39]
	v_lshl_add_u64 v[106:107], v[36:37], 0, s[22:23]
	v_lshl_add_u64 v[108:109], v[30:31], 0, v[34:35]
	v_lshl_add_u64 v[110:111], v[32:33], 0, s[22:23]
	v_lshl_add_u64 v[112:113], v[30:31], 0, v[0:1]
	v_lshl_add_u64 v[114:115], v[28:29], 0, s[22:23]
	global_load_dword v84, v[84:85], off nt
	s_nop 0
	global_load_dword v85, v[86:87], off
	s_nop 0
	global_load_dword v86, v[88:89], off nt
	global_load_dword v87, v[90:91], off
	s_nop 0
	global_load_dword v88, v[92:93], off nt
	global_load_dword v89, v[94:95], off
	global_load_dword v90, v[96:97], off nt
	global_load_dword v91, v[98:99], off
	s_nop 0
	global_load_dword v92, v[100:101], off nt
	global_load_dword v93, v[102:103], off
	global_load_dword v94, v[104:105], off nt
	global_load_dword v95, v[106:107], off
	global_load_dword v96, v[108:109], off nt
	global_load_dword v97, v[110:111], off
	global_load_dword v98, v[112:113], off nt
	global_load_dword v99, v[114:115], off
	s_add_u32 s22, s22, 64
	s_addc_u32 s23, s23, 0
	v_add_u32_e32 v100, 0x400, v83
	v_lshl_add_u64 v[30:31], v[30:31], 0, s[52:53]
	s_cmpk_lg_i32 s22, 0x100
	s_waitcnt vmcnt(0)
	v_mul_f32_e32 v84, v84, v85
	v_mul_f32_e32 v85, v86, v87
	v_mul_f32_e32 v86, v88, v89
	v_mul_f32_e32 v87, v90, v91
	v_mul_f32_e32 v88, v92, v93
	v_mul_f32_e32 v89, v94, v95
	v_mul_f32_e32 v90, v96, v97
	v_mul_f32_e32 v91, v98, v99
	ds_write2_b32 v83, v84, v85 offset1:66
	ds_write2_b32 v83, v86, v87 offset0:132 offset1:198
	ds_write2_b32 v100, v88, v89 offset0:8 offset1:74
	ds_write2_b32 v100, v90, v91 offset0:140 offset1:206
	v_add_u32_e32 v83, 0x840, v83
	s_cbranch_scc1 .LBB0_189
	v_lshlrev_b32_e32 v28, 5, v82
	v_add_u32_e32 v0, 0xe000, v82
	v_and_b32_e32 v36, 0x1fe0, v28
	s_waitcnt lgkmcnt(0)
	v_mov_b32_e32 v28, 7
	v_lshlrev_b32_sdwa v0, v28, v0 dst_sel:DWORD dst_unused:UNUSED_PAD src0_sel:DWORD src1_sel:BYTE_1
	ds_read_b32 v28, v63
	ds_read_b32 v29, v63 offset:132
	ds_read_b32 v30, v63 offset:264
	ds_read_b32 v31, v63 offset:396
	ds_read_b32 v34, v63 offset:528
	ds_read_b32 v35, v63 offset:660
	ds_read_b32 v37, v63 offset:792
	ds_read_b32 v38, v63 offset:924
	v_lshl_add_u64 v[32:33], v[8:9], 0, v[0:1]
	v_or_b32_e32 v0, v36, v62
	v_lshlrev_b32_e32 v0, 12, v0
	s_waitcnt lgkmcnt(0)
	v_cvt_pk_bf16_f32 v28, v28, v29
	v_cvt_pk_bf16_f32 v29, v30, v31
	v_cvt_pk_bf16_f32 v30, v34, v35
	v_cvt_pk_bf16_f32 v31, v37, v38
	v_lshl_add_u64 v[34:35], v[32:33], 0, v[0:1]
	global_store_dwordx4 v[34:35], v[28:31], off
	ds_read_b32 v0, v63 offset:32
	ds_read_b32 v28, v63 offset:164
	ds_read_b32 v29, v63 offset:296
	ds_read_b32 v30, v63 offset:428
	ds_read_b32 v31, v63 offset:560
	ds_read_b32 v34, v63 offset:692
	ds_read_b32 v35, v63 offset:824
	ds_read_b32 v37, v63 offset:956
	s_waitcnt lgkmcnt(0)
	v_cvt_pk_bf16_f32 v28, v0, v28
	v_or_b32_e32 v0, v36, v64
	v_lshlrev_b32_e32 v0, 12, v0
	v_cvt_pk_bf16_f32 v29, v29, v30
	v_cvt_pk_bf16_f32 v30, v31, v34
	v_cvt_pk_bf16_f32 v31, v35, v37
	v_lshl_add_u64 v[34:35], v[32:33], 0, v[0:1]
	global_store_dwordx4 v[34:35], v[28:31], off
	ds_read_b32 v0, v63 offset:64
	ds_read_b32 v28, v63 offset:196
	ds_read_b32 v29, v63 offset:328
	ds_read_b32 v30, v63 offset:460
	ds_read_b32 v31, v63 offset:592
	ds_read_b32 v34, v63 offset:724
	ds_read_b32 v35, v63 offset:856
	ds_read_b32 v37, v63 offset:988
	s_waitcnt lgkmcnt(0)
	v_cvt_pk_bf16_f32 v28, v0, v28
	v_or_b32_e32 v0, v36, v65
	v_lshlrev_b32_e32 v0, 12, v0
	v_cvt_pk_bf16_f32 v29, v29, v30
	v_cvt_pk_bf16_f32 v30, v31, v34
	v_cvt_pk_bf16_f32 v31, v35, v37
	v_lshl_add_u64 v[34:35], v[32:33], 0, v[0:1]
	global_store_dwordx4 v[34:35], v[28:31], off
	ds_read_b32 v0, v63 offset:96
	ds_read_b32 v28, v63 offset:228
	ds_read_b32 v29, v63 offset:360
	ds_read_b32 v30, v63 offset:492
	ds_read_b32 v31, v63 offset:624
	ds_read_b32 v34, v63 offset:756
	ds_read_b32 v35, v63 offset:888
	ds_read_b32 v37, v63 offset:1020
	s_waitcnt lgkmcnt(0)
	v_cvt_pk_bf16_f32 v28, v0, v28
	v_or_b32_e32 v0, v36, v66
	v_lshlrev_b32_e32 v0, 12, v0
	v_cvt_pk_bf16_f32 v29, v29, v30
	v_cvt_pk_bf16_f32 v30, v31, v34
	v_cvt_pk_bf16_f32 v31, v35, v37
	v_lshl_add_u64 v[32:33], v[32:33], 0, v[0:1]
	global_store_dwordx4 v[32:33], v[28:31], off
	s_waitcnt lgkmcnt(0)

; #define LAS __attribute__((address_space(3)))
; DI unsigned pk2(float lo, float hi) { f32x2_t f = {lo, hi}; bf16x2_t v = __builtin_convertvector(f, bf16x2_t); return __builtin_bit_cast(unsigned, v); }
; DI void transpose_item(const float* W, int K, int N, bf16_t* WT, LAS float* scr, int item, int lane, const float* gk = nullptr) {
;     ...
;     for (int i = 0; i < 32; ++i) { const int kk = 2 * i + (lane >> 5); scr[kk * 33 + (lane & 31)] = __builtin_nontemporal_load(W + (size_t)(k0 + kk) * N + n0 + (lane & 31)) * (gk ? gk[k0 + kk] : 1.f); }
;     asm volatile("s_waitcnt lgkmcnt(0)" ::: "memory");
;     const int c = lane & 7;
; #pragma unroll
;     for (int j = 0; j < 4; ++j) { const int n = (lane >> 3) + 8 * j; const LAS float* s = scr + (8 * c) * 33 + n;
;         u32x4 o; o.x = pk2(s[0 * 33], s[1 * 33]); o.y = pk2(s[2 * 33], s[3 * 33]); o.z = pk2(s[4 * 33], s[5 * 33]); o.w = pk2(s[6 * 33], s[7 * 33]);
;         *(u32x4*)(WT + (size_t)(n0 + n) * K + k0 + 8 * c) = o; }
.LBB0_194:
	v_lshl_add_u64 v[44:45], v[42:43], 0, s[22:23]
	v_lshl_add_u64 v[46:47], v[40:41], 0, s[22:23]
	v_lshl_add_u64 v[48:49], v[38:39], 0, s[22:23]
	v_lshl_add_u64 v[50:51], v[36:37], 0, s[22:23]
	v_lshl_add_u64 v[52:53], v[34:35], 0, s[22:23]
	v_lshl_add_u64 v[54:55], v[32:33], 0, s[22:23]
	v_lshl_add_u64 v[56:57], v[30:31], 0, s[22:23]
	v_lshl_add_u64 v[58:59], v[28:29], 0, s[22:23]
	global_load_dword v44, v[44:45], off nt
	s_nop 0
	global_load_dword v45, v[46:47], off nt
	s_nop 0
	global_load_dword v46, v[48:49], off nt
	global_load_dword v47, v[50:51], off nt
	s_nop 0
	global_load_dword v48, v[52:53], off nt
	global_load_dword v49, v[54:55], off nt
	global_load_dword v50, v[56:57], off nt
	global_load_dword v51, v[58:59], off nt
	s_add_u32 s22, s22, 0x20000
	s_addc_u32 s23, s23, 0
	v_add_u32_e32 v52, 0x400, v0
	s_cmp_lg_u32 s22, 0x80000
	s_waitcnt vmcnt(0)
	ds_write2_b32 v0, v44, v45 offset1:66
	ds_write2_b32 v0, v46, v47 offset0:132 offset1:198
	ds_write2_b32 v52, v48, v49 offset0:8 offset1:74
	ds_write2_b32 v52, v50, v51 offset0:140 offset1:206
	v_add_u32_e32 v0, 0x840, v0
	s_cbranch_scc1 .LBB0_194
	v_lshlrev_b32_e32 v28, 5, v82
	s_waitcnt lgkmcnt(0)
	v_add_u32_e32 v0, 0xe800, v82
	v_and_b32_e32 v36, 0x7e0, v28
	ds_read_b32 v28, v63
	ds_read_b32 v29, v63 offset:132
	ds_read_b32 v30, v63 offset:264
	ds_read_b32 v31, v63 offset:396
	ds_read_b32 v34, v63 offset:528
	ds_read_b32 v35, v63 offset:660
	ds_read_b32 v37, v63 offset:792
	ds_read_b32 v38, v63 offset:924
	v_and_b32_e32 v0, 0xffc0, v0
	v_lshlrev_b32_e32 v0, 1, v0
	v_lshl_add_u64 v[32:33], v[10:11], 0, v[0:1]
	v_or_b32_e32 v0, v36, v62
	v_lshlrev_b32_e32 v0, 12, v0
	s_waitcnt lgkmcnt(0)
	v_cvt_pk_bf16_f32 v28, v28, v29
	v_cvt_pk_bf16_f32 v29, v30, v31
	v_cvt_pk_bf16_f32 v30, v34, v35
	v_cvt_pk_bf16_f32 v31, v37, v38
	v_lshl_add_u64 v[34:35], v[32:33], 0, v[0:1]
	global_store_dwordx4 v[34:35], v[28:31], off
	ds_read_b32 v0, v63 offset:32
	ds_read_b32 v28, v63 offset:164
	ds_read_b32 v29, v63 offset:296
	ds_read_b32 v30, v63 offset:428
	ds_read_b32 v31, v63 offset:560
	ds_read_b32 v34, v63 offset:692
	ds_read_b32 v35, v63 offset:824
	ds_read_b32 v37, v63 offset:956
	s_waitcnt lgkmcnt(0)
	v_cvt_pk_bf16_f32 v28, v0, v28
	v_or_b32_e32 v0, v36, v64
	v_lshlrev_b32_e32 v0, 12, v0
	v_cvt_pk_bf16_f32 v29, v29, v30
	v_cvt_pk_bf16_f32 v30, v31, v34
	v_cvt_pk_bf16_f32 v31, v35, v37
	v_lshl_add_u64 v[34:35], v[32:33], 0, v[0:1]
	global_store_dwordx4 v[34:35], v[28:31], off
	ds_read_b32 v0, v63 offset:64
	ds_read_b32 v28, v63 offset:196
	ds_read_b32 v29, v63 offset:328
	ds_read_b32 v30, v63 offset:460
	ds_read_b32 v31, v63 offset:592
	ds_read_b32 v34, v63 offset:724
	ds_read_b32 v35, v63 offset:856
	ds_read_b32 v37, v63 offset:988
	s_waitcnt lgkmcnt(0)
	v_cvt_pk_bf16_f32 v28, v0, v28
	v_or_b32_e32 v0, v36, v65
	v_lshlrev_b32_e32 v0, 12, v0
	v_cvt_pk_bf16_f32 v29, v29, v30
	v_cvt_pk_bf16_f32 v30, v31, v34
	v_cvt_pk_bf16_f32 v31, v35, v37
	v_lshl_add_u64 v[34:35], v[32:33], 0, v[0:1]
	global_store_dwordx4 v[34:35], v[28:31], off
	ds_read_b32 v0, v63 offset:96
	ds_read_b32 v28, v63 offset:228
	ds_read_b32 v29, v63 offset:360
	ds_read_b32 v30, v63 offset:492
	ds_read_b32 v31, v63 offset:624
	ds_read_b32 v34, v63 offset:756
	ds_read_b32 v35, v63 offset:888
	ds_read_b32 v37, v63 offset:1020
	s_waitcnt lgkmcnt(0)
	v_cvt_pk_bf16_f32 v28, v0, v28
	v_or_b32_e32 v0, v36, v66
	v_lshlrev_b32_e32 v0, 12, v0
	v_cvt_pk_bf16_f32 v29, v29, v30
	v_cvt_pk_bf16_f32 v30, v31, v34
	v_cvt_pk_bf16_f32 v31, v35, v37
	v_lshl_add_u64 v[32:33], v[32:33], 0, v[0:1]
	global_store_dwordx4 v[32:33], v[28:31], off
	s_waitcnt lgkmcnt(0)

; #define LAS __attribute__((address_space(3)))
; DI unsigned pk2(float lo, float hi) { f32x2_t f = {lo, hi}; bf16x2_t v = __builtin_convertvector(f, bf16x2_t); return __builtin_bit_cast(unsigned, v); }
; DI void transpose_item(const float* W, int K, int N, bf16_t* WT, LAS float* scr, int item, int lane, const float* gk = nullptr) {
;     ...
;     for (int i = 0; i < 32; ++i) { const int kk = 2 * i + (lane >> 5); scr[kk * 33 + (lane & 31)] = __builtin_nontemporal_load(W + (size_t)(k0 + kk) * N + n0 + (lane & 31)) * (gk ? gk[k0 + kk] : 1.f); }
;     asm volatile("s_waitcnt lgkmcnt(0)" ::: "memory");
;     const int c = lane & 7;
; #pragma unroll
;     for (int j = 0; j < 4; ++j) { const int n = (lane >> 3) + 8 * j; const LAS float* s = scr + (8 * c) * 33 + n;
;         u32x4 o; o.x = pk2(s[0 * 33], s[1 * 33]); o.y = pk2(s[2 * 33], s[3 * 33]); o.z = pk2(s[4 * 33], s[5 * 33]); o.w = pk2(s[6 * 33], s[7 * 33]);
;         *(u32x4*)(WT + (size_t)(n0 + n) * K + k0 + 8 * c) = o; }
; DI void prologue(const Params& P, LAS unsigned char* lds) {
;     ...
;     for (int it = gw; it < NITEMS; it += NGW) {
;         int r = it;
;         if (r < I_INE) { transpose_item(P.w_in_e, DM, 6144, (bf16_t*)(ws + WS_WINE), scr, r, lane); continue; } r -= I_INE;
.LBB0_199:
	v_lshl_add_u64 v[48:49], v[46:47], 0, s[18:19]
	v_lshl_add_u64 v[50:51], v[44:45], 0, s[18:19]
	v_lshl_add_u64 v[52:53], v[42:43], 0, s[18:19]
	v_lshl_add_u64 v[54:55], v[40:41], 0, s[18:19]
	v_lshl_add_u64 v[56:57], v[38:39], 0, s[18:19]
	v_lshl_add_u64 v[58:59], v[36:37], 0, s[18:19]
	v_lshl_add_u64 v[84:85], v[34:35], 0, s[18:19]
	v_lshl_add_u64 v[86:87], v[32:33], 0, s[18:19]
	global_load_dword v29, v[48:49], off nt
	global_load_dword v31, v[50:51], off nt
	s_nop 0
	global_load_dword v48, v[52:53], off nt
	global_load_dword v49, v[54:55], off nt
	global_load_dword v50, v[56:57], off nt
	global_load_dword v51, v[58:59], off nt
	s_nop 0
	global_load_dword v52, v[84:85], off nt
	global_load_dword v53, v[86:87], off nt
	s_add_u32 s18, s18, 0x60000
	s_addc_u32 s19, s19, 0
	v_add_u32_e32 v54, 0x400, v0
	s_cmp_lg_u32 s18, 0x180000
	s_waitcnt vmcnt(0)
	ds_write2_b32 v0, v29, v31 offset1:66
	ds_write2_b32 v0, v48, v49 offset0:132 offset1:198
	ds_write2_b32 v54, v50, v51 offset0:8 offset1:74
	ds_write2_b32 v54, v52, v53 offset0:140 offset1:206
	v_add_u32_e32 v0, 0x840, v0
	s_cbranch_scc1 .LBB0_199
	s_waitcnt lgkmcnt(0)
	ds_read_b32 v0, v63
	ds_read_b32 v29, v63 offset:132
	ds_read_b32 v32, v63 offset:264
	ds_read_b32 v33, v63 offset:396
	ds_read_b32 v36, v63 offset:528
	ds_read_b32 v37, v63 offset:660
	ds_read_b32 v38, v63 offset:792
	ds_read_b32 v39, v63 offset:924
	v_ashrrev_i32_e32 v31, 31, v30
	v_lshl_add_u64 v[34:35], v[30:31], 1, v[12:13]
	s_waitcnt lgkmcnt(0)
	v_cvt_pk_bf16_f32 v31, v32, v33
	v_cvt_pk_bf16_f32 v32, v36, v37
	v_or_b32_e32 v36, v28, v62
	v_ashrrev_i32_e32 v37, 31, v36
	v_lshlrev_b64 v[36:37], 12, v[36:37]
	v_cvt_pk_bf16_f32 v30, v0, v29
	v_cvt_pk_bf16_f32 v33, v38, v39
	v_lshl_add_u64 v[36:37], v[34:35], 0, v[36:37]
	global_store_dwordx4 v[36:37], v[30:33], off
	ds_read_b32 v0, v63 offset:32
	ds_read_b32 v29, v63 offset:164
	ds_read_b32 v31, v63 offset:296
	ds_read_b32 v32, v63 offset:428
	ds_read_b32 v33, v63 offset:560
	ds_read_b32 v36, v63 offset:692
	ds_read_b32 v37, v63 offset:824
	ds_read_b32 v38, v63 offset:956
	s_waitcnt lgkmcnt(0)
	v_cvt_pk_bf16_f32 v31, v31, v32
	v_cvt_pk_bf16_f32 v30, v0, v29
	v_cvt_pk_bf16_f32 v32, v33, v36
	v_or_b32_e32 v36, v28, v64
	v_cvt_pk_bf16_f32 v33, v37, v38
	v_ashrrev_i32_e32 v37, 31, v36
	v_lshlrev_b64 v[36:37], 12, v[36:37]
	v_lshl_add_u64 v[36:37], v[34:35], 0, v[36:37]
	global_store_dwordx4 v[36:37], v[30:33], off
	ds_read_b32 v0, v63 offset:64
	ds_read_b32 v29, v63 offset:196
	ds_read_b32 v31, v63 offset:328
	ds_read_b32 v32, v63 offset:460
	ds_read_b32 v33, v63 offset:592
	ds_read_b32 v36, v63 offset:724
	ds_read_b32 v37, v63 offset:856
	ds_read_b32 v38, v63 offset:988
	s_waitcnt lgkmcnt(0)
	v_cvt_pk_bf16_f32 v31, v31, v32
	v_cvt_pk_bf16_f32 v30, v0, v29
	v_cvt_pk_bf16_f32 v32, v33, v36
	v_or_b32_e32 v36, v28, v65
	v_cvt_pk_bf16_f32 v33, v37, v38
	v_ashrrev_i32_e32 v37, 31, v36
	v_lshlrev_b64 v[36:37], 12, v[36:37]
	v_lshl_add_u64 v[36:37], v[34:35], 0, v[36:37]
	global_store_dwordx4 v[36:37], v[30:33], off
	ds_read_b32 v0, v63 offset:96
	ds_read_b32 v29, v63 offset:228
	ds_read_b32 v31, v63 offset:360
	ds_read_b32 v32, v63 offset:492
	ds_read_b32 v33, v63 offset:624
	ds_read_b32 v36, v63 offset:756
	ds_read_b32 v37, v63 offset:888
	ds_read_b32 v38, v63 offset:1020
	v_or_b32_e32 v28, v28, v66
	s_waitcnt lgkmcnt(0)
	v_cvt_pk_bf16_f32 v30, v0, v29
	v_ashrrev_i32_e32 v29, 31, v28
	v_lshlrev_b64 v[28:29], 12, v[28:29]
	v_cvt_pk_bf16_f32 v31, v31, v32
	v_cvt_pk_bf16_f32 v32, v33, v36
	v_cvt_pk_bf16_f32 v33, v37, v38
	v_lshl_add_u64 v[28:29], v[34:35], 0, v[28:29]
	global_store_dwordx4 v[28:29], v[30:33], off
	s_waitcnt lgkmcnt(0)
	s_branch .LBB0_162

; DI unsigned pk2(float lo, float hi) { f32x2_t f = {lo, hi}; bf16x2_t v = __builtin_convertvector(f, bf16x2_t); return __builtin_bit_cast(unsigned, v); }
; DI int opq_bid() { int b = blockIdx.x; asm volatile("" : "+s"(b)); return b; }
; DI void prologue(const Params& P, LAS unsigned char* lds) {
;     ...
;       for (int i = opq_bid() * NTH + tid_; i < 2 * DM * DM / 4; i += gridDim.x * NTH) { const float gr = P.g_xa[i >> 9]; const f32x4 v = __builtin_nontemporal_load(src + i) * gr; u32x2 w; w.x = pk2(v.x, v.y); w.y = pk2(v.z, v.w); dst[i] = w; } }
.LBB0_203:
	v_ashrrev_i32_e32 v4, 9, v2
	v_ashrrev_i32_e32 v3, 31, v2
	v_ashrrev_i32_e32 v5, 31, v4
	v_lshl_add_u64 v[8:9], v[2:3], 4, s[64:65]
	v_lshl_add_u64 v[4:5], v[4:5], 2, s[50:51]
	global_load_dwordx4 v[8:11], v[8:9], off nt
	s_nop 0
	global_load_dword v0, v[4:5], off
	v_lshl_add_u64 v[4:5], v[2:3], 3, s[12:13]
	v_add_u32_e32 v2, s68, v2
	s_mov_b32 s8, 0x1fffff
	v_cmp_lt_i32_e32 vcc, s8, v2
	s_or_b64 s[6:7], vcc, s[6:7]
	s_waitcnt vmcnt(0)
	v_pk_mul_f32 v[10:11], v[10:11], v[0:1] op_sel_hi:[1,0]
	v_pk_mul_f32 v[8:9], v[8:9], v[0:1] op_sel_hi:[1,0]
	s_nop 0
	v_cvt_pk_bf16_f32 v8, v8, v9
	v_cvt_pk_bf16_f32 v9, v10, v11
	global_store_dwordx2 v[4:5], v[8:9], off
	s_andn2_b64 exec, exec, s[6:7]
	s_cbranch_execnz .LBB0_203

; DI int opq_bid() { int b = blockIdx.x; asm volatile("" : "+s"(b)); return b; }
; DI void prologue(const Params& P, LAS unsigned char* lds) {
;     ...
;     { float* ss = (float*)(ws + WS_SS); for (int i = opq_bid() * NTH + tid_; i < 4 * MT; i += gridDim.x * NTH) ss[i] = 0.f; }
.LBB0_206:
	v_ashrrev_i32_e32 v3, 31, v2
	v_lshl_add_u64 v[4:5], v[2:3], 2, s[12:13]
	v_add_u32_e32 v2, s68, v2
	s_mov_b32 s8, 0xffff
	v_cmp_lt_i32_e32 vcc, s8, v2
	s_or_b64 s[6:7], vcc, s[6:7]
	global_store_dword v[4:5], v1, off
	s_andn2_b64 exec, exec, s[6:7]
	s_cbranch_execnz .LBB0_206

; DI unsigned pk2(float lo, float hi) { f32x2_t f = {lo, hi}; bf16x2_t v = __builtin_convertvector(f, bf16x2_t); return __builtin_bit_cast(unsigned, v); }
; DI void rms_row_bf16(const float* xrow, const float* g, bf16_t* orow, int lane) {
;     const f32x4* xr = (const f32x4*)xrow + lane; const f32x4* gr = (const f32x4*)g + lane;
;     f32x4 v[8]; float s = 0.f;
; #pragma unroll
;     for (int j = 0; j < 8; ++j) { v[j] = __builtin_nontemporal_load(xr + 64 * j); s += (v[j].x * v[j].x + v[j].y * v[j].y) + (v[j].z * v[j].z + v[j].w * v[j].w); }
;     const float r = rsqrtf(wave_sum(s) * (1.f / DM) + EPS);
;     u32x2* o8 = (u32x2*)orow + lane;
; #pragma unroll
;     for (int j = 0; j < 8; ++j) { const f32x4 gg = gr[64 * j]; u32x2 w; w.x = pk2(v[j].x * r * gg.x, v[j].y * r * gg.y); w.y = pk2(v[j].z * r * gg.z, v[j].w * r * gg.w); o8[64 * j] = w; }
; DI void rms_rows_phase(const float* X, const float* g, bf16_t* O, int nrows) {
;     ...
;     for (int m = gw; m < nrows; m += NGW) rms_row_bf16(X + (size_t)m * DM, g, O + (size_t)m * DM, lane);
.LBB0_209:
	global_load_dwordx4 v[24:27], v[14:15], off offset:-4096 nt
	global_load_dwordx4 v[28:31], v[14:15], off offset:-3072 nt
	global_load_dwordx4 v[32:35], v[14:15], off offset:-2048 nt
	global_load_dwordx4 v[36:39], v[14:15], off nt
	global_load_dwordx4 v[40:43], v[14:15], off offset:-1024 nt
	global_load_dwordx4 v[44:47], v[14:15], off offset:1024 nt
	global_load_dwordx4 v[48:51], v[14:15], off offset:2048 nt
	global_load_dwordx4 v[52:55], v[14:15], off offset:3072 nt
	global_load_dwordx4 v[56:59], v[2:3], off
	v_add_u32_e32 v7, s88, v7
	v_lshl_add_u64 v[14:15], v[14:15], 0, s[74:75]
	s_waitcnt vmcnt(0)
	v_mov_b32_e32 v64, v25
	v_mov_b32_e32 v65, v29
	v_mov_b32_e32 v68, v27
	v_mov_b32_e32 v69, v31
	v_mov_b32_e32 v62, v24
	v_mov_b32_e32 v63, v28
	v_mov_b32_e32 v66, v26
	v_mov_b32_e32 v67, v30
	v_pk_mul_f32 v[70:71], v[34:35], v[34:35]
	v_pk_mul_f32 v[72:73], v[32:33], v[32:33]
	v_pk_mul_f32 v[64:65], v[64:65], v[64:65]
	v_pk_mul_f32 v[68:69], v[68:69], v[68:69]
	v_pk_mov_b32 v[84:85], v[72:73], v[70:71] op_sel:[1,0]
	v_mov_b32_e32 v73, v71
	v_pk_fma_f32 v[62:63], v[62:63], v[62:63], v[64:65]
	v_pk_fma_f32 v[64:65], v[66:67], v[66:67], v[68:69]
	v_mul_f32_e32 v0, v41, v41
	v_mul_f32_e32 v74, v43, v43
	v_pk_add_f32 v[66:67], v[84:85], v[72:73]
	v_pk_add_f32 v[62:63], v[62:63], v[64:65]
	v_mul_f32_e32 v83, v36, v36
	v_mul_f32_e32 v88, v37, v37
	v_mul_f32_e32 v89, v38, v38
	v_mul_f32_e32 v90, v39, v39
	v_pk_fma_f32 v[70:71], v[40:41], v[40:41], v[0:1] op_sel_hi:[1,1,0]
	v_pk_fma_f32 v[74:75], v[42:43], v[42:43], v[74:75] op_sel_hi:[1,1,0]
	v_pk_add_f32 v[64:65], v[66:67], v[66:67] op_sel:[0,1] op_sel_hi:[1,0]
	v_pk_add_f32 v[62:63], v[62:63], v[62:63] op_sel:[0,1] op_sel_hi:[1,0]
	v_pk_mul_f32 v[76:77], v[46:47], v[46:47]
	v_pk_mul_f32 v[78:79], v[44:45], v[44:45]
	v_mov_b32_e32 v71, v89
	v_mov_b32_e32 v75, v90
	v_mov_b32_e32 v65, v88
	v_mov_b32_e32 v63, v83
	v_pk_mov_b32 v[86:87], v[78:79], v[76:77] op_sel:[1,0]
	v_mov_b32_e32 v79, v77
	v_pk_add_f32 v[66:67], v[70:71], v[74:75]
	v_pk_add_f32 v[62:63], v[62:63], v[64:65]
	v_mul_f32_e32 v80, v49, v49
	v_mul_f32_e32 v82, v51, v51
	v_pk_add_f32 v[68:69], v[86:87], v[78:79]
	v_pk_add_f32 v[62:63], v[62:63], v[66:67]
	v_mul_f32_e32 v91, v52, v52
	v_mul_f32_e32 v92, v53, v53
	v_mul_f32_e32 v93, v54, v54
	v_mul_f32_e32 v94, v55, v55
	v_pk_fma_f32 v[76:77], v[48:49], v[48:49], v[80:81] op_sel_hi:[1,1,0]
	v_pk_fma_f32 v[80:81], v[50:51], v[50:51], v[82:83] op_sel_hi:[1,1,0]
	v_pk_add_f32 v[68:69], v[68:69], v[68:69] op_sel:[0,1] op_sel_hi:[1,0]
	v_pk_add_f32 v[62:63], v[62:63], v[62:63] op_sel:[0,1] op_sel_hi:[1,0]
	v_mov_b32_e32 v77, v93
	v_mov_b32_e32 v81, v94
	v_mov_b32_e32 v69, v92
	v_mov_b32_e32 v63, v91
	v_pk_add_f32 v[70:71], v[76:77], v[80:81]
	v_pk_add_f32 v[62:63], v[62:63], v[68:69]
	s_nop 0
	v_pk_add_f32 v[62:63], v[62:63], v[70:71]
	s_nop 0
	v_add_f32_e32 v0, v62, v63
	ds_bpermute_b32 v62, v18, v0
	s_waitcnt lgkmcnt(0)
	v_add_f32_e32 v0, v0, v62
	ds_bpermute_b32 v62, v19, v0
	s_waitcnt lgkmcnt(0)
	v_add_f32_e32 v0, v0, v62
	ds_bpermute_b32 v62, v20, v0
	s_waitcnt lgkmcnt(0)
	v_add_f32_e32 v0, v0, v62
	ds_bpermute_b32 v62, v21, v0
	s_waitcnt lgkmcnt(0)
	v_add_f32_e32 v0, v0, v62
	ds_bpermute_b32 v62, v22, v0
	s_waitcnt lgkmcnt(0)
	v_add_f32_e32 v0, v0, v62
	ds_bpermute_b32 v62, v23, v0
	s_waitcnt lgkmcnt(0)
	v_add_f32_e32 v0, v0, v62
	v_fmamk_f32 v0, v0, 0x3a000000, v229
	v_mul_f32_e32 v62, 0x4b800000, v0
	v_cmp_gt_f32_e32 vcc, s33, v0
	s_nop 1
	v_cndmask_b32_e32 v0, v0, v62, vcc
	v_rsq_f32_e32 v0, v0
	s_nop 0
	v_mul_f32_e32 v62, 0x45800000, v0
	v_cndmask_b32_e32 v0, v0, v62, vcc
	v_pk_mul_f32 v[24:25], v[24:25], v[0:1] op_sel_hi:[1,0]
	v_pk_mul_f32 v[26:27], v[26:27], v[0:1] op_sel_hi:[1,0]
	v_pk_mul_f32 v[24:25], v[56:57], v[24:25]
	v_pk_mul_f32 v[26:27], v[58:59], v[26:27]
	v_cvt_pk_bf16_f32 v24, v24, v25
	v_cvt_pk_bf16_f32 v25, v26, v27
	global_store_dwordx2 v[16:17], v[24:25], off
	global_load_dwordx4 v[24:27], v[2:3], off offset:1024
	v_pk_mul_f32 v[28:29], v[28:29], v[0:1] op_sel_hi:[1,0]
	v_pk_mul_f32 v[30:31], v[30:31], v[0:1] op_sel_hi:[1,0]
	v_cmp_lt_i32_e32 vcc, s8, v7
	s_or_b64 s[6:7], vcc, s[6:7]
	s_waitcnt vmcnt(0)
	v_pk_mul_f32 v[24:25], v[24:25], v[28:29]
	v_pk_mul_f32 v[26:27], v[26:27], v[30:31]
	v_cvt_pk_bf16_f32 v24, v24, v25
	v_cvt_pk_bf16_f32 v25, v26, v27
	global_store_dwordx2 v[16:17], v[24:25], off offset:512
	global_load_dwordx4 v[24:27], v[2:3], off offset:2048
	v_pk_mul_f32 v[28:29], v[32:33], v[0:1] op_sel_hi:[1,0]
	v_pk_mul_f32 v[30:31], v[34:35], v[0:1] op_sel_hi:[1,0]
	s_waitcnt vmcnt(0)
	v_pk_mul_f32 v[24:25], v[24:25], v[28:29]
	v_pk_mul_f32 v[26:27], v[26:27], v[30:31]
	v_cvt_pk_bf16_f32 v24, v24, v25
	v_cvt_pk_bf16_f32 v25, v26, v27
	global_store_dwordx2 v[16:17], v[24:25], off offset:1024
	global_load_dwordx4 v[24:27], v[2:3], off offset:3072
	v_pk_mul_f32 v[28:29], v[40:41], v[0:1] op_sel_hi:[1,0]
	v_pk_mul_f32 v[30:31], v[42:43], v[0:1] op_sel_hi:[1,0]
	s_waitcnt vmcnt(0)
	v_pk_mul_f32 v[24:25], v[24:25], v[28:29]
	v_pk_mul_f32 v[26:27], v[26:27], v[30:31]
	v_cvt_pk_bf16_f32 v24, v24, v25
	v_cvt_pk_bf16_f32 v25, v26, v27
	global_store_dwordx2 v[16:17], v[24:25], off offset:1536
	global_load_dwordx4 v[24:27], v[4:5], off
	v_pk_mul_f32 v[28:29], v[36:37], v[0:1] op_sel_hi:[1,0]
	v_pk_mul_f32 v[30:31], v[38:39], v[0:1] op_sel_hi:[1,0]
	s_waitcnt vmcnt(0)
	v_pk_mul_f32 v[24:25], v[24:25], v[28:29]
	v_pk_mul_f32 v[26:27], v[26:27], v[30:31]
	v_cvt_pk_bf16_f32 v24, v24, v25
	v_cvt_pk_bf16_f32 v25, v26, v27
	global_store_dwordx2 v[16:17], v[24:25], off offset:2048
	global_load_dwordx4 v[24:27], v[8:9], off
	v_pk_mul_f32 v[28:29], v[44:45], v[0:1] op_sel_hi:[1,0]
	v_pk_mul_f32 v[30:31], v[46:47], v[0:1] op_sel_hi:[1,0]
	s_waitcnt vmcnt(0)
	v_pk_mul_f32 v[24:25], v[24:25], v[28:29]
	v_pk_mul_f32 v[26:27], v[26:27], v[30:31]
	v_cvt_pk_bf16_f32 v24, v24, v25
	v_cvt_pk_bf16_f32 v25, v26, v27
	global_store_dwordx2 v[16:17], v[24:25], off offset:2560
	global_load_dwordx4 v[24:27], v[10:11], off
	v_pk_mul_f32 v[28:29], v[48:49], v[0:1] op_sel_hi:[1,0]
	v_pk_mul_f32 v[30:31], v[50:51], v[0:1] op_sel_hi:[1,0]
	s_waitcnt vmcnt(0)
	v_pk_mul_f32 v[24:25], v[28:29], v[24:25]
	v_pk_mul_f32 v[26:27], v[30:31], v[26:27]
	v_cvt_pk_bf16_f32 v24, v24, v25
	v_cvt_pk_bf16_f32 v25, v26, v27
	global_store_dwordx2 v[16:17], v[24:25], off offset:3072
	global_load_dwordx4 v[24:27], v[12:13], off
	v_pk_mul_f32 v[28:29], v[52:53], v[0:1] op_sel_hi:[1,0]
	v_pk_mul_f32 v[30:31], v[54:55], v[0:1] op_sel_hi:[1,0]
	s_waitcnt vmcnt(0)
	v_pk_mul_f32 v[24:25], v[28:29], v[24:25]
	v_pk_mul_f32 v[26:27], v[30:31], v[26:27]
	v_cvt_pk_bf16_f32 v24, v24, v25
	v_cvt_pk_bf16_f32 v25, v26, v27
	global_store_dwordx2 v[16:17], v[24:25], off offset:3584
	v_lshl_add_u64 v[16:17], v[16:17], 0, s[76:77]
	s_andn2_b64 exec, exec, s[6:7]
	s_cbranch_execnz .LBB0_209

; DI void rms_row_bf16(const float* xrow, const float* g, bf16_t* orow, int lane) {
;     const f32x4* xr = (const f32x4*)xrow + lane; const f32x4* gr = (const f32x4*)g + lane;
;     f32x4 v[8]; float s = 0.f;
; #pragma unroll
;     for (int j = 0; j < 8; ++j) { v[j] = __builtin_nontemporal_load(xr + 64 * j); s += (v[j].x * v[j].x + v[j].y * v[j].y) + (v[j].z * v[j].z + v[j].w * v[j].w); }
;     const float r = rsqrtf(wave_sum(s) * (1.f / DM) + EPS);
; DI void prologue(const Params& P, LAS unsigned char* lds) {
;     ...
;     for (int m = gw; m < 1024; m += NGW) { const int l = m >> 9, row = m & 511;
;         rms_row_bf16(P.mem + (size_t)row * DM, P.g_mem + l * DM, (bf16_t*)(ws + WS_HM) + (size_t)m * DM, lane); }
.LBB0_212:
	v_and_b32_e32 v0, 0xff800, v20
	v_lshlrev_b32_e32 v0, 2, v0
	v_lshl_add_u64 v[2:3], v[8:9], 0, v[0:1]
	global_load_dwordx4 v[22:25], v[2:3], off nt
	global_load_dwordx4 v[26:29], v[2:3], off offset:1024 nt
	global_load_dwordx4 v[30:33], v[2:3], off offset:2048 nt
	global_load_dwordx4 v[34:37], v[2:3], off offset:3072 nt
	v_add_co_u32_e32 v2, vcc, s9, v2
	v_and_b32_e32 v50, 0xfffff800, v7
	s_nop 0
	v_addc_co_u32_e32 v3, vcc, 0, v3, vcc
	global_load_dwordx4 v[38:41], v[2:3], off nt
	global_load_dwordx4 v[42:45], v[2:3], off offset:1024 nt
	global_load_dwordx4 v[46:49], v[2:3], off offset:2048 nt
	s_nop 0
	global_load_dwordx4 v[2:5], v[2:3], off offset:3072 nt
	v_ashrrev_i32_e32 v51, 31, v50
	v_lshl_add_u64 v[54:55], v[50:51], 2, v[10:11]
	global_load_dwordx4 v[50:53], v[54:55], off
	v_add_u32_e32 v6, s88, v6
	s_movk_i32 s8, 0x3ff
	v_add_u32_e32 v7, s85, v7
	v_add_u32_e32 v20, s15, v20
	s_waitcnt vmcnt(0)
	v_mov_b32_e32 v58, v23
	v_mov_b32_e32 v59, v27
	v_mov_b32_e32 v62, v25
	v_mov_b32_e32 v63, v29
	v_mov_b32_e32 v56, v22
	v_mov_b32_e32 v57, v26
	v_mov_b32_e32 v60, v24
	v_mov_b32_e32 v61, v28
	v_pk_mul_f32 v[64:65], v[32:33], v[32:33]
	v_pk_mul_f32 v[66:67], v[30:31], v[30:31]
	v_pk_mul_f32 v[58:59], v[58:59], v[58:59]
	v_pk_mul_f32 v[62:63], v[62:63], v[62:63]
	v_pk_mov_b32 v[70:71], v[66:67], v[64:65] op_sel:[1,0]
	v_mov_b32_e32 v67, v65
	v_pk_fma_f32 v[56:57], v[56:57], v[56:57], v[58:59]
	v_pk_fma_f32 v[58:59], v[60:61], v[60:61], v[62:63]
	v_mul_f32_e32 v0, v35, v35
	v_mul_f32_e32 v68, v37, v37
	v_pk_add_f32 v[60:61], v[70:71], v[66:67]
	v_pk_add_f32 v[56:57], v[56:57], v[58:59]
	v_pk_fma_f32 v[64:65], v[34:35], v[34:35], v[0:1] op_sel_hi:[1,1,0]
	v_pk_fma_f32 v[68:69], v[36:37], v[36:37], v[68:69] op_sel_hi:[1,1,0]
	v_mul_f32_e32 v21, v38, v38
	v_mul_f32_e32 v77, v39, v39
	v_pk_add_f32 v[58:59], v[60:61], v[60:61] op_sel:[0,1] op_sel_hi:[1,0]
	v_pk_add_f32 v[56:57], v[56:57], v[56:57] op_sel:[0,1] op_sel_hi:[1,0]
	v_mul_f32_e32 v65, v40, v40
	v_mul_f32_e32 v69, v41, v41
	v_pk_mul_f32 v[72:73], v[44:45], v[44:45]
	v_pk_mul_f32 v[74:75], v[42:43], v[42:43]
	v_mov_b32_e32 v59, v77
	v_mov_b32_e32 v57, v21
	v_pk_mov_b32 v[62:63], v[74:75], v[72:73] op_sel:[1,0]
	v_mov_b32_e32 v75, v73
	v_pk_add_f32 v[60:61], v[64:65], v[68:69]
	v_pk_add_f32 v[56:57], v[56:57], v[58:59]
	v_mul_f32_e32 v0, v47, v47
	v_mul_f32_e32 v76, v49, v49
	v_pk_add_f32 v[62:63], v[62:63], v[74:75]
	v_pk_add_f32 v[56:57], v[56:57], v[60:61]
	v_mul_f32_e32 v78, v2, v2
	v_mul_f32_e32 v79, v3, v3
	v_mul_f32_e32 v80, v4, v4
	v_mul_f32_e32 v81, v5, v5
	v_pk_fma_f32 v[66:67], v[46:47], v[46:47], v[0:1] op_sel_hi:[1,1,0]
	v_pk_fma_f32 v[70:71], v[48:49], v[48:49], v[76:77] op_sel_hi:[1,1,0]
	v_pk_add_f32 v[62:63], v[62:63], v[62:63] op_sel:[0,1] op_sel_hi:[1,0]
	v_pk_add_f32 v[56:57], v[56:57], v[56:57] op_sel:[0,1] op_sel_hi:[1,0]
	v_mov_b32_e32 v67, v80
	v_mov_b32_e32 v71, v81
	v_mov_b32_e32 v63, v79
	v_mov_b32_e32 v57, v78
	v_pk_add_f32 v[64:65], v[66:67], v[70:71]
	v_pk_add_f32 v[56:57], v[56:57], v[62:63]
	s_nop 0
	v_pk_add_f32 v[56:57], v[56:57], v[64:65]
	s_nop 0
	v_add_f32_e32 v0, v56, v57
	ds_bpermute_b32 v21, v14, v0
	s_waitcnt lgkmcnt(0)
	v_add_f32_e32 v0, v0, v21
	ds_bpermute_b32 v21, v15, v0
	s_waitcnt lgkmcnt(0)
	v_add_f32_e32 v0, v0, v21
	ds_bpermute_b32 v21, v16, v0
	s_waitcnt lgkmcnt(0)
	v_add_f32_e32 v0, v0, v21
	ds_bpermute_b32 v21, v17, v0
	s_waitcnt lgkmcnt(0)
	v_add_f32_e32 v0, v0, v21
	ds_bpermute_b32 v21, v18, v0
	s_waitcnt lgkmcnt(0)
	v_add_f32_e32 v0, v0, v21
	ds_bpermute_b32 v21, v19, v0
	s_waitcnt lgkmcnt(0)
; DI unsigned pk2(float lo, float hi) { f32x2_t f = {lo, hi}; bf16x2_t v = __builtin_convertvector(f, bf16x2_t); return __builtin_bit_cast(unsigned, v); }
; DI void rms_row_bf16(const float* xrow, const float* g, bf16_t* orow, int lane) {
;     ...
;     const float r = rsqrtf(wave_sum(s) * (1.f / DM) + EPS);
;     u32x2* o8 = (u32x2*)orow + lane;
; #pragma unroll
;     for (int j = 0; j < 8; ++j) { const f32x4 gg = gr[64 * j]; u32x2 w; w.x = pk2(v[j].x * r * gg.x, v[j].y * r * gg.y); w.y = pk2(v[j].z * r * gg.z, v[j].w * r * gg.w); o8[64 * j] = w; }
	v_add_f32_e32 v0, v0, v21
	v_fmamk_f32 v0, v0, 0x3a000000, v229
	v_mul_f32_e32 v21, 0x4b800000, v0
	v_cmp_gt_f32_e32 vcc, s33, v0
	s_nop 1
	v_cndmask_b32_e32 v0, v0, v21, vcc
	v_rsq_f32_e32 v0, v0
	s_nop 0
	v_mul_f32_e32 v21, 0x45800000, v0
	v_cndmask_b32_e32 v0, v0, v21, vcc
	v_pk_mul_f32 v[22:23], v[22:23], v[0:1] op_sel_hi:[1,0]
	v_pk_mul_f32 v[24:25], v[24:25], v[0:1] op_sel_hi:[1,0]
	v_pk_mul_f32 v[22:23], v[50:51], v[22:23]
	v_pk_mul_f32 v[24:25], v[52:53], v[24:25]
	v_cvt_pk_bf16_f32 v22, v22, v23
	v_cvt_pk_bf16_f32 v23, v24, v25
	global_store_dwordx2 v[12:13], v[22:23], off
	global_load_dwordx4 v[22:25], v[54:55], off offset:1024
	v_pk_mul_f32 v[26:27], v[26:27], v[0:1] op_sel_hi:[1,0]
	v_pk_mul_f32 v[28:29], v[28:29], v[0:1] op_sel_hi:[1,0]
	v_pk_mul_f32 v[2:3], v[2:3], v[0:1] op_sel_hi:[1,0]
	v_pk_mul_f32 v[4:5], v[4:5], v[0:1] op_sel_hi:[1,0]
	s_waitcnt vmcnt(0)
	v_pk_mul_f32 v[22:23], v[22:23], v[26:27]
	v_pk_mul_f32 v[24:25], v[24:25], v[28:29]
	v_cvt_pk_bf16_f32 v22, v22, v23
	v_cvt_pk_bf16_f32 v23, v24, v25
	global_store_dwordx2 v[12:13], v[22:23], off offset:512
	global_load_dwordx4 v[22:25], v[54:55], off offset:2048
	v_pk_mul_f32 v[26:27], v[30:31], v[0:1] op_sel_hi:[1,0]
	v_pk_mul_f32 v[28:29], v[32:33], v[0:1] op_sel_hi:[1,0]
	v_pk_mul_f32 v[30:31], v[36:37], v[0:1] op_sel_hi:[1,0]
	s_waitcnt vmcnt(0)
	v_pk_mul_f32 v[22:23], v[22:23], v[26:27]
	v_pk_mul_f32 v[24:25], v[24:25], v[28:29]
	v_cvt_pk_bf16_f32 v22, v22, v23
	v_cvt_pk_bf16_f32 v23, v24, v25
	global_store_dwordx2 v[12:13], v[22:23], off offset:1024
	global_load_dwordx4 v[22:25], v[54:55], off offset:3072
	v_pk_mul_f32 v[28:29], v[34:35], v[0:1] op_sel_hi:[1,0]
	v_add_co_u32_e32 v26, vcc, s9, v54
	s_waitcnt vmcnt(0)
	v_pk_mul_f32 v[22:23], v[22:23], v[28:29]
	v_pk_mul_f32 v[24:25], v[24:25], v[30:31]
	v_cvt_pk_bf16_f32 v22, v22, v23
	v_cvt_pk_bf16_f32 v23, v24, v25
	v_addc_co_u32_e32 v27, vcc, 0, v55, vcc
	global_store_dwordx2 v[12:13], v[22:23], off offset:1536
	global_load_dwordx4 v[22:25], v[26:27], off
	v_pk_mul_f32 v[28:29], v[38:39], v[0:1] op_sel_hi:[1,0]
	v_pk_mul_f32 v[30:31], v[40:41], v[0:1] op_sel_hi:[1,0]
	v_cmp_lt_i32_e32 vcc, s8, v6
	s_or_b64 s[6:7], vcc, s[6:7]
	s_waitcnt vmcnt(0)
	v_pk_mul_f32 v[22:23], v[22:23], v[28:29]
	v_pk_mul_f32 v[24:25], v[24:25], v[30:31]
	v_cvt_pk_bf16_f32 v22, v22, v23
	v_cvt_pk_bf16_f32 v23, v24, v25
	global_store_dwordx2 v[12:13], v[22:23], off offset:2048
	global_load_dwordx4 v[22:25], v[26:27], off offset:1024
	v_pk_mul_f32 v[28:29], v[42:43], v[0:1] op_sel_hi:[1,0]
	v_pk_mul_f32 v[30:31], v[44:45], v[0:1] op_sel_hi:[1,0]
	s_waitcnt vmcnt(0)
	v_pk_mul_f32 v[22:23], v[22:23], v[28:29]
	v_pk_mul_f32 v[24:25], v[24:25], v[30:31]
	v_cvt_pk_bf16_f32 v22, v22, v23
	v_cvt_pk_bf16_f32 v23, v24, v25
	global_store_dwordx2 v[12:13], v[22:23], off offset:2560
	global_load_dwordx4 v[22:25], v[26:27], off offset:2048
	v_pk_mul_f32 v[28:29], v[46:47], v[0:1] op_sel_hi:[1,0]
	v_pk_mul_f32 v[30:31], v[48:49], v[0:1] op_sel_hi:[1,0]
	s_waitcnt vmcnt(0)
	v_pk_mul_f32 v[22:23], v[28:29], v[22:23]
	v_pk_mul_f32 v[24:25], v[30:31], v[24:25]
	v_cvt_pk_bf16_f32 v22, v22, v23
	v_cvt_pk_bf16_f32 v23, v24, v25
	global_store_dwordx2 v[12:13], v[22:23], off offset:3072
	global_load_dwordx4 v[22:25], v[26:27], off offset:3072
	s_waitcnt vmcnt(0)
	v_pk_mul_f32 v[2:3], v[2:3], v[22:23]
	v_pk_mul_f32 v[4:5], v[4:5], v[24:25]
	v_cvt_pk_bf16_f32 v2, v2, v3
	v_cvt_pk_bf16_f32 v3, v4, v5
	global_store_dwordx2 v[12:13], v[2:3], off offset:3584
	v_lshl_add_u64 v[12:13], v[12:13], 0, s[76:77]
	s_andn2_b64 exec, exec, s[6:7]
	s_cbranch_execnz .LBB0_212

; DI unsigned pk2(float lo, float hi) { f32x2_t f = {lo, hi}; bf16x2_t v = __builtin_convertvector(f, bf16x2_t); return __builtin_bit_cast(unsigned, v); }
; DI float silu(float v) { return v / (1.f + __expf(-v)); }
;     DI void operator()(const f32x4 (&acc)[2][2][4][2], const Unit& u, int wr, int wc, int fr, int fq) const {
;     ...
;             const int row0 = u.pm * BM + wr * 64 + fr, col0 = u.pn * BM + wc * 32 + 8 * fq;
; #pragma unroll
;             for (int ai = 0; ai < 2; ++ai)
; #pragma unroll
;                 for (int m = 0; m < 4; ++m) { const int row = row0 + ai * HALF + m * 16;
; #pragma unroll
;                     for (int bj = 0; bj < 2; ++bj) { const int col = col0 + bj * HALF;
;                         const u32x4 gv = *(const u32x4*)(gate + (size_t)row * LDU_E + col);
;                         const f32x4 s0 = *(const f32x4*)(pscale + col), s1 = *(const f32x4*)(pscale + col + 4);
;                         const f32x4 v0 = acc[ai][bj][m][0], v1 = acc[ai][bj][m][1];
;                         u32x4 w;
;                         w.x = pk2(v0[0] * s0[0] * silu(bflo(gv.x)), v0[1] * s0[1] * silu(bfhi(gv.x)));
;                         w.y = pk2(v0[2] * s0[2] * silu(bflo(gv.y)), v0[3] * s0[3] * silu(bfhi(gv.y)));
;                         w.z = pk2(v1[0] * s1[0] * silu(bflo(gv.z)), v1[1] * s1[1] * silu(bfhi(gv.z)));
;                         w.w = pk2(v1[2] * s1[2] * silu(bflo(gv.w)), v1[3] * s1[3] * silu(bfhi(gv.w)));
;                         *(u32x4*)(O + (size_t)row * ldc + col) = w; } }
.LBB0_373:
	s_andn2_b64 vcc, exec, s[68:69]
	s_cbranch_vccnz .LBB0_470
	s_lshl_b32 s12, s76, 8
	s_cmp_lt_i32 s65, 1
	s_mov_b64 s[16:17], -1
	s_cbranch_scc1 .LBB0_421
	s_cmp_lg_u32 s65, 1
	v_lshl_or_b32 v206, s18, 8, v248
	s_cbranch_scc0 .LBB0_377
	v_readlane_b32 s16, v255, 41
	v_readlane_b32 s17, v255, 42
	v_add_u32_e32 v0, s12, v251
	v_ashrrev_i32_e32 v207, 31, v206
	v_mov_b64_e32 v[142:143], s[16:17]
	v_mad_i64_i32 v[130:131], s[16:17], v0, s86, v[142:143]
	v_lshlrev_b64 v[138:139], 1, v[206:207]
	v_lshl_add_u64 v[144:145], v[130:131], 0, v[138:139]
	global_load_dwordx4 v[130:133], v[144:145], off
	s_mov_b64 s[16:17], s[48:49]
	s_mov_b64 s[24:25], s[50:51]
	s_mov_b64 s[44:45], s[60:61]
	v_readlane_b32 s48, v254, 26
	v_readlane_b32 s49, v254, 27
	v_readlane_b32 s52, v254, 30
	v_readlane_b32 s53, v254, 31
	v_lshl_add_u64 v[140:141], v[206:207], 2, s[48:49]
	global_load_dwordx4 v[134:137], v[140:141], off offset:16
	global_load_dwordx4 v[146:149], v[140:141], off
	s_mov_b64 s[48:49], s[16:17]
	v_readlane_b32 s54, v254, 32
	v_readlane_b32 s55, v254, 33
	v_readlane_b32 s56, v254, 34
	v_readlane_b32 s57, v254, 35
	v_readlane_b32 s58, v254, 36
	v_readlane_b32 s59, v254, 37
	v_readlane_b32 s50, v254, 28
	v_readlane_b32 s51, v254, 29
	v_readlane_b32 s60, v254, 38
	v_readlane_b32 s61, v254, 39
	v_readlane_b32 s58, v255, 26
	v_readlane_b32 s56, v255, 32
	v_readlane_b32 s52, v255, 34
	v_readlane_b32 s54, v254, 46
	v_readlane_b32 s62, v254, 40
	v_readlane_b32 s63, v254, 41
	s_mov_b64 s[60:61], s[44:45]
	v_readlane_b32 s59, v255, 27
	v_readlane_b32 s57, v255, 33
	v_readlane_b32 s53, v255, 35
	s_mov_b64 s[50:51], s[24:25]
	v_readlane_b32 s55, v254, 47
	s_waitcnt vmcnt(0) lgkmcnt(0)
	v_lshlrev_b32_e32 v152, 16, v130
	v_and_b32_e32 v130, 0xffff0000, v130
	v_mul_f32_e32 v150, 0xbfb8aa3b, v152
	v_mul_f32_e32 v151, 0xbfb8aa3b, v130
	v_exp_f32_e32 v150, v150
	v_exp_f32_e32 v151, v151
	v_pk_mul_f32 v[134:135], v[122:123], v[134:135]
	v_pk_add_f32 v[150:151], v[150:151], 1.0 op_sel_hi:[1,0]
	v_pk_mul_f32 v[146:147], v[126:127], v[146:147]
	v_div_scale_f32 v153, s[16:17], v151, v151, v130
	v_rcp_f32_e32 v154, v153
	v_pk_mul_f32 v[148:149], v[128:129], v[148:149]
	v_pk_mul_f32 v[136:137], v[124:125], v[136:137]
	v_fma_f32 v155, -v153, v154, 1.0
	v_fmac_f32_e32 v154, v155, v154
	v_div_scale_f32 v155, vcc, v130, v151, v130
	v_mul_f32_e32 v156, v155, v154
	v_fma_f32 v157, -v153, v156, v155
	v_fmac_f32_e32 v156, v157, v154
	v_fma_f32 v153, -v153, v156, v155
	v_div_fmas_f32 v153, v153, v154, v156
	v_div_fixup_f32 v151, v153, v151, v130
	v_div_scale_f32 v130, s[16:17], v150, v150, v152
	v_rcp_f32_e32 v153, v130
	s_nop 0
	v_fma_f32 v154, -v130, v153, 1.0
	v_fmac_f32_e32 v153, v154, v153
	v_div_scale_f32 v154, vcc, v152, v150, v152
	v_mul_f32_e32 v155, v154, v153
	v_fma_f32 v156, -v130, v155, v154
	v_fmac_f32_e32 v155, v156, v153
	v_fma_f32 v130, -v130, v155, v154
	v_div_fmas_f32 v130, v130, v153, v155
	v_div_fixup_f32 v150, v130, v150, v152
	v_pk_mul_f32 v[146:147], v[146:147], v[150:151]
	v_lshlrev_b32_e32 v150, 16, v131
	v_and_b32_e32 v131, 0xffff0000, v131
	v_cvt_pk_bf16_f32 v130, v146, v147
	v_mul_f32_e32 v146, 0xbfb8aa3b, v150
	v_mul_f32_e32 v147, 0xbfb8aa3b, v131
	v_exp_f32_e32 v146, v146
	v_exp_f32_e32 v147, v147
	s_nop 0
	v_pk_add_f32 v[146:147], v[146:147], 1.0 op_sel_hi:[1,0]
	s_nop 0
	v_div_scale_f32 v151, s[16:17], v147, v147, v131
	v_rcp_f32_e32 v152, v151
	s_nop 0
	v_fma_f32 v153, -v151, v152, 1.0
	v_fmac_f32_e32 v152, v153, v152
	v_div_scale_f32 v153, vcc, v131, v147, v131
	v_mul_f32_e32 v154, v153, v152
	v_fma_f32 v155, -v151, v154, v153
	v_fmac_f32_e32 v154, v155, v152
	v_fma_f32 v151, -v151, v154, v153
	v_div_fmas_f32 v151, v151, v152, v154
	v_div_fixup_f32 v147, v151, v147, v131
	v_div_scale_f32 v131, s[16:17], v146, v146, v150
	v_rcp_f32_e32 v151, v131
	s_nop 0
	v_fma_f32 v152, -v131, v151, 1.0
	v_fmac_f32_e32 v151, v152, v151
	v_div_scale_f32 v152, vcc, v150, v146, v150
	v_mul_f32_e32 v153, v152, v151
	v_fma_f32 v154, -v131, v153, v152
	v_fmac_f32_e32 v153, v154, v151
	v_fma_f32 v131, -v131, v153, v152
	v_div_fmas_f32 v131, v131, v151, v153
	v_div_fixup_f32 v146, v131, v146, v150
	v_pk_mul_f32 v[146:147], v[148:149], v[146:147]
	v_lshlrev_b32_e32 v148, 16, v132
	v_and_b32_e32 v132, 0xffff0000, v132
	v_cvt_pk_bf16_f32 v131, v146, v147
	v_mul_f32_e32 v146, 0xbfb8aa3b, v148
	v_mul_f32_e32 v147, 0xbfb8aa3b, v132
	v_exp_f32_e32 v146, v146
	v_exp_f32_e32 v147, v147
	s_nop 0
	v_pk_add_f32 v[146:147], v[146:147], 1.0 op_sel_hi:[1,0]
	s_nop 0
	v_div_scale_f32 v149, s[16:17], v147, v147, v132
	v_rcp_f32_e32 v150, v149
	s_nop 0
	v_fma_f32 v151, -v149, v150, 1.0
	v_fmac_f32_e32 v150, v151, v150
	v_div_scale_f32 v151, vcc, v132, v147, v132
	v_mul_f32_e32 v152, v151, v150
	v_fma_f32 v153, -v149, v152, v151
	v_fmac_f32_e32 v152, v153, v150
	v_fma_f32 v149, -v149, v152, v151
	v_div_fmas_f32 v149, v149, v150, v152
	v_div_fixup_f32 v147, v149, v147, v132
	v_div_scale_f32 v132, s[16:17], v146, v146, v148
	v_rcp_f32_e32 v149, v132
	s_nop 0
	v_fma_f32 v150, -v132, v149, 1.0
	v_fmac_f32_e32 v149, v150, v149
	v_div_scale_f32 v150, vcc, v148, v146, v148
	v_mul_f32_e32 v151, v150, v149
	v_fma_f32 v152, -v132, v151, v150
	v_fmac_f32_e32 v151, v152, v149
	v_fma_f32 v132, -v132, v151, v150
	v_div_fmas_f32 v132, v132, v149, v151
	v_div_fixup_f32 v146, v132, v146, v148
	v_pk_mul_f32 v[134:135], v[134:135], v[146:147]
	v_lshlrev_b32_e32 v146, 16, v133
	v_and_b32_e32 v133, 0xffff0000, v133
	v_cvt_pk_bf16_f32 v132, v134, v135
	v_mul_f32_e32 v134, 0xbfb8aa3b, v146
	v_mul_f32_e32 v135, 0xbfb8aa3b, v133
	v_exp_f32_e32 v134, v134
	v_exp_f32_e32 v135, v135
	s_nop 0
	v_pk_add_f32 v[134:135], v[134:135], 1.0 op_sel_hi:[1,0]
	s_nop 0
	v_div_scale_f32 v147, s[16:17], v135, v135, v133
	v_rcp_f32_e32 v148, v147
	s_nop 0
	v_fma_f32 v149, -v147, v148, 1.0
	v_fmac_f32_e32 v148, v149, v148
	v_div_scale_f32 v149, vcc, v133, v135, v133
	v_mul_f32_e32 v150, v149, v148
	v_fma_f32 v151, -v147, v150, v149
	v_fmac_f32_e32 v150, v151, v148
	v_fma_f32 v147, -v147, v150, v149
	v_div_fmas_f32 v147, v147, v148, v150
	v_div_fixup_f32 v135, v147, v135, v133
	v_div_scale_f32 v133, s[16:17], v134, v134, v146
	v_rcp_f32_e32 v147, v133
	s_nop 0
	v_fma_f32 v148, -v133, v147, 1.0
	v_fmac_f32_e32 v147, v148, v147
	v_div_scale_f32 v148, vcc, v146, v134, v146
	v_mul_f32_e32 v149, v148, v147
	v_fma_f32 v150, -v133, v149, v148
	v_fmac_f32_e32 v149, v150, v147
	v_fma_f32 v133, -v133, v149, v148
	v_div_fmas_f32 v133, v133, v147, v149
	v_div_fixup_f32 v134, v133, v134, v146
	v_pk_mul_f32 v[134:135], v[136:137], v[134:135]
	s_nop 0
	v_cvt_pk_bf16_f32 v133, v134, v135
	v_mad_i64_i32 v[134:135], s[16:17], s48, v0, 0
	v_lshl_add_u64 v[134:135], v[134:135], 1, s[20:21]
	v_lshl_add_u64 v[146:147], v[134:135], 0, v[138:139]
	global_store_dwordx4 v[146:147], v[130:133], off
	global_load_dwordx4 v[130:133], v[144:145], off offset:256
	s_nop 0
	global_load_dwordx4 v[134:137], v[140:141], off offset:528
	global_load_dwordx4 v[148:151], v[140:141], off offset:512
	s_waitcnt vmcnt(0) lgkmcnt(0)
; DI unsigned pk2(float lo, float hi) { f32x2_t f = {lo, hi}; bf16x2_t v = __builtin_convertvector(f, bf16x2_t); return __builtin_bit_cast(unsigned, v); }
; DI float silu(float v) { return v / (1.f + __expf(-v)); }
;     DI void operator()(const f32x4 (&acc)[2][2][4][2], const Unit& u, int wr, int wc, int fr, int fq) const {
;     ...
;                         const u32x4 gv = *(const u32x4*)(gate + (size_t)row * LDU_E + col);
;                         const f32x4 s0 = *(const f32x4*)(pscale + col), s1 = *(const f32x4*)(pscale + col + 4);
;                         const f32x4 v0 = acc[ai][bj][m][0], v1 = acc[ai][bj][m][1];
;                         u32x4 w;
;                         w.x = pk2(v0[0] * s0[0] * silu(bflo(gv.x)), v0[1] * s0[1] * silu(bfhi(gv.x)));
;                         w.y = pk2(v0[2] * s0[2] * silu(bflo(gv.y)), v0[3] * s0[3] * silu(bfhi(gv.y)));
;                         w.z = pk2(v1[0] * s1[0] * silu(bflo(gv.z)), v1[1] * s1[1] * silu(bfhi(gv.z)));
;                         w.w = pk2(v1[2] * s1[2] * silu(bflo(gv.w)), v1[3] * s1[3] * silu(bfhi(gv.w)));
;                         *(u32x4*)(O + (size_t)row * ldc + col) = w; } }
	v_lshlrev_b32_e32 v154, 16, v130
	v_and_b32_e32 v130, 0xffff0000, v130
	v_mul_f32_e32 v144, 0xbfb8aa3b, v154
	v_exp_f32_e32 v152, v144
	v_pk_mul_f32 v[144:145], v[120:121], v[150:151]
	v_mul_f32_e32 v150, 0xbfb8aa3b, v130
	v_exp_f32_e32 v153, v150
	v_pk_mul_f32 v[148:149], v[118:119], v[148:149]
	v_pk_mul_f32 v[134:135], v[114:115], v[134:135]
	v_pk_mul_f32 v[136:137], v[116:117], v[136:137]
	v_pk_add_f32 v[150:151], v[152:153], 1.0 op_sel_hi:[1,0]
	s_nop 0
	v_div_scale_f32 v152, s[16:17], v151, v151, v130
	v_rcp_f32_e32 v153, v152
	s_nop 0
	v_fma_f32 v155, -v152, v153, 1.0
	v_fmac_f32_e32 v153, v155, v153
	v_div_scale_f32 v155, vcc, v130, v151, v130
	v_mul_f32_e32 v156, v155, v153
	v_fma_f32 v157, -v152, v156, v155
	v_fmac_f32_e32 v156, v157, v153
	v_fma_f32 v152, -v152, v156, v155
	v_div_fmas_f32 v152, v152, v153, v156
	v_div_fixup_f32 v151, v152, v151, v130
	v_div_scale_f32 v130, s[16:17], v150, v150, v154
	v_rcp_f32_e32 v152, v130
	s_nop 0
	v_fma_f32 v153, -v130, v152, 1.0
	v_fmac_f32_e32 v152, v153, v152
	v_div_scale_f32 v153, vcc, v154, v150, v154
	v_mul_f32_e32 v155, v153, v152
	v_fma_f32 v156, -v130, v155, v153
	v_fmac_f32_e32 v155, v156, v152
	v_fma_f32 v130, -v130, v155, v153
	v_div_fmas_f32 v130, v130, v152, v155
	v_div_fixup_f32 v150, v130, v150, v154
	v_pk_mul_f32 v[148:149], v[148:149], v[150:151]
	v_lshlrev_b32_e32 v150, 16, v131
	v_and_b32_e32 v131, 0xffff0000, v131
	v_cvt_pk_bf16_f32 v130, v148, v149
	v_mul_f32_e32 v148, 0xbfb8aa3b, v150
	v_mul_f32_e32 v149, 0xbfb8aa3b, v131
	v_exp_f32_e32 v148, v148
	v_exp_f32_e32 v149, v149
	s_nop 0
	v_pk_add_f32 v[148:149], v[148:149], 1.0 op_sel_hi:[1,0]
	s_nop 0
	v_div_scale_f32 v151, s[16:17], v149, v149, v131
	v_rcp_f32_e32 v152, v151
	s_nop 0
	v_fma_f32 v153, -v151, v152, 1.0
	v_fmac_f32_e32 v152, v153, v152
	v_div_scale_f32 v153, vcc, v131, v149, v131
	v_mul_f32_e32 v154, v153, v152
	v_fma_f32 v155, -v151, v154, v153
	v_fmac_f32_e32 v154, v155, v152
	v_fma_f32 v151, -v151, v154, v153
	v_div_fmas_f32 v151, v151, v152, v154
	v_div_fixup_f32 v149, v151, v149, v131
	v_div_scale_f32 v131, s[16:17], v148, v148, v150
	v_rcp_f32_e32 v151, v131
	s_nop 0
	v_fma_f32 v152, -v131, v151, 1.0
	v_fmac_f32_e32 v151, v152, v151
	v_div_scale_f32 v152, vcc, v150, v148, v150
	v_mul_f32_e32 v153, v152, v151
	v_fma_f32 v154, -v131, v153, v152
	v_fmac_f32_e32 v153, v154, v151
	v_fma_f32 v131, -v131, v153, v152
	v_div_fmas_f32 v131, v131, v151, v153
	v_div_fixup_f32 v148, v131, v148, v150
	v_pk_mul_f32 v[144:145], v[144:145], v[148:149]
	v_lshlrev_b32_e32 v148, 16, v132
	v_and_b32_e32 v132, 0xffff0000, v132
	v_cvt_pk_bf16_f32 v131, v144, v145
	v_mul_f32_e32 v144, 0xbfb8aa3b, v148
	v_mul_f32_e32 v145, 0xbfb8aa3b, v132
	v_exp_f32_e32 v144, v144
	v_exp_f32_e32 v145, v145
	s_nop 0
	v_pk_add_f32 v[144:145], v[144:145], 1.0 op_sel_hi:[1,0]
	s_nop 0
	v_div_scale_f32 v149, s[16:17], v145, v145, v132
	v_rcp_f32_e32 v150, v149
	s_nop 0
	v_fma_f32 v151, -v149, v150, 1.0
	v_fmac_f32_e32 v150, v151, v150
	v_div_scale_f32 v151, vcc, v132, v145, v132
	v_mul_f32_e32 v152, v151, v150
	v_fma_f32 v153, -v149, v152, v151
	v_fmac_f32_e32 v152, v153, v150
	v_fma_f32 v149, -v149, v152, v151
	v_div_fmas_f32 v149, v149, v150, v152
	v_div_fixup_f32 v145, v149, v145, v132
	v_div_scale_f32 v132, s[16:17], v144, v144, v148
	v_rcp_f32_e32 v149, v132
	s_nop 0
	v_fma_f32 v150, -v132, v149, 1.0
	v_fmac_f32_e32 v149, v150, v149
	v_div_scale_f32 v150, vcc, v148, v144, v148
	v_mul_f32_e32 v151, v150, v149
	v_fma_f32 v152, -v132, v151, v150
	v_fmac_f32_e32 v151, v152, v149
	v_fma_f32 v132, -v132, v151, v150
	v_div_fmas_f32 v132, v132, v149, v151
	v_div_fixup_f32 v144, v132, v144, v148
	v_pk_mul_f32 v[134:135], v[134:135], v[144:145]
	v_lshlrev_b32_e32 v144, 16, v133
	v_and_b32_e32 v133, 0xffff0000, v133
	v_cvt_pk_bf16_f32 v132, v134, v135
	v_mul_f32_e32 v134, 0xbfb8aa3b, v144
	v_mul_f32_e32 v135, 0xbfb8aa3b, v133
	v_exp_f32_e32 v134, v134
	v_exp_f32_e32 v135, v135
	v_or_b32_e32 v152, 16, v0
	v_pk_add_f32 v[134:135], v[134:135], 1.0 op_sel_hi:[1,0]
	s_nop 0
	v_div_scale_f32 v145, s[16:17], v135, v135, v133
	v_rcp_f32_e32 v148, v145
	s_nop 0
	v_fma_f32 v149, -v145, v148, 1.0
	v_fmac_f32_e32 v148, v149, v148
	v_div_scale_f32 v149, vcc, v133, v135, v133
	v_mul_f32_e32 v150, v149, v148
	v_fma_f32 v151, -v145, v150, v149
	v_fmac_f32_e32 v150, v151, v148
	v_fma_f32 v145, -v145, v150, v149
	v_div_fmas_f32 v145, v145, v148, v150
	v_div_fixup_f32 v135, v145, v135, v133
	v_div_scale_f32 v133, s[16:17], v134, v134, v144
	v_rcp_f32_e32 v145, v133
	s_nop 0
	v_fma_f32 v148, -v133, v145, 1.0
	v_fmac_f32_e32 v145, v148, v145
	v_div_scale_f32 v148, vcc, v144, v134, v144
	v_mul_f32_e32 v149, v148, v145
	v_fma_f32 v150, -v133, v149, v148
	v_fmac_f32_e32 v149, v150, v145
	v_fma_f32 v133, -v133, v149, v148
	v_div_fmas_f32 v133, v133, v145, v149
	v_div_fixup_f32 v134, v133, v134, v144
	v_pk_mul_f32 v[134:135], v[136:137], v[134:135]
	s_nop 0
	v_cvt_pk_bf16_f32 v133, v134, v135
	global_store_dwordx4 v[146:147], v[130:133], off offset:256
	s_nop 1
	v_mad_i64_i32 v[130:131], s[16:17], v152, s86, v[142:143]
	v_lshl_add_u64 v[134:135], v[130:131], 0, v[138:139]
	global_load_dwordx4 v[130:133], v[134:135], off
	global_load_dwordx4 v[144:147], v[140:141], off offset:16
	global_load_dwordx4 v[148:151], v[140:141], off
	s_waitcnt vmcnt(0) lgkmcnt(0)
; DI unsigned pk2(float lo, float hi) { f32x2_t f = {lo, hi}; bf16x2_t v = __builtin_convertvector(f, bf16x2_t); return __builtin_bit_cast(unsigned, v); }
; DI float silu(float v) { return v / (1.f + __expf(-v)); }
;     DI void operator()(const f32x4 (&acc)[2][2][4][2], const Unit& u, int wr, int wc, int fr, int fq) const {
;     ...
;                         const u32x4 gv = *(const u32x4*)(gate + (size_t)row * LDU_E + col);
;                         const f32x4 s0 = *(const f32x4*)(pscale + col), s1 = *(const f32x4*)(pscale + col + 4);
;                         const f32x4 v0 = acc[ai][bj][m][0], v1 = acc[ai][bj][m][1];
;                         u32x4 w;
;                         w.x = pk2(v0[0] * s0[0] * silu(bflo(gv.x)), v0[1] * s0[1] * silu(bfhi(gv.x)));
;                         w.y = pk2(v0[2] * s0[2] * silu(bflo(gv.y)), v0[3] * s0[3] * silu(bfhi(gv.y)));
;                         w.z = pk2(v1[0] * s1[0] * silu(bflo(gv.z)), v1[1] * s1[1] * silu(bfhi(gv.z)));
;                         w.w = pk2(v1[2] * s1[2] * silu(bflo(gv.w)), v1[3] * s1[3] * silu(bfhi(gv.w)));
;                         *(u32x4*)(O + (size_t)row * ldc + col) = w; } }
	v_lshlrev_b32_e32 v153, 16, v130
	v_and_b32_e32 v130, 0xffff0000, v130
	v_mul_f32_e32 v136, 0xbfb8aa3b, v153
	v_mul_f32_e32 v137, 0xbfb8aa3b, v130
	v_exp_f32_e32 v136, v136
	v_exp_f32_e32 v137, v137
	v_pk_mul_f32 v[148:149], v[110:111], v[148:149]
	v_pk_mul_f32 v[150:151], v[112:113], v[150:151]
	v_pk_mul_f32 v[144:145], v[106:107], v[144:145]
	v_pk_add_f32 v[136:137], v[136:137], 1.0 op_sel_hi:[1,0]
	v_pk_mul_f32 v[146:147], v[108:109], v[146:147]
	v_div_scale_f32 v154, s[16:17], v137, v137, v130
	v_rcp_f32_e32 v155, v154
	s_nop 0
	v_fma_f32 v156, -v154, v155, 1.0
	v_fmac_f32_e32 v155, v156, v155
	v_div_scale_f32 v156, vcc, v130, v137, v130
	v_mul_f32_e32 v157, v156, v155
	v_fma_f32 v158, -v154, v157, v156
	v_fmac_f32_e32 v157, v158, v155
	v_fma_f32 v154, -v154, v157, v156
	v_div_fmas_f32 v154, v154, v155, v157
	v_div_fixup_f32 v137, v154, v137, v130
	v_div_scale_f32 v130, s[16:17], v136, v136, v153
	v_rcp_f32_e32 v154, v130
	s_nop 0
	v_fma_f32 v155, -v130, v154, 1.0
	v_fmac_f32_e32 v154, v155, v154
	v_div_scale_f32 v155, vcc, v153, v136, v153
	v_mul_f32_e32 v156, v155, v154
	v_fma_f32 v157, -v130, v156, v155
	v_fmac_f32_e32 v156, v157, v154
	v_fma_f32 v130, -v130, v156, v155
	v_div_fmas_f32 v130, v130, v154, v156
	v_div_fixup_f32 v136, v130, v136, v153
	v_pk_mul_f32 v[136:137], v[148:149], v[136:137]
	v_lshlrev_b32_e32 v148, 16, v131
	v_and_b32_e32 v131, 0xffff0000, v131
	v_cvt_pk_bf16_f32 v130, v136, v137
	v_mul_f32_e32 v136, 0xbfb8aa3b, v148
	v_mul_f32_e32 v137, 0xbfb8aa3b, v131
	v_exp_f32_e32 v136, v136
	v_exp_f32_e32 v137, v137
	s_nop 0
	v_pk_add_f32 v[136:137], v[136:137], 1.0 op_sel_hi:[1,0]
	s_nop 0
	v_div_scale_f32 v149, s[16:17], v137, v137, v131
	v_rcp_f32_e32 v153, v149
	s_nop 0
	v_fma_f32 v154, -v149, v153, 1.0
	v_fmac_f32_e32 v153, v154, v153
	v_div_scale_f32 v154, vcc, v131, v137, v131
	v_mul_f32_e32 v155, v154, v153
	v_fma_f32 v156, -v149, v155, v154
	v_fmac_f32_e32 v155, v156, v153
	v_fma_f32 v149, -v149, v155, v154
	v_div_fmas_f32 v149, v149, v153, v155
	v_div_fixup_f32 v137, v149, v137, v131
	v_div_scale_f32 v131, s[16:17], v136, v136, v148
	v_rcp_f32_e32 v149, v131
	s_nop 0
	v_fma_f32 v153, -v131, v149, 1.0
	v_fmac_f32_e32 v149, v153, v149
	v_div_scale_f32 v153, vcc, v148, v136, v148
	v_mul_f32_e32 v154, v153, v149
	v_fma_f32 v155, -v131, v154, v153
	v_fmac_f32_e32 v154, v155, v149
	v_fma_f32 v131, -v131, v154, v153
	v_div_fmas_f32 v131, v131, v149, v154
	v_div_fixup_f32 v136, v131, v136, v148
	v_pk_mul_f32 v[136:137], v[150:151], v[136:137]
	v_lshlrev_b32_e32 v148, 16, v132
	v_and_b32_e32 v132, 0xffff0000, v132
	v_cvt_pk_bf16_f32 v131, v136, v137
	v_mul_f32_e32 v136, 0xbfb8aa3b, v148
	v_mul_f32_e32 v137, 0xbfb8aa3b, v132
	v_exp_f32_e32 v136, v136
	v_exp_f32_e32 v137, v137
	s_nop 0
	v_pk_add_f32 v[136:137], v[136:137], 1.0 op_sel_hi:[1,0]
	s_nop 0
	v_div_scale_f32 v149, s[16:17], v137, v137, v132
	v_rcp_f32_e32 v150, v149
	s_nop 0
	v_fma_f32 v151, -v149, v150, 1.0
	v_fmac_f32_e32 v150, v151, v150
	v_div_scale_f32 v151, vcc, v132, v137, v132
	v_mul_f32_e32 v153, v151, v150
	v_fma_f32 v154, -v149, v153, v151
	v_fmac_f32_e32 v153, v154, v150
	v_fma_f32 v149, -v149, v153, v151
	v_div_fmas_f32 v149, v149, v150, v153
	v_div_fixup_f32 v137, v149, v137, v132
	v_div_scale_f32 v132, s[16:17], v136, v136, v148
	v_rcp_f32_e32 v149, v132
	s_nop 0
	v_fma_f32 v150, -v132, v149, 1.0
	v_fmac_f32_e32 v149, v150, v149
	v_div_scale_f32 v150, vcc, v148, v136, v148
	v_mul_f32_e32 v151, v150, v149
	v_fma_f32 v153, -v132, v151, v150
	v_fmac_f32_e32 v151, v153, v149
	v_fma_f32 v132, -v132, v151, v150
	v_div_fmas_f32 v132, v132, v149, v151
	v_div_fixup_f32 v136, v132, v136, v148
	v_pk_mul_f32 v[136:137], v[144:145], v[136:137]
	v_lshlrev_b32_e32 v144, 16, v133
	v_and_b32_e32 v133, 0xffff0000, v133
	v_cvt_pk_bf16_f32 v132, v136, v137
	v_mul_f32_e32 v136, 0xbfb8aa3b, v144
	v_mul_f32_e32 v137, 0xbfb8aa3b, v133
	v_exp_f32_e32 v136, v136
	v_exp_f32_e32 v137, v137
	s_nop 0
	v_pk_add_f32 v[136:137], v[136:137], 1.0 op_sel_hi:[1,0]
	s_nop 0
	v_div_scale_f32 v145, s[16:17], v137, v137, v133
	v_rcp_f32_e32 v148, v145
	s_nop 0
	v_fma_f32 v149, -v145, v148, 1.0
	v_fmac_f32_e32 v148, v149, v148
	v_div_scale_f32 v149, vcc, v133, v137, v133
	v_mul_f32_e32 v150, v149, v148
	v_fma_f32 v151, -v145, v150, v149
	v_fmac_f32_e32 v150, v151, v148
	v_fma_f32 v145, -v145, v150, v149
	v_div_fmas_f32 v145, v145, v148, v150
	v_div_fixup_f32 v137, v145, v137, v133
	v_div_scale_f32 v133, s[16:17], v136, v136, v144
	v_rcp_f32_e32 v145, v133
	s_nop 0
	v_fma_f32 v148, -v133, v145, 1.0
	v_fmac_f32_e32 v145, v148, v145
	v_div_scale_f32 v148, vcc, v144, v136, v144
	v_mul_f32_e32 v149, v148, v145
	v_fma_f32 v150, -v133, v149, v148
	v_fmac_f32_e32 v149, v150, v145
	v_fma_f32 v133, -v133, v149, v148
	v_div_fmas_f32 v133, v133, v145, v149
	v_div_fixup_f32 v136, v133, v136, v144
	v_pk_mul_f32 v[136:137], v[146:147], v[136:137]
	s_nop 0
	v_cvt_pk_bf16_f32 v133, v136, v137
	v_mad_i64_i32 v[136:137], s[16:17], s48, v152, 0
	v_lshl_add_u64 v[136:137], v[136:137], 1, s[20:21]
	v_lshl_add_u64 v[136:137], v[136:137], 0, v[138:139]
	global_store_dwordx4 v[136:137], v[130:133], off
	global_load_dwordx4 v[130:133], v[134:135], off offset:256
	s_nop 0
	global_load_dwordx4 v[144:147], v[140:141], off offset:528
	global_load_dwordx4 v[148:151], v[140:141], off offset:512
	s_waitcnt vmcnt(0) lgkmcnt(0)
; DI unsigned pk2(float lo, float hi) { f32x2_t f = {lo, hi}; bf16x2_t v = __builtin_convertvector(f, bf16x2_t); return __builtin_bit_cast(unsigned, v); }
; DI float silu(float v) { return v / (1.f + __expf(-v)); }
;     DI void operator()(const f32x4 (&acc)[2][2][4][2], const Unit& u, int wr, int wc, int fr, int fq) const {
;     ...
;                         const u32x4 gv = *(const u32x4*)(gate + (size_t)row * LDU_E + col);
;                         const f32x4 s0 = *(const f32x4*)(pscale + col), s1 = *(const f32x4*)(pscale + col + 4);
;                         const f32x4 v0 = acc[ai][bj][m][0], v1 = acc[ai][bj][m][1];
;                         u32x4 w;
;                         w.x = pk2(v0[0] * s0[0] * silu(bflo(gv.x)), v0[1] * s0[1] * silu(bfhi(gv.x)));
;                         w.y = pk2(v0[2] * s0[2] * silu(bflo(gv.y)), v0[3] * s0[3] * silu(bfhi(gv.y)));
;                         w.z = pk2(v1[0] * s1[0] * silu(bflo(gv.z)), v1[1] * s1[1] * silu(bfhi(gv.z)));
;                         w.w = pk2(v1[2] * s1[2] * silu(bflo(gv.w)), v1[3] * s1[3] * silu(bfhi(gv.w)));
;                         *(u32x4*)(O + (size_t)row * ldc + col) = w; } }
	v_lshlrev_b32_e32 v152, 16, v130
	v_and_b32_e32 v130, 0xffff0000, v130
	v_mul_f32_e32 v134, 0xbfb8aa3b, v152
	v_mul_f32_e32 v135, 0xbfb8aa3b, v130
	v_exp_f32_e32 v134, v134
	v_exp_f32_e32 v135, v135
	v_pk_mul_f32 v[148:149], v[102:103], v[148:149]
	v_pk_mul_f32 v[150:151], v[104:105], v[150:151]
	v_pk_mul_f32 v[144:145], v[98:99], v[144:145]
	v_pk_add_f32 v[134:135], v[134:135], 1.0 op_sel_hi:[1,0]
	v_pk_mul_f32 v[146:147], v[100:101], v[146:147]
	v_div_scale_f32 v153, s[16:17], v135, v135, v130
	v_rcp_f32_e32 v154, v153
	s_nop 0
	v_fma_f32 v155, -v153, v154, 1.0
	v_fmac_f32_e32 v154, v155, v154
	v_div_scale_f32 v155, vcc, v130, v135, v130
	v_mul_f32_e32 v156, v155, v154
	v_fma_f32 v157, -v153, v156, v155
	v_fmac_f32_e32 v156, v157, v154
	v_fma_f32 v153, -v153, v156, v155
	v_div_fmas_f32 v153, v153, v154, v156
	v_div_fixup_f32 v135, v153, v135, v130
	v_div_scale_f32 v130, s[16:17], v134, v134, v152
	v_rcp_f32_e32 v153, v130
	s_nop 0
	v_fma_f32 v154, -v130, v153, 1.0
	v_fmac_f32_e32 v153, v154, v153
	v_div_scale_f32 v154, vcc, v152, v134, v152
	v_mul_f32_e32 v155, v154, v153
	v_fma_f32 v156, -v130, v155, v154
	v_fmac_f32_e32 v155, v156, v153
	v_fma_f32 v130, -v130, v155, v154
	v_div_fmas_f32 v130, v130, v153, v155
	v_div_fixup_f32 v134, v130, v134, v152
	v_pk_mul_f32 v[134:135], v[148:149], v[134:135]
	v_lshlrev_b32_e32 v148, 16, v131
	v_and_b32_e32 v131, 0xffff0000, v131
	v_cvt_pk_bf16_f32 v130, v134, v135
	v_mul_f32_e32 v134, 0xbfb8aa3b, v148
	v_mul_f32_e32 v135, 0xbfb8aa3b, v131
	v_exp_f32_e32 v134, v134
	v_exp_f32_e32 v135, v135
	s_nop 0
	v_pk_add_f32 v[134:135], v[134:135], 1.0 op_sel_hi:[1,0]
	s_nop 0
	v_div_scale_f32 v149, s[16:17], v135, v135, v131
	v_rcp_f32_e32 v152, v149
	s_nop 0
	v_fma_f32 v153, -v149, v152, 1.0
	v_fmac_f32_e32 v152, v153, v152
	v_div_scale_f32 v153, vcc, v131, v135, v131
	v_mul_f32_e32 v154, v153, v152
	v_fma_f32 v155, -v149, v154, v153
	v_fmac_f32_e32 v154, v155, v152
	v_fma_f32 v149, -v149, v154, v153
	v_div_fmas_f32 v149, v149, v152, v154
	v_div_fixup_f32 v135, v149, v135, v131
	v_div_scale_f32 v131, s[16:17], v134, v134, v148
	v_rcp_f32_e32 v149, v131
	s_nop 0
	v_fma_f32 v152, -v131, v149, 1.0
	v_fmac_f32_e32 v149, v152, v149
	v_div_scale_f32 v152, vcc, v148, v134, v148
	v_mul_f32_e32 v153, v152, v149
	v_fma_f32 v154, -v131, v153, v152
	v_fmac_f32_e32 v153, v154, v149
	v_fma_f32 v131, -v131, v153, v152
	v_div_fmas_f32 v131, v131, v149, v153
	v_div_fixup_f32 v134, v131, v134, v148
	v_pk_mul_f32 v[134:135], v[150:151], v[134:135]
	v_lshlrev_b32_e32 v148, 16, v132
	v_and_b32_e32 v132, 0xffff0000, v132
	v_cvt_pk_bf16_f32 v131, v134, v135
	v_mul_f32_e32 v134, 0xbfb8aa3b, v148
	v_mul_f32_e32 v135, 0xbfb8aa3b, v132
	v_exp_f32_e32 v134, v134
	v_exp_f32_e32 v135, v135
	s_nop 0
	v_pk_add_f32 v[134:135], v[134:135], 1.0 op_sel_hi:[1,0]
	s_nop 0
	v_div_scale_f32 v149, s[16:17], v135, v135, v132
	v_rcp_f32_e32 v150, v149
	s_nop 0
	v_fma_f32 v151, -v149, v150, 1.0
	v_fmac_f32_e32 v150, v151, v150
	v_div_scale_f32 v151, vcc, v132, v135, v132
	v_mul_f32_e32 v152, v151, v150
	v_fma_f32 v153, -v149, v152, v151
	v_fmac_f32_e32 v152, v153, v150
	v_fma_f32 v149, -v149, v152, v151
	v_div_fmas_f32 v149, v149, v150, v152
	v_div_fixup_f32 v135, v149, v135, v132
	v_div_scale_f32 v132, s[16:17], v134, v134, v148
	v_rcp_f32_e32 v149, v132
	s_nop 0
	v_fma_f32 v150, -v132, v149, 1.0
	v_fmac_f32_e32 v149, v150, v149
	v_div_scale_f32 v150, vcc, v148, v134, v148
	v_mul_f32_e32 v151, v150, v149
	v_fma_f32 v152, -v132, v151, v150
	v_fmac_f32_e32 v151, v152, v149
	v_fma_f32 v132, -v132, v151, v150
	v_div_fmas_f32 v132, v132, v149, v151
	v_div_fixup_f32 v134, v132, v134, v148
	v_pk_mul_f32 v[134:135], v[144:145], v[134:135]
	v_lshlrev_b32_e32 v144, 16, v133
	v_and_b32_e32 v133, 0xffff0000, v133
	v_cvt_pk_bf16_f32 v132, v134, v135
	v_mul_f32_e32 v134, 0xbfb8aa3b, v144
	v_mul_f32_e32 v135, 0xbfb8aa3b, v133
	v_exp_f32_e32 v134, v134
	v_exp_f32_e32 v135, v135
	v_or_b32_e32 v152, 32, v0
	v_pk_add_f32 v[134:135], v[134:135], 1.0 op_sel_hi:[1,0]
	s_nop 0
	v_div_scale_f32 v145, s[16:17], v135, v135, v133
	v_rcp_f32_e32 v148, v145
	s_nop 0
	v_fma_f32 v149, -v145, v148, 1.0
	v_fmac_f32_e32 v148, v149, v148
	v_div_scale_f32 v149, vcc, v133, v135, v133
	v_mul_f32_e32 v150, v149, v148
	v_fma_f32 v151, -v145, v150, v149
	v_fmac_f32_e32 v150, v151, v148
	v_fma_f32 v145, -v145, v150, v149
	v_div_fmas_f32 v145, v145, v148, v150
	v_div_fixup_f32 v135, v145, v135, v133
	v_div_scale_f32 v133, s[16:17], v134, v134, v144
	v_rcp_f32_e32 v145, v133
	s_nop 0
	v_fma_f32 v148, -v133, v145, 1.0
	v_fmac_f32_e32 v145, v148, v145
	v_div_scale_f32 v148, vcc, v144, v134, v144
	v_mul_f32_e32 v149, v148, v145
	v_fma_f32 v150, -v133, v149, v148
	v_fmac_f32_e32 v149, v150, v145
	v_fma_f32 v133, -v133, v149, v148
	v_div_fmas_f32 v133, v133, v145, v149
	v_div_fixup_f32 v134, v133, v134, v144
	v_pk_mul_f32 v[134:135], v[146:147], v[134:135]
	s_nop 0
	v_cvt_pk_bf16_f32 v133, v134, v135
	global_store_dwordx4 v[136:137], v[130:133], off offset:256
	s_nop 1
	v_mad_i64_i32 v[130:131], s[16:17], v152, s86, v[142:143]
	v_lshl_add_u64 v[134:135], v[130:131], 0, v[138:139]
	global_load_dwordx4 v[130:133], v[134:135], off
	global_load_dwordx4 v[144:147], v[140:141], off offset:16
	global_load_dwordx4 v[148:151], v[140:141], off
	s_waitcnt vmcnt(0) lgkmcnt(0)
; DI unsigned pk2(float lo, float hi) { f32x2_t f = {lo, hi}; bf16x2_t v = __builtin_convertvector(f, bf16x2_t); return __builtin_bit_cast(unsigned, v); }
; DI float silu(float v) { return v / (1.f + __expf(-v)); }
;     DI void operator()(const f32x4 (&acc)[2][2][4][2], const Unit& u, int wr, int wc, int fr, int fq) const {
;     ...
;                         const u32x4 gv = *(const u32x4*)(gate + (size_t)row * LDU_E + col);
;                         const f32x4 s0 = *(const f32x4*)(pscale + col), s1 = *(const f32x4*)(pscale + col + 4);
;                         const f32x4 v0 = acc[ai][bj][m][0], v1 = acc[ai][bj][m][1];
;                         u32x4 w;
;                         w.x = pk2(v0[0] * s0[0] * silu(bflo(gv.x)), v0[1] * s0[1] * silu(bfhi(gv.x)));
;                         w.y = pk2(v0[2] * s0[2] * silu(bflo(gv.y)), v0[3] * s0[3] * silu(bfhi(gv.y)));
;                         w.z = pk2(v1[0] * s1[0] * silu(bflo(gv.z)), v1[1] * s1[1] * silu(bfhi(gv.z)));
;                         w.w = pk2(v1[2] * s1[2] * silu(bflo(gv.w)), v1[3] * s1[3] * silu(bfhi(gv.w)));
;                         *(u32x4*)(O + (size_t)row * ldc + col) = w; } }
	v_lshlrev_b32_e32 v153, 16, v130
	v_and_b32_e32 v130, 0xffff0000, v130
	v_mul_f32_e32 v136, 0xbfb8aa3b, v153
	v_mul_f32_e32 v137, 0xbfb8aa3b, v130
	v_exp_f32_e32 v136, v136
	v_exp_f32_e32 v137, v137
	v_pk_mul_f32 v[148:149], v[94:95], v[148:149]
	v_pk_mul_f32 v[150:151], v[96:97], v[150:151]
	v_pk_mul_f32 v[144:145], v[90:91], v[144:145]
	v_pk_add_f32 v[136:137], v[136:137], 1.0 op_sel_hi:[1,0]
	v_pk_mul_f32 v[146:147], v[92:93], v[146:147]
	v_div_scale_f32 v154, s[16:17], v137, v137, v130
	v_rcp_f32_e32 v155, v154
	s_nop 0
	v_fma_f32 v156, -v154, v155, 1.0
	v_fmac_f32_e32 v155, v156, v155
	v_div_scale_f32 v156, vcc, v130, v137, v130
	v_mul_f32_e32 v157, v156, v155
	v_fma_f32 v158, -v154, v157, v156
	v_fmac_f32_e32 v157, v158, v155
	v_fma_f32 v154, -v154, v157, v156
	v_div_fmas_f32 v154, v154, v155, v157
	v_div_fixup_f32 v137, v154, v137, v130
	v_div_scale_f32 v130, s[16:17], v136, v136, v153
	v_rcp_f32_e32 v154, v130
	s_nop 0
	v_fma_f32 v155, -v130, v154, 1.0
	v_fmac_f32_e32 v154, v155, v154
	v_div_scale_f32 v155, vcc, v153, v136, v153
	v_mul_f32_e32 v156, v155, v154
	v_fma_f32 v157, -v130, v156, v155
	v_fmac_f32_e32 v156, v157, v154
	v_fma_f32 v130, -v130, v156, v155
	v_div_fmas_f32 v130, v130, v154, v156
	v_div_fixup_f32 v136, v130, v136, v153
	v_pk_mul_f32 v[136:137], v[148:149], v[136:137]
	v_lshlrev_b32_e32 v148, 16, v131
	v_and_b32_e32 v131, 0xffff0000, v131
	v_cvt_pk_bf16_f32 v130, v136, v137
	v_mul_f32_e32 v136, 0xbfb8aa3b, v148
	v_mul_f32_e32 v137, 0xbfb8aa3b, v131
	v_exp_f32_e32 v136, v136
	v_exp_f32_e32 v137, v137
	s_nop 0
	v_pk_add_f32 v[136:137], v[136:137], 1.0 op_sel_hi:[1,0]
	s_nop 0
	v_div_scale_f32 v149, s[16:17], v137, v137, v131
	v_rcp_f32_e32 v153, v149
	s_nop 0
	v_fma_f32 v154, -v149, v153, 1.0
	v_fmac_f32_e32 v153, v154, v153
	v_div_scale_f32 v154, vcc, v131, v137, v131
	v_mul_f32_e32 v155, v154, v153
	v_fma_f32 v156, -v149, v155, v154
	v_fmac_f32_e32 v155, v156, v153
	v_fma_f32 v149, -v149, v155, v154
	v_div_fmas_f32 v149, v149, v153, v155
	v_div_fixup_f32 v137, v149, v137, v131
	v_div_scale_f32 v131, s[16:17], v136, v136, v148
	v_rcp_f32_e32 v149, v131
	s_nop 0
	v_fma_f32 v153, -v131, v149, 1.0
	v_fmac_f32_e32 v149, v153, v149
	v_div_scale_f32 v153, vcc, v148, v136, v148
	v_mul_f32_e32 v154, v153, v149
	v_fma_f32 v155, -v131, v154, v153
	v_fmac_f32_e32 v154, v155, v149
	v_fma_f32 v131, -v131, v154, v153
	v_div_fmas_f32 v131, v131, v149, v154
	v_div_fixup_f32 v136, v131, v136, v148
	v_pk_mul_f32 v[136:137], v[150:151], v[136:137]
	v_lshlrev_b32_e32 v148, 16, v132
	v_and_b32_e32 v132, 0xffff0000, v132
	v_cvt_pk_bf16_f32 v131, v136, v137
	v_mul_f32_e32 v136, 0xbfb8aa3b, v148
	v_mul_f32_e32 v137, 0xbfb8aa3b, v132
	v_exp_f32_e32 v136, v136
	v_exp_f32_e32 v137, v137
	s_nop 0
	v_pk_add_f32 v[136:137], v[136:137], 1.0 op_sel_hi:[1,0]
	s_nop 0
	v_div_scale_f32 v149, s[16:17], v137, v137, v132
	v_rcp_f32_e32 v150, v149
	s_nop 0
	v_fma_f32 v151, -v149, v150, 1.0
	v_fmac_f32_e32 v150, v151, v150
	v_div_scale_f32 v151, vcc, v132, v137, v132
	v_mul_f32_e32 v153, v151, v150
	v_fma_f32 v154, -v149, v153, v151
	v_fmac_f32_e32 v153, v154, v150
	v_fma_f32 v149, -v149, v153, v151
	v_div_fmas_f32 v149, v149, v150, v153
	v_div_fixup_f32 v137, v149, v137, v132
	v_div_scale_f32 v132, s[16:17], v136, v136, v148
	v_rcp_f32_e32 v149, v132
	s_nop 0
	v_fma_f32 v150, -v132, v149, 1.0
	v_fmac_f32_e32 v149, v150, v149
	v_div_scale_f32 v150, vcc, v148, v136, v148
	v_mul_f32_e32 v151, v150, v149
	v_fma_f32 v153, -v132, v151, v150
	v_fmac_f32_e32 v151, v153, v149
	v_fma_f32 v132, -v132, v151, v150
	v_div_fmas_f32 v132, v132, v149, v151
	v_div_fixup_f32 v136, v132, v136, v148
	v_pk_mul_f32 v[136:137], v[144:145], v[136:137]
	v_lshlrev_b32_e32 v144, 16, v133
	v_and_b32_e32 v133, 0xffff0000, v133
	v_cvt_pk_bf16_f32 v132, v136, v137
	v_mul_f32_e32 v136, 0xbfb8aa3b, v144
	v_mul_f32_e32 v137, 0xbfb8aa3b, v133
	v_exp_f32_e32 v136, v136
	v_exp_f32_e32 v137, v137
	s_nop 0
	v_pk_add_f32 v[136:137], v[136:137], 1.0 op_sel_hi:[1,0]
	s_nop 0
	v_div_scale_f32 v145, s[16:17], v137, v137, v133
	v_rcp_f32_e32 v148, v145
	s_nop 0
	v_fma_f32 v149, -v145, v148, 1.0
	v_fmac_f32_e32 v148, v149, v148
	v_div_scale_f32 v149, vcc, v133, v137, v133
	v_mul_f32_e32 v150, v149, v148
	v_fma_f32 v151, -v145, v150, v149
	v_fmac_f32_e32 v150, v151, v148
	v_fma_f32 v145, -v145, v150, v149
	v_div_fmas_f32 v145, v145, v148, v150
	v_div_fixup_f32 v137, v145, v137, v133
	v_div_scale_f32 v133, s[16:17], v136, v136, v144
	v_rcp_f32_e32 v145, v133
	s_nop 0
	v_fma_f32 v148, -v133, v145, 1.0
	v_fmac_f32_e32 v145, v148, v145
	v_div_scale_f32 v148, vcc, v144, v136, v144
	v_mul_f32_e32 v149, v148, v145
	v_fma_f32 v150, -v133, v149, v148
	v_fmac_f32_e32 v149, v150, v145
	v_fma_f32 v133, -v133, v149, v148
	v_div_fmas_f32 v133, v133, v145, v149
	v_div_fixup_f32 v136, v133, v136, v144
	v_pk_mul_f32 v[136:137], v[146:147], v[136:137]
	s_nop 0
	v_cvt_pk_bf16_f32 v133, v136, v137
	v_mad_i64_i32 v[136:137], s[16:17], s48, v152, 0
	v_lshl_add_u64 v[136:137], v[136:137], 1, s[20:21]
	v_lshl_add_u64 v[136:137], v[136:137], 0, v[138:139]
	global_store_dwordx4 v[136:137], v[130:133], off
	global_load_dwordx4 v[130:133], v[134:135], off offset:256
	s_nop 0
	global_load_dwordx4 v[144:147], v[140:141], off offset:528
	global_load_dwordx4 v[148:151], v[140:141], off offset:512
	s_waitcnt vmcnt(0) lgkmcnt(0)
; DI unsigned pk2(float lo, float hi) { f32x2_t f = {lo, hi}; bf16x2_t v = __builtin_convertvector(f, bf16x2_t); return __builtin_bit_cast(unsigned, v); }
; DI float silu(float v) { return v / (1.f + __expf(-v)); }
;     DI void operator()(const f32x4 (&acc)[2][2][4][2], const Unit& u, int wr, int wc, int fr, int fq) const {
;     ...
;                         const u32x4 gv = *(const u32x4*)(gate + (size_t)row * LDU_E + col);
;                         const f32x4 s0 = *(const f32x4*)(pscale + col), s1 = *(const f32x4*)(pscale + col + 4);
;                         const f32x4 v0 = acc[ai][bj][m][0], v1 = acc[ai][bj][m][1];
;                         u32x4 w;
;                         w.x = pk2(v0[0] * s0[0] * silu(bflo(gv.x)), v0[1] * s0[1] * silu(bfhi(gv.x)));
;                         w.y = pk2(v0[2] * s0[2] * silu(bflo(gv.y)), v0[3] * s0[3] * silu(bfhi(gv.y)));
;                         w.z = pk2(v1[0] * s1[0] * silu(bflo(gv.z)), v1[1] * s1[1] * silu(bfhi(gv.z)));
;                         w.w = pk2(v1[2] * s1[2] * silu(bflo(gv.w)), v1[3] * s1[3] * silu(bfhi(gv.w)));
;                         *(u32x4*)(O + (size_t)row * ldc + col) = w; } }
	v_lshlrev_b32_e32 v152, 16, v130
	v_and_b32_e32 v130, 0xffff0000, v130
	v_mul_f32_e32 v134, 0xbfb8aa3b, v152
	v_mul_f32_e32 v135, 0xbfb8aa3b, v130
	v_exp_f32_e32 v134, v134
	v_exp_f32_e32 v135, v135
	v_pk_mul_f32 v[148:149], v[86:87], v[148:149]
	v_pk_mul_f32 v[150:151], v[88:89], v[150:151]
	v_pk_mul_f32 v[144:145], v[82:83], v[144:145]
	v_pk_add_f32 v[134:135], v[134:135], 1.0 op_sel_hi:[1,0]
	v_pk_mul_f32 v[146:147], v[84:85], v[146:147]
	v_div_scale_f32 v153, s[16:17], v135, v135, v130
	v_rcp_f32_e32 v154, v153
	s_nop 0
	v_fma_f32 v155, -v153, v154, 1.0
	v_fmac_f32_e32 v154, v155, v154
	v_div_scale_f32 v155, vcc, v130, v135, v130
	v_mul_f32_e32 v156, v155, v154
	v_fma_f32 v157, -v153, v156, v155
	v_fmac_f32_e32 v156, v157, v154
	v_fma_f32 v153, -v153, v156, v155
	v_div_fmas_f32 v153, v153, v154, v156
	v_div_fixup_f32 v135, v153, v135, v130
	v_div_scale_f32 v130, s[16:17], v134, v134, v152
	v_rcp_f32_e32 v153, v130
	s_nop 0
	v_fma_f32 v154, -v130, v153, 1.0
	v_fmac_f32_e32 v153, v154, v153
	v_div_scale_f32 v154, vcc, v152, v134, v152
	v_mul_f32_e32 v155, v154, v153
	v_fma_f32 v156, -v130, v155, v154
	v_fmac_f32_e32 v155, v156, v153
	v_fma_f32 v130, -v130, v155, v154
	v_div_fmas_f32 v130, v130, v153, v155
	v_div_fixup_f32 v134, v130, v134, v152
	v_pk_mul_f32 v[134:135], v[148:149], v[134:135]
	v_lshlrev_b32_e32 v148, 16, v131
	v_and_b32_e32 v131, 0xffff0000, v131
	v_cvt_pk_bf16_f32 v130, v134, v135
	v_mul_f32_e32 v134, 0xbfb8aa3b, v148
	v_mul_f32_e32 v135, 0xbfb8aa3b, v131
	v_exp_f32_e32 v134, v134
	v_exp_f32_e32 v135, v135
	s_nop 0
	v_pk_add_f32 v[134:135], v[134:135], 1.0 op_sel_hi:[1,0]
	s_nop 0
	v_div_scale_f32 v149, s[16:17], v135, v135, v131
	v_rcp_f32_e32 v152, v149
	s_nop 0
	v_fma_f32 v153, -v149, v152, 1.0
	v_fmac_f32_e32 v152, v153, v152
	v_div_scale_f32 v153, vcc, v131, v135, v131
	v_mul_f32_e32 v154, v153, v152
	v_fma_f32 v155, -v149, v154, v153
	v_fmac_f32_e32 v154, v155, v152
	v_fma_f32 v149, -v149, v154, v153
	v_div_fmas_f32 v149, v149, v152, v154
	v_div_fixup_f32 v135, v149, v135, v131
	v_div_scale_f32 v131, s[16:17], v134, v134, v148
	v_rcp_f32_e32 v149, v131
	s_nop 0
	v_fma_f32 v152, -v131, v149, 1.0
	v_fmac_f32_e32 v149, v152, v149
	v_div_scale_f32 v152, vcc, v148, v134, v148
	v_mul_f32_e32 v153, v152, v149
	v_fma_f32 v154, -v131, v153, v152
	v_fmac_f32_e32 v153, v154, v149
	v_fma_f32 v131, -v131, v153, v152
	v_div_fmas_f32 v131, v131, v149, v153
	v_div_fixup_f32 v134, v131, v134, v148
	v_pk_mul_f32 v[134:135], v[150:151], v[134:135]
	v_lshlrev_b32_e32 v148, 16, v132
	v_and_b32_e32 v132, 0xffff0000, v132
	v_cvt_pk_bf16_f32 v131, v134, v135
	v_mul_f32_e32 v134, 0xbfb8aa3b, v148
	v_mul_f32_e32 v135, 0xbfb8aa3b, v132
	v_exp_f32_e32 v134, v134
	v_exp_f32_e32 v135, v135
	s_nop 0
	v_pk_add_f32 v[134:135], v[134:135], 1.0 op_sel_hi:[1,0]
	s_nop 0
	v_div_scale_f32 v149, s[16:17], v135, v135, v132
	v_rcp_f32_e32 v150, v149
	s_nop 0
	v_fma_f32 v151, -v149, v150, 1.0
	v_fmac_f32_e32 v150, v151, v150
	v_div_scale_f32 v151, vcc, v132, v135, v132
	v_mul_f32_e32 v152, v151, v150
	v_fma_f32 v153, -v149, v152, v151
	v_fmac_f32_e32 v152, v153, v150
	v_fma_f32 v149, -v149, v152, v151
	v_div_fmas_f32 v149, v149, v150, v152
	v_div_fixup_f32 v135, v149, v135, v132
	v_div_scale_f32 v132, s[16:17], v134, v134, v148
	v_rcp_f32_e32 v149, v132
	s_nop 0
	v_fma_f32 v150, -v132, v149, 1.0
	v_fmac_f32_e32 v149, v150, v149
	v_div_scale_f32 v150, vcc, v148, v134, v148
	v_mul_f32_e32 v151, v150, v149
	v_fma_f32 v152, -v132, v151, v150
	v_fmac_f32_e32 v151, v152, v149
	v_fma_f32 v132, -v132, v151, v150
	v_div_fmas_f32 v132, v132, v149, v151
	v_div_fixup_f32 v134, v132, v134, v148
	v_pk_mul_f32 v[134:135], v[144:145], v[134:135]
	v_lshlrev_b32_e32 v144, 16, v133
	v_and_b32_e32 v133, 0xffff0000, v133
	v_cvt_pk_bf16_f32 v132, v134, v135
	v_mul_f32_e32 v134, 0xbfb8aa3b, v144
	v_mul_f32_e32 v135, 0xbfb8aa3b, v133
	v_exp_f32_e32 v134, v134
	v_exp_f32_e32 v135, v135
	v_or_b32_e32 v152, 48, v0
	v_pk_add_f32 v[134:135], v[134:135], 1.0 op_sel_hi:[1,0]
	s_nop 0
	v_div_scale_f32 v145, s[16:17], v135, v135, v133
	v_rcp_f32_e32 v148, v145
	s_nop 0
	v_fma_f32 v149, -v145, v148, 1.0
	v_fmac_f32_e32 v148, v149, v148
	v_div_scale_f32 v149, vcc, v133, v135, v133
	v_mul_f32_e32 v150, v149, v148
	v_fma_f32 v151, -v145, v150, v149
	v_fmac_f32_e32 v150, v151, v148
	v_fma_f32 v145, -v145, v150, v149
	v_div_fmas_f32 v145, v145, v148, v150
	v_div_fixup_f32 v135, v145, v135, v133
	v_div_scale_f32 v133, s[16:17], v134, v134, v144
	v_rcp_f32_e32 v145, v133
	s_nop 0
	v_fma_f32 v148, -v133, v145, 1.0
	v_fmac_f32_e32 v145, v148, v145
	v_div_scale_f32 v148, vcc, v144, v134, v144
	v_mul_f32_e32 v149, v148, v145
	v_fma_f32 v150, -v133, v149, v148
	v_fmac_f32_e32 v149, v150, v145
	v_fma_f32 v133, -v133, v149, v148
	v_div_fmas_f32 v133, v133, v145, v149
	v_div_fixup_f32 v134, v133, v134, v144
	v_pk_mul_f32 v[134:135], v[146:147], v[134:135]
	s_nop 0
	v_cvt_pk_bf16_f32 v133, v134, v135
	global_store_dwordx4 v[136:137], v[130:133], off offset:256
	s_nop 1
	v_mad_i64_i32 v[130:131], s[16:17], v152, s86, v[142:143]
	v_lshl_add_u64 v[134:135], v[130:131], 0, v[138:139]
	global_load_dwordx4 v[130:133], v[134:135], off
	global_load_dwordx4 v[144:147], v[140:141], off offset:16
	global_load_dwordx4 v[148:151], v[140:141], off
	s_waitcnt vmcnt(0) lgkmcnt(0)
; DI unsigned pk2(float lo, float hi) { f32x2_t f = {lo, hi}; bf16x2_t v = __builtin_convertvector(f, bf16x2_t); return __builtin_bit_cast(unsigned, v); }
; DI float silu(float v) { return v / (1.f + __expf(-v)); }
;     DI void operator()(const f32x4 (&acc)[2][2][4][2], const Unit& u, int wr, int wc, int fr, int fq) const {
;     ...
;                         const u32x4 gv = *(const u32x4*)(gate + (size_t)row * LDU_E + col);
;                         const f32x4 s0 = *(const f32x4*)(pscale + col), s1 = *(const f32x4*)(pscale + col + 4);
;                         const f32x4 v0 = acc[ai][bj][m][0], v1 = acc[ai][bj][m][1];
;                         u32x4 w;
;                         w.x = pk2(v0[0] * s0[0] * silu(bflo(gv.x)), v0[1] * s0[1] * silu(bfhi(gv.x)));
;                         w.y = pk2(v0[2] * s0[2] * silu(bflo(gv.y)), v0[3] * s0[3] * silu(bfhi(gv.y)));
;                         w.z = pk2(v1[0] * s1[0] * silu(bflo(gv.z)), v1[1] * s1[1] * silu(bfhi(gv.z)));
;                         w.w = pk2(v1[2] * s1[2] * silu(bflo(gv.w)), v1[3] * s1[3] * silu(bfhi(gv.w)));
;                         *(u32x4*)(O + (size_t)row * ldc + col) = w; } }
	v_lshlrev_b32_e32 v153, 16, v130
	v_and_b32_e32 v130, 0xffff0000, v130
	v_mul_f32_e32 v136, 0xbfb8aa3b, v153
	v_mul_f32_e32 v137, 0xbfb8aa3b, v130
	v_exp_f32_e32 v136, v136
	v_exp_f32_e32 v137, v137
	v_pk_mul_f32 v[148:149], v[78:79], v[148:149]
	v_pk_mul_f32 v[150:151], v[80:81], v[150:151]
	v_pk_mul_f32 v[144:145], v[74:75], v[144:145]
	v_pk_add_f32 v[136:137], v[136:137], 1.0 op_sel_hi:[1,0]
	v_pk_mul_f32 v[146:147], v[76:77], v[146:147]
	v_div_scale_f32 v154, s[16:17], v137, v137, v130
	v_rcp_f32_e32 v155, v154
	s_nop 0
	v_fma_f32 v156, -v154, v155, 1.0
	v_fmac_f32_e32 v155, v156, v155
	v_div_scale_f32 v156, vcc, v130, v137, v130
	v_mul_f32_e32 v157, v156, v155
	v_fma_f32 v158, -v154, v157, v156
	v_fmac_f32_e32 v157, v158, v155
	v_fma_f32 v154, -v154, v157, v156
	v_div_fmas_f32 v154, v154, v155, v157
	v_div_fixup_f32 v137, v154, v137, v130
	v_div_scale_f32 v130, s[16:17], v136, v136, v153
	v_rcp_f32_e32 v154, v130
	s_nop 0
	v_fma_f32 v155, -v130, v154, 1.0
	v_fmac_f32_e32 v154, v155, v154
	v_div_scale_f32 v155, vcc, v153, v136, v153
	v_mul_f32_e32 v156, v155, v154
	v_fma_f32 v157, -v130, v156, v155
	v_fmac_f32_e32 v156, v157, v154
	v_fma_f32 v130, -v130, v156, v155
	v_div_fmas_f32 v130, v130, v154, v156
	v_div_fixup_f32 v136, v130, v136, v153
	v_pk_mul_f32 v[136:137], v[148:149], v[136:137]
	v_lshlrev_b32_e32 v148, 16, v131
	v_and_b32_e32 v131, 0xffff0000, v131
	v_cvt_pk_bf16_f32 v130, v136, v137
	v_mul_f32_e32 v136, 0xbfb8aa3b, v148
	v_mul_f32_e32 v137, 0xbfb8aa3b, v131
	v_exp_f32_e32 v136, v136
	v_exp_f32_e32 v137, v137
	s_nop 0
	v_pk_add_f32 v[136:137], v[136:137], 1.0 op_sel_hi:[1,0]
	s_nop 0
	v_div_scale_f32 v149, s[16:17], v137, v137, v131
	v_rcp_f32_e32 v153, v149
	s_nop 0
	v_fma_f32 v154, -v149, v153, 1.0
	v_fmac_f32_e32 v153, v154, v153
	v_div_scale_f32 v154, vcc, v131, v137, v131
	v_mul_f32_e32 v155, v154, v153
	v_fma_f32 v156, -v149, v155, v154
	v_fmac_f32_e32 v155, v156, v153
	v_fma_f32 v149, -v149, v155, v154
	v_div_fmas_f32 v149, v149, v153, v155
	v_div_fixup_f32 v137, v149, v137, v131
	v_div_scale_f32 v131, s[16:17], v136, v136, v148
	v_rcp_f32_e32 v149, v131
	s_nop 0
	v_fma_f32 v153, -v131, v149, 1.0
	v_fmac_f32_e32 v149, v153, v149
	v_div_scale_f32 v153, vcc, v148, v136, v148
	v_mul_f32_e32 v154, v153, v149
	v_fma_f32 v155, -v131, v154, v153
	v_fmac_f32_e32 v154, v155, v149
	v_fma_f32 v131, -v131, v154, v153
	v_div_fmas_f32 v131, v131, v149, v154
	v_div_fixup_f32 v136, v131, v136, v148
	v_pk_mul_f32 v[136:137], v[150:151], v[136:137]
	v_lshlrev_b32_e32 v148, 16, v132
	v_and_b32_e32 v132, 0xffff0000, v132
	v_cvt_pk_bf16_f32 v131, v136, v137
	v_mul_f32_e32 v136, 0xbfb8aa3b, v148
	v_mul_f32_e32 v137, 0xbfb8aa3b, v132
	v_exp_f32_e32 v136, v136
	v_exp_f32_e32 v137, v137
	s_nop 0
	v_pk_add_f32 v[136:137], v[136:137], 1.0 op_sel_hi:[1,0]
	s_nop 0
	v_div_scale_f32 v149, s[16:17], v137, v137, v132
	v_rcp_f32_e32 v150, v149
	s_nop 0
	v_fma_f32 v151, -v149, v150, 1.0
	v_fmac_f32_e32 v150, v151, v150
	v_div_scale_f32 v151, vcc, v132, v137, v132
	v_mul_f32_e32 v153, v151, v150
	v_fma_f32 v154, -v149, v153, v151
	v_fmac_f32_e32 v153, v154, v150
	v_fma_f32 v149, -v149, v153, v151
	v_div_fmas_f32 v149, v149, v150, v153
	v_div_fixup_f32 v137, v149, v137, v132
	v_div_scale_f32 v132, s[16:17], v136, v136, v148
	v_rcp_f32_e32 v149, v132
	s_nop 0
	v_fma_f32 v150, -v132, v149, 1.0
	v_fmac_f32_e32 v149, v150, v149
	v_div_scale_f32 v150, vcc, v148, v136, v148
	v_mul_f32_e32 v151, v150, v149
	v_fma_f32 v153, -v132, v151, v150
	v_fmac_f32_e32 v151, v153, v149
	v_fma_f32 v132, -v132, v151, v150
	v_div_fmas_f32 v132, v132, v149, v151
	v_div_fixup_f32 v136, v132, v136, v148
	v_pk_mul_f32 v[136:137], v[144:145], v[136:137]
	v_lshlrev_b32_e32 v144, 16, v133
	v_and_b32_e32 v133, 0xffff0000, v133
	v_cvt_pk_bf16_f32 v132, v136, v137
	v_mul_f32_e32 v136, 0xbfb8aa3b, v144
	v_mul_f32_e32 v137, 0xbfb8aa3b, v133
	v_exp_f32_e32 v136, v136
	v_exp_f32_e32 v137, v137
	s_nop 0
	v_pk_add_f32 v[136:137], v[136:137], 1.0 op_sel_hi:[1,0]
	s_nop 0
	v_div_scale_f32 v145, s[16:17], v137, v137, v133
	v_rcp_f32_e32 v148, v145
	s_nop 0
	v_fma_f32 v149, -v145, v148, 1.0
	v_fmac_f32_e32 v148, v149, v148
	v_div_scale_f32 v149, vcc, v133, v137, v133
	v_mul_f32_e32 v150, v149, v148
	v_fma_f32 v151, -v145, v150, v149
	v_fmac_f32_e32 v150, v151, v148
	v_fma_f32 v145, -v145, v150, v149
	v_div_fmas_f32 v145, v145, v148, v150
	v_div_fixup_f32 v137, v145, v137, v133
	v_div_scale_f32 v133, s[16:17], v136, v136, v144
	v_rcp_f32_e32 v145, v133
	s_nop 0
	v_fma_f32 v148, -v133, v145, 1.0
	v_fmac_f32_e32 v145, v148, v145
	v_div_scale_f32 v148, vcc, v144, v136, v144
	v_mul_f32_e32 v149, v148, v145
	v_fma_f32 v150, -v133, v149, v148
	v_fmac_f32_e32 v149, v150, v145
	v_fma_f32 v133, -v133, v149, v148
	v_div_fmas_f32 v133, v133, v145, v149
	v_div_fixup_f32 v136, v133, v136, v144
	v_pk_mul_f32 v[136:137], v[146:147], v[136:137]
	s_nop 0
	v_cvt_pk_bf16_f32 v133, v136, v137
	v_mad_i64_i32 v[136:137], s[16:17], s48, v152, 0
	v_lshl_add_u64 v[136:137], v[136:137], 1, s[20:21]
	v_lshl_add_u64 v[136:137], v[136:137], 0, v[138:139]
	global_store_dwordx4 v[136:137], v[130:133], off
	global_load_dwordx4 v[130:133], v[134:135], off offset:256
	s_nop 0
	global_load_dwordx4 v[144:147], v[140:141], off offset:528
	global_load_dwordx4 v[148:151], v[140:141], off offset:512
	s_waitcnt vmcnt(0) lgkmcnt(0)
; DI unsigned pk2(float lo, float hi) { f32x2_t f = {lo, hi}; bf16x2_t v = __builtin_convertvector(f, bf16x2_t); return __builtin_bit_cast(unsigned, v); }
; DI float silu(float v) { return v / (1.f + __expf(-v)); }
;     DI void operator()(const f32x4 (&acc)[2][2][4][2], const Unit& u, int wr, int wc, int fr, int fq) const {
;     ...
;                         const u32x4 gv = *(const u32x4*)(gate + (size_t)row * LDU_E + col);
;                         const f32x4 s0 = *(const f32x4*)(pscale + col), s1 = *(const f32x4*)(pscale + col + 4);
;                         const f32x4 v0 = acc[ai][bj][m][0], v1 = acc[ai][bj][m][1];
;                         u32x4 w;
;                         w.x = pk2(v0[0] * s0[0] * silu(bflo(gv.x)), v0[1] * s0[1] * silu(bfhi(gv.x)));
;                         w.y = pk2(v0[2] * s0[2] * silu(bflo(gv.y)), v0[3] * s0[3] * silu(bfhi(gv.y)));
;                         w.z = pk2(v1[0] * s1[0] * silu(bflo(gv.z)), v1[1] * s1[1] * silu(bfhi(gv.z)));
;                         w.w = pk2(v1[2] * s1[2] * silu(bflo(gv.w)), v1[3] * s1[3] * silu(bfhi(gv.w)));
;                         *(u32x4*)(O + (size_t)row * ldc + col) = w; } }
	v_lshlrev_b32_e32 v152, 16, v130
	v_and_b32_e32 v130, 0xffff0000, v130
	v_mul_f32_e32 v134, 0xbfb8aa3b, v152
	v_mul_f32_e32 v135, 0xbfb8aa3b, v130
	v_exp_f32_e32 v134, v134
	v_exp_f32_e32 v135, v135
	v_pk_mul_f32 v[148:149], v[70:71], v[148:149]
	v_pk_mul_f32 v[150:151], v[72:73], v[150:151]
	v_pk_mul_f32 v[144:145], v[66:67], v[144:145]
	v_pk_add_f32 v[134:135], v[134:135], 1.0 op_sel_hi:[1,0]
	v_pk_mul_f32 v[146:147], v[68:69], v[146:147]
	v_div_scale_f32 v153, s[16:17], v135, v135, v130
	v_rcp_f32_e32 v154, v153
	s_nop 0
	v_fma_f32 v155, -v153, v154, 1.0
	v_fmac_f32_e32 v154, v155, v154
	v_div_scale_f32 v155, vcc, v130, v135, v130
	v_mul_f32_e32 v156, v155, v154
	v_fma_f32 v157, -v153, v156, v155
	v_fmac_f32_e32 v156, v157, v154
	v_fma_f32 v153, -v153, v156, v155
	v_div_fmas_f32 v153, v153, v154, v156
	v_div_fixup_f32 v135, v153, v135, v130
	v_div_scale_f32 v130, s[16:17], v134, v134, v152
	v_rcp_f32_e32 v153, v130
	s_nop 0
	v_fma_f32 v154, -v130, v153, 1.0
	v_fmac_f32_e32 v153, v154, v153
	v_div_scale_f32 v154, vcc, v152, v134, v152
	v_mul_f32_e32 v155, v154, v153
	v_fma_f32 v156, -v130, v155, v154
	v_fmac_f32_e32 v155, v156, v153
	v_fma_f32 v130, -v130, v155, v154
	v_div_fmas_f32 v130, v130, v153, v155
	v_div_fixup_f32 v134, v130, v134, v152
	v_pk_mul_f32 v[134:135], v[148:149], v[134:135]
	v_lshlrev_b32_e32 v148, 16, v131
	v_and_b32_e32 v131, 0xffff0000, v131
	v_cvt_pk_bf16_f32 v130, v134, v135
	v_mul_f32_e32 v134, 0xbfb8aa3b, v148
	v_mul_f32_e32 v135, 0xbfb8aa3b, v131
	v_exp_f32_e32 v134, v134
	v_exp_f32_e32 v135, v135
	s_nop 0
	v_pk_add_f32 v[134:135], v[134:135], 1.0 op_sel_hi:[1,0]
	s_nop 0
	v_div_scale_f32 v149, s[16:17], v135, v135, v131
	v_rcp_f32_e32 v152, v149
	s_nop 0
	v_fma_f32 v153, -v149, v152, 1.0
	v_fmac_f32_e32 v152, v153, v152
	v_div_scale_f32 v153, vcc, v131, v135, v131
	v_mul_f32_e32 v154, v153, v152
	v_fma_f32 v155, -v149, v154, v153
	v_fmac_f32_e32 v154, v155, v152
	v_fma_f32 v149, -v149, v154, v153
	v_div_fmas_f32 v149, v149, v152, v154
	v_div_fixup_f32 v135, v149, v135, v131
	v_div_scale_f32 v131, s[16:17], v134, v134, v148
	v_rcp_f32_e32 v149, v131
	s_nop 0
	v_fma_f32 v152, -v131, v149, 1.0
	v_fmac_f32_e32 v149, v152, v149
	v_div_scale_f32 v152, vcc, v148, v134, v148
	v_mul_f32_e32 v153, v152, v149
	v_fma_f32 v154, -v131, v153, v152
	v_fmac_f32_e32 v153, v154, v149
	v_fma_f32 v131, -v131, v153, v152
	v_div_fmas_f32 v131, v131, v149, v153
	v_div_fixup_f32 v134, v131, v134, v148
	v_pk_mul_f32 v[134:135], v[150:151], v[134:135]
	v_lshlrev_b32_e32 v148, 16, v132
	v_and_b32_e32 v132, 0xffff0000, v132
	v_cvt_pk_bf16_f32 v131, v134, v135
	v_mul_f32_e32 v134, 0xbfb8aa3b, v148
	v_mul_f32_e32 v135, 0xbfb8aa3b, v132
	v_exp_f32_e32 v134, v134
	v_exp_f32_e32 v135, v135
	s_nop 0
	v_pk_add_f32 v[134:135], v[134:135], 1.0 op_sel_hi:[1,0]
	s_nop 0
	v_div_scale_f32 v149, s[16:17], v135, v135, v132
	v_rcp_f32_e32 v150, v149
	s_nop 0
	v_fma_f32 v151, -v149, v150, 1.0
	v_fmac_f32_e32 v150, v151, v150
	v_div_scale_f32 v151, vcc, v132, v135, v132
	v_mul_f32_e32 v152, v151, v150
	v_fma_f32 v153, -v149, v152, v151
	v_fmac_f32_e32 v152, v153, v150
	v_fma_f32 v149, -v149, v152, v151
	v_div_fmas_f32 v149, v149, v150, v152
	v_div_fixup_f32 v135, v149, v135, v132
	v_div_scale_f32 v132, s[16:17], v134, v134, v148
	v_rcp_f32_e32 v149, v132
	s_nop 0
	v_fma_f32 v150, -v132, v149, 1.0
	v_fmac_f32_e32 v149, v150, v149
	v_div_scale_f32 v150, vcc, v148, v134, v148
	v_mul_f32_e32 v151, v150, v149
	v_fma_f32 v152, -v132, v151, v150
	v_fmac_f32_e32 v151, v152, v149
	v_fma_f32 v132, -v132, v151, v150
	v_div_fmas_f32 v132, v132, v149, v151
	v_div_fixup_f32 v134, v132, v134, v148
	v_pk_mul_f32 v[134:135], v[144:145], v[134:135]
	v_lshlrev_b32_e32 v144, 16, v133
	v_and_b32_e32 v133, 0xffff0000, v133
	v_cvt_pk_bf16_f32 v132, v134, v135
	v_mul_f32_e32 v134, 0xbfb8aa3b, v144
	v_mul_f32_e32 v135, 0xbfb8aa3b, v133
	v_exp_f32_e32 v134, v134
	v_exp_f32_e32 v135, v135
	v_add_u32_e32 v152, 0x80, v0
	v_pk_add_f32 v[134:135], v[134:135], 1.0 op_sel_hi:[1,0]
	s_nop 0
	v_div_scale_f32 v145, s[16:17], v135, v135, v133
	v_rcp_f32_e32 v148, v145
	s_nop 0
	v_fma_f32 v149, -v145, v148, 1.0
	v_fmac_f32_e32 v148, v149, v148
	v_div_scale_f32 v149, vcc, v133, v135, v133
	v_mul_f32_e32 v150, v149, v148
	v_fma_f32 v151, -v145, v150, v149
	v_fmac_f32_e32 v150, v151, v148
	v_fma_f32 v145, -v145, v150, v149
	v_div_fmas_f32 v145, v145, v148, v150
	v_div_fixup_f32 v135, v145, v135, v133
	v_div_scale_f32 v133, s[16:17], v134, v134, v144
	v_rcp_f32_e32 v145, v133
	s_nop 0
	v_fma_f32 v148, -v133, v145, 1.0
	v_fmac_f32_e32 v145, v148, v145
	v_div_scale_f32 v148, vcc, v144, v134, v144
	v_mul_f32_e32 v149, v148, v145
	v_fma_f32 v150, -v133, v149, v148
	v_fmac_f32_e32 v149, v150, v145
	v_fma_f32 v133, -v133, v149, v148
	v_div_fmas_f32 v133, v133, v145, v149
	v_div_fixup_f32 v134, v133, v134, v144
	v_pk_mul_f32 v[134:135], v[146:147], v[134:135]
	s_nop 0
	v_cvt_pk_bf16_f32 v133, v134, v135
	global_store_dwordx4 v[136:137], v[130:133], off offset:256
	s_nop 1
	v_mad_i64_i32 v[130:131], s[16:17], v152, s86, v[142:143]
	v_lshl_add_u64 v[134:135], v[130:131], 0, v[138:139]
	global_load_dwordx4 v[130:133], v[134:135], off
	global_load_dwordx4 v[144:147], v[140:141], off offset:16
	global_load_dwordx4 v[148:151], v[140:141], off
	s_waitcnt vmcnt(0) lgkmcnt(0)
; DI unsigned pk2(float lo, float hi) { f32x2_t f = {lo, hi}; bf16x2_t v = __builtin_convertvector(f, bf16x2_t); return __builtin_bit_cast(unsigned, v); }
; DI float silu(float v) { return v / (1.f + __expf(-v)); }
;     DI void operator()(const f32x4 (&acc)[2][2][4][2], const Unit& u, int wr, int wc, int fr, int fq) const {
;     ...
;                         const u32x4 gv = *(const u32x4*)(gate + (size_t)row * LDU_E + col);
;                         const f32x4 s0 = *(const f32x4*)(pscale + col), s1 = *(const f32x4*)(pscale + col + 4);
;                         const f32x4 v0 = acc[ai][bj][m][0], v1 = acc[ai][bj][m][1];
;                         u32x4 w;
;                         w.x = pk2(v0[0] * s0[0] * silu(bflo(gv.x)), v0[1] * s0[1] * silu(bfhi(gv.x)));
;                         w.y = pk2(v0[2] * s0[2] * silu(bflo(gv.y)), v0[3] * s0[3] * silu(bfhi(gv.y)));
;                         w.z = pk2(v1[0] * s1[0] * silu(bflo(gv.z)), v1[1] * s1[1] * silu(bfhi(gv.z)));
;                         w.w = pk2(v1[2] * s1[2] * silu(bflo(gv.w)), v1[3] * s1[3] * silu(bfhi(gv.w)));
;                         *(u32x4*)(O + (size_t)row * ldc + col) = w; } }
	v_lshlrev_b32_e32 v153, 16, v130
	v_and_b32_e32 v130, 0xffff0000, v130
	v_mul_f32_e32 v136, 0xbfb8aa3b, v153
	v_mul_f32_e32 v137, 0xbfb8aa3b, v130
	v_exp_f32_e32 v136, v136
	v_exp_f32_e32 v137, v137
	v_pk_mul_f32 v[148:149], v[62:63], v[148:149]
	v_pk_mul_f32 v[150:151], v[64:65], v[150:151]
	v_pk_mul_f32 v[144:145], v[58:59], v[144:145]
	v_pk_add_f32 v[136:137], v[136:137], 1.0 op_sel_hi:[1,0]
	v_pk_mul_f32 v[146:147], v[60:61], v[146:147]
	v_div_scale_f32 v154, s[16:17], v137, v137, v130
	v_rcp_f32_e32 v155, v154
	s_nop 0
	v_fma_f32 v156, -v154, v155, 1.0
	v_fmac_f32_e32 v155, v156, v155
	v_div_scale_f32 v156, vcc, v130, v137, v130
	v_mul_f32_e32 v157, v156, v155
	v_fma_f32 v158, -v154, v157, v156
	v_fmac_f32_e32 v157, v158, v155
	v_fma_f32 v154, -v154, v157, v156
	v_div_fmas_f32 v154, v154, v155, v157
	v_div_fixup_f32 v137, v154, v137, v130
	v_div_scale_f32 v130, s[16:17], v136, v136, v153
	v_rcp_f32_e32 v154, v130
	s_nop 0
	v_fma_f32 v155, -v130, v154, 1.0
	v_fmac_f32_e32 v154, v155, v154
	v_div_scale_f32 v155, vcc, v153, v136, v153
	v_mul_f32_e32 v156, v155, v154
	v_fma_f32 v157, -v130, v156, v155
	v_fmac_f32_e32 v156, v157, v154
	v_fma_f32 v130, -v130, v156, v155
	v_div_fmas_f32 v130, v130, v154, v156
	v_div_fixup_f32 v136, v130, v136, v153
	v_pk_mul_f32 v[136:137], v[148:149], v[136:137]
	v_lshlrev_b32_e32 v148, 16, v131
	v_and_b32_e32 v131, 0xffff0000, v131
	v_cvt_pk_bf16_f32 v130, v136, v137
	v_mul_f32_e32 v136, 0xbfb8aa3b, v148
	v_mul_f32_e32 v137, 0xbfb8aa3b, v131
	v_exp_f32_e32 v136, v136
	v_exp_f32_e32 v137, v137
	s_nop 0
	v_pk_add_f32 v[136:137], v[136:137], 1.0 op_sel_hi:[1,0]
	s_nop 0
	v_div_scale_f32 v149, s[16:17], v137, v137, v131
	v_rcp_f32_e32 v153, v149
	s_nop 0
	v_fma_f32 v154, -v149, v153, 1.0
	v_fmac_f32_e32 v153, v154, v153
	v_div_scale_f32 v154, vcc, v131, v137, v131
	v_mul_f32_e32 v155, v154, v153
	v_fma_f32 v156, -v149, v155, v154
	v_fmac_f32_e32 v155, v156, v153
	v_fma_f32 v149, -v149, v155, v154
	v_div_fmas_f32 v149, v149, v153, v155
	v_div_fixup_f32 v137, v149, v137, v131
	v_div_scale_f32 v131, s[16:17], v136, v136, v148
	v_rcp_f32_e32 v149, v131
	s_nop 0
	v_fma_f32 v153, -v131, v149, 1.0
	v_fmac_f32_e32 v149, v153, v149
	v_div_scale_f32 v153, vcc, v148, v136, v148
	v_mul_f32_e32 v154, v153, v149
	v_fma_f32 v155, -v131, v154, v153
	v_fmac_f32_e32 v154, v155, v149
	v_fma_f32 v131, -v131, v154, v153
	v_div_fmas_f32 v131, v131, v149, v154
	v_div_fixup_f32 v136, v131, v136, v148
	v_pk_mul_f32 v[136:137], v[150:151], v[136:137]
	v_lshlrev_b32_e32 v148, 16, v132
	v_and_b32_e32 v132, 0xffff0000, v132
	v_cvt_pk_bf16_f32 v131, v136, v137
	v_mul_f32_e32 v136, 0xbfb8aa3b, v148
	v_mul_f32_e32 v137, 0xbfb8aa3b, v132
	v_exp_f32_e32 v136, v136
	v_exp_f32_e32 v137, v137
	s_nop 0
	v_pk_add_f32 v[136:137], v[136:137], 1.0 op_sel_hi:[1,0]
	s_nop 0
	v_div_scale_f32 v149, s[16:17], v137, v137, v132
	v_rcp_f32_e32 v150, v149
	s_nop 0
	v_fma_f32 v151, -v149, v150, 1.0
	v_fmac_f32_e32 v150, v151, v150
	v_div_scale_f32 v151, vcc, v132, v137, v132
	v_mul_f32_e32 v153, v151, v150
	v_fma_f32 v154, -v149, v153, v151
	v_fmac_f32_e32 v153, v154, v150
	v_fma_f32 v149, -v149, v153, v151
	v_div_fmas_f32 v149, v149, v150, v153
	v_div_fixup_f32 v137, v149, v137, v132
	v_div_scale_f32 v132, s[16:17], v136, v136, v148
	v_rcp_f32_e32 v149, v132
	s_nop 0
	v_fma_f32 v150, -v132, v149, 1.0
	v_fmac_f32_e32 v149, v150, v149
	v_div_scale_f32 v150, vcc, v148, v136, v148
	v_mul_f32_e32 v151, v150, v149
	v_fma_f32 v153, -v132, v151, v150
	v_fmac_f32_e32 v151, v153, v149
	v_fma_f32 v132, -v132, v151, v150
	v_div_fmas_f32 v132, v132, v149, v151
	v_div_fixup_f32 v136, v132, v136, v148
	v_pk_mul_f32 v[136:137], v[144:145], v[136:137]
	v_lshlrev_b32_e32 v144, 16, v133
	v_and_b32_e32 v133, 0xffff0000, v133
	v_cvt_pk_bf16_f32 v132, v136, v137
	v_mul_f32_e32 v136, 0xbfb8aa3b, v144
	v_mul_f32_e32 v137, 0xbfb8aa3b, v133
	v_exp_f32_e32 v136, v136
	v_exp_f32_e32 v137, v137
	s_nop 0
	v_pk_add_f32 v[136:137], v[136:137], 1.0 op_sel_hi:[1,0]
	s_nop 0
	v_div_scale_f32 v145, s[16:17], v137, v137, v133
	v_rcp_f32_e32 v148, v145
	s_nop 0
	v_fma_f32 v149, -v145, v148, 1.0
	v_fmac_f32_e32 v148, v149, v148
	v_div_scale_f32 v149, vcc, v133, v137, v133
	v_mul_f32_e32 v150, v149, v148
	v_fma_f32 v151, -v145, v150, v149
	v_fmac_f32_e32 v150, v151, v148
	v_fma_f32 v145, -v145, v150, v149
	v_div_fmas_f32 v145, v145, v148, v150
	v_div_fixup_f32 v137, v145, v137, v133
	v_div_scale_f32 v133, s[16:17], v136, v136, v144
	v_rcp_f32_e32 v145, v133
	s_nop 0
	v_fma_f32 v148, -v133, v145, 1.0
	v_fmac_f32_e32 v145, v148, v145
	v_div_scale_f32 v148, vcc, v144, v136, v144
	v_mul_f32_e32 v149, v148, v145
	v_fma_f32 v150, -v133, v149, v148
	v_fmac_f32_e32 v149, v150, v145
	v_fma_f32 v133, -v133, v149, v148
	v_div_fmas_f32 v133, v133, v145, v149
	v_div_fixup_f32 v136, v133, v136, v144
	v_pk_mul_f32 v[136:137], v[146:147], v[136:137]
	s_nop 0
	v_cvt_pk_bf16_f32 v133, v136, v137
	v_mad_i64_i32 v[136:137], s[16:17], s48, v152, 0
	v_lshl_add_u64 v[136:137], v[136:137], 1, s[20:21]
	v_lshl_add_u64 v[136:137], v[136:137], 0, v[138:139]
	global_store_dwordx4 v[136:137], v[130:133], off
	global_load_dwordx4 v[130:133], v[134:135], off offset:256
	s_nop 0
	global_load_dwordx4 v[144:147], v[140:141], off offset:528
	global_load_dwordx4 v[148:151], v[140:141], off offset:512
	s_waitcnt vmcnt(0) lgkmcnt(0)
; DI unsigned pk2(float lo, float hi) { f32x2_t f = {lo, hi}; bf16x2_t v = __builtin_convertvector(f, bf16x2_t); return __builtin_bit_cast(unsigned, v); }
; DI float silu(float v) { return v / (1.f + __expf(-v)); }
;     DI void operator()(const f32x4 (&acc)[2][2][4][2], const Unit& u, int wr, int wc, int fr, int fq) const {
;     ...
;                         const u32x4 gv = *(const u32x4*)(gate + (size_t)row * LDU_E + col);
;                         const f32x4 s0 = *(const f32x4*)(pscale + col), s1 = *(const f32x4*)(pscale + col + 4);
;                         const f32x4 v0 = acc[ai][bj][m][0], v1 = acc[ai][bj][m][1];
;                         u32x4 w;
;                         w.x = pk2(v0[0] * s0[0] * silu(bflo(gv.x)), v0[1] * s0[1] * silu(bfhi(gv.x)));
;                         w.y = pk2(v0[2] * s0[2] * silu(bflo(gv.y)), v0[3] * s0[3] * silu(bfhi(gv.y)));
;                         w.z = pk2(v1[0] * s1[0] * silu(bflo(gv.z)), v1[1] * s1[1] * silu(bfhi(gv.z)));
;                         w.w = pk2(v1[2] * s1[2] * silu(bflo(gv.w)), v1[3] * s1[3] * silu(bfhi(gv.w)));
;                         *(u32x4*)(O + (size_t)row * ldc + col) = w; } }
	v_lshlrev_b32_e32 v152, 16, v130
	v_and_b32_e32 v130, 0xffff0000, v130
	v_mul_f32_e32 v134, 0xbfb8aa3b, v152
	v_mul_f32_e32 v135, 0xbfb8aa3b, v130
	v_exp_f32_e32 v134, v134
	v_exp_f32_e32 v135, v135
	v_pk_mul_f32 v[148:149], v[54:55], v[148:149]
	v_pk_mul_f32 v[150:151], v[56:57], v[150:151]
	v_pk_mul_f32 v[144:145], v[50:51], v[144:145]
	v_pk_add_f32 v[134:135], v[134:135], 1.0 op_sel_hi:[1,0]
	v_pk_mul_f32 v[146:147], v[52:53], v[146:147]
	v_div_scale_f32 v153, s[16:17], v135, v135, v130
	v_rcp_f32_e32 v154, v153
	s_nop 0
	v_fma_f32 v155, -v153, v154, 1.0
	v_fmac_f32_e32 v154, v155, v154
	v_div_scale_f32 v155, vcc, v130, v135, v130
	v_mul_f32_e32 v156, v155, v154
	v_fma_f32 v157, -v153, v156, v155
	v_fmac_f32_e32 v156, v157, v154
	v_fma_f32 v153, -v153, v156, v155
	v_div_fmas_f32 v153, v153, v154, v156
	v_div_fixup_f32 v135, v153, v135, v130
	v_div_scale_f32 v130, s[16:17], v134, v134, v152
	v_rcp_f32_e32 v153, v130
	s_nop 0
	v_fma_f32 v154, -v130, v153, 1.0
	v_fmac_f32_e32 v153, v154, v153
	v_div_scale_f32 v154, vcc, v152, v134, v152
	v_mul_f32_e32 v155, v154, v153
	v_fma_f32 v156, -v130, v155, v154
	v_fmac_f32_e32 v155, v156, v153
	v_fma_f32 v130, -v130, v155, v154
	v_div_fmas_f32 v130, v130, v153, v155
	v_div_fixup_f32 v134, v130, v134, v152
	v_pk_mul_f32 v[134:135], v[148:149], v[134:135]
	v_lshlrev_b32_e32 v148, 16, v131
	v_and_b32_e32 v131, 0xffff0000, v131
	v_cvt_pk_bf16_f32 v130, v134, v135
	v_mul_f32_e32 v134, 0xbfb8aa3b, v148
	v_mul_f32_e32 v135, 0xbfb8aa3b, v131
	v_exp_f32_e32 v134, v134
	v_exp_f32_e32 v135, v135
	s_nop 0
	v_pk_add_f32 v[134:135], v[134:135], 1.0 op_sel_hi:[1,0]
	s_nop 0
	v_div_scale_f32 v149, s[16:17], v135, v135, v131
	v_rcp_f32_e32 v152, v149
	s_nop 0
	v_fma_f32 v153, -v149, v152, 1.0
	v_fmac_f32_e32 v152, v153, v152
	v_div_scale_f32 v153, vcc, v131, v135, v131
	v_mul_f32_e32 v154, v153, v152
	v_fma_f32 v155, -v149, v154, v153
	v_fmac_f32_e32 v154, v155, v152
	v_fma_f32 v149, -v149, v154, v153
	v_div_fmas_f32 v149, v149, v152, v154
	v_div_fixup_f32 v135, v149, v135, v131
	v_div_scale_f32 v131, s[16:17], v134, v134, v148
	v_rcp_f32_e32 v149, v131
	s_nop 0
	v_fma_f32 v152, -v131, v149, 1.0
	v_fmac_f32_e32 v149, v152, v149
	v_div_scale_f32 v152, vcc, v148, v134, v148
	v_mul_f32_e32 v153, v152, v149
	v_fma_f32 v154, -v131, v153, v152
	v_fmac_f32_e32 v153, v154, v149
	v_fma_f32 v131, -v131, v153, v152
	v_div_fmas_f32 v131, v131, v149, v153
	v_div_fixup_f32 v134, v131, v134, v148
	v_pk_mul_f32 v[134:135], v[150:151], v[134:135]
	v_lshlrev_b32_e32 v148, 16, v132
	v_and_b32_e32 v132, 0xffff0000, v132
	v_cvt_pk_bf16_f32 v131, v134, v135
	v_mul_f32_e32 v134, 0xbfb8aa3b, v148
	v_mul_f32_e32 v135, 0xbfb8aa3b, v132
	v_exp_f32_e32 v134, v134
	v_exp_f32_e32 v135, v135
	s_nop 0
	v_pk_add_f32 v[134:135], v[134:135], 1.0 op_sel_hi:[1,0]
	s_nop 0
	v_div_scale_f32 v149, s[16:17], v135, v135, v132
	v_rcp_f32_e32 v150, v149
	s_nop 0
	v_fma_f32 v151, -v149, v150, 1.0
	v_fmac_f32_e32 v150, v151, v150
	v_div_scale_f32 v151, vcc, v132, v135, v132
	v_mul_f32_e32 v152, v151, v150
	v_fma_f32 v153, -v149, v152, v151
	v_fmac_f32_e32 v152, v153, v150
	v_fma_f32 v149, -v149, v152, v151
	v_div_fmas_f32 v149, v149, v150, v152
	v_div_fixup_f32 v135, v149, v135, v132
	v_div_scale_f32 v132, s[16:17], v134, v134, v148
	v_rcp_f32_e32 v149, v132
	s_nop 0
	v_fma_f32 v150, -v132, v149, 1.0
	v_fmac_f32_e32 v149, v150, v149
	v_div_scale_f32 v150, vcc, v148, v134, v148
	v_mul_f32_e32 v151, v150, v149
	v_fma_f32 v152, -v132, v151, v150
	v_fmac_f32_e32 v151, v152, v149
	v_fma_f32 v132, -v132, v151, v150
	v_div_fmas_f32 v132, v132, v149, v151
	v_div_fixup_f32 v134, v132, v134, v148
	v_pk_mul_f32 v[134:135], v[144:145], v[134:135]
	v_lshlrev_b32_e32 v144, 16, v133
	v_and_b32_e32 v133, 0xffff0000, v133
	v_cvt_pk_bf16_f32 v132, v134, v135
	v_mul_f32_e32 v134, 0xbfb8aa3b, v144
	v_mul_f32_e32 v135, 0xbfb8aa3b, v133
	v_exp_f32_e32 v134, v134
	v_exp_f32_e32 v135, v135
	v_add_u32_e32 v152, 0x90, v0
	v_pk_add_f32 v[134:135], v[134:135], 1.0 op_sel_hi:[1,0]
	s_nop 0
	v_div_scale_f32 v145, s[16:17], v135, v135, v133
	v_rcp_f32_e32 v148, v145
	s_nop 0
	v_fma_f32 v149, -v145, v148, 1.0
	v_fmac_f32_e32 v148, v149, v148
	v_div_scale_f32 v149, vcc, v133, v135, v133
	v_mul_f32_e32 v150, v149, v148
	v_fma_f32 v151, -v145, v150, v149
	v_fmac_f32_e32 v150, v151, v148
	v_fma_f32 v145, -v145, v150, v149
	v_div_fmas_f32 v145, v145, v148, v150
	v_div_fixup_f32 v135, v145, v135, v133
	v_div_scale_f32 v133, s[16:17], v134, v134, v144
	v_rcp_f32_e32 v145, v133
	s_nop 0
	v_fma_f32 v148, -v133, v145, 1.0
	v_fmac_f32_e32 v145, v148, v145
	v_div_scale_f32 v148, vcc, v144, v134, v144
	v_mul_f32_e32 v149, v148, v145
	v_fma_f32 v150, -v133, v149, v148
	v_fmac_f32_e32 v149, v150, v145
	v_fma_f32 v133, -v133, v149, v148
	v_div_fmas_f32 v133, v133, v145, v149
	v_div_fixup_f32 v134, v133, v134, v144
	v_pk_mul_f32 v[134:135], v[146:147], v[134:135]
	s_nop 0
	v_cvt_pk_bf16_f32 v133, v134, v135
	global_store_dwordx4 v[136:137], v[130:133], off offset:256
	s_nop 1
	v_mad_i64_i32 v[130:131], s[16:17], v152, s86, v[142:143]
	v_lshl_add_u64 v[134:135], v[130:131], 0, v[138:139]
	global_load_dwordx4 v[130:133], v[134:135], off
	global_load_dwordx4 v[144:147], v[140:141], off offset:16
	global_load_dwordx4 v[148:151], v[140:141], off
	s_waitcnt vmcnt(0) lgkmcnt(0)
; DI unsigned pk2(float lo, float hi) { f32x2_t f = {lo, hi}; bf16x2_t v = __builtin_convertvector(f, bf16x2_t); return __builtin_bit_cast(unsigned, v); }
; DI float silu(float v) { return v / (1.f + __expf(-v)); }
;     DI void operator()(const f32x4 (&acc)[2][2][4][2], const Unit& u, int wr, int wc, int fr, int fq) const {
;     ...
;                         const u32x4 gv = *(const u32x4*)(gate + (size_t)row * LDU_E + col);
;                         const f32x4 s0 = *(const f32x4*)(pscale + col), s1 = *(const f32x4*)(pscale + col + 4);
;                         const f32x4 v0 = acc[ai][bj][m][0], v1 = acc[ai][bj][m][1];
;                         u32x4 w;
;                         w.x = pk2(v0[0] * s0[0] * silu(bflo(gv.x)), v0[1] * s0[1] * silu(bfhi(gv.x)));
;                         w.y = pk2(v0[2] * s0[2] * silu(bflo(gv.y)), v0[3] * s0[3] * silu(bfhi(gv.y)));
;                         w.z = pk2(v1[0] * s1[0] * silu(bflo(gv.z)), v1[1] * s1[1] * silu(bfhi(gv.z)));
;                         w.w = pk2(v1[2] * s1[2] * silu(bflo(gv.w)), v1[3] * s1[3] * silu(bfhi(gv.w)));
;                         *(u32x4*)(O + (size_t)row * ldc + col) = w; } }
	v_lshlrev_b32_e32 v153, 16, v130
	v_and_b32_e32 v130, 0xffff0000, v130
	v_mul_f32_e32 v136, 0xbfb8aa3b, v153
	v_mul_f32_e32 v137, 0xbfb8aa3b, v130
	v_exp_f32_e32 v136, v136
	v_exp_f32_e32 v137, v137
	v_pk_mul_f32 v[148:149], v[46:47], v[148:149]
	v_pk_mul_f32 v[150:151], v[48:49], v[150:151]
	v_pk_mul_f32 v[144:145], v[42:43], v[144:145]
	v_pk_add_f32 v[136:137], v[136:137], 1.0 op_sel_hi:[1,0]
	v_pk_mul_f32 v[146:147], v[44:45], v[146:147]
	v_div_scale_f32 v154, s[16:17], v137, v137, v130
	v_rcp_f32_e32 v155, v154
	s_nop 0
	v_fma_f32 v156, -v154, v155, 1.0
	v_fmac_f32_e32 v155, v156, v155
	v_div_scale_f32 v156, vcc, v130, v137, v130
	v_mul_f32_e32 v157, v156, v155
	v_fma_f32 v158, -v154, v157, v156
	v_fmac_f32_e32 v157, v158, v155
	v_fma_f32 v154, -v154, v157, v156
	v_div_fmas_f32 v154, v154, v155, v157
	v_div_fixup_f32 v137, v154, v137, v130
	v_div_scale_f32 v130, s[16:17], v136, v136, v153
	v_rcp_f32_e32 v154, v130
	s_nop 0
	v_fma_f32 v155, -v130, v154, 1.0
	v_fmac_f32_e32 v154, v155, v154
	v_div_scale_f32 v155, vcc, v153, v136, v153
	v_mul_f32_e32 v156, v155, v154
	v_fma_f32 v157, -v130, v156, v155
	v_fmac_f32_e32 v156, v157, v154
	v_fma_f32 v130, -v130, v156, v155
	v_div_fmas_f32 v130, v130, v154, v156
	v_div_fixup_f32 v136, v130, v136, v153
	v_pk_mul_f32 v[136:137], v[148:149], v[136:137]
	v_lshlrev_b32_e32 v148, 16, v131
	v_and_b32_e32 v131, 0xffff0000, v131
	v_cvt_pk_bf16_f32 v130, v136, v137
	v_mul_f32_e32 v136, 0xbfb8aa3b, v148
	v_mul_f32_e32 v137, 0xbfb8aa3b, v131
	v_exp_f32_e32 v136, v136
	v_exp_f32_e32 v137, v137
	s_nop 0
	v_pk_add_f32 v[136:137], v[136:137], 1.0 op_sel_hi:[1,0]
	s_nop 0
	v_div_scale_f32 v149, s[16:17], v137, v137, v131
	v_rcp_f32_e32 v153, v149
	s_nop 0
	v_fma_f32 v154, -v149, v153, 1.0
	v_fmac_f32_e32 v153, v154, v153
	v_div_scale_f32 v154, vcc, v131, v137, v131
	v_mul_f32_e32 v155, v154, v153
	v_fma_f32 v156, -v149, v155, v154
	v_fmac_f32_e32 v155, v156, v153
	v_fma_f32 v149, -v149, v155, v154
	v_div_fmas_f32 v149, v149, v153, v155
	v_div_fixup_f32 v137, v149, v137, v131
	v_div_scale_f32 v131, s[16:17], v136, v136, v148
	v_rcp_f32_e32 v149, v131
	s_nop 0
	v_fma_f32 v153, -v131, v149, 1.0
	v_fmac_f32_e32 v149, v153, v149
	v_div_scale_f32 v153, vcc, v148, v136, v148
	v_mul_f32_e32 v154, v153, v149
	v_fma_f32 v155, -v131, v154, v153
	v_fmac_f32_e32 v154, v155, v149
	v_fma_f32 v131, -v131, v154, v153
	v_div_fmas_f32 v131, v131, v149, v154
	v_div_fixup_f32 v136, v131, v136, v148
	v_pk_mul_f32 v[136:137], v[150:151], v[136:137]
	v_lshlrev_b32_e32 v148, 16, v132
	v_and_b32_e32 v132, 0xffff0000, v132
	v_cvt_pk_bf16_f32 v131, v136, v137
	v_mul_f32_e32 v136, 0xbfb8aa3b, v148
	v_mul_f32_e32 v137, 0xbfb8aa3b, v132
	v_exp_f32_e32 v136, v136
	v_exp_f32_e32 v137, v137
	s_nop 0
	v_pk_add_f32 v[136:137], v[136:137], 1.0 op_sel_hi:[1,0]
	s_nop 0
	v_div_scale_f32 v149, s[16:17], v137, v137, v132
	v_rcp_f32_e32 v150, v149
	s_nop 0
	v_fma_f32 v151, -v149, v150, 1.0
	v_fmac_f32_e32 v150, v151, v150
	v_div_scale_f32 v151, vcc, v132, v137, v132
	v_mul_f32_e32 v153, v151, v150
	v_fma_f32 v154, -v149, v153, v151
	v_fmac_f32_e32 v153, v154, v150
	v_fma_f32 v149, -v149, v153, v151
	v_div_fmas_f32 v149, v149, v150, v153
	v_div_fixup_f32 v137, v149, v137, v132
	v_div_scale_f32 v132, s[16:17], v136, v136, v148
	v_rcp_f32_e32 v149, v132
	s_nop 0
	v_fma_f32 v150, -v132, v149, 1.0
	v_fmac_f32_e32 v149, v150, v149
	v_div_scale_f32 v150, vcc, v148, v136, v148
	v_mul_f32_e32 v151, v150, v149
	v_fma_f32 v153, -v132, v151, v150
	v_fmac_f32_e32 v151, v153, v149
	v_fma_f32 v132, -v132, v151, v150
	v_div_fmas_f32 v132, v132, v149, v151
	v_div_fixup_f32 v136, v132, v136, v148
	v_pk_mul_f32 v[136:137], v[144:145], v[136:137]
	v_lshlrev_b32_e32 v144, 16, v133
	v_and_b32_e32 v133, 0xffff0000, v133
	v_cvt_pk_bf16_f32 v132, v136, v137
	v_mul_f32_e32 v136, 0xbfb8aa3b, v144
	v_mul_f32_e32 v137, 0xbfb8aa3b, v133
	v_exp_f32_e32 v136, v136
	v_exp_f32_e32 v137, v137
	s_nop 0
	v_pk_add_f32 v[136:137], v[136:137], 1.0 op_sel_hi:[1,0]
	s_nop 0
	v_div_scale_f32 v145, s[16:17], v137, v137, v133
	v_rcp_f32_e32 v148, v145
	s_nop 0
	v_fma_f32 v149, -v145, v148, 1.0
	v_fmac_f32_e32 v148, v149, v148
	v_div_scale_f32 v149, vcc, v133, v137, v133
	v_mul_f32_e32 v150, v149, v148
	v_fma_f32 v151, -v145, v150, v149
	v_fmac_f32_e32 v150, v151, v148
	v_fma_f32 v145, -v145, v150, v149
	v_div_fmas_f32 v145, v145, v148, v150
	v_div_fixup_f32 v137, v145, v137, v133
	v_div_scale_f32 v133, s[16:17], v136, v136, v144
	v_rcp_f32_e32 v145, v133
	s_nop 0
	v_fma_f32 v148, -v133, v145, 1.0
	v_fmac_f32_e32 v145, v148, v145
	v_div_scale_f32 v148, vcc, v144, v136, v144
	v_mul_f32_e32 v149, v148, v145
	v_fma_f32 v150, -v133, v149, v148
	v_fmac_f32_e32 v149, v150, v145
	v_fma_f32 v133, -v133, v149, v148
	v_div_fmas_f32 v133, v133, v145, v149
	v_div_fixup_f32 v136, v133, v136, v144
	v_pk_mul_f32 v[136:137], v[146:147], v[136:137]
	s_nop 0
	v_cvt_pk_bf16_f32 v133, v136, v137
	v_mad_i64_i32 v[136:137], s[16:17], s48, v152, 0
	v_lshl_add_u64 v[136:137], v[136:137], 1, s[20:21]
	v_lshl_add_u64 v[136:137], v[136:137], 0, v[138:139]
	global_store_dwordx4 v[136:137], v[130:133], off
	global_load_dwordx4 v[130:133], v[134:135], off offset:256
	s_nop 0
	global_load_dwordx4 v[144:147], v[140:141], off offset:528
	global_load_dwordx4 v[148:151], v[140:141], off offset:512
	s_waitcnt vmcnt(0) lgkmcnt(0)
; DI unsigned pk2(float lo, float hi) { f32x2_t f = {lo, hi}; bf16x2_t v = __builtin_convertvector(f, bf16x2_t); return __builtin_bit_cast(unsigned, v); }
; DI float silu(float v) { return v / (1.f + __expf(-v)); }
;     DI void operator()(const f32x4 (&acc)[2][2][4][2], const Unit& u, int wr, int wc, int fr, int fq) const {
;     ...
;                         const u32x4 gv = *(const u32x4*)(gate + (size_t)row * LDU_E + col);
;                         const f32x4 s0 = *(const f32x4*)(pscale + col), s1 = *(const f32x4*)(pscale + col + 4);
;                         const f32x4 v0 = acc[ai][bj][m][0], v1 = acc[ai][bj][m][1];
;                         u32x4 w;
;                         w.x = pk2(v0[0] * s0[0] * silu(bflo(gv.x)), v0[1] * s0[1] * silu(bfhi(gv.x)));
;                         w.y = pk2(v0[2] * s0[2] * silu(bflo(gv.y)), v0[3] * s0[3] * silu(bfhi(gv.y)));
;                         w.z = pk2(v1[0] * s1[0] * silu(bflo(gv.z)), v1[1] * s1[1] * silu(bfhi(gv.z)));
;                         w.w = pk2(v1[2] * s1[2] * silu(bflo(gv.w)), v1[3] * s1[3] * silu(bfhi(gv.w)));
;                         *(u32x4*)(O + (size_t)row * ldc + col) = w; } }
	v_lshlrev_b32_e32 v152, 16, v130
	v_and_b32_e32 v130, 0xffff0000, v130
	v_mul_f32_e32 v134, 0xbfb8aa3b, v152
	v_mul_f32_e32 v135, 0xbfb8aa3b, v130
	v_exp_f32_e32 v134, v134
	v_exp_f32_e32 v135, v135
	v_pk_mul_f32 v[148:149], v[38:39], v[148:149]
	v_pk_mul_f32 v[150:151], v[40:41], v[150:151]
	v_pk_mul_f32 v[144:145], v[34:35], v[144:145]
	v_pk_add_f32 v[134:135], v[134:135], 1.0 op_sel_hi:[1,0]
	v_pk_mul_f32 v[146:147], v[36:37], v[146:147]
	v_div_scale_f32 v153, s[16:17], v135, v135, v130
	v_rcp_f32_e32 v154, v153
	s_nop 0
	v_fma_f32 v155, -v153, v154, 1.0
	v_fmac_f32_e32 v154, v155, v154
	v_div_scale_f32 v155, vcc, v130, v135, v130
	v_mul_f32_e32 v156, v155, v154
	v_fma_f32 v157, -v153, v156, v155
	v_fmac_f32_e32 v156, v157, v154
	v_fma_f32 v153, -v153, v156, v155
	v_div_fmas_f32 v153, v153, v154, v156
	v_div_fixup_f32 v135, v153, v135, v130
	v_div_scale_f32 v130, s[16:17], v134, v134, v152
	v_rcp_f32_e32 v153, v130
	s_nop 0
	v_fma_f32 v154, -v130, v153, 1.0
	v_fmac_f32_e32 v153, v154, v153
	v_div_scale_f32 v154, vcc, v152, v134, v152
	v_mul_f32_e32 v155, v154, v153
	v_fma_f32 v156, -v130, v155, v154
	v_fmac_f32_e32 v155, v156, v153
	v_fma_f32 v130, -v130, v155, v154
	v_div_fmas_f32 v130, v130, v153, v155
	v_div_fixup_f32 v134, v130, v134, v152
	v_pk_mul_f32 v[134:135], v[148:149], v[134:135]
	v_lshlrev_b32_e32 v148, 16, v131
	v_and_b32_e32 v131, 0xffff0000, v131
	v_cvt_pk_bf16_f32 v130, v134, v135
	v_mul_f32_e32 v134, 0xbfb8aa3b, v148
	v_mul_f32_e32 v135, 0xbfb8aa3b, v131
	v_exp_f32_e32 v134, v134
	v_exp_f32_e32 v135, v135
	s_nop 0
	v_pk_add_f32 v[134:135], v[134:135], 1.0 op_sel_hi:[1,0]
	s_nop 0
	v_div_scale_f32 v149, s[16:17], v135, v135, v131
	v_rcp_f32_e32 v152, v149
	s_nop 0
	v_fma_f32 v153, -v149, v152, 1.0
	v_fmac_f32_e32 v152, v153, v152
	v_div_scale_f32 v153, vcc, v131, v135, v131
	v_mul_f32_e32 v154, v153, v152
	v_fma_f32 v155, -v149, v154, v153
	v_fmac_f32_e32 v154, v155, v152
	v_fma_f32 v149, -v149, v154, v153
	v_div_fmas_f32 v149, v149, v152, v154
	v_div_fixup_f32 v135, v149, v135, v131
	v_div_scale_f32 v131, s[16:17], v134, v134, v148
	v_rcp_f32_e32 v149, v131
	s_nop 0
	v_fma_f32 v152, -v131, v149, 1.0
	v_fmac_f32_e32 v149, v152, v149
	v_div_scale_f32 v152, vcc, v148, v134, v148
	v_mul_f32_e32 v153, v152, v149
	v_fma_f32 v154, -v131, v153, v152
	v_fmac_f32_e32 v153, v154, v149
	v_fma_f32 v131, -v131, v153, v152
	v_div_fmas_f32 v131, v131, v149, v153
	v_div_fixup_f32 v134, v131, v134, v148
	v_pk_mul_f32 v[134:135], v[150:151], v[134:135]
	v_lshlrev_b32_e32 v148, 16, v132
	v_and_b32_e32 v132, 0xffff0000, v132
	v_cvt_pk_bf16_f32 v131, v134, v135
	v_mul_f32_e32 v134, 0xbfb8aa3b, v148
	v_mul_f32_e32 v135, 0xbfb8aa3b, v132
	v_exp_f32_e32 v134, v134
	v_exp_f32_e32 v135, v135
	s_nop 0
	v_pk_add_f32 v[134:135], v[134:135], 1.0 op_sel_hi:[1,0]
	s_nop 0
	v_div_scale_f32 v149, s[16:17], v135, v135, v132
	v_rcp_f32_e32 v150, v149
	s_nop 0
	v_fma_f32 v151, -v149, v150, 1.0
	v_fmac_f32_e32 v150, v151, v150
	v_div_scale_f32 v151, vcc, v132, v135, v132
	v_mul_f32_e32 v152, v151, v150
	v_fma_f32 v153, -v149, v152, v151
	v_fmac_f32_e32 v152, v153, v150
	v_fma_f32 v149, -v149, v152, v151
	v_div_fmas_f32 v149, v149, v150, v152
	v_div_fixup_f32 v135, v149, v135, v132
	v_div_scale_f32 v132, s[16:17], v134, v134, v148
	v_rcp_f32_e32 v149, v132
	s_nop 0
	v_fma_f32 v150, -v132, v149, 1.0
	v_fmac_f32_e32 v149, v150, v149
	v_div_scale_f32 v150, vcc, v148, v134, v148
	v_mul_f32_e32 v151, v150, v149
	v_fma_f32 v152, -v132, v151, v150
	v_fmac_f32_e32 v151, v152, v149
	v_fma_f32 v132, -v132, v151, v150
	v_div_fmas_f32 v132, v132, v149, v151
	v_div_fixup_f32 v134, v132, v134, v148
	v_pk_mul_f32 v[134:135], v[144:145], v[134:135]
	v_lshlrev_b32_e32 v144, 16, v133
	v_and_b32_e32 v133, 0xffff0000, v133
	v_cvt_pk_bf16_f32 v132, v134, v135
	v_mul_f32_e32 v134, 0xbfb8aa3b, v144
	v_mul_f32_e32 v135, 0xbfb8aa3b, v133
	v_exp_f32_e32 v134, v134
	v_exp_f32_e32 v135, v135
	v_add_u32_e32 v152, 0xa0, v0
	v_add_u32_e32 v0, 0xb0, v0
	v_pk_add_f32 v[134:135], v[134:135], 1.0 op_sel_hi:[1,0]
	s_nop 0
	v_div_scale_f32 v145, s[16:17], v135, v135, v133
	v_rcp_f32_e32 v148, v145
	s_nop 0
	v_fma_f32 v149, -v145, v148, 1.0
	v_fmac_f32_e32 v148, v149, v148
	v_div_scale_f32 v149, vcc, v133, v135, v133
	v_mul_f32_e32 v150, v149, v148
	v_fma_f32 v151, -v145, v150, v149
	v_fmac_f32_e32 v150, v151, v148
	v_fma_f32 v145, -v145, v150, v149
	v_div_fmas_f32 v145, v145, v148, v150
	v_div_fixup_f32 v135, v145, v135, v133
	v_div_scale_f32 v133, s[16:17], v134, v134, v144
	v_rcp_f32_e32 v145, v133
	s_nop 0
	v_fma_f32 v148, -v133, v145, 1.0
	v_fmac_f32_e32 v145, v148, v145
	v_div_scale_f32 v148, vcc, v144, v134, v144
	v_mul_f32_e32 v149, v148, v145
	v_fma_f32 v150, -v133, v149, v148
	v_fmac_f32_e32 v149, v150, v145
	v_fma_f32 v133, -v133, v149, v148
	v_div_fmas_f32 v133, v133, v145, v149
	v_div_fixup_f32 v134, v133, v134, v144
	v_pk_mul_f32 v[134:135], v[146:147], v[134:135]
	s_nop 0
	v_cvt_pk_bf16_f32 v133, v134, v135
	global_store_dwordx4 v[136:137], v[130:133], off offset:256
	s_nop 1
	v_mad_i64_i32 v[130:131], s[16:17], v152, s86, v[142:143]
	v_lshl_add_u64 v[134:135], v[130:131], 0, v[138:139]
	global_load_dwordx4 v[130:133], v[134:135], off
	global_load_dwordx4 v[144:147], v[140:141], off offset:16
	global_load_dwordx4 v[148:151], v[140:141], off
	s_waitcnt vmcnt(0) lgkmcnt(0)
; DI unsigned pk2(float lo, float hi) { f32x2_t f = {lo, hi}; bf16x2_t v = __builtin_convertvector(f, bf16x2_t); return __builtin_bit_cast(unsigned, v); }
; DI float silu(float v) { return v / (1.f + __expf(-v)); }
;     DI void operator()(const f32x4 (&acc)[2][2][4][2], const Unit& u, int wr, int wc, int fr, int fq) const {
;     ...
;                         const u32x4 gv = *(const u32x4*)(gate + (size_t)row * LDU_E + col);
;                         const f32x4 s0 = *(const f32x4*)(pscale + col), s1 = *(const f32x4*)(pscale + col + 4);
;                         const f32x4 v0 = acc[ai][bj][m][0], v1 = acc[ai][bj][m][1];
;                         u32x4 w;
;                         w.x = pk2(v0[0] * s0[0] * silu(bflo(gv.x)), v0[1] * s0[1] * silu(bfhi(gv.x)));
;                         w.y = pk2(v0[2] * s0[2] * silu(bflo(gv.y)), v0[3] * s0[3] * silu(bfhi(gv.y)));
;                         w.z = pk2(v1[0] * s1[0] * silu(bflo(gv.z)), v1[1] * s1[1] * silu(bfhi(gv.z)));
;                         w.w = pk2(v1[2] * s1[2] * silu(bflo(gv.w)), v1[3] * s1[3] * silu(bfhi(gv.w)));
;                         *(u32x4*)(O + (size_t)row * ldc + col) = w; } }
	v_lshlrev_b32_e32 v153, 16, v130
	v_and_b32_e32 v130, 0xffff0000, v130
	v_mul_f32_e32 v136, 0xbfb8aa3b, v153
	v_mul_f32_e32 v137, 0xbfb8aa3b, v130
	v_exp_f32_e32 v136, v136
	v_exp_f32_e32 v137, v137
	v_pk_mul_f32 v[148:149], v[30:31], v[148:149]
	v_pk_mul_f32 v[150:151], v[32:33], v[150:151]
	v_pk_mul_f32 v[144:145], v[26:27], v[144:145]
	v_pk_add_f32 v[136:137], v[136:137], 1.0 op_sel_hi:[1,0]
	v_pk_mul_f32 v[146:147], v[28:29], v[146:147]
	v_div_scale_f32 v154, s[16:17], v137, v137, v130
	v_rcp_f32_e32 v155, v154
	s_nop 0
	v_fma_f32 v156, -v154, v155, 1.0
	v_fmac_f32_e32 v155, v156, v155
	v_div_scale_f32 v156, vcc, v130, v137, v130
	v_mul_f32_e32 v157, v156, v155
	v_fma_f32 v158, -v154, v157, v156
	v_fmac_f32_e32 v157, v158, v155
	v_fma_f32 v154, -v154, v157, v156
	v_div_fmas_f32 v154, v154, v155, v157
	v_div_fixup_f32 v137, v154, v137, v130
	v_div_scale_f32 v130, s[16:17], v136, v136, v153
	v_rcp_f32_e32 v154, v130
	s_nop 0
	v_fma_f32 v155, -v130, v154, 1.0
	v_fmac_f32_e32 v154, v155, v154
	v_div_scale_f32 v155, vcc, v153, v136, v153
	v_mul_f32_e32 v156, v155, v154
	v_fma_f32 v157, -v130, v156, v155
	v_fmac_f32_e32 v156, v157, v154
	v_fma_f32 v130, -v130, v156, v155
	v_div_fmas_f32 v130, v130, v154, v156
	v_div_fixup_f32 v136, v130, v136, v153
	v_pk_mul_f32 v[136:137], v[148:149], v[136:137]
	v_lshlrev_b32_e32 v148, 16, v131
	v_and_b32_e32 v131, 0xffff0000, v131
	v_cvt_pk_bf16_f32 v130, v136, v137
	v_mul_f32_e32 v136, 0xbfb8aa3b, v148
	v_mul_f32_e32 v137, 0xbfb8aa3b, v131
	v_exp_f32_e32 v136, v136
	v_exp_f32_e32 v137, v137
	s_nop 0
	v_pk_add_f32 v[136:137], v[136:137], 1.0 op_sel_hi:[1,0]
	s_nop 0
	v_div_scale_f32 v149, s[16:17], v137, v137, v131
	v_rcp_f32_e32 v153, v149
	s_nop 0
	v_fma_f32 v154, -v149, v153, 1.0
	v_fmac_f32_e32 v153, v154, v153
	v_div_scale_f32 v154, vcc, v131, v137, v131
	v_mul_f32_e32 v155, v154, v153
	v_fma_f32 v156, -v149, v155, v154
	v_fmac_f32_e32 v155, v156, v153
	v_fma_f32 v149, -v149, v155, v154
	v_div_fmas_f32 v149, v149, v153, v155
	v_div_fixup_f32 v137, v149, v137, v131
	v_div_scale_f32 v131, s[16:17], v136, v136, v148
	v_rcp_f32_e32 v149, v131
	s_nop 0
	v_fma_f32 v153, -v131, v149, 1.0
	v_fmac_f32_e32 v149, v153, v149
	v_div_scale_f32 v153, vcc, v148, v136, v148
	v_mul_f32_e32 v154, v153, v149
	v_fma_f32 v155, -v131, v154, v153
	v_fmac_f32_e32 v154, v155, v149
	v_fma_f32 v131, -v131, v154, v153
	v_div_fmas_f32 v131, v131, v149, v154
	v_div_fixup_f32 v136, v131, v136, v148
	v_pk_mul_f32 v[136:137], v[150:151], v[136:137]
	v_lshlrev_b32_e32 v148, 16, v132
	v_and_b32_e32 v132, 0xffff0000, v132
	v_cvt_pk_bf16_f32 v131, v136, v137
	v_mul_f32_e32 v136, 0xbfb8aa3b, v148
	v_mul_f32_e32 v137, 0xbfb8aa3b, v132
	v_exp_f32_e32 v136, v136
	v_exp_f32_e32 v137, v137
	s_nop 0
	v_pk_add_f32 v[136:137], v[136:137], 1.0 op_sel_hi:[1,0]
	s_nop 0
	v_div_scale_f32 v149, s[16:17], v137, v137, v132
	v_rcp_f32_e32 v150, v149
	s_nop 0
	v_fma_f32 v151, -v149, v150, 1.0
	v_fmac_f32_e32 v150, v151, v150
	v_div_scale_f32 v151, vcc, v132, v137, v132
	v_mul_f32_e32 v153, v151, v150
	v_fma_f32 v154, -v149, v153, v151
	v_fmac_f32_e32 v153, v154, v150
	v_fma_f32 v149, -v149, v153, v151
	v_div_fmas_f32 v149, v149, v150, v153
	v_div_fixup_f32 v137, v149, v137, v132
	v_div_scale_f32 v132, s[16:17], v136, v136, v148
	v_rcp_f32_e32 v149, v132
	s_nop 0
	v_fma_f32 v150, -v132, v149, 1.0
	v_fmac_f32_e32 v149, v150, v149
	v_div_scale_f32 v150, vcc, v148, v136, v148
	v_mul_f32_e32 v151, v150, v149
	v_fma_f32 v153, -v132, v151, v150
	v_fmac_f32_e32 v151, v153, v149
	v_fma_f32 v132, -v132, v151, v150
	v_div_fmas_f32 v132, v132, v149, v151
	v_div_fixup_f32 v136, v132, v136, v148
	v_pk_mul_f32 v[136:137], v[144:145], v[136:137]
	v_lshlrev_b32_e32 v144, 16, v133
	v_and_b32_e32 v133, 0xffff0000, v133
	v_cvt_pk_bf16_f32 v132, v136, v137
	v_mul_f32_e32 v136, 0xbfb8aa3b, v144
	v_mul_f32_e32 v137, 0xbfb8aa3b, v133
	v_exp_f32_e32 v136, v136
	v_exp_f32_e32 v137, v137
	s_nop 0
	v_pk_add_f32 v[136:137], v[136:137], 1.0 op_sel_hi:[1,0]
	s_nop 0
	v_div_scale_f32 v145, s[16:17], v137, v137, v133
	v_rcp_f32_e32 v148, v145
	s_nop 0
	v_fma_f32 v149, -v145, v148, 1.0
	v_fmac_f32_e32 v148, v149, v148
	v_div_scale_f32 v149, vcc, v133, v137, v133
	v_mul_f32_e32 v150, v149, v148
	v_fma_f32 v151, -v145, v150, v149
	v_fmac_f32_e32 v150, v151, v148
	v_fma_f32 v145, -v145, v150, v149
	v_div_fmas_f32 v145, v145, v148, v150
	v_div_fixup_f32 v137, v145, v137, v133
	v_div_scale_f32 v133, s[16:17], v136, v136, v144
	v_rcp_f32_e32 v145, v133
	s_nop 0
	v_fma_f32 v148, -v133, v145, 1.0
	v_fmac_f32_e32 v145, v148, v145
	v_div_scale_f32 v148, vcc, v144, v136, v144
	v_mul_f32_e32 v149, v148, v145
	v_fma_f32 v150, -v133, v149, v148
	v_fmac_f32_e32 v149, v150, v145
	v_fma_f32 v133, -v133, v149, v148
	v_div_fmas_f32 v133, v133, v145, v149
	v_div_fixup_f32 v136, v133, v136, v144
	v_pk_mul_f32 v[136:137], v[146:147], v[136:137]
	s_nop 0
	v_cvt_pk_bf16_f32 v133, v136, v137
	v_mad_i64_i32 v[136:137], s[16:17], s48, v152, 0
	v_lshl_add_u64 v[136:137], v[136:137], 1, s[20:21]
	v_lshl_add_u64 v[136:137], v[136:137], 0, v[138:139]
	global_store_dwordx4 v[136:137], v[130:133], off
	global_load_dwordx4 v[130:133], v[134:135], off offset:256
	s_nop 0
	global_load_dwordx4 v[144:147], v[140:141], off offset:528
	global_load_dwordx4 v[148:151], v[140:141], off offset:512
	s_waitcnt vmcnt(0) lgkmcnt(0)
; DI unsigned pk2(float lo, float hi) { f32x2_t f = {lo, hi}; bf16x2_t v = __builtin_convertvector(f, bf16x2_t); return __builtin_bit_cast(unsigned, v); }
; DI float silu(float v) { return v / (1.f + __expf(-v)); }
;     DI void operator()(const f32x4 (&acc)[2][2][4][2], const Unit& u, int wr, int wc, int fr, int fq) const {
;     ...
;                         const u32x4 gv = *(const u32x4*)(gate + (size_t)row * LDU_E + col);
;                         const f32x4 s0 = *(const f32x4*)(pscale + col), s1 = *(const f32x4*)(pscale + col + 4);
;                         const f32x4 v0 = acc[ai][bj][m][0], v1 = acc[ai][bj][m][1];
;                         u32x4 w;
;                         w.x = pk2(v0[0] * s0[0] * silu(bflo(gv.x)), v0[1] * s0[1] * silu(bfhi(gv.x)));
;                         w.y = pk2(v0[2] * s0[2] * silu(bflo(gv.y)), v0[3] * s0[3] * silu(bfhi(gv.y)));
;                         w.z = pk2(v1[0] * s1[0] * silu(bflo(gv.z)), v1[1] * s1[1] * silu(bfhi(gv.z)));
;                         w.w = pk2(v1[2] * s1[2] * silu(bflo(gv.w)), v1[3] * s1[3] * silu(bfhi(gv.w)));
;                         *(u32x4*)(O + (size_t)row * ldc + col) = w; } }
	v_lshlrev_b32_e32 v152, 16, v130
	v_and_b32_e32 v130, 0xffff0000, v130
	v_mul_f32_e32 v134, 0xbfb8aa3b, v152
	v_mul_f32_e32 v135, 0xbfb8aa3b, v130
	v_exp_f32_e32 v134, v134
	v_exp_f32_e32 v135, v135
	v_pk_mul_f32 v[148:149], v[22:23], v[148:149]
	v_pk_mul_f32 v[150:151], v[24:25], v[150:151]
	v_pk_mul_f32 v[144:145], v[18:19], v[144:145]
	v_pk_add_f32 v[134:135], v[134:135], 1.0 op_sel_hi:[1,0]
	v_pk_mul_f32 v[146:147], v[20:21], v[146:147]
	v_div_scale_f32 v153, s[16:17], v135, v135, v130
	v_rcp_f32_e32 v154, v153
	s_nop 0
	v_fma_f32 v155, -v153, v154, 1.0
	v_fmac_f32_e32 v154, v155, v154
	v_div_scale_f32 v155, vcc, v130, v135, v130
	v_mul_f32_e32 v156, v155, v154
	v_fma_f32 v157, -v153, v156, v155
	v_fmac_f32_e32 v156, v157, v154
	v_fma_f32 v153, -v153, v156, v155
	v_div_fmas_f32 v153, v153, v154, v156
	v_div_fixup_f32 v135, v153, v135, v130
	v_div_scale_f32 v130, s[16:17], v134, v134, v152
	v_rcp_f32_e32 v153, v130
	s_nop 0
	v_fma_f32 v154, -v130, v153, 1.0
	v_fmac_f32_e32 v153, v154, v153
	v_div_scale_f32 v154, vcc, v152, v134, v152
	v_mul_f32_e32 v155, v154, v153
	v_fma_f32 v156, -v130, v155, v154
	v_fmac_f32_e32 v155, v156, v153
	v_fma_f32 v130, -v130, v155, v154
	v_div_fmas_f32 v130, v130, v153, v155
	v_div_fixup_f32 v134, v130, v134, v152
	v_pk_mul_f32 v[134:135], v[148:149], v[134:135]
	v_lshlrev_b32_e32 v148, 16, v131
	v_and_b32_e32 v131, 0xffff0000, v131
	v_cvt_pk_bf16_f32 v130, v134, v135
	v_mul_f32_e32 v134, 0xbfb8aa3b, v148
	v_mul_f32_e32 v135, 0xbfb8aa3b, v131
	v_exp_f32_e32 v134, v134
	v_exp_f32_e32 v135, v135
	s_nop 0
	v_pk_add_f32 v[134:135], v[134:135], 1.0 op_sel_hi:[1,0]
	s_nop 0
	v_div_scale_f32 v149, s[16:17], v135, v135, v131
	v_rcp_f32_e32 v152, v149
	s_nop 0
	v_fma_f32 v153, -v149, v152, 1.0
	v_fmac_f32_e32 v152, v153, v152
	v_div_scale_f32 v153, vcc, v131, v135, v131
	v_mul_f32_e32 v154, v153, v152
	v_fma_f32 v155, -v149, v154, v153
	v_fmac_f32_e32 v154, v155, v152
	v_fma_f32 v149, -v149, v154, v153
	v_div_fmas_f32 v149, v149, v152, v154
	v_div_fixup_f32 v135, v149, v135, v131
	v_div_scale_f32 v131, s[16:17], v134, v134, v148
	v_rcp_f32_e32 v149, v131
	s_nop 0
	v_fma_f32 v152, -v131, v149, 1.0
	v_fmac_f32_e32 v149, v152, v149
	v_div_scale_f32 v152, vcc, v148, v134, v148
	v_mul_f32_e32 v153, v152, v149
	v_fma_f32 v154, -v131, v153, v152
	v_fmac_f32_e32 v153, v154, v149
	v_fma_f32 v131, -v131, v153, v152
	v_div_fmas_f32 v131, v131, v149, v153
	v_div_fixup_f32 v134, v131, v134, v148
	v_pk_mul_f32 v[134:135], v[150:151], v[134:135]
	v_lshlrev_b32_e32 v148, 16, v132
	v_and_b32_e32 v132, 0xffff0000, v132
	v_cvt_pk_bf16_f32 v131, v134, v135
	v_mul_f32_e32 v134, 0xbfb8aa3b, v148
	v_mul_f32_e32 v135, 0xbfb8aa3b, v132
	v_exp_f32_e32 v134, v134
	v_exp_f32_e32 v135, v135
	s_nop 0
	v_pk_add_f32 v[134:135], v[134:135], 1.0 op_sel_hi:[1,0]
	s_nop 0
	v_div_scale_f32 v149, s[16:17], v135, v135, v132
	v_rcp_f32_e32 v150, v149
	s_nop 0
	v_fma_f32 v151, -v149, v150, 1.0
	v_fmac_f32_e32 v150, v151, v150
	v_div_scale_f32 v151, vcc, v132, v135, v132
	v_mul_f32_e32 v152, v151, v150
	v_fma_f32 v153, -v149, v152, v151
	v_fmac_f32_e32 v152, v153, v150
	v_fma_f32 v149, -v149, v152, v151
	v_div_fmas_f32 v149, v149, v150, v152
	v_div_fixup_f32 v135, v149, v135, v132
	v_div_scale_f32 v132, s[16:17], v134, v134, v148
	v_rcp_f32_e32 v149, v132
	s_nop 0
	v_fma_f32 v150, -v132, v149, 1.0
	v_fmac_f32_e32 v149, v150, v149
	v_div_scale_f32 v150, vcc, v148, v134, v148
	v_mul_f32_e32 v151, v150, v149
	v_fma_f32 v152, -v132, v151, v150
	v_fmac_f32_e32 v151, v152, v149
	v_fma_f32 v132, -v132, v151, v150
	v_div_fmas_f32 v132, v132, v149, v151
	v_div_fixup_f32 v134, v132, v134, v148
	v_pk_mul_f32 v[134:135], v[144:145], v[134:135]
	v_lshlrev_b32_e32 v144, 16, v133
	v_and_b32_e32 v133, 0xffff0000, v133
	v_cvt_pk_bf16_f32 v132, v134, v135
	v_mul_f32_e32 v134, 0xbfb8aa3b, v144
	v_mul_f32_e32 v135, 0xbfb8aa3b, v133
	v_exp_f32_e32 v134, v134
	v_exp_f32_e32 v135, v135
	s_nop 0
	v_pk_add_f32 v[134:135], v[134:135], 1.0 op_sel_hi:[1,0]
	s_nop 0
	v_div_scale_f32 v145, s[16:17], v135, v135, v133
	v_rcp_f32_e32 v148, v145
	s_nop 0
	v_fma_f32 v149, -v145, v148, 1.0
	v_fmac_f32_e32 v148, v149, v148
	v_div_scale_f32 v149, vcc, v133, v135, v133
	v_mul_f32_e32 v150, v149, v148
	v_fma_f32 v151, -v145, v150, v149
	v_fmac_f32_e32 v150, v151, v148
	v_fma_f32 v145, -v145, v150, v149
	v_div_fmas_f32 v145, v145, v148, v150
	v_div_fixup_f32 v135, v145, v135, v133
	v_div_scale_f32 v133, s[16:17], v134, v134, v144
	v_rcp_f32_e32 v145, v133
	s_nop 0
	v_fma_f32 v148, -v133, v145, 1.0
	v_fmac_f32_e32 v145, v148, v145
	v_div_scale_f32 v148, vcc, v144, v134, v144
	v_mul_f32_e32 v149, v148, v145
	v_fma_f32 v150, -v133, v149, v148
	v_fmac_f32_e32 v149, v150, v145
	v_fma_f32 v133, -v133, v149, v148
	v_div_fmas_f32 v133, v133, v145, v149
	v_div_fixup_f32 v134, v133, v134, v144
	v_pk_mul_f32 v[134:135], v[146:147], v[134:135]
	s_nop 0
	v_cvt_pk_bf16_f32 v133, v134, v135
	global_store_dwordx4 v[136:137], v[130:133], off offset:256
	s_nop 1
	v_mad_i64_i32 v[130:131], s[16:17], v0, s86, v[142:143]
	v_lshl_add_u64 v[134:135], v[130:131], 0, v[138:139]
	global_load_dwordx4 v[130:133], v[134:135], off
	global_load_dwordx4 v[142:145], v[140:141], off offset:16
	global_load_dwordx4 v[146:149], v[140:141], off
	s_waitcnt vmcnt(0) lgkmcnt(0)
; DI unsigned pk2(float lo, float hi) { f32x2_t f = {lo, hi}; bf16x2_t v = __builtin_convertvector(f, bf16x2_t); return __builtin_bit_cast(unsigned, v); }
; DI float silu(float v) { return v / (1.f + __expf(-v)); }
;     DI void operator()(const f32x4 (&acc)[2][2][4][2], const Unit& u, int wr, int wc, int fr, int fq) const {
;     ...
;                         const u32x4 gv = *(const u32x4*)(gate + (size_t)row * LDU_E + col);
;                         const f32x4 s0 = *(const f32x4*)(pscale + col), s1 = *(const f32x4*)(pscale + col + 4);
;                         const f32x4 v0 = acc[ai][bj][m][0], v1 = acc[ai][bj][m][1];
;                         u32x4 w;
;                         w.x = pk2(v0[0] * s0[0] * silu(bflo(gv.x)), v0[1] * s0[1] * silu(bfhi(gv.x)));
;                         w.y = pk2(v0[2] * s0[2] * silu(bflo(gv.y)), v0[3] * s0[3] * silu(bfhi(gv.y)));
;                         w.z = pk2(v1[0] * s1[0] * silu(bflo(gv.z)), v1[1] * s1[1] * silu(bfhi(gv.z)));
;                         w.w = pk2(v1[2] * s1[2] * silu(bflo(gv.w)), v1[3] * s1[3] * silu(bfhi(gv.w)));
;                         *(u32x4*)(O + (size_t)row * ldc + col) = w; } }
	v_lshlrev_b32_e32 v150, 16, v130
	v_and_b32_e32 v130, 0xffff0000, v130
	v_mul_f32_e32 v136, 0xbfb8aa3b, v150
	v_mul_f32_e32 v137, 0xbfb8aa3b, v130
	v_exp_f32_e32 v136, v136
	v_exp_f32_e32 v137, v137
	v_pk_mul_f32 v[146:147], v[14:15], v[146:147]
	v_pk_mul_f32 v[148:149], v[16:17], v[148:149]
	v_pk_mul_f32 v[142:143], v[10:11], v[142:143]
	v_pk_add_f32 v[136:137], v[136:137], 1.0 op_sel_hi:[1,0]
	v_pk_mul_f32 v[144:145], v[12:13], v[144:145]
	v_div_scale_f32 v151, s[16:17], v137, v137, v130
	v_rcp_f32_e32 v152, v151
	s_nop 0
	v_fma_f32 v153, -v151, v152, 1.0
	v_fmac_f32_e32 v152, v153, v152
	v_div_scale_f32 v153, vcc, v130, v137, v130
	v_mul_f32_e32 v154, v153, v152
	v_fma_f32 v155, -v151, v154, v153
	v_fmac_f32_e32 v154, v155, v152
	v_fma_f32 v151, -v151, v154, v153
	v_div_fmas_f32 v151, v151, v152, v154
	v_div_fixup_f32 v137, v151, v137, v130
	v_div_scale_f32 v130, s[16:17], v136, v136, v150
	v_rcp_f32_e32 v151, v130
	s_nop 0
	v_fma_f32 v152, -v130, v151, 1.0
	v_fmac_f32_e32 v151, v152, v151
	v_div_scale_f32 v152, vcc, v150, v136, v150
	v_mul_f32_e32 v153, v152, v151
	v_fma_f32 v154, -v130, v153, v152
	v_fmac_f32_e32 v153, v154, v151
	v_fma_f32 v130, -v130, v153, v152
	v_div_fmas_f32 v130, v130, v151, v153
	v_div_fixup_f32 v136, v130, v136, v150
	v_pk_mul_f32 v[136:137], v[146:147], v[136:137]
	v_lshlrev_b32_e32 v146, 16, v131
	v_and_b32_e32 v131, 0xffff0000, v131
	v_cvt_pk_bf16_f32 v130, v136, v137
	v_mul_f32_e32 v136, 0xbfb8aa3b, v146
	v_mul_f32_e32 v137, 0xbfb8aa3b, v131
	v_exp_f32_e32 v136, v136
	v_exp_f32_e32 v137, v137
	s_nop 0
	v_pk_add_f32 v[136:137], v[136:137], 1.0 op_sel_hi:[1,0]
	s_nop 0
	v_div_scale_f32 v147, s[16:17], v137, v137, v131
	v_rcp_f32_e32 v150, v147
	s_nop 0
	v_fma_f32 v151, -v147, v150, 1.0
	v_fmac_f32_e32 v150, v151, v150
	v_div_scale_f32 v151, vcc, v131, v137, v131
	v_mul_f32_e32 v152, v151, v150
	v_fma_f32 v153, -v147, v152, v151
	v_fmac_f32_e32 v152, v153, v150
	v_fma_f32 v147, -v147, v152, v151
	v_div_fmas_f32 v147, v147, v150, v152
	v_div_fixup_f32 v137, v147, v137, v131
	v_div_scale_f32 v131, s[16:17], v136, v136, v146
	v_rcp_f32_e32 v147, v131
	s_nop 0
	v_fma_f32 v150, -v131, v147, 1.0
	v_fmac_f32_e32 v147, v150, v147
	v_div_scale_f32 v150, vcc, v146, v136, v146
	v_mul_f32_e32 v151, v150, v147
	v_fma_f32 v152, -v131, v151, v150
	v_fmac_f32_e32 v151, v152, v147
	v_fma_f32 v131, -v131, v151, v150
	v_div_fmas_f32 v131, v131, v147, v151
	v_div_fixup_f32 v136, v131, v136, v146
	v_pk_mul_f32 v[136:137], v[148:149], v[136:137]
	v_lshlrev_b32_e32 v146, 16, v132
	v_and_b32_e32 v132, 0xffff0000, v132
	v_cvt_pk_bf16_f32 v131, v136, v137
	v_mul_f32_e32 v136, 0xbfb8aa3b, v146
	v_mul_f32_e32 v137, 0xbfb8aa3b, v132
	v_exp_f32_e32 v136, v136
	v_exp_f32_e32 v137, v137
	s_nop 0
	v_pk_add_f32 v[136:137], v[136:137], 1.0 op_sel_hi:[1,0]
	s_nop 0
	v_div_scale_f32 v147, s[16:17], v137, v137, v132
	v_rcp_f32_e32 v148, v147
	s_nop 0
	v_fma_f32 v149, -v147, v148, 1.0
	v_fmac_f32_e32 v148, v149, v148
	v_div_scale_f32 v149, vcc, v132, v137, v132
	v_mul_f32_e32 v150, v149, v148
	v_fma_f32 v151, -v147, v150, v149
	v_fmac_f32_e32 v150, v151, v148
	v_fma_f32 v147, -v147, v150, v149
	v_div_fmas_f32 v147, v147, v148, v150
	v_div_fixup_f32 v137, v147, v137, v132
	v_div_scale_f32 v132, s[16:17], v136, v136, v146
	v_rcp_f32_e32 v147, v132
	s_nop 0
	v_fma_f32 v148, -v132, v147, 1.0
	v_fmac_f32_e32 v147, v148, v147
	v_div_scale_f32 v148, vcc, v146, v136, v146
	v_mul_f32_e32 v149, v148, v147
	v_fma_f32 v150, -v132, v149, v148
	v_fmac_f32_e32 v149, v150, v147
	v_fma_f32 v132, -v132, v149, v148
	v_div_fmas_f32 v132, v132, v147, v149
	v_div_fixup_f32 v136, v132, v136, v146
	v_pk_mul_f32 v[136:137], v[142:143], v[136:137]
	v_lshlrev_b32_e32 v142, 16, v133
	v_and_b32_e32 v133, 0xffff0000, v133
	v_cvt_pk_bf16_f32 v132, v136, v137
	v_mul_f32_e32 v136, 0xbfb8aa3b, v142
	v_mul_f32_e32 v137, 0xbfb8aa3b, v133
	v_exp_f32_e32 v136, v136
	v_exp_f32_e32 v137, v137
	s_nop 0
	v_pk_add_f32 v[136:137], v[136:137], 1.0 op_sel_hi:[1,0]
	s_nop 0
	v_div_scale_f32 v143, s[16:17], v137, v137, v133
	v_rcp_f32_e32 v146, v143
	s_nop 0
	v_fma_f32 v147, -v143, v146, 1.0
	v_fmac_f32_e32 v146, v147, v146
	v_div_scale_f32 v147, vcc, v133, v137, v133
	v_mul_f32_e32 v148, v147, v146
	v_fma_f32 v149, -v143, v148, v147
	v_fmac_f32_e32 v148, v149, v146
	v_fma_f32 v143, -v143, v148, v147
	v_div_fmas_f32 v143, v143, v146, v148
	v_div_fixup_f32 v137, v143, v137, v133
	v_div_scale_f32 v133, s[16:17], v136, v136, v142
	v_rcp_f32_e32 v143, v133
	s_nop 0
	v_fma_f32 v146, -v133, v143, 1.0
	v_fmac_f32_e32 v143, v146, v143
	v_div_scale_f32 v146, vcc, v142, v136, v142
	v_mul_f32_e32 v147, v146, v143
	v_fma_f32 v148, -v133, v147, v146
	v_fmac_f32_e32 v147, v148, v143
	v_fma_f32 v133, -v133, v147, v146
	v_div_fmas_f32 v133, v133, v143, v147
	v_div_fixup_f32 v136, v133, v136, v142
	v_pk_mul_f32 v[136:137], v[144:145], v[136:137]
	s_nop 0
	v_cvt_pk_bf16_f32 v133, v136, v137
	v_mad_i64_i32 v[136:137], s[16:17], s48, v0, 0
	v_lshl_add_u64 v[136:137], v[136:137], 1, s[20:21]
	v_lshl_add_u64 v[136:137], v[136:137], 0, v[138:139]
	global_store_dwordx4 v[136:137], v[130:133], off
	global_load_dwordx4 v[130:133], v[134:135], off offset:256
	s_nop 0
	global_load_dwordx4 v[142:145], v[140:141], off offset:528
	s_nop 0
	global_load_dwordx4 v[138:141], v[140:141], off offset:512
	s_waitcnt vmcnt(0) lgkmcnt(0)
; DI unsigned pk2(float lo, float hi) { f32x2_t f = {lo, hi}; bf16x2_t v = __builtin_convertvector(f, bf16x2_t); return __builtin_bit_cast(unsigned, v); }
; DI float silu(float v) { return v / (1.f + __expf(-v)); }
;     DI void operator()(const f32x4 (&acc)[2][2][4][2], const Unit& u, int wr, int wc, int fr, int fq) const {
;     ...
;                         const u32x4 gv = *(const u32x4*)(gate + (size_t)row * LDU_E + col);
;                         const f32x4 s0 = *(const f32x4*)(pscale + col), s1 = *(const f32x4*)(pscale + col + 4);
;                         const f32x4 v0 = acc[ai][bj][m][0], v1 = acc[ai][bj][m][1];
;                         u32x4 w;
;                         w.x = pk2(v0[0] * s0[0] * silu(bflo(gv.x)), v0[1] * s0[1] * silu(bfhi(gv.x)));
;                         w.y = pk2(v0[2] * s0[2] * silu(bflo(gv.y)), v0[3] * s0[3] * silu(bfhi(gv.y)));
;                         w.z = pk2(v1[0] * s1[0] * silu(bflo(gv.z)), v1[1] * s1[1] * silu(bfhi(gv.z)));
;                         w.w = pk2(v1[2] * s1[2] * silu(bflo(gv.w)), v1[3] * s1[3] * silu(bfhi(gv.w)));
;                         *(u32x4*)(O + (size_t)row * ldc + col) = w; } }
	v_lshlrev_b32_e32 v0, 16, v130
	v_and_b32_e32 v130, 0xffff0000, v130
	v_mul_f32_e32 v134, 0xbfb8aa3b, v0
	v_mul_f32_e32 v135, 0xbfb8aa3b, v130
	v_exp_f32_e32 v134, v134
	v_exp_f32_e32 v135, v135
	v_pk_mul_f32 v[138:139], v[6:7], v[138:139]
	v_pk_mul_f32 v[140:141], v[8:9], v[140:141]
	v_pk_add_f32 v[134:135], v[134:135], 1.0 op_sel_hi:[1,0]
	s_nop 0
	v_div_scale_f32 v146, s[16:17], v135, v135, v130
	v_rcp_f32_e32 v147, v146
	s_nop 0
	v_fma_f32 v148, -v146, v147, 1.0
	v_fmac_f32_e32 v147, v148, v147
	v_div_scale_f32 v148, vcc, v130, v135, v130
	v_mul_f32_e32 v149, v148, v147
	v_fma_f32 v150, -v146, v149, v148
	v_fmac_f32_e32 v149, v150, v147
	v_fma_f32 v146, -v146, v149, v148
	v_div_fmas_f32 v146, v146, v147, v149
	v_div_fixup_f32 v135, v146, v135, v130
	v_div_scale_f32 v130, s[16:17], v134, v134, v0
	v_rcp_f32_e32 v146, v130
	s_nop 0
	v_fma_f32 v147, -v130, v146, 1.0
	v_fmac_f32_e32 v146, v147, v146
	v_div_scale_f32 v147, vcc, v0, v134, v0
	v_mul_f32_e32 v148, v147, v146
	v_fma_f32 v149, -v130, v148, v147
	v_fmac_f32_e32 v148, v149, v146
	v_fma_f32 v130, -v130, v148, v147
	v_div_fmas_f32 v130, v130, v146, v148
	v_div_fixup_f32 v134, v130, v134, v0
	v_pk_mul_f32 v[134:135], v[138:139], v[134:135]
	v_lshlrev_b32_e32 v0, 16, v131
	v_and_b32_e32 v131, 0xffff0000, v131
	v_cvt_pk_bf16_f32 v130, v134, v135
	v_mul_f32_e32 v134, 0xbfb8aa3b, v0
	v_mul_f32_e32 v135, 0xbfb8aa3b, v131
	v_exp_f32_e32 v134, v134
	v_exp_f32_e32 v135, v135
	s_nop 0
	v_pk_add_f32 v[134:135], v[134:135], 1.0 op_sel_hi:[1,0]
	s_nop 0
	v_div_scale_f32 v138, s[16:17], v135, v135, v131
	v_rcp_f32_e32 v139, v138
	s_nop 0
	v_fma_f32 v146, -v138, v139, 1.0
	v_fmac_f32_e32 v139, v146, v139
	v_div_scale_f32 v146, vcc, v131, v135, v131
	v_mul_f32_e32 v147, v146, v139
	v_fma_f32 v148, -v138, v147, v146
	v_fmac_f32_e32 v147, v148, v139
	v_fma_f32 v138, -v138, v147, v146
	v_div_fmas_f32 v138, v138, v139, v147
	v_div_fixup_f32 v135, v138, v135, v131
	v_div_scale_f32 v131, s[16:17], v134, v134, v0
	v_rcp_f32_e32 v138, v131
	s_nop 0
	v_fma_f32 v139, -v131, v138, 1.0
	v_fmac_f32_e32 v138, v139, v138
	v_div_scale_f32 v139, vcc, v0, v134, v0
	v_mul_f32_e32 v146, v139, v138
	v_fma_f32 v147, -v131, v146, v139
	v_fmac_f32_e32 v146, v147, v138
	v_fma_f32 v131, -v131, v146, v139
	v_div_fmas_f32 v131, v131, v138, v146
	v_div_fixup_f32 v134, v131, v134, v0
	v_pk_mul_f32 v[134:135], v[140:141], v[134:135]
	v_lshlrev_b32_e32 v0, 16, v132
	v_and_b32_e32 v132, 0xffff0000, v132
	v_cvt_pk_bf16_f32 v131, v134, v135
	v_mul_f32_e32 v134, 0xbfb8aa3b, v0
	v_mul_f32_e32 v135, 0xbfb8aa3b, v132
	v_exp_f32_e32 v134, v134
	v_exp_f32_e32 v135, v135
	v_pk_mul_f32 v[140:141], v[2:3], v[142:143]
	v_pk_mul_f32 v[138:139], v[4:5], v[144:145]
	v_pk_add_f32 v[134:135], v[134:135], 1.0 op_sel_hi:[1,0]
	s_nop 0
	v_div_scale_f32 v142, s[16:17], v135, v135, v132
	v_rcp_f32_e32 v143, v142
	s_nop 0
	v_fma_f32 v144, -v142, v143, 1.0
	v_fmac_f32_e32 v143, v144, v143
	v_div_scale_f32 v144, vcc, v132, v135, v132
	v_mul_f32_e32 v145, v144, v143
	v_fma_f32 v146, -v142, v145, v144
	v_fmac_f32_e32 v145, v146, v143
	v_fma_f32 v142, -v142, v145, v144
	v_div_fmas_f32 v142, v142, v143, v145
	v_div_fixup_f32 v135, v142, v135, v132
	v_div_scale_f32 v132, s[16:17], v134, v134, v0
	v_rcp_f32_e32 v142, v132
	s_nop 0
	v_fma_f32 v143, -v132, v142, 1.0
	v_fmac_f32_e32 v142, v143, v142
	v_div_scale_f32 v143, vcc, v0, v134, v0
	v_mul_f32_e32 v144, v143, v142
	v_fma_f32 v145, -v132, v144, v143
	v_fmac_f32_e32 v144, v145, v142
	v_fma_f32 v132, -v132, v144, v143
	v_div_fmas_f32 v132, v132, v142, v144
	v_div_fixup_f32 v134, v132, v134, v0
	v_pk_mul_f32 v[134:135], v[140:141], v[134:135]
	v_lshlrev_b32_e32 v0, 16, v133
	v_and_b32_e32 v133, 0xffff0000, v133
	v_cvt_pk_bf16_f32 v132, v134, v135
	v_mul_f32_e32 v134, 0xbfb8aa3b, v0
	v_mul_f32_e32 v135, 0xbfb8aa3b, v133
	v_exp_f32_e32 v134, v134
	v_exp_f32_e32 v135, v135
	s_nop 0
	v_pk_add_f32 v[134:135], v[134:135], 1.0 op_sel_hi:[1,0]
	s_nop 0
	v_div_scale_f32 v140, s[16:17], v135, v135, v133
	v_rcp_f32_e32 v141, v140
	s_nop 0
	v_fma_f32 v142, -v140, v141, 1.0
	v_fmac_f32_e32 v141, v142, v141
	v_div_scale_f32 v142, vcc, v133, v135, v133
	v_mul_f32_e32 v143, v142, v141
	v_fma_f32 v144, -v140, v143, v142
	v_fmac_f32_e32 v143, v144, v141
	v_fma_f32 v140, -v140, v143, v142
	v_div_fmas_f32 v140, v140, v141, v143
	v_div_fixup_f32 v135, v140, v135, v133
	v_div_scale_f32 v133, s[16:17], v134, v134, v0
	v_rcp_f32_e32 v140, v133
	s_mov_b64 s[16:17], 0
	v_fma_f32 v141, -v133, v140, 1.0
	v_fmac_f32_e32 v140, v141, v140
	v_div_scale_f32 v141, vcc, v0, v134, v0
	v_mul_f32_e32 v142, v141, v140
	v_fma_f32 v143, -v133, v142, v141
	v_fmac_f32_e32 v142, v143, v140
	v_fma_f32 v133, -v133, v142, v141
	v_div_fmas_f32 v133, v133, v140, v142
	v_div_fixup_f32 v134, v133, v134, v0
	v_pk_mul_f32 v[134:135], v[138:139], v[134:135]
	s_nop 0
	v_cvt_pk_bf16_f32 v133, v134, v135
	global_store_dwordx4 v[136:137], v[130:133], off offset:256
;     DI void operator()(const f32x4 (&acc)[2][2][4][2], const Unit& u, int wr, int wc, int fr, int fq) const {
;     ...
;             for (int ai = 0; ai < 2; ++ai) {
;                 f32x4 rr[4][2][2];
;                 if (resb) {
;                     u32x4 rb[4][2];
; #pragma unroll
;                     for (int m = 0; m < 4; ++m)
; #pragma unroll
;                         for (int bj = 0; bj < 2; ++bj) rb[m][bj] = *(const u32x4*)(resb + (size_t)(row0 + ai * HALF + m * 16) * DM + col0 + bj * HALF);
; #pragma unroll
;                     for (int m = 0; m < 4; ++m)
; #pragma unroll
;                         for (int bj = 0; bj < 2; ++bj) { rr[m][bj][0] = (f32x4){bflo(rb[m][bj].x), bfhi(rb[m][bj].x), bflo(rb[m][bj].y), bfhi(rb[m][bj].y)};
;                             rr[m][bj][1] = (f32x4){bflo(rb[m][bj].z), bfhi(rb[m][bj].z), bflo(rb[m][bj].w), bfhi(rb[m][bj].w)}; }
.LBB0_377:
	s_andn2_b64 vcc, exec, s[16:17]
	s_cbranch_vccnz .LBB0_420
	v_readlane_b32 s16, v254, 62
	v_readlane_b32 s17, v254, 63
	v_add_u32_e32 v208, s12, v251
	s_and_b64 vcc, exec, s[16:17]
	v_readlane_b32 s16, v255, 43
	v_ashrrev_i32_e32 v207, 31, v206
	v_ashrrev_i32_e32 v209, 31, v208
	v_readlane_b32 s17, v255, 44
	v_lshlrev_b64 v[210:211], 12, v[208:209]
	v_or_b32_e32 v222, 16, v208
	v_lshl_add_u64 v[216:217], v[206:207], 1, s[16:17]
	v_or_b32_e32 v220, 32, v208
	v_or_b32_e32 v218, 48, v208
	s_cbranch_vccz .LBB0_382
	v_ashrrev_i32_e32 v223, 31, v222
	v_ashrrev_i32_e32 v221, 31, v220
	v_lshlrev_b64 v[224:225], 12, v[208:209]
	v_lshlrev_b64 v[138:139], 12, v[222:223]
	v_lshlrev_b64 v[146:147], 12, v[220:221]
	v_lshl_add_u64 v[134:135], v[216:217], 0, v[224:225]
	v_lshl_add_u64 v[142:143], v[216:217], 0, v[138:139]
	v_lshl_add_u64 v[146:147], v[216:217], 0, v[146:147]
	v_ashrrev_i32_e32 v219, 31, v218
	global_load_dwordx4 v[130:133], v[134:135], off
	s_nop 0
	global_load_dwordx4 v[134:137], v[134:135], off offset:256
	s_nop 0
	global_load_dwordx4 v[138:141], v[142:143], off
	s_nop 0
	global_load_dwordx4 v[142:145], v[142:143], off offset:256
	s_nop 0
	global_load_dwordx4 v[150:153], v[146:147], off
	global_load_dwordx4 v[158:161], v[146:147], off offset:256
	v_lshlrev_b64 v[146:147], 12, v[218:219]
	v_lshl_add_u64 v[146:147], v[216:217], 0, v[146:147]
	global_load_dwordx4 v[212:215], v[146:147], off
	global_load_dwordx4 v[240:243], v[146:147], off offset:256
	s_mov_b64 s[16:17], 0
	s_waitcnt vmcnt(0) lgkmcnt(0)
	v_lshlrev_b32_e32 v178, 16, v130
	v_and_b32_e32 v179, 0xffff0000, v130
	v_lshlrev_b32_e32 v180, 16, v131
	v_and_b32_e32 v181, 0xffff0000, v131
	v_lshlrev_b32_e32 v182, 16, v132
	v_and_b32_e32 v183, 0xffff0000, v132
	v_lshlrev_b32_e32 v184, 16, v133
	v_and_b32_e32 v185, 0xffff0000, v133
	v_lshlrev_b32_e32 v186, 16, v134
	v_and_b32_e32 v187, 0xffff0000, v134
	v_lshlrev_b32_e32 v188, 16, v135
	v_and_b32_e32 v189, 0xffff0000, v135
	v_lshlrev_b32_e32 v190, 16, v136
	v_and_b32_e32 v191, 0xffff0000, v136
	v_lshlrev_b32_e32 v192, 16, v137
	v_and_b32_e32 v193, 0xffff0000, v137
	v_lshlrev_b32_e32 v162, 16, v138
	v_and_b32_e32 v163, 0xffff0000, v138
	v_lshlrev_b32_e32 v164, 16, v139
	v_and_b32_e32 v165, 0xffff0000, v139
	v_lshlrev_b32_e32 v166, 16, v140
	v_and_b32_e32 v167, 0xffff0000, v140
	v_lshlrev_b32_e32 v168, 16, v141
	v_and_b32_e32 v169, 0xffff0000, v141
	v_lshlrev_b32_e32 v170, 16, v142
	v_and_b32_e32 v171, 0xffff0000, v142
	v_lshlrev_b32_e32 v172, 16, v143
	v_and_b32_e32 v173, 0xffff0000, v143
	v_lshlrev_b32_e32 v174, 16, v144
	v_and_b32_e32 v175, 0xffff0000, v144
	v_lshlrev_b32_e32 v176, 16, v145
	v_and_b32_e32 v177, 0xffff0000, v145
	v_lshlrev_b32_e32 v146, 16, v150
	v_and_b32_e32 v147, 0xffff0000, v150
	v_lshlrev_b32_e32 v148, 16, v151
	v_and_b32_e32 v149, 0xffff0000, v151
	v_lshlrev_b32_e32 v150, 16, v152
	v_and_b32_e32 v151, 0xffff0000, v152
	v_lshlrev_b32_e32 v152, 16, v153
	v_and_b32_e32 v153, 0xffff0000, v153
	v_lshlrev_b32_e32 v154, 16, v158
	v_and_b32_e32 v155, 0xffff0000, v158
	v_lshlrev_b32_e32 v156, 16, v159
	v_and_b32_e32 v157, 0xffff0000, v159
	v_lshlrev_b32_e32 v158, 16, v160
	v_and_b32_e32 v159, 0xffff0000, v160
	v_lshlrev_b32_e32 v160, 16, v161
	v_and_b32_e32 v161, 0xffff0000, v161
	v_lshlrev_b32_e32 v130, 16, v212
	v_and_b32_e32 v131, 0xffff0000, v212
	v_lshlrev_b32_e32 v132, 16, v213
	v_and_b32_e32 v133, 0xffff0000, v213
	v_lshlrev_b32_e32 v134, 16, v214
	v_and_b32_e32 v135, 0xffff0000, v214
	v_lshlrev_b32_e32 v136, 16, v215
	v_and_b32_e32 v137, 0xffff0000, v215
	v_lshlrev_b32_e32 v138, 16, v240
	v_and_b32_e32 v139, 0xffff0000, v240
	v_lshlrev_b32_e32 v140, 16, v241
	v_and_b32_e32 v141, 0xffff0000, v241
	v_lshlrev_b32_e32 v142, 16, v242
	v_and_b32_e32 v143, 0xffff0000, v242
	v_lshlrev_b32_e32 v144, 16, v243
	v_and_b32_e32 v145, 0xffff0000, v243
	s_branch .LBB0_383

; DI unsigned pk2(float lo, float hi) { f32x2_t f = {lo, hi}; bf16x2_t v = __builtin_convertvector(f, bf16x2_t); return __builtin_bit_cast(unsigned, v); }
;     DI void operator()(const f32x4 (&acc)[2][2][4][2], const Unit& u, int wr, int wc, int fr, int fq) const {
;     ...
;                 for (int m = 0; m < 4; ++m) { const int row = row0 + ai * HALF + m * 16; const size_t ro = (size_t)row * DM + col0; float ssq = 0.f;
; #pragma unroll
;                     for (int bj = 0; bj < 2; ++bj) { const f32x4 v0 = acc[ai][bj][m][0] + rr[m][bj][0], v1 = acc[ai][bj][m][1] + rr[m][bj][1];
;                         if (xr_out) { u32x4 w; w.x = pk2(v0[0], v0[1]); w.y = pk2(v0[2], v0[3]); w.z = pk2(v1[0], v1[1]); w.w = pk2(v1[2], v1[3]); *(u32x4*)(xr_out + ro + bj * HALF) = w; }
;                         else { *(f32x4*)(out + ro + bj * HALF) = v0; *(f32x4*)(out + ro + bj * HALF + 4) = v1; }
;                         ssq += ((v0[0] * v0[0] + v0[1] * v0[1]) + (v0[2] * v0[2] + v0[3] * v0[3])) + ((v1[0] * v1[0] + v1[1] * v1[1]) + (v1[2] * v1[2] + v1[3] * v1[3])); }
;                     if (ss_out) { ssq += __shfl_xor(ssq, 16); ssq += __shfl_xor(ssq, 32); if (fq == 0) atomicAdd(ss_out + row, ssq); } }
.LBB0_385:
	v_readlane_b32 s16, v255, 8
	s_waitcnt vmcnt(0)
	v_pk_add_f32 v[226:227], v[126:127], v[178:179]
	v_pk_add_f32 v[178:179], v[124:125], v[184:185]
	v_lshl_add_u64 v[184:185], s[66:67], 0, v[224:225]
	v_readlane_b32 s17, v255, 9
	v_pk_add_f32 v[180:181], v[128:129], v[180:181]
	v_pk_add_f32 v[182:183], v[122:123], v[182:183]
	v_lshl_add_u64 v[244:245], v[206:207], 1, v[184:185]
	v_pk_add_f32 v[188:189], v[120:121], v[188:189]
	v_pk_add_f32 v[224:225], v[118:119], v[186:187]
	v_pk_add_f32 v[184:185], v[116:117], v[192:193]
	v_pk_add_f32 v[186:187], v[114:115], v[190:191]
	v_cndmask_b32_e64 v0, 0, 1, s[16:17]
	v_cvt_pk_bf16_f32 v240, v226, v227
	v_cvt_pk_bf16_f32 v241, v180, v181
	v_cvt_pk_bf16_f32 v242, v182, v183
	v_cvt_pk_bf16_f32 v243, v178, v179
	v_cvt_pk_bf16_f32 v190, v224, v225
	v_cvt_pk_bf16_f32 v191, v188, v189
	v_cvt_pk_bf16_f32 v192, v186, v187
	v_cvt_pk_bf16_f32 v193, v184, v185
	v_cmp_ne_u32_e64 s[44:45], 1, v0
	s_andn2_b64 vcc, exec, s[16:17]
	global_store_dwordx4 v[244:245], v[240:243], off
	global_store_dwordx4 v[244:245], v[190:193], off offset:256
	s_cbranch_vccnz .LBB0_389
	v_mul_f32_e32 v181, v181, v181
	v_mul_f32_e32 v0, v227, v227
	v_fmac_f32_e32 v181, v180, v180
	v_mul_f32_e32 v180, v183, v183
	v_mul_f32_e32 v179, v179, v179
	v_fmac_f32_e32 v0, v226, v226
	v_fmac_f32_e32 v180, v182, v182
	v_fmac_f32_e32 v179, v178, v178
	v_add_f32_e32 v0, v0, v181
	v_add_f32_e32 v178, v180, v179
	v_add_f32_e32 v0, v178, v0
	v_mul_f32_e32 v178, v225, v225
	v_mul_f32_e32 v179, v189, v189
	v_fmac_f32_e32 v178, v224, v224
	v_fmac_f32_e32 v179, v188, v188
	v_add_f32_e32 v178, v178, v179
	v_mul_f32_e32 v179, v187, v187
	v_mul_f32_e32 v180, v185, v185
	v_fmac_f32_e32 v179, v186, v186
	v_fmac_f32_e32 v180, v184, v184
	v_add_f32_e32 v179, v179, v180
	v_add_f32_e32 v178, v179, v178
	v_and_b32_e32 v179, 64, v231
	v_add_f32_e32 v0, v178, v0
	v_xor_b32_e32 v178, 16, v231
	v_add_u32_e32 v179, 64, v179
	v_cmp_lt_i32_e32 vcc, v178, v179
	s_nop 1
	v_cndmask_b32_e32 v178, v231, v178, vcc
	v_lshlrev_b32_e32 v178, 2, v178
	ds_bpermute_b32 v178, v178, v0
	s_waitcnt lgkmcnt(0)
	v_add_f32_e32 v0, v0, v178
	v_xor_b32_e32 v178, 32, v231
	v_cmp_lt_i32_e32 vcc, v178, v179
	s_nop 1
	v_cndmask_b32_e32 v178, v231, v178, vcc
	v_lshlrev_b32_e32 v178, 2, v178
	ds_bpermute_b32 v178, v178, v0
	s_and_saveexec_b64 s[16:17], s[36:37]
	s_cbranch_execz .LBB0_388
	v_lshl_add_u64 v[180:181], v[208:209], 2, s[74:75]
	s_waitcnt lgkmcnt(0)
	v_add_f32_e32 v0, v0, v178
	global_atomic_add_f32 v[180:181], v0, off

; DI unsigned pk2(float lo, float hi) { f32x2_t f = {lo, hi}; bf16x2_t v = __builtin_convertvector(f, bf16x2_t); return __builtin_bit_cast(unsigned, v); }
;     DI void operator()(const f32x4 (&acc)[2][2][4][2], const Unit& u, int wr, int wc, int fr, int fq) const {
;     ...
;                 for (int m = 0; m < 4; ++m) { const int row = row0 + ai * HALF + m * 16; const size_t ro = (size_t)row * DM + col0; float ssq = 0.f;
; #pragma unroll
;                     for (int bj = 0; bj < 2; ++bj) { const f32x4 v0 = acc[ai][bj][m][0] + rr[m][bj][0], v1 = acc[ai][bj][m][1] + rr[m][bj][1];
;                         if (xr_out) { u32x4 w; w.x = pk2(v0[0], v0[1]); w.y = pk2(v0[2], v0[3]); w.z = pk2(v1[0], v1[1]); w.w = pk2(v1[2], v1[3]); *(u32x4*)(xr_out + ro + bj * HALF) = w; }
;                         else { *(f32x4*)(out + ro + bj * HALF) = v0; *(f32x4*)(out + ro + bj * HALF + 4) = v1; }
;                         ssq += ((v0[0] * v0[0] + v0[1] * v0[1]) + (v0[2] * v0[2] + v0[3] * v0[3])) + ((v1[0] * v1[0] + v1[1] * v1[1]) + (v1[2] * v1[2] + v1[3] * v1[3])); }
;                     if (ss_out) { ssq += __shfl_xor(ssq, 16); ssq += __shfl_xor(ssq, 32); if (fq == 0) atomicAdd(ss_out + row, ssq); } }
.LBB0_389:
	v_ashrrev_i32_e32 v223, 31, v222
	s_waitcnt lgkmcnt(0)
	v_pk_add_f32 v[178:179], v[110:111], v[162:163]
	v_pk_add_f32 v[162:163], v[108:109], v[168:169]
	v_lshlrev_b64 v[168:169], 12, v[222:223]
	v_pk_add_f32 v[164:165], v[112:113], v[164:165]
	v_pk_add_f32 v[166:167], v[106:107], v[166:167]
	v_lshl_add_u64 v[168:169], s[66:67], 0, v[168:169]
	v_cvt_pk_bf16_f32 v180, v178, v179
	v_cvt_pk_bf16_f32 v181, v164, v165
	v_cvt_pk_bf16_f32 v182, v166, v167
	v_cvt_pk_bf16_f32 v183, v162, v163
	v_lshl_add_u64 v[184:185], v[206:207], 1, v[168:169]
	global_store_dwordx4 v[184:185], v[180:183], off
	v_pk_add_f32 v[172:173], v[104:105], v[172:173]
	v_pk_add_f32 v[168:169], v[100:101], v[176:177]
	v_pk_add_f32 v[180:181], v[102:103], v[170:171]
	v_pk_add_f32 v[170:171], v[98:99], v[174:175]
	v_cvt_pk_bf16_f32 v174, v180, v181
	v_cvt_pk_bf16_f32 v175, v172, v173
	v_cvt_pk_bf16_f32 v176, v170, v171
	v_cvt_pk_bf16_f32 v177, v168, v169
	s_and_b64 vcc, exec, s[44:45]
	global_store_dwordx4 v[184:185], v[174:177], off offset:256
	s_cbranch_vccnz .LBB0_393
	v_mul_f32_e32 v165, v165, v165
	v_mul_f32_e32 v0, v179, v179
	v_fmac_f32_e32 v165, v164, v164
	v_mul_f32_e32 v164, v167, v167
	v_mul_f32_e32 v163, v163, v163
	v_fmac_f32_e32 v0, v178, v178
	v_fmac_f32_e32 v164, v166, v166
	v_fmac_f32_e32 v163, v162, v162
	v_add_f32_e32 v0, v0, v165
	v_add_f32_e32 v162, v164, v163
	v_add_f32_e32 v0, v162, v0
	v_mul_f32_e32 v162, v181, v181
	v_mul_f32_e32 v163, v173, v173
	v_fmac_f32_e32 v162, v180, v180
	v_fmac_f32_e32 v163, v172, v172
	v_add_f32_e32 v162, v162, v163
	v_mul_f32_e32 v163, v171, v171
	v_mul_f32_e32 v164, v169, v169
	v_fmac_f32_e32 v163, v170, v170
	v_fmac_f32_e32 v164, v168, v168
	v_add_f32_e32 v163, v163, v164
	v_add_f32_e32 v162, v163, v162
	v_and_b32_e32 v163, 64, v231
	v_add_f32_e32 v0, v162, v0
	v_xor_b32_e32 v162, 16, v231
	v_add_u32_e32 v163, 64, v163
	v_cmp_lt_i32_e32 vcc, v162, v163
	s_nop 1
	v_cndmask_b32_e32 v162, v231, v162, vcc
	v_lshlrev_b32_e32 v162, 2, v162
	ds_bpermute_b32 v162, v162, v0
	s_waitcnt lgkmcnt(0)
	v_add_f32_e32 v0, v0, v162
	v_xor_b32_e32 v162, 32, v231
	v_cmp_lt_i32_e32 vcc, v162, v163
	s_nop 1
	v_cndmask_b32_e32 v162, v231, v162, vcc
	v_lshlrev_b32_e32 v162, 2, v162
	ds_bpermute_b32 v162, v162, v0
	s_and_saveexec_b64 s[16:17], s[36:37]
	s_cbranch_execz .LBB0_392
	v_lshl_add_u64 v[164:165], v[208:209], 2, s[74:75]
	s_waitcnt lgkmcnt(0)
	v_add_f32_e32 v0, v0, v162
	global_atomic_add_f32 v[164:165], v0, off offset:64

; DI unsigned pk2(float lo, float hi) { f32x2_t f = {lo, hi}; bf16x2_t v = __builtin_convertvector(f, bf16x2_t); return __builtin_bit_cast(unsigned, v); }
;     DI void operator()(const f32x4 (&acc)[2][2][4][2], const Unit& u, int wr, int wc, int fr, int fq) const {
;     ...
;                 for (int m = 0; m < 4; ++m) { const int row = row0 + ai * HALF + m * 16; const size_t ro = (size_t)row * DM + col0; float ssq = 0.f;
; #pragma unroll
;                     for (int bj = 0; bj < 2; ++bj) { const f32x4 v0 = acc[ai][bj][m][0] + rr[m][bj][0], v1 = acc[ai][bj][m][1] + rr[m][bj][1];
;                         if (xr_out) { u32x4 w; w.x = pk2(v0[0], v0[1]); w.y = pk2(v0[2], v0[3]); w.z = pk2(v1[0], v1[1]); w.w = pk2(v1[2], v1[3]); *(u32x4*)(xr_out + ro + bj * HALF) = w; }
;                         else { *(f32x4*)(out + ro + bj * HALF) = v0; *(f32x4*)(out + ro + bj * HALF + 4) = v1; }
;                         ssq += ((v0[0] * v0[0] + v0[1] * v0[1]) + (v0[2] * v0[2] + v0[3] * v0[3])) + ((v1[0] * v1[0] + v1[1] * v1[1]) + (v1[2] * v1[2] + v1[3] * v1[3])); }
;                     if (ss_out) { ssq += __shfl_xor(ssq, 16); ssq += __shfl_xor(ssq, 32); if (fq == 0) atomicAdd(ss_out + row, ssq); } }
.LBB0_393:
	v_ashrrev_i32_e32 v221, 31, v220
	s_waitcnt lgkmcnt(0)
	v_pk_add_f32 v[162:163], v[94:95], v[146:147]
	v_pk_add_f32 v[146:147], v[92:93], v[152:153]
	v_lshlrev_b64 v[152:153], 12, v[220:221]
	v_pk_add_f32 v[148:149], v[96:97], v[148:149]
	v_pk_add_f32 v[150:151], v[90:91], v[150:151]
	v_lshl_add_u64 v[152:153], s[66:67], 0, v[152:153]
	v_cvt_pk_bf16_f32 v164, v162, v163
	v_cvt_pk_bf16_f32 v165, v148, v149
	v_cvt_pk_bf16_f32 v166, v150, v151
	v_cvt_pk_bf16_f32 v167, v146, v147
	v_lshl_add_u64 v[168:169], v[206:207], 1, v[152:153]
	global_store_dwordx4 v[168:169], v[164:167], off
	v_pk_add_f32 v[156:157], v[88:89], v[156:157]
	v_pk_add_f32 v[152:153], v[84:85], v[160:161]
	v_pk_add_f32 v[164:165], v[86:87], v[154:155]
	v_pk_add_f32 v[154:155], v[82:83], v[158:159]
	v_cvt_pk_bf16_f32 v158, v164, v165
	v_cvt_pk_bf16_f32 v159, v156, v157
	v_cvt_pk_bf16_f32 v160, v154, v155
	v_cvt_pk_bf16_f32 v161, v152, v153
	s_and_b64 vcc, exec, s[44:45]
	global_store_dwordx4 v[168:169], v[158:161], off offset:256
	s_cbranch_vccnz .LBB0_397
	v_mul_f32_e32 v149, v149, v149
	v_mul_f32_e32 v0, v163, v163
	v_fmac_f32_e32 v149, v148, v148
	v_mul_f32_e32 v148, v151, v151
	v_mul_f32_e32 v147, v147, v147
	v_fmac_f32_e32 v0, v162, v162
	v_fmac_f32_e32 v148, v150, v150
	v_fmac_f32_e32 v147, v146, v146
	v_add_f32_e32 v0, v0, v149
	v_add_f32_e32 v146, v148, v147
	v_add_f32_e32 v0, v146, v0
	v_mul_f32_e32 v146, v165, v165
	v_mul_f32_e32 v147, v157, v157
	v_fmac_f32_e32 v146, v164, v164
	v_fmac_f32_e32 v147, v156, v156
	v_add_f32_e32 v146, v146, v147
	v_mul_f32_e32 v147, v155, v155
	v_mul_f32_e32 v148, v153, v153
	v_fmac_f32_e32 v147, v154, v154
	v_fmac_f32_e32 v148, v152, v152
	v_add_f32_e32 v147, v147, v148
	v_add_f32_e32 v146, v147, v146
	v_and_b32_e32 v147, 64, v231
	v_add_f32_e32 v0, v146, v0
	v_xor_b32_e32 v146, 16, v231
	v_add_u32_e32 v147, 64, v147
	v_cmp_lt_i32_e32 vcc, v146, v147
	s_nop 1
	v_cndmask_b32_e32 v146, v231, v146, vcc
	v_lshlrev_b32_e32 v146, 2, v146
	ds_bpermute_b32 v146, v146, v0
	s_waitcnt lgkmcnt(0)
	v_add_f32_e32 v0, v0, v146
	v_xor_b32_e32 v146, 32, v231
	v_cmp_lt_i32_e32 vcc, v146, v147
	s_nop 1
	v_cndmask_b32_e32 v146, v231, v146, vcc
	v_lshlrev_b32_e32 v146, 2, v146
	ds_bpermute_b32 v146, v146, v0
	s_and_saveexec_b64 s[16:17], s[36:37]
	s_cbranch_execz .LBB0_396
	v_lshl_add_u64 v[148:149], v[208:209], 2, s[74:75]
	s_waitcnt lgkmcnt(0)
	v_add_f32_e32 v0, v0, v146
	global_atomic_add_f32 v[148:149], v0, off offset:128

; DI unsigned pk2(float lo, float hi) { f32x2_t f = {lo, hi}; bf16x2_t v = __builtin_convertvector(f, bf16x2_t); return __builtin_bit_cast(unsigned, v); }
;     DI void operator()(const f32x4 (&acc)[2][2][4][2], const Unit& u, int wr, int wc, int fr, int fq) const {
;     ...
;                 for (int m = 0; m < 4; ++m) { const int row = row0 + ai * HALF + m * 16; const size_t ro = (size_t)row * DM + col0; float ssq = 0.f;
; #pragma unroll
;                     for (int bj = 0; bj < 2; ++bj) { const f32x4 v0 = acc[ai][bj][m][0] + rr[m][bj][0], v1 = acc[ai][bj][m][1] + rr[m][bj][1];
;                         if (xr_out) { u32x4 w; w.x = pk2(v0[0], v0[1]); w.y = pk2(v0[2], v0[3]); w.z = pk2(v1[0], v1[1]); w.w = pk2(v1[2], v1[3]); *(u32x4*)(xr_out + ro + bj * HALF) = w; }
;                         else { *(f32x4*)(out + ro + bj * HALF) = v0; *(f32x4*)(out + ro + bj * HALF + 4) = v1; }
;                         ssq += ((v0[0] * v0[0] + v0[1] * v0[1]) + (v0[2] * v0[2] + v0[3] * v0[3])) + ((v1[0] * v1[0] + v1[1] * v1[1]) + (v1[2] * v1[2] + v1[3] * v1[3])); }
;                     if (ss_out) { ssq += __shfl_xor(ssq, 16); ssq += __shfl_xor(ssq, 32); if (fq == 0) atomicAdd(ss_out + row, ssq); } }
.LBB0_397:
	v_ashrrev_i32_e32 v219, 31, v218
	s_waitcnt lgkmcnt(0)
	v_pk_add_f32 v[146:147], v[78:79], v[130:131]
	v_pk_add_f32 v[130:131], v[76:77], v[136:137]
	v_lshlrev_b64 v[136:137], 12, v[218:219]
	v_pk_add_f32 v[132:133], v[80:81], v[132:133]
	v_pk_add_f32 v[134:135], v[74:75], v[134:135]
	v_lshl_add_u64 v[136:137], s[66:67], 0, v[136:137]
	v_cvt_pk_bf16_f32 v148, v146, v147
	v_cvt_pk_bf16_f32 v149, v132, v133
	v_cvt_pk_bf16_f32 v150, v134, v135
	v_cvt_pk_bf16_f32 v151, v130, v131
	v_lshl_add_u64 v[152:153], v[206:207], 1, v[136:137]
	global_store_dwordx4 v[152:153], v[148:151], off
	v_pk_add_f32 v[140:141], v[72:73], v[140:141]
	v_pk_add_f32 v[136:137], v[68:69], v[144:145]
	v_pk_add_f32 v[148:149], v[70:71], v[138:139]
	v_pk_add_f32 v[138:139], v[66:67], v[142:143]
	v_cvt_pk_bf16_f32 v142, v148, v149
	v_cvt_pk_bf16_f32 v143, v140, v141
	v_cvt_pk_bf16_f32 v144, v138, v139
	v_cvt_pk_bf16_f32 v145, v136, v137
	s_and_b64 vcc, exec, s[44:45]
	global_store_dwordx4 v[152:153], v[142:145], off offset:256
	s_cbranch_vccnz .LBB0_401
	v_mul_f32_e32 v133, v133, v133
	v_mul_f32_e32 v0, v147, v147
	v_fmac_f32_e32 v133, v132, v132
	v_mul_f32_e32 v132, v135, v135
	v_mul_f32_e32 v131, v131, v131
	v_fmac_f32_e32 v0, v146, v146
	v_fmac_f32_e32 v132, v134, v134
	v_fmac_f32_e32 v131, v130, v130
	v_add_f32_e32 v0, v0, v133
	v_add_f32_e32 v130, v132, v131
	v_add_f32_e32 v0, v130, v0
	v_mul_f32_e32 v130, v149, v149
	v_mul_f32_e32 v131, v141, v141
	v_fmac_f32_e32 v130, v148, v148
	v_fmac_f32_e32 v131, v140, v140
	v_add_f32_e32 v130, v130, v131
	v_mul_f32_e32 v131, v139, v139
	v_mul_f32_e32 v132, v137, v137
	v_fmac_f32_e32 v131, v138, v138
	v_fmac_f32_e32 v132, v136, v136
	v_add_f32_e32 v131, v131, v132
	v_add_f32_e32 v130, v131, v130
	v_and_b32_e32 v131, 64, v231
	v_add_f32_e32 v0, v130, v0
	v_xor_b32_e32 v130, 16, v231
	v_add_u32_e32 v131, 64, v131
	v_cmp_lt_i32_e32 vcc, v130, v131
	s_nop 1
	v_cndmask_b32_e32 v130, v231, v130, vcc
	v_lshlrev_b32_e32 v130, 2, v130
	ds_bpermute_b32 v130, v130, v0
	s_waitcnt lgkmcnt(0)
	v_add_f32_e32 v0, v0, v130
	v_xor_b32_e32 v130, 32, v231
	v_cmp_lt_i32_e32 vcc, v130, v131
	s_nop 1
	v_cndmask_b32_e32 v130, v231, v130, vcc
	v_lshlrev_b32_e32 v130, 2, v130
	ds_bpermute_b32 v130, v130, v0
	s_and_saveexec_b64 s[16:17], s[36:37]
	s_cbranch_execz .LBB0_400
	v_lshl_add_u64 v[132:133], v[208:209], 2, s[74:75]
	s_waitcnt lgkmcnt(0)
	v_add_f32_e32 v0, v0, v130
	global_atomic_add_f32 v[132:133], v0, off offset:192

;     DI void operator()(const f32x4 (&acc)[2][2][4][2], const Unit& u, int wr, int wc, int fr, int fq) const {
;     ...
;             for (int ai = 0; ai < 2; ++ai) {
;                 f32x4 rr[4][2][2];
;                 if (resb) {
;                     u32x4 rb[4][2];
; #pragma unroll
;                     for (int m = 0; m < 4; ++m)
; #pragma unroll
;                         for (int bj = 0; bj < 2; ++bj) rb[m][bj] = *(const u32x4*)(resb + (size_t)(row0 + ai * HALF + m * 16) * DM + col0 + bj * HALF);
; #pragma unroll
;                     for (int m = 0; m < 4; ++m)
; #pragma unroll
;                         for (int bj = 0; bj < 2; ++bj) { rr[m][bj][0] = (f32x4){bflo(rb[m][bj].x), bfhi(rb[m][bj].x), bflo(rb[m][bj].y), bfhi(rb[m][bj].y)};
;                             rr[m][bj][1] = (f32x4){bflo(rb[m][bj].z), bfhi(rb[m][bj].z), bflo(rb[m][bj].w), bfhi(rb[m][bj].w)}; }
.LBB0_401:
	v_add_u32_e32 v222, 0x80, v208
	v_readlane_b32 s16, v254, 62
	v_ashrrev_i32_e32 v223, 31, v222
	v_readlane_b32 s17, v254, 63
	s_andn2_b64 vcc, exec, s[16:17]
	v_lshlrev_b64 v[218:219], 12, v[222:223]
	s_cbranch_vccnz .LBB0_474
	v_lshl_add_u64 v[146:147], v[216:217], 0, v[210:211]
	v_add_co_u32_e32 v138, vcc, 0x90000, v146
	v_lshlrev_b64 v[220:221], 12, v[222:223]
	s_nop 0
	v_addc_co_u32_e32 v139, vcc, 0, v147, vcc
	s_mov_b64 s[16:17], 0x90000
	v_add_co_u32_e32 v148, vcc, 0xa0000, v146
	v_lshl_add_u64 v[134:135], v[216:217], 0, v[220:221]
	v_lshl_add_u64 v[142:143], v[146:147], 0, s[16:17]
	v_addc_co_u32_e32 v149, vcc, 0, v147, vcc
	s_mov_b64 s[16:17], 0xa0000
	s_waitcnt lgkmcnt(0)
	global_load_dwordx4 v[130:133], v[134:135], off
	s_nop 0
	global_load_dwordx4 v[134:137], v[134:135], off offset:256
	s_waitcnt vmcnt(0) lgkmcnt(0)
	v_lshlrev_b32_e32 v178, 16, v130
	global_load_dwordx4 v[150:153], v[148:149], off
	v_lshl_add_u64 v[148:149], v[146:147], 0, s[16:17]
	global_load_dwordx4 v[158:161], v[148:149], off offset:256
	v_add_co_u32_e32 v148, vcc, 0xb0000, v146
	s_mov_b64 s[16:17], 0xb0000
	s_nop 0
	v_addc_co_u32_e32 v149, vcc, 0, v147, vcc
	v_lshl_add_u64 v[146:147], v[146:147], 0, s[16:17]
	global_load_dwordx4 v[138:141], v[138:139], off
	v_and_b32_e32 v179, 0xffff0000, v130
	global_load_dwordx4 v[142:145], v[142:143], off offset:256
	v_lshlrev_b32_e32 v180, 16, v131
	global_load_dwordx4 v[224:227], v[148:149], off
	global_load_dwordx4 v[240:243], v[146:147], off offset:256
	v_and_b32_e32 v181, 0xffff0000, v131
	v_lshlrev_b32_e32 v182, 16, v132
	v_and_b32_e32 v183, 0xffff0000, v132
	v_lshlrev_b32_e32 v184, 16, v133
	v_and_b32_e32 v185, 0xffff0000, v133
	v_lshlrev_b32_e32 v186, 16, v134
	v_and_b32_e32 v187, 0xffff0000, v134
	v_lshlrev_b32_e32 v188, 16, v135
	v_and_b32_e32 v189, 0xffff0000, v135
	v_lshlrev_b32_e32 v190, 16, v136
	v_and_b32_e32 v191, 0xffff0000, v136
	v_lshlrev_b32_e32 v192, 16, v137
	v_and_b32_e32 v193, 0xffff0000, v137
	s_waitcnt vmcnt(0) lgkmcnt(0)
	v_lshlrev_b32_e32 v146, 16, v150
	v_and_b32_e32 v147, 0xffff0000, v150
	v_lshlrev_b32_e32 v148, 16, v151
	v_and_b32_e32 v149, 0xffff0000, v151
	v_lshlrev_b32_e32 v150, 16, v152
	v_and_b32_e32 v151, 0xffff0000, v152
	v_lshlrev_b32_e32 v152, 16, v153
	v_and_b32_e32 v153, 0xffff0000, v153
	v_lshlrev_b32_e32 v154, 16, v158
	v_lshlrev_b32_e32 v162, 16, v138
	v_and_b32_e32 v163, 0xffff0000, v138
	v_lshlrev_b32_e32 v164, 16, v139
	v_and_b32_e32 v165, 0xffff0000, v139
	v_lshlrev_b32_e32 v166, 16, v140
	v_and_b32_e32 v167, 0xffff0000, v140
	v_lshlrev_b32_e32 v168, 16, v141
	v_and_b32_e32 v169, 0xffff0000, v141
	v_lshlrev_b32_e32 v170, 16, v142
	v_and_b32_e32 v171, 0xffff0000, v142
	v_lshlrev_b32_e32 v172, 16, v143
	v_and_b32_e32 v173, 0xffff0000, v143
	v_lshlrev_b32_e32 v174, 16, v144
	v_and_b32_e32 v175, 0xffff0000, v144
	v_lshlrev_b32_e32 v176, 16, v145
	v_and_b32_e32 v177, 0xffff0000, v145
	v_and_b32_e32 v155, 0xffff0000, v158
	v_lshlrev_b32_e32 v156, 16, v159
	v_and_b32_e32 v157, 0xffff0000, v159
	v_lshlrev_b32_e32 v158, 16, v160
	v_and_b32_e32 v159, 0xffff0000, v160
	v_lshlrev_b32_e32 v160, 16, v161
	v_and_b32_e32 v161, 0xffff0000, v161
	v_lshlrev_b32_e32 v130, 16, v224
	v_and_b32_e32 v131, 0xffff0000, v224
	v_lshlrev_b32_e32 v132, 16, v225
	v_and_b32_e32 v133, 0xffff0000, v225
	v_lshlrev_b32_e32 v134, 16, v226
	v_and_b32_e32 v135, 0xffff0000, v226
	v_lshlrev_b32_e32 v136, 16, v227
	v_and_b32_e32 v137, 0xffff0000, v227
	v_lshlrev_b32_e32 v138, 16, v240
	v_and_b32_e32 v139, 0xffff0000, v240
	v_lshlrev_b32_e32 v140, 16, v241
	v_and_b32_e32 v141, 0xffff0000, v241
	v_lshlrev_b32_e32 v142, 16, v242
	v_and_b32_e32 v143, 0xffff0000, v242
	v_lshlrev_b32_e32 v144, 16, v243
	v_and_b32_e32 v145, 0xffff0000, v243
	s_cbranch_execnz .LBB0_404

; DI unsigned pk2(float lo, float hi) { f32x2_t f = {lo, hi}; bf16x2_t v = __builtin_convertvector(f, bf16x2_t); return __builtin_bit_cast(unsigned, v); }
;     DI void operator()(const f32x4 (&acc)[2][2][4][2], const Unit& u, int wr, int wc, int fr, int fq) const {
;     ...
;                 for (int m = 0; m < 4; ++m) { const int row = row0 + ai * HALF + m * 16; const size_t ro = (size_t)row * DM + col0; float ssq = 0.f;
; #pragma unroll
;                     for (int bj = 0; bj < 2; ++bj) { const f32x4 v0 = acc[ai][bj][m][0] + rr[m][bj][0], v1 = acc[ai][bj][m][1] + rr[m][bj][1];
;                         if (xr_out) { u32x4 w; w.x = pk2(v0[0], v0[1]); w.y = pk2(v0[2], v0[3]); w.z = pk2(v1[0], v1[1]); w.w = pk2(v1[2], v1[3]); *(u32x4*)(xr_out + ro + bj * HALF) = w; }
;                         else { *(f32x4*)(out + ro + bj * HALF) = v0; *(f32x4*)(out + ro + bj * HALF + 4) = v1; }
;                         ssq += ((v0[0] * v0[0] + v0[1] * v0[1]) + (v0[2] * v0[2] + v0[3] * v0[3])) + ((v1[0] * v1[0] + v1[1] * v1[1]) + (v1[2] * v1[2] + v1[3] * v1[3])); }
;                     if (ss_out) { ssq += __shfl_xor(ssq, 16); ssq += __shfl_xor(ssq, 32); if (fq == 0) atomicAdd(ss_out + row, ssq); } }
.LBB0_404:
	s_waitcnt vmcnt(0)
	v_pk_add_f32 v[180:181], v[64:65], v[180:181]
	v_pk_add_f32 v[212:213], v[62:63], v[178:179]
	v_pk_add_f32 v[178:179], v[60:61], v[184:185]
	v_pk_add_f32 v[182:183], v[58:59], v[182:183]
	v_lshl_add_u64 v[184:185], s[66:67], 0, v[220:221]
	v_cvt_pk_bf16_f32 v214, v212, v213
	v_cvt_pk_bf16_f32 v215, v180, v181
	v_cvt_pk_bf16_f32 v216, v182, v183
	v_cvt_pk_bf16_f32 v217, v178, v179
	v_lshl_add_u64 v[218:219], v[206:207], 1, v[184:185]
	global_store_dwordx4 v[218:219], v[214:217], off
	v_pk_add_f32 v[188:189], v[56:57], v[188:189]
	v_pk_add_f32 v[184:185], v[52:53], v[192:193]
	v_pk_add_f32 v[214:215], v[54:55], v[186:187]
	v_pk_add_f32 v[186:187], v[50:51], v[190:191]
	v_cvt_pk_bf16_f32 v190, v214, v215
	v_cvt_pk_bf16_f32 v191, v188, v189
	v_cvt_pk_bf16_f32 v192, v186, v187
	v_cvt_pk_bf16_f32 v193, v184, v185
	s_and_b64 vcc, exec, s[44:45]
	global_store_dwordx4 v[218:219], v[190:193], off offset:256
	s_cbranch_vccnz .LBB0_408
	v_mul_f32_e32 v181, v181, v181
	v_mul_f32_e32 v0, v213, v213
	v_fmac_f32_e32 v181, v180, v180
	v_mul_f32_e32 v180, v183, v183
	v_mul_f32_e32 v179, v179, v179
	v_fmac_f32_e32 v0, v212, v212
	v_fmac_f32_e32 v180, v182, v182
	v_fmac_f32_e32 v179, v178, v178
	v_add_f32_e32 v0, v0, v181
	v_add_f32_e32 v178, v180, v179
	v_add_f32_e32 v0, v178, v0
	v_mul_f32_e32 v178, v215, v215
	v_mul_f32_e32 v179, v189, v189
	v_fmac_f32_e32 v178, v214, v214
	v_fmac_f32_e32 v179, v188, v188
	v_add_f32_e32 v178, v178, v179
	v_mul_f32_e32 v179, v187, v187
	v_mul_f32_e32 v180, v185, v185
	v_fmac_f32_e32 v179, v186, v186
	v_fmac_f32_e32 v180, v184, v184
	v_add_f32_e32 v179, v179, v180
	v_add_f32_e32 v178, v179, v178
	v_and_b32_e32 v179, 64, v231
	v_add_f32_e32 v0, v178, v0
	v_xor_b32_e32 v178, 16, v231
	v_add_u32_e32 v179, 64, v179
	v_cmp_lt_i32_e32 vcc, v178, v179
	s_nop 1
	v_cndmask_b32_e32 v178, v231, v178, vcc
	v_lshlrev_b32_e32 v178, 2, v178
	ds_bpermute_b32 v178, v178, v0
	s_waitcnt lgkmcnt(0)
	v_add_f32_e32 v0, v0, v178
	v_xor_b32_e32 v178, 32, v231
	v_cmp_lt_i32_e32 vcc, v178, v179
	s_nop 1
	v_cndmask_b32_e32 v178, v231, v178, vcc
	v_lshlrev_b32_e32 v178, 2, v178
	ds_bpermute_b32 v178, v178, v0
	s_and_saveexec_b64 s[16:17], s[36:37]
	s_cbranch_execz .LBB0_407
	v_lshl_add_u64 v[180:181], v[208:209], 2, s[74:75]
	s_waitcnt lgkmcnt(0)
	v_add_f32_e32 v0, v0, v178
	global_atomic_add_f32 v[180:181], v0, off offset:512

; DI unsigned pk2(float lo, float hi) { f32x2_t f = {lo, hi}; bf16x2_t v = __builtin_convertvector(f, bf16x2_t); return __builtin_bit_cast(unsigned, v); }
;     DI void operator()(const f32x4 (&acc)[2][2][4][2], const Unit& u, int wr, int wc, int fr, int fq) const {
;     ...
;                 for (int m = 0; m < 4; ++m) { const int row = row0 + ai * HALF + m * 16; const size_t ro = (size_t)row * DM + col0; float ssq = 0.f;
; #pragma unroll
;                     for (int bj = 0; bj < 2; ++bj) { const f32x4 v0 = acc[ai][bj][m][0] + rr[m][bj][0], v1 = acc[ai][bj][m][1] + rr[m][bj][1];
;                         if (xr_out) { u32x4 w; w.x = pk2(v0[0], v0[1]); w.y = pk2(v0[2], v0[3]); w.z = pk2(v1[0], v1[1]); w.w = pk2(v1[2], v1[3]); *(u32x4*)(xr_out + ro + bj * HALF) = w; }
;                         else { *(f32x4*)(out + ro + bj * HALF) = v0; *(f32x4*)(out + ro + bj * HALF + 4) = v1; }
;                         ssq += ((v0[0] * v0[0] + v0[1] * v0[1]) + (v0[2] * v0[2] + v0[3] * v0[3])) + ((v1[0] * v1[0] + v1[1] * v1[1]) + (v1[2] * v1[2] + v1[3] * v1[3])); }
;                     if (ss_out) { ssq += __shfl_xor(ssq, 16); ssq += __shfl_xor(ssq, 32); if (fq == 0) atomicAdd(ss_out + row, ssq); } }
.LBB0_408:
	v_pk_add_f32 v[180:181], v[46:47], v[162:163]
	v_lshl_add_u64 v[162:163], s[66:67], 0, v[210:211]
	v_lshl_add_u64 v[162:163], v[206:207], 1, v[162:163]
	s_mov_b32 s3, 0x90000
	s_waitcnt lgkmcnt(0)
	v_pk_add_f32 v[178:179], v[48:49], v[164:165]
	v_pk_add_f32 v[164:165], v[44:45], v[168:169]
	v_pk_add_f32 v[166:167], v[42:43], v[166:167]
	v_add_co_u32_e32 v168, vcc, s3, v162
	v_cvt_pk_bf16_f32 v182, v180, v181
	v_cvt_pk_bf16_f32 v183, v178, v179
	v_cvt_pk_bf16_f32 v184, v166, v167
	v_cvt_pk_bf16_f32 v185, v164, v165
	v_addc_co_u32_e32 v169, vcc, 0, v163, vcc
	s_mov_b64 s[16:17], 0x90000
	global_store_dwordx4 v[168:169], v[182:185], off
	v_pk_add_f32 v[172:173], v[40:41], v[172:173]
	v_pk_add_f32 v[168:169], v[36:37], v[176:177]
	v_pk_add_f32 v[182:183], v[38:39], v[170:171]
	v_pk_add_f32 v[170:171], v[34:35], v[174:175]
	v_lshl_add_u64 v[186:187], v[162:163], 0, s[16:17]
	v_cvt_pk_bf16_f32 v174, v182, v183
	v_cvt_pk_bf16_f32 v175, v172, v173
	v_cvt_pk_bf16_f32 v176, v170, v171
	v_cvt_pk_bf16_f32 v177, v168, v169
	s_and_b64 vcc, exec, s[44:45]
	global_store_dwordx4 v[186:187], v[174:177], off offset:256
	s_cbranch_vccnz .LBB0_412
	v_mul_f32_e32 v0, v181, v181
	v_mul_f32_e32 v174, v179, v179
	v_mul_f32_e32 v167, v167, v167
	v_mul_f32_e32 v165, v165, v165
	v_fmac_f32_e32 v0, v180, v180
	v_fmac_f32_e32 v174, v178, v178
	v_fmac_f32_e32 v167, v166, v166
	v_fmac_f32_e32 v165, v164, v164
	v_add_f32_e32 v0, v0, v174
	v_add_f32_e32 v164, v167, v165
	v_add_f32_e32 v0, v164, v0
	v_mul_f32_e32 v164, v183, v183
	v_mul_f32_e32 v165, v173, v173
	v_fmac_f32_e32 v164, v182, v182
	v_fmac_f32_e32 v165, v172, v172
	v_add_f32_e32 v164, v164, v165
	v_mul_f32_e32 v165, v171, v171
	v_mul_f32_e32 v166, v169, v169
	v_fmac_f32_e32 v165, v170, v170
	v_fmac_f32_e32 v166, v168, v168
	v_add_f32_e32 v165, v165, v166
	v_add_f32_e32 v164, v165, v164
	v_and_b32_e32 v165, 64, v231
	v_add_f32_e32 v0, v164, v0
	v_xor_b32_e32 v164, 16, v231
	v_add_u32_e32 v165, 64, v165
	v_cmp_lt_i32_e32 vcc, v164, v165
	s_nop 1
	v_cndmask_b32_e32 v164, v231, v164, vcc
	v_lshlrev_b32_e32 v164, 2, v164
	ds_bpermute_b32 v164, v164, v0
	s_waitcnt lgkmcnt(0)
	v_add_f32_e32 v0, v0, v164
	v_xor_b32_e32 v164, 32, v231
	v_cmp_lt_i32_e32 vcc, v164, v165
	s_nop 1
	v_cndmask_b32_e32 v164, v231, v164, vcc
	v_lshlrev_b32_e32 v164, 2, v164
	ds_bpermute_b32 v164, v164, v0
	s_and_saveexec_b64 s[16:17], s[36:37]
	s_cbranch_execz .LBB0_411
	v_lshl_add_u64 v[166:167], v[208:209], 2, s[74:75]
	s_waitcnt lgkmcnt(0)
	v_add_f32_e32 v0, v0, v164
	global_atomic_add_f32 v[166:167], v0, off offset:576

; DI unsigned pk2(float lo, float hi) { f32x2_t f = {lo, hi}; bf16x2_t v = __builtin_convertvector(f, bf16x2_t); return __builtin_bit_cast(unsigned, v); }
;     DI void operator()(const f32x4 (&acc)[2][2][4][2], const Unit& u, int wr, int wc, int fr, int fq) const {
;     ...
;                 for (int m = 0; m < 4; ++m) { const int row = row0 + ai * HALF + m * 16; const size_t ro = (size_t)row * DM + col0; float ssq = 0.f;
; #pragma unroll
;                     for (int bj = 0; bj < 2; ++bj) { const f32x4 v0 = acc[ai][bj][m][0] + rr[m][bj][0], v1 = acc[ai][bj][m][1] + rr[m][bj][1];
;                         if (xr_out) { u32x4 w; w.x = pk2(v0[0], v0[1]); w.y = pk2(v0[2], v0[3]); w.z = pk2(v1[0], v1[1]); w.w = pk2(v1[2], v1[3]); *(u32x4*)(xr_out + ro + bj * HALF) = w; }
;                         else { *(f32x4*)(out + ro + bj * HALF) = v0; *(f32x4*)(out + ro + bj * HALF + 4) = v1; }
;                         ssq += ((v0[0] * v0[0] + v0[1] * v0[1]) + (v0[2] * v0[2] + v0[3] * v0[3])) + ((v1[0] * v1[0] + v1[1] * v1[1]) + (v1[2] * v1[2] + v1[3] * v1[3])); }
;                     if (ss_out) { ssq += __shfl_xor(ssq, 16); ssq += __shfl_xor(ssq, 32); if (fq == 0) atomicAdd(ss_out + row, ssq); } }
.LBB0_412:
	s_mov_b32 s3, 0xa0000
	v_pk_add_f32 v[148:149], v[32:33], v[148:149]
	s_waitcnt lgkmcnt(0)
	v_pk_add_f32 v[164:165], v[30:31], v[146:147]
	v_pk_add_f32 v[146:147], v[28:29], v[152:153]
	v_pk_add_f32 v[150:151], v[26:27], v[150:151]
	v_add_co_u32_e32 v152, vcc, s3, v162
	v_cvt_pk_bf16_f32 v166, v164, v165
	v_cvt_pk_bf16_f32 v167, v148, v149
	v_cvt_pk_bf16_f32 v168, v150, v151
	v_cvt_pk_bf16_f32 v169, v146, v147
	v_addc_co_u32_e32 v153, vcc, 0, v163, vcc
	s_mov_b64 s[16:17], 0xa0000
	global_store_dwordx4 v[152:153], v[166:169], off
	v_pk_add_f32 v[156:157], v[24:25], v[156:157]
	v_pk_add_f32 v[152:153], v[20:21], v[160:161]
	v_pk_add_f32 v[166:167], v[22:23], v[154:155]
	v_pk_add_f32 v[154:155], v[18:19], v[158:159]
	v_lshl_add_u64 v[170:171], v[162:163], 0, s[16:17]
	v_cvt_pk_bf16_f32 v158, v166, v167
	v_cvt_pk_bf16_f32 v159, v156, v157
	v_cvt_pk_bf16_f32 v160, v154, v155
	v_cvt_pk_bf16_f32 v161, v152, v153
	s_and_b64 vcc, exec, s[44:45]
	global_store_dwordx4 v[170:171], v[158:161], off offset:256
	s_cbranch_vccnz .LBB0_416
	v_mul_f32_e32 v149, v149, v149
	v_mul_f32_e32 v0, v165, v165
	v_fmac_f32_e32 v149, v148, v148
	v_mul_f32_e32 v148, v151, v151
	v_mul_f32_e32 v147, v147, v147
	v_fmac_f32_e32 v0, v164, v164
	v_fmac_f32_e32 v148, v150, v150
	v_fmac_f32_e32 v147, v146, v146
	v_add_f32_e32 v0, v0, v149
	v_add_f32_e32 v146, v148, v147
	v_add_f32_e32 v0, v146, v0
	v_mul_f32_e32 v146, v167, v167
	v_mul_f32_e32 v147, v157, v157
	v_fmac_f32_e32 v146, v166, v166
	v_fmac_f32_e32 v147, v156, v156
	v_add_f32_e32 v146, v146, v147
	v_mul_f32_e32 v147, v155, v155
	v_mul_f32_e32 v148, v153, v153
	v_fmac_f32_e32 v147, v154, v154
	v_fmac_f32_e32 v148, v152, v152
	v_add_f32_e32 v147, v147, v148
	v_add_f32_e32 v146, v147, v146
	v_and_b32_e32 v147, 64, v231
	v_add_f32_e32 v0, v146, v0
	v_xor_b32_e32 v146, 16, v231
	v_add_u32_e32 v147, 64, v147
	v_cmp_lt_i32_e32 vcc, v146, v147
	s_nop 1
	v_cndmask_b32_e32 v146, v231, v146, vcc
	v_lshlrev_b32_e32 v146, 2, v146
	ds_bpermute_b32 v146, v146, v0
	s_waitcnt lgkmcnt(0)
	v_add_f32_e32 v0, v0, v146
	v_xor_b32_e32 v146, 32, v231
	v_cmp_lt_i32_e32 vcc, v146, v147
	s_nop 1
	v_cndmask_b32_e32 v146, v231, v146, vcc
	v_lshlrev_b32_e32 v146, 2, v146
	ds_bpermute_b32 v146, v146, v0
	s_and_saveexec_b64 s[16:17], s[36:37]
	s_cbranch_execz .LBB0_415
	v_lshl_add_u64 v[148:149], v[208:209], 2, s[74:75]
	s_waitcnt lgkmcnt(0)
	v_add_f32_e32 v0, v0, v146
	global_atomic_add_f32 v[148:149], v0, off offset:640

; DI unsigned pk2(float lo, float hi) { f32x2_t f = {lo, hi}; bf16x2_t v = __builtin_convertvector(f, bf16x2_t); return __builtin_bit_cast(unsigned, v); }
;     DI void operator()(const f32x4 (&acc)[2][2][4][2], const Unit& u, int wr, int wc, int fr, int fq) const {
;     ...
;                 for (int m = 0; m < 4; ++m) { const int row = row0 + ai * HALF + m * 16; const size_t ro = (size_t)row * DM + col0; float ssq = 0.f;
; #pragma unroll
;                     for (int bj = 0; bj < 2; ++bj) { const f32x4 v0 = acc[ai][bj][m][0] + rr[m][bj][0], v1 = acc[ai][bj][m][1] + rr[m][bj][1];
;                         if (xr_out) { u32x4 w; w.x = pk2(v0[0], v0[1]); w.y = pk2(v0[2], v0[3]); w.z = pk2(v1[0], v1[1]); w.w = pk2(v1[2], v1[3]); *(u32x4*)(xr_out + ro + bj * HALF) = w; }
;                         else { *(f32x4*)(out + ro + bj * HALF) = v0; *(f32x4*)(out + ro + bj * HALF + 4) = v1; }
;                         ssq += ((v0[0] * v0[0] + v0[1] * v0[1]) + (v0[2] * v0[2] + v0[3] * v0[3])) + ((v1[0] * v1[0] + v1[1] * v1[1]) + (v1[2] * v1[2] + v1[3] * v1[3])); }
;                     if (ss_out) { ssq += __shfl_xor(ssq, 16); ssq += __shfl_xor(ssq, 32); if (fq == 0) atomicAdd(ss_out + row, ssq); } }
.LBB0_416:
	s_mov_b32 s3, 0xb0000
	v_pk_add_f32 v[132:133], v[16:17], v[132:133]
	s_waitcnt lgkmcnt(0)
	v_pk_add_f32 v[146:147], v[14:15], v[130:131]
	v_pk_add_f32 v[130:131], v[12:13], v[136:137]
	v_pk_add_f32 v[134:135], v[10:11], v[134:135]
	v_add_co_u32_e32 v136, vcc, s3, v162
	v_cvt_pk_bf16_f32 v148, v146, v147
	v_cvt_pk_bf16_f32 v149, v132, v133
	v_cvt_pk_bf16_f32 v150, v134, v135
	v_cvt_pk_bf16_f32 v151, v130, v131
	v_addc_co_u32_e32 v137, vcc, 0, v163, vcc
	s_mov_b64 s[16:17], 0xb0000
	global_store_dwordx4 v[136:137], v[148:151], off
	v_pk_add_f32 v[140:141], v[8:9], v[140:141]
	v_pk_add_f32 v[136:137], v[4:5], v[144:145]
	v_pk_add_f32 v[148:149], v[6:7], v[138:139]
	v_pk_add_f32 v[138:139], v[2:3], v[142:143]
	v_lshl_add_u64 v[152:153], v[162:163], 0, s[16:17]
	v_cvt_pk_bf16_f32 v142, v148, v149
	v_cvt_pk_bf16_f32 v143, v140, v141
	v_cvt_pk_bf16_f32 v144, v138, v139
	v_cvt_pk_bf16_f32 v145, v136, v137
	s_and_b64 vcc, exec, s[44:45]
	global_store_dwordx4 v[152:153], v[142:145], off offset:256
	s_cbranch_vccnz .LBB0_420
	v_mul_f32_e32 v133, v133, v133
	v_mul_f32_e32 v0, v147, v147
	v_fmac_f32_e32 v133, v132, v132
	v_mul_f32_e32 v132, v135, v135
	v_mul_f32_e32 v131, v131, v131
	v_fmac_f32_e32 v0, v146, v146
	v_fmac_f32_e32 v132, v134, v134
	v_fmac_f32_e32 v131, v130, v130
	v_add_f32_e32 v0, v0, v133
	v_add_f32_e32 v130, v132, v131
	v_add_f32_e32 v0, v130, v0
	v_mul_f32_e32 v130, v149, v149
	v_mul_f32_e32 v131, v141, v141
	v_fmac_f32_e32 v130, v148, v148
	v_fmac_f32_e32 v131, v140, v140
	v_add_f32_e32 v130, v130, v131
	v_mul_f32_e32 v131, v139, v139
	v_mul_f32_e32 v132, v137, v137
	v_fmac_f32_e32 v131, v138, v138
	v_fmac_f32_e32 v132, v136, v136
	v_add_f32_e32 v131, v131, v132
	v_add_f32_e32 v130, v131, v130
	v_and_b32_e32 v131, 64, v231
	v_add_f32_e32 v0, v130, v0
	v_xor_b32_e32 v130, 16, v231
	v_add_u32_e32 v131, 64, v131
	v_cmp_lt_i32_e32 vcc, v130, v131
	s_nop 1
	v_cndmask_b32_e32 v130, v231, v130, vcc
	v_lshlrev_b32_e32 v130, 2, v130
	ds_bpermute_b32 v130, v130, v0
	s_waitcnt lgkmcnt(0)
	v_add_f32_e32 v0, v0, v130
	v_xor_b32_e32 v130, 32, v231
	v_cmp_lt_i32_e32 vcc, v130, v131
	s_nop 1
	v_cndmask_b32_e32 v130, v231, v130, vcc
	v_lshlrev_b32_e32 v130, 2, v130
	ds_bpermute_b32 v130, v130, v0
	s_and_saveexec_b64 s[16:17], s[36:37]
	s_cbranch_execz .LBB0_419
	v_lshl_add_u64 v[132:133], v[208:209], 2, s[74:75]
	s_waitcnt lgkmcnt(0)
	v_add_f32_e32 v0, v0, v130
	global_atomic_add_f32 v[132:133], v0, off offset:704

; DI unsigned cvt_pk_bf16(float lo, float hi) { unsigned r; asm volatile("v_cvt_pk_bf16_f32 %0, %1, %2" : "=v"(r) : "v"(lo), "v"(hi)); return r; }
;     DI void operator()(const f32x4 (&acc)[2][2][4][2], const Unit& u, int wr, int wc, int fr, int fq) const {
;     ...
;                 const int rloc = wr * 64 + fr, col0 = colb + wc * 32 + 8 * fq;
; #pragma unroll
;                 for (int ai = 0; ai < 2; ++ai)
; #pragma unroll
;                     for (int m = 0; m < 4; ++m) { bf16_t* rowp = base + (size_t)(rowb + rloc + ai * HALF + m * 16) * ld + col0;
;                         const float rs_ = ss_in ? rsqrtf(ss_in[row0 + ai * HALF + m * 16] * (1.f / DM) + EPS) : 1.f;
; #pragma unroll
;                         for (int bj = 0; bj < 2; ++bj) { const f32x4 v0 = acc[ai][bj][m][0] * rs_, v1 = acc[ai][bj][m][1] * rs_;
;                             u32x4 w; w.x = cvt_pk_bf16(v0[0], v0[1]); w.y = cvt_pk_bf16(v0[2], v0[3]); w.z = cvt_pk_bf16(v1[0], v1[1]); w.w = cvt_pk_bf16(v1[2], v1[3]);
;                             *(u32x4*)(rowp + bj * HALF) = w; } }
.LBB0_435:
	v_readlane_b32 s62, v255, 4
	v_readlane_b32 s63, v255, 5
	v_mov_b32_e32 v0, 1.0
	s_andn2_b64 vcc, exec, s[62:63]
	v_cndmask_b32_e64 v131, 0, 1, s[62:63]
	v_cmp_ne_u32_e64 s[44:45], 1, v131
	v_mov_b32_e32 v134, 1.0
	s_cbranch_vccnz .LBB0_437
	v_ashrrev_i32_e32 v131, 31, v130
	v_lshl_add_u64 v[132:133], v[130:131], 2, s[74:75]
	global_load_dword v232, v[132:133], off
	global_load_dword v233, v[132:133], off offset:64
	global_load_dword v234, v[132:133], off offset:128
	global_load_dword v235, v[132:133], off offset:192
	global_load_dword v236, v[132:133], off offset:512
	global_load_dword v237, v[132:133], off offset:576
	global_load_dword v238, v[132:133], off offset:640
	global_load_dword v239, v[132:133], off offset:704
	s_waitcnt vmcnt(0) lgkmcnt(0)
	v_fmamk_f32 v232, v232, 0x3a000000, v229
	v_mul_f32_e32 v246, 0x4b800000, v232
	v_cmp_gt_f32_e32 vcc, s33, v232
	s_nop 1
	v_cndmask_b32_e32 v232, v232, v246, vcc
	v_rsq_f32_e32 v232, v232
	s_nop 0
	v_mul_f32_e32 v246, 0x45800000, v232
	v_cndmask_b32_e32 v232, v232, v246, vcc
	v_fmamk_f32 v233, v233, 0x3a000000, v229
	v_mul_f32_e32 v246, 0x4b800000, v233
	v_cmp_gt_f32_e32 vcc, s33, v233
	s_nop 1
	v_cndmask_b32_e32 v233, v233, v246, vcc
	v_rsq_f32_e32 v233, v233
	s_nop 0
	v_mul_f32_e32 v246, 0x45800000, v233
	v_cndmask_b32_e32 v233, v233, v246, vcc
	v_fmamk_f32 v234, v234, 0x3a000000, v229
	v_mul_f32_e32 v246, 0x4b800000, v234
	v_cmp_gt_f32_e32 vcc, s33, v234
	s_nop 1
	v_cndmask_b32_e32 v234, v234, v246, vcc
	v_rsq_f32_e32 v234, v234
	s_nop 0
	v_mul_f32_e32 v246, 0x45800000, v234
	v_cndmask_b32_e32 v234, v234, v246, vcc
	v_fmamk_f32 v235, v235, 0x3a000000, v229
	v_mul_f32_e32 v246, 0x4b800000, v235
	v_cmp_gt_f32_e32 vcc, s33, v235
	s_nop 1
	v_cndmask_b32_e32 v235, v235, v246, vcc
	v_rsq_f32_e32 v235, v235
	s_nop 0
	v_mul_f32_e32 v246, 0x45800000, v235
	v_cndmask_b32_e32 v235, v235, v246, vcc
	v_fmamk_f32 v236, v236, 0x3a000000, v229
	v_mul_f32_e32 v246, 0x4b800000, v236
	v_cmp_gt_f32_e32 vcc, s33, v236
	s_nop 1
	v_cndmask_b32_e32 v236, v236, v246, vcc
	v_rsq_f32_e32 v236, v236
	s_nop 0
	v_mul_f32_e32 v246, 0x45800000, v236
	v_cndmask_b32_e32 v236, v236, v246, vcc
	v_fmamk_f32 v237, v237, 0x3a000000, v229
	v_mul_f32_e32 v246, 0x4b800000, v237
	v_cmp_gt_f32_e32 vcc, s33, v237
	s_nop 1
	v_cndmask_b32_e32 v237, v237, v246, vcc
	v_rsq_f32_e32 v237, v237
	s_nop 0
	v_mul_f32_e32 v246, 0x45800000, v237
	v_cndmask_b32_e32 v237, v237, v246, vcc
	v_fmamk_f32 v238, v238, 0x3a000000, v229
	v_mul_f32_e32 v246, 0x4b800000, v238
	v_cmp_gt_f32_e32 vcc, s33, v238
	s_nop 1
	v_cndmask_b32_e32 v238, v238, v246, vcc
	v_rsq_f32_e32 v238, v238
	s_nop 0
	v_mul_f32_e32 v246, 0x45800000, v238
	v_cndmask_b32_e32 v238, v238, v246, vcc
	v_fmamk_f32 v239, v239, 0x3a000000, v229
	v_mul_f32_e32 v246, 0x4b800000, v239
	v_cmp_gt_f32_e32 vcc, s33, v239
	s_nop 1
	v_cndmask_b32_e32 v239, v239, v246, vcc
	v_rsq_f32_e32 v239, v239
	s_nop 0
	v_mul_f32_e32 v246, 0x45800000, v239
	v_cndmask_b32_e32 v239, v239, v246, vcc
	v_mov_b32_e32 v134, v232
.LBB0_437:
	v_or_b32_e32 v132, s3, v248
	v_add_u32_e32 v135, s53, v251
	v_ashrrev_i32_e32 v133, 31, v132
	v_ashrrev_i32_e32 v131, 31, v135
	v_lshl_add_u64 v[132:133], v[132:133], 1, s[24:25]
	v_mul_lo_u32 v136, s16, v131
	v_mul_lo_u32 v131, s17, v135
	v_mad_u64_u32 v[138:139], s[24:25], s16, v135, 0
	v_add3_u32 v139, v139, v136, v131
	v_lshl_add_u64 v[142:143], v[138:139], 1, v[132:133]
	v_pk_mul_f32 v[140:141], v[128:129], v[134:135] op_sel_hi:[1,0]
	v_pk_mul_f32 v[138:139], v[126:127], v[134:135] op_sel_hi:[1,0]
	v_pk_mul_f32 v[144:145], v[124:125], v[134:135] op_sel_hi:[1,0]
	v_pk_mul_f32 v[146:147], v[122:123], v[134:135] op_sel_hi:[1,0]
	v_cvt_pk_bf16_f32 v138, v138, v139
	v_cvt_pk_bf16_f32 v139, v140, v141
	s_and_b64 vcc, exec, s[44:45]
	v_cvt_pk_bf16_f32 v140, v146, v147
	v_cvt_pk_bf16_f32 v141, v144, v145
	global_store_dwordx4 v[142:143], v[138:141], off
	v_pk_mul_f32 v[144:145], v[116:117], v[134:135] op_sel_hi:[1,0]
	v_pk_mul_f32 v[146:147], v[114:115], v[134:135] op_sel_hi:[1,0]
	v_pk_mul_f32 v[140:141], v[120:121], v[134:135] op_sel_hi:[1,0]
	v_pk_mul_f32 v[138:139], v[118:119], v[134:135] op_sel_hi:[1,0]
	s_nop 0
	v_cvt_pk_bf16_f32 v138, v138, v139
	v_cvt_pk_bf16_f32 v139, v140, v141
	v_cvt_pk_bf16_f32 v140, v146, v147
	v_cvt_pk_bf16_f32 v141, v144, v145
	global_store_dwordx4 v[142:143], v[138:141], off offset:256
	s_cbranch_vccnz .LBB0_439
	v_mov_b32_e32 v0, v233
.LBB0_439:
	v_or_b32_e32 v131, 16, v135
	v_mul_lo_u32 v134, s17, v131
	v_mad_u64_u32 v[138:139], s[24:25], s16, v131, 0
	v_add3_u32 v139, v139, v136, v134
	v_lshl_add_u64 v[142:143], v[138:139], 1, v[132:133]
	v_pk_mul_f32 v[140:141], v[112:113], v[0:1] op_sel_hi:[1,0]
	v_pk_mul_f32 v[138:139], v[110:111], v[0:1] op_sel_hi:[1,0]
	v_pk_mul_f32 v[144:145], v[108:109], v[0:1] op_sel_hi:[1,0]
	v_pk_mul_f32 v[146:147], v[106:107], v[0:1] op_sel_hi:[1,0]
	v_cvt_pk_bf16_f32 v138, v138, v139
	v_cvt_pk_bf16_f32 v139, v140, v141
	s_and_b64 vcc, exec, s[44:45]
	v_cvt_pk_bf16_f32 v140, v146, v147
	v_cvt_pk_bf16_f32 v141, v144, v145
	global_store_dwordx4 v[142:143], v[138:141], off
	v_pk_mul_f32 v[144:145], v[100:101], v[0:1] op_sel_hi:[1,0]
	v_pk_mul_f32 v[146:147], v[98:99], v[0:1] op_sel_hi:[1,0]
	v_pk_mul_f32 v[140:141], v[104:105], v[0:1] op_sel_hi:[1,0]
	v_pk_mul_f32 v[138:139], v[102:103], v[0:1] op_sel_hi:[1,0]
	v_mov_b32_e32 v0, 1.0
	v_mov_b32_e32 v134, 1.0
	v_cvt_pk_bf16_f32 v138, v138, v139
	v_cvt_pk_bf16_f32 v139, v140, v141
	v_cvt_pk_bf16_f32 v140, v146, v147
	v_cvt_pk_bf16_f32 v141, v144, v145
	global_store_dwordx4 v[142:143], v[138:141], off offset:256
	s_cbranch_vccnz .LBB0_441
	v_mov_b32_e32 v134, v234
; DI unsigned cvt_pk_bf16(float lo, float hi) { unsigned r; asm volatile("v_cvt_pk_bf16_f32 %0, %1, %2" : "=v"(r) : "v"(lo), "v"(hi)); return r; }
;     DI void operator()(const f32x4 (&acc)[2][2][4][2], const Unit& u, int wr, int wc, int fr, int fq) const {
;     ...
;                 const int rloc = wr * 64 + fr, col0 = colb + wc * 32 + 8 * fq;
; #pragma unroll
;                 for (int ai = 0; ai < 2; ++ai)
; #pragma unroll
;                     for (int m = 0; m < 4; ++m) { bf16_t* rowp = base + (size_t)(rowb + rloc + ai * HALF + m * 16) * ld + col0;
;                         const float rs_ = ss_in ? rsqrtf(ss_in[row0 + ai * HALF + m * 16] * (1.f / DM) + EPS) : 1.f;
; #pragma unroll
;                         for (int bj = 0; bj < 2; ++bj) { const f32x4 v0 = acc[ai][bj][m][0] * rs_, v1 = acc[ai][bj][m][1] * rs_;
;                             u32x4 w; w.x = cvt_pk_bf16(v0[0], v0[1]); w.y = cvt_pk_bf16(v0[2], v0[3]); w.z = cvt_pk_bf16(v1[0], v1[1]); w.w = cvt_pk_bf16(v1[2], v1[3]);
;                             *(u32x4*)(rowp + bj * HALF) = w; } }
.LBB0_441:
	v_or_b32_e32 v131, 32, v135
	v_mul_lo_u32 v137, s17, v131
	v_mad_u64_u32 v[138:139], s[24:25], s16, v131, 0
	v_add3_u32 v139, v139, v136, v137
	v_lshl_add_u64 v[142:143], v[138:139], 1, v[132:133]
	v_pk_mul_f32 v[140:141], v[96:97], v[134:135] op_sel_hi:[1,0]
	v_pk_mul_f32 v[138:139], v[94:95], v[134:135] op_sel_hi:[1,0]
	v_pk_mul_f32 v[144:145], v[92:93], v[134:135] op_sel_hi:[1,0]
	v_pk_mul_f32 v[146:147], v[90:91], v[134:135] op_sel_hi:[1,0]
	v_cvt_pk_bf16_f32 v138, v138, v139
	v_cvt_pk_bf16_f32 v139, v140, v141
	s_and_b64 vcc, exec, s[44:45]
	v_cvt_pk_bf16_f32 v140, v146, v147
	v_cvt_pk_bf16_f32 v141, v144, v145
	global_store_dwordx4 v[142:143], v[138:141], off
	v_pk_mul_f32 v[144:145], v[84:85], v[134:135] op_sel_hi:[1,0]
	v_pk_mul_f32 v[146:147], v[82:83], v[134:135] op_sel_hi:[1,0]
	v_pk_mul_f32 v[140:141], v[88:89], v[134:135] op_sel_hi:[1,0]
	v_pk_mul_f32 v[138:139], v[86:87], v[134:135] op_sel_hi:[1,0]
	s_nop 0
	v_cvt_pk_bf16_f32 v138, v138, v139
	v_cvt_pk_bf16_f32 v139, v140, v141
	v_cvt_pk_bf16_f32 v140, v146, v147
	v_cvt_pk_bf16_f32 v141, v144, v145
	global_store_dwordx4 v[142:143], v[138:141], off offset:256
	s_cbranch_vccnz .LBB0_443
	v_mov_b32_e32 v0, v235
.LBB0_443:
	v_or_b32_e32 v131, 48, v135
	v_mul_lo_u32 v134, s17, v131
	v_mad_u64_u32 v[138:139], s[24:25], s16, v131, 0
	v_add3_u32 v139, v139, v136, v134
	v_lshl_add_u64 v[140:141], v[138:139], 1, v[132:133]
	v_pk_mul_f32 v[138:139], v[80:81], v[0:1] op_sel_hi:[1,0]
	v_pk_mul_f32 v[136:137], v[78:79], v[0:1] op_sel_hi:[1,0]
	v_pk_mul_f32 v[142:143], v[76:77], v[0:1] op_sel_hi:[1,0]
	v_pk_mul_f32 v[144:145], v[74:75], v[0:1] op_sel_hi:[1,0]
	v_cvt_pk_bf16_f32 v136, v136, v137
	v_cvt_pk_bf16_f32 v137, v138, v139
	s_and_b64 vcc, exec, s[44:45]
	v_cvt_pk_bf16_f32 v138, v144, v145
	v_cvt_pk_bf16_f32 v139, v142, v143
	global_store_dwordx4 v[140:141], v[136:139], off
	v_pk_mul_f32 v[142:143], v[68:69], v[0:1] op_sel_hi:[1,0]
	v_pk_mul_f32 v[144:145], v[66:67], v[0:1] op_sel_hi:[1,0]
	v_pk_mul_f32 v[138:139], v[72:73], v[0:1] op_sel_hi:[1,0]
	v_pk_mul_f32 v[136:137], v[70:71], v[0:1] op_sel_hi:[1,0]
	v_mov_b32_e32 v0, 1.0
	v_mov_b32_e32 v134, 1.0
	v_cvt_pk_bf16_f32 v136, v136, v137
	v_cvt_pk_bf16_f32 v137, v138, v139
	v_cvt_pk_bf16_f32 v138, v144, v145
	v_cvt_pk_bf16_f32 v139, v142, v143
	global_store_dwordx4 v[140:141], v[136:139], off offset:256
	s_cbranch_vccnz .LBB0_445
	v_mov_b32_e32 v134, v236
.LBB0_445:
	v_add_u32_e32 v131, 0x80, v135
	v_ashrrev_i32_e32 v136, 31, v131
	v_mul_lo_u32 v138, s16, v136
	v_mul_lo_u32 v139, s17, v131
	v_mad_u64_u32 v[136:137], s[24:25], s16, v131, 0
	v_add3_u32 v137, v137, v138, v139
	v_lshl_add_u64 v[140:141], v[136:137], 1, v[132:133]
	v_pk_mul_f32 v[138:139], v[64:65], v[134:135] op_sel_hi:[1,0]
	v_pk_mul_f32 v[136:137], v[62:63], v[134:135] op_sel_hi:[1,0]
	v_pk_mul_f32 v[142:143], v[60:61], v[134:135] op_sel_hi:[1,0]
	v_pk_mul_f32 v[144:145], v[58:59], v[134:135] op_sel_hi:[1,0]
	v_cvt_pk_bf16_f32 v136, v136, v137
	v_cvt_pk_bf16_f32 v137, v138, v139
	s_and_b64 vcc, exec, s[44:45]
	v_cvt_pk_bf16_f32 v138, v144, v145
	v_cvt_pk_bf16_f32 v139, v142, v143
	global_store_dwordx4 v[140:141], v[136:139], off
	v_pk_mul_f32 v[142:143], v[52:53], v[134:135] op_sel_hi:[1,0]
	v_pk_mul_f32 v[144:145], v[50:51], v[134:135] op_sel_hi:[1,0]
	v_pk_mul_f32 v[138:139], v[56:57], v[134:135] op_sel_hi:[1,0]
	v_pk_mul_f32 v[136:137], v[54:55], v[134:135] op_sel_hi:[1,0]
	s_nop 0
	v_cvt_pk_bf16_f32 v136, v136, v137
	v_cvt_pk_bf16_f32 v137, v138, v139
	v_cvt_pk_bf16_f32 v138, v144, v145
	v_cvt_pk_bf16_f32 v139, v142, v143
	global_store_dwordx4 v[140:141], v[136:139], off offset:256
	s_cbranch_vccnz .LBB0_447
	v_mov_b32_e32 v0, v237
.LBB0_447:
	v_add_u32_e32 v131, 0x90, v135
	v_ashrrev_i32_e32 v134, 31, v131
	v_mul_lo_u32 v134, s16, v134
	v_mul_lo_u32 v138, s17, v131
	v_mad_u64_u32 v[136:137], s[24:25], s16, v131, 0
	v_add3_u32 v137, v137, v134, v138
	v_lshl_add_u64 v[140:141], v[136:137], 1, v[132:133]
	v_pk_mul_f32 v[138:139], v[48:49], v[0:1] op_sel_hi:[1,0]
	v_pk_mul_f32 v[136:137], v[46:47], v[0:1] op_sel_hi:[1,0]
	v_pk_mul_f32 v[142:143], v[44:45], v[0:1] op_sel_hi:[1,0]
	v_pk_mul_f32 v[144:145], v[42:43], v[0:1] op_sel_hi:[1,0]
	v_cvt_pk_bf16_f32 v136, v136, v137
	v_cvt_pk_bf16_f32 v137, v138, v139
	s_and_b64 vcc, exec, s[44:45]
	v_cvt_pk_bf16_f32 v138, v144, v145
	v_cvt_pk_bf16_f32 v139, v142, v143
	global_store_dwordx4 v[140:141], v[136:139], off
	v_pk_mul_f32 v[142:143], v[36:37], v[0:1] op_sel_hi:[1,0]
	v_pk_mul_f32 v[144:145], v[34:35], v[0:1] op_sel_hi:[1,0]
	v_pk_mul_f32 v[138:139], v[40:41], v[0:1] op_sel_hi:[1,0]
	v_pk_mul_f32 v[136:137], v[38:39], v[0:1] op_sel_hi:[1,0]
	v_mov_b32_e32 v0, 1.0
	v_mov_b32_e32 v134, 1.0
	v_cvt_pk_bf16_f32 v136, v136, v137
	v_cvt_pk_bf16_f32 v137, v138, v139
	v_cvt_pk_bf16_f32 v138, v144, v145
	v_cvt_pk_bf16_f32 v139, v142, v143
	global_store_dwordx4 v[140:141], v[136:139], off offset:256
	s_cbranch_vccnz .LBB0_449
	v_mov_b32_e32 v134, v238
.LBB0_449:
	v_add_u32_e32 v131, 0xa0, v135
	v_ashrrev_i32_e32 v136, 31, v131
	v_mul_lo_u32 v138, s16, v136
	v_mul_lo_u32 v139, s17, v131
	v_mad_u64_u32 v[136:137], s[24:25], s16, v131, 0
	v_add3_u32 v137, v137, v138, v139
	v_lshl_add_u64 v[140:141], v[136:137], 1, v[132:133]
	v_pk_mul_f32 v[138:139], v[32:33], v[134:135] op_sel_hi:[1,0]
	v_pk_mul_f32 v[136:137], v[30:31], v[134:135] op_sel_hi:[1,0]
	v_pk_mul_f32 v[142:143], v[28:29], v[134:135] op_sel_hi:[1,0]
	v_pk_mul_f32 v[144:145], v[26:27], v[134:135] op_sel_hi:[1,0]
	v_cvt_pk_bf16_f32 v136, v136, v137
	v_cvt_pk_bf16_f32 v137, v138, v139
	s_and_b64 vcc, exec, s[44:45]
	v_cvt_pk_bf16_f32 v138, v144, v145
	v_cvt_pk_bf16_f32 v139, v142, v143
	global_store_dwordx4 v[140:141], v[136:139], off
	v_pk_mul_f32 v[142:143], v[20:21], v[134:135] op_sel_hi:[1,0]
	v_pk_mul_f32 v[144:145], v[18:19], v[134:135] op_sel_hi:[1,0]
	v_pk_mul_f32 v[138:139], v[24:25], v[134:135] op_sel_hi:[1,0]
	v_pk_mul_f32 v[136:137], v[22:23], v[134:135] op_sel_hi:[1,0]
	s_nop 0
	v_cvt_pk_bf16_f32 v136, v136, v137
	v_cvt_pk_bf16_f32 v137, v138, v139
	v_cvt_pk_bf16_f32 v138, v144, v145
	v_cvt_pk_bf16_f32 v139, v142, v143
	global_store_dwordx4 v[140:141], v[136:139], off offset:256
	s_cbranch_vccnz .LBB0_451
	v_mov_b32_e32 v0, v239
; DI unsigned cvt_pk_bf16(float lo, float hi) { unsigned r; asm volatile("v_cvt_pk_bf16_f32 %0, %1, %2" : "=v"(r) : "v"(lo), "v"(hi)); return r; }
;     DI void operator()(const f32x4 (&acc)[2][2][4][2], const Unit& u, int wr, int wc, int fr, int fq) const {
;     ...
;                     for (int m = 0; m < 4; ++m) { bf16_t* rowp = base + (size_t)(rowb + rloc + ai * HALF + m * 16) * ld + col0;
;                         const float rs_ = ss_in ? rsqrtf(ss_in[row0 + ai * HALF + m * 16] * (1.f / DM) + EPS) : 1.f;
; #pragma unroll
;                         for (int bj = 0; bj < 2; ++bj) { const f32x4 v0 = acc[ai][bj][m][0] * rs_, v1 = acc[ai][bj][m][1] * rs_;
;                             u32x4 w; w.x = cvt_pk_bf16(v0[0], v0[1]); w.y = cvt_pk_bf16(v0[2], v0[3]); w.z = cvt_pk_bf16(v1[0], v1[1]); w.w = cvt_pk_bf16(v1[2], v1[3]);
;                             *(u32x4*)(rowp + bj * HALF) = w; } }
;     ...
;                 bf16_t* base = ((u.pm * BM) >> 13) ? VTS1 : VTS0; const int ldt = SEQ, rowi = ((u.pm * BM) & (SEQ - 1)) + wr * 64 + fr, col0 = (u.pn - vt_lo) * BM + wc * 32 + 8 * fq;
; #pragma unroll
;                 for (int ai = 0; ai < 2; ++ai)
; #pragma unroll
;                     for (int m = 0; m < 4; ++m) { const int row = rowi + ai * HALF + m * 16;
;                         const float rs_ = ss_in ? rsqrtf(ss_in[row0 + ai * HALF + m * 16] * (1.f / DM) + EPS) : 1.f;
.LBB0_451:
	v_add_u32_e32 v131, 0xb0, v135
	v_ashrrev_i32_e32 v134, 31, v131
	v_mul_lo_u32 v136, s16, v134
	v_mul_lo_u32 v137, s17, v131
	v_mad_u64_u32 v[134:135], s[16:17], s16, v131, 0
	v_add3_u32 v135, v135, v136, v137
	v_lshl_add_u64 v[136:137], v[134:135], 1, v[132:133]
	v_pk_mul_f32 v[134:135], v[16:17], v[0:1] op_sel_hi:[1,0]
	v_pk_mul_f32 v[132:133], v[14:15], v[0:1] op_sel_hi:[1,0]
	v_pk_mul_f32 v[138:139], v[12:13], v[0:1] op_sel_hi:[1,0]
	v_pk_mul_f32 v[140:141], v[10:11], v[0:1] op_sel_hi:[1,0]
	v_cvt_pk_bf16_f32 v132, v132, v133
	v_cvt_pk_bf16_f32 v133, v134, v135
	s_mov_b64 s[24:25], 0
	v_cvt_pk_bf16_f32 v134, v140, v141
	v_cvt_pk_bf16_f32 v135, v138, v139
	global_store_dwordx4 v[136:137], v[132:135], off
	v_pk_mul_f32 v[138:139], v[4:5], v[0:1] op_sel_hi:[1,0]
	v_pk_mul_f32 v[140:141], v[2:3], v[0:1] op_sel_hi:[1,0]
	v_pk_mul_f32 v[134:135], v[8:9], v[0:1] op_sel_hi:[1,0]
	v_pk_mul_f32 v[132:133], v[6:7], v[0:1] op_sel_hi:[1,0]
	s_nop 0
	v_cvt_pk_bf16_f32 v132, v132, v133
	v_cvt_pk_bf16_f32 v133, v134, v135
	v_cvt_pk_bf16_f32 v134, v140, v141
	v_cvt_pk_bf16_f32 v135, v138, v139
	global_store_dwordx4 v[136:137], v[132:135], off offset:256
.LBB0_452:
	s_and_b64 vcc, exec, s[24:25]
	s_cbranch_vccz .LBB0_470
	v_mov_b32_e32 v232, 1.0
	v_mov_b32_e32 v233, 1.0
	v_mov_b32_e32 v234, 1.0
	v_mov_b32_e32 v235, 1.0
	v_mov_b32_e32 v236, 1.0
	v_mov_b32_e32 v237, 1.0
	v_mov_b32_e32 v238, 1.0
	v_mov_b32_e32 v239, 1.0
	v_readlane_b32 s16, v255, 4
	v_readlane_b32 s17, v255, 5
	s_nop 0
	s_andn2_b64 vcc, exec, s[16:17]
	s_cbranch_vccnz .Lsbv_noss
	v_ashrrev_i32_e32 v131, 31, v130
	v_lshl_add_u64 v[132:133], v[130:131], 2, s[74:75]
	global_load_dword v232, v[132:133], off
	global_load_dword v233, v[132:133], off offset:64
	global_load_dword v234, v[132:133], off offset:128
	global_load_dword v235, v[132:133], off offset:192
	global_load_dword v236, v[132:133], off offset:512
	global_load_dword v237, v[132:133], off offset:576
	global_load_dword v238, v[132:133], off offset:640
	global_load_dword v239, v[132:133], off offset:704
	s_waitcnt vmcnt(0)
	v_fmamk_f32 v232, v232, 0x3a000000, v229
	v_mul_f32_e32 v246, 0x4b800000, v232
	v_cmp_gt_f32_e32 vcc, s33, v232
	s_nop 1
	v_cndmask_b32_e32 v232, v232, v246, vcc
	v_rsq_f32_e32 v232, v232
	s_nop 0
	v_mul_f32_e32 v246, 0x45800000, v232
	v_cndmask_b32_e32 v232, v232, v246, vcc
	v_fmamk_f32 v233, v233, 0x3a000000, v229
	v_mul_f32_e32 v246, 0x4b800000, v233
	v_cmp_gt_f32_e32 vcc, s33, v233
	s_nop 1
	v_cndmask_b32_e32 v233, v233, v246, vcc
	v_rsq_f32_e32 v233, v233
	s_nop 0
	v_mul_f32_e32 v246, 0x45800000, v233
	v_cndmask_b32_e32 v233, v233, v246, vcc
	v_fmamk_f32 v234, v234, 0x3a000000, v229
	v_mul_f32_e32 v246, 0x4b800000, v234
	v_cmp_gt_f32_e32 vcc, s33, v234
	s_nop 1
	v_cndmask_b32_e32 v234, v234, v246, vcc
	v_rsq_f32_e32 v234, v234
	s_nop 0
	v_mul_f32_e32 v246, 0x45800000, v234
	v_cndmask_b32_e32 v234, v234, v246, vcc
	v_fmamk_f32 v235, v235, 0x3a000000, v229
	v_mul_f32_e32 v246, 0x4b800000, v235
	v_cmp_gt_f32_e32 vcc, s33, v235
	s_nop 1
	v_cndmask_b32_e32 v235, v235, v246, vcc
	v_rsq_f32_e32 v235, v235
	s_nop 0
	v_mul_f32_e32 v246, 0x45800000, v235
	v_cndmask_b32_e32 v235, v235, v246, vcc
	v_fmamk_f32 v236, v236, 0x3a000000, v229
	v_mul_f32_e32 v246, 0x4b800000, v236
	v_cmp_gt_f32_e32 vcc, s33, v236
	s_nop 1
	v_cndmask_b32_e32 v236, v236, v246, vcc
	v_rsq_f32_e32 v236, v236
	s_nop 0
	v_mul_f32_e32 v246, 0x45800000, v236
	v_cndmask_b32_e32 v236, v236, v246, vcc
	v_fmamk_f32 v237, v237, 0x3a000000, v229
	v_mul_f32_e32 v246, 0x4b800000, v237
	v_cmp_gt_f32_e32 vcc, s33, v237
	s_nop 1
	v_cndmask_b32_e32 v237, v237, v246, vcc
	v_rsq_f32_e32 v237, v237
	s_nop 0
	v_mul_f32_e32 v246, 0x45800000, v237
	v_cndmask_b32_e32 v237, v237, v246, vcc
	v_fmamk_f32 v238, v238, 0x3a000000, v229
	v_mul_f32_e32 v246, 0x4b800000, v238
	v_cmp_gt_f32_e32 vcc, s33, v238
	s_nop 1
	v_cndmask_b32_e32 v238, v238, v246, vcc
	v_rsq_f32_e32 v238, v238
	s_nop 0
	v_mul_f32_e32 v246, 0x45800000, v238
	v_cndmask_b32_e32 v238, v238, v246, vcc
	v_fmamk_f32 v239, v239, 0x3a000000, v229
	v_mul_f32_e32 v246, 0x4b800000, v239
	v_cmp_gt_f32_e32 vcc, s33, v239
	s_nop 1
	v_cndmask_b32_e32 v239, v239, v246, vcc
	v_rsq_f32_e32 v239, v239
	s_nop 0
	v_mul_f32_e32 v246, 0x45800000, v239
	v_cndmask_b32_e32 v239, v239, v246, vcc
; DI unsigned f2bf(float f) { unsigned u = __builtin_bit_cast(unsigned, f); return (u + 0x7fffu + ((u >> 16) & 1u)) >> 16; }
;     DI void operator()(const f32x4 (&acc)[2][2][4][2], const Unit& u, int wr, int wc, int fr, int fq) const {
;     ...
;                 bf16_t* base = ((u.pm * BM) >> 13) ? VTS1 : VTS0; const int ldt = SEQ, rowi = ((u.pm * BM) & (SEQ - 1)) + wr * 64 + fr, col0 = (u.pn - vt_lo) * BM + wc * 32 + 8 * fq;
; #pragma unroll
;                 for (int ai = 0; ai < 2; ++ai)
; #pragma unroll
;                     for (int m = 0; m < 4; ++m) { const int row = rowi + ai * HALF + m * 16;
;                         const float rs_ = ss_in ? rsqrtf(ss_in[row0 + ai * HALF + m * 16] * (1.f / DM) + EPS) : 1.f;
; #pragma unroll
;                         for (int bj = 0; bj < 2; ++bj)
; #pragma unroll
;                             for (int n = 0; n < 2; ++n)
; #pragma unroll
;                                 for (int j = 0; j < 4; ++j) base[(size_t)(col0 + bj * HALF + 4 * n + j) * ldt + row] = (bf16_t)f2bf(acc[ai][bj][m][n][j] * rs_); }
.Lsbv_noss:
	v_readlane_b32 s16, v255, 2
	v_readlane_b32 s17, v255, 3
	s_cmp_lt_u32 s76, 32
	s_cselect_b32 s17, s17, s99
	s_cselect_b32 s16, s16, s98
	v_readfirstlane_b32 s44, v248
	v_readfirstlane_b32 s45, v251
	s_nop 0
	s_and_b32 s44, s44, 0x60
	s_and_b32 s45, s45, 0x40
	s_lshl_b32 s3, s8, 8
	s_add_i32 s3, s3, s44
	s_lshl_b32 s3, s3, 14
	s_add_u32 s16, s16, s3
	s_addc_u32 s17, s17, 0
	s_and_b32 s3, s12, 0x1f00
	s_add_i32 s3, s3, s45
	s_lshl_b32 s3, s3, 1
	s_add_u32 s16, s16, s3
	s_addc_u32 s17, s17, 0
	s_lshr_b32 s3, s45, 4
	s_lshr_b32 s44, s44, 5
	s_add_i32 s3, s3, s44
	s_mul_i32 s44, s3, 0x880
	s_add_i32 s44, s44, 0x20000
	s_cmp_eq_u32 s3, 7
	s_cselect_b32 s3, 0x480, 0
	s_add_i32 s44, s44, s3
	v_bfe_u32 v134, v248, 3, 2
	v_and_b32_e32 v135, 15, v251
	v_mul_u32_u24_e32 v134, 0x220, v134
	v_lshl_add_u32 v130, v135, 1, v134
	v_add_u32_e32 v130, s44, v130
	v_lshrrev_b32_e32 v134, 3, v231
	v_and_b32_e32 v135, 7, v231
	v_mul_u32_u24_e32 v136, 0x88, v134
	v_lshl_add_u32 v131, v135, 4, v136
	v_add_u32_e32 v131, s44, v131
	v_lshrrev_b32_e32 v136, 2, v134
	v_and_b32_e32 v137, 3, v134
	v_lshl_add_u32 v136, v136, 3, v137
	v_lshlrev_b32_e32 v136, 14, v136
	v_lshl_add_u32 v132, v135, 4, v136
	v_add_u32_e32 v133, 0x40000, v132
	s_mov_b32 s12, s16
	s_mov_b32 s13, s17
	v_mul_f32_e32 v134, v126, v232
	v_mul_f32_e32 v135, v127, v232
	v_mul_f32_e32 v136, v128, v232
	v_mul_f32_e32 v137, v129, v232
	v_cvt_pk_bf16_f32 v138, v134, v135
	v_cvt_pk_bf16_f32 v139, v136, v137
	ds_write_b16 v130, v138 offset:0
	ds_write_b16_d16_hi v130, v138 offset:136
	ds_write_b16 v130, v139 offset:272
	ds_write_b16_d16_hi v130, v139 offset:408
	v_mul_f32_e32 v140, v110, v233
	v_mul_f32_e32 v141, v111, v233
	v_mul_f32_e32 v142, v112, v233
	v_mul_f32_e32 v143, v113, v233
	v_cvt_pk_bf16_f32 v144, v140, v141
	v_cvt_pk_bf16_f32 v145, v142, v143
	ds_write_b16 v130, v144 offset:32
	ds_write_b16_d16_hi v130, v144 offset:168
	ds_write_b16 v130, v145 offset:304
	ds_write_b16_d16_hi v130, v145 offset:440
	v_mul_f32_e32 v134, v94, v234
	v_mul_f32_e32 v135, v95, v234
	v_mul_f32_e32 v136, v96, v234
	v_mul_f32_e32 v137, v97, v234
	v_cvt_pk_bf16_f32 v138, v134, v135
	v_cvt_pk_bf16_f32 v139, v136, v137
	ds_write_b16 v130, v138 offset:64
	ds_write_b16_d16_hi v130, v138 offset:200
	ds_write_b16 v130, v139 offset:336
	ds_write_b16_d16_hi v130, v139 offset:472
	v_mul_f32_e32 v140, v78, v235
	v_mul_f32_e32 v141, v79, v235
	v_mul_f32_e32 v142, v80, v235
	v_mul_f32_e32 v143, v81, v235
	v_cvt_pk_bf16_f32 v144, v140, v141
	v_cvt_pk_bf16_f32 v145, v142, v143
	ds_write_b16 v130, v144 offset:96
	ds_write_b16_d16_hi v130, v144 offset:232
	ds_write_b16 v130, v145 offset:368
	ds_write_b16_d16_hi v130, v145 offset:504
	ds_read2_b64 v[146:149], v131 offset1:1
	ds_read2_b64 v[150:153], v131 offset0:136 offset1:137
	s_waitcnt lgkmcnt(0)
	global_store_dwordx4 v132, v[146:149], s[12:13]
	global_store_dwordx4 v133, v[150:153], s[12:13]
	v_mul_f32_e32 v134, v62, v236
	v_mul_f32_e32 v135, v63, v236
	v_mul_f32_e32 v136, v64, v236
	v_mul_f32_e32 v137, v65, v236
	v_cvt_pk_bf16_f32 v138, v134, v135
	v_cvt_pk_bf16_f32 v139, v136, v137
	ds_write_b16 v130, v138 offset:0
	ds_write_b16_d16_hi v130, v138 offset:136
	ds_write_b16 v130, v139 offset:272
	ds_write_b16_d16_hi v130, v139 offset:408
	v_mul_f32_e32 v140, v46, v237
	v_mul_f32_e32 v141, v47, v237
	v_mul_f32_e32 v142, v48, v237
	v_mul_f32_e32 v143, v49, v237
	v_cvt_pk_bf16_f32 v144, v140, v141
	v_cvt_pk_bf16_f32 v145, v142, v143
	ds_write_b16 v130, v144 offset:32
	ds_write_b16_d16_hi v130, v144 offset:168
	ds_write_b16 v130, v145 offset:304
	ds_write_b16_d16_hi v130, v145 offset:440
	v_mul_f32_e32 v134, v30, v238
	v_mul_f32_e32 v135, v31, v238
	v_mul_f32_e32 v136, v32, v238
	v_mul_f32_e32 v137, v33, v238
	v_cvt_pk_bf16_f32 v138, v134, v135
	v_cvt_pk_bf16_f32 v139, v136, v137
	ds_write_b16 v130, v138 offset:64
	ds_write_b16_d16_hi v130, v138 offset:200
	ds_write_b16 v130, v139 offset:336
	ds_write_b16_d16_hi v130, v139 offset:472
	v_mul_f32_e32 v140, v14, v239
	v_mul_f32_e32 v141, v15, v239
	v_mul_f32_e32 v142, v16, v239
	v_mul_f32_e32 v143, v17, v239
	v_cvt_pk_bf16_f32 v144, v140, v141
	v_cvt_pk_bf16_f32 v145, v142, v143
	ds_write_b16 v130, v144 offset:96
	ds_write_b16_d16_hi v130, v144 offset:232
	ds_write_b16 v130, v145 offset:368
	ds_write_b16_d16_hi v130, v145 offset:504
	ds_read2_b64 v[154:157], v131 offset1:1
	ds_read2_b64 v[158:161], v131 offset0:136 offset1:137
	s_waitcnt lgkmcnt(0)
	global_store_dwordx4 v132, v[154:157], s[12:13] offset:256
	global_store_dwordx4 v133, v[158:161], s[12:13] offset:256
	s_add_u32 s12, s16, 0x10000
	s_addc_u32 s13, s17, 0
	v_mul_f32_e32 v134, v122, v232
	v_mul_f32_e32 v135, v123, v232
	v_mul_f32_e32 v136, v124, v232
	v_mul_f32_e32 v137, v125, v232
	v_cvt_pk_bf16_f32 v138, v134, v135
	v_cvt_pk_bf16_f32 v139, v136, v137
	ds_write_b16 v130, v138 offset:0
	ds_write_b16_d16_hi v130, v138 offset:136
	ds_write_b16 v130, v139 offset:272
	ds_write_b16_d16_hi v130, v139 offset:408
	v_mul_f32_e32 v140, v106, v233
	v_mul_f32_e32 v141, v107, v233
	v_mul_f32_e32 v142, v108, v233
	v_mul_f32_e32 v143, v109, v233
	v_cvt_pk_bf16_f32 v144, v140, v141
	v_cvt_pk_bf16_f32 v145, v142, v143
	ds_write_b16 v130, v144 offset:32
	ds_write_b16_d16_hi v130, v144 offset:168
	ds_write_b16 v130, v145 offset:304
	ds_write_b16_d16_hi v130, v145 offset:440
	v_mul_f32_e32 v134, v90, v234
	v_mul_f32_e32 v135, v91, v234
	v_mul_f32_e32 v136, v92, v234
	v_mul_f32_e32 v137, v93, v234
	v_cvt_pk_bf16_f32 v138, v134, v135
	v_cvt_pk_bf16_f32 v139, v136, v137
	ds_write_b16 v130, v138 offset:64
	ds_write_b16_d16_hi v130, v138 offset:200
	ds_write_b16 v130, v139 offset:336
	ds_write_b16_d16_hi v130, v139 offset:472
	v_mul_f32_e32 v140, v74, v235
	v_mul_f32_e32 v141, v75, v235
	v_mul_f32_e32 v142, v76, v235
	v_mul_f32_e32 v143, v77, v235
	v_cvt_pk_bf16_f32 v144, v140, v141
	v_cvt_pk_bf16_f32 v145, v142, v143
	ds_write_b16 v130, v144 offset:96
	ds_write_b16_d16_hi v130, v144 offset:232
	ds_write_b16 v130, v145 offset:368
	ds_write_b16_d16_hi v130, v145 offset:504
	ds_read2_b64 v[146:149], v131 offset1:1
	ds_read2_b64 v[150:153], v131 offset0:136 offset1:137
	s_waitcnt lgkmcnt(0)
; DI unsigned f2bf(float f) { unsigned u = __builtin_bit_cast(unsigned, f); return (u + 0x7fffu + ((u >> 16) & 1u)) >> 16; }
;     DI void operator()(const f32x4 (&acc)[2][2][4][2], const Unit& u, int wr, int wc, int fr, int fq) const {
;     ...
;                     for (int m = 0; m < 4; ++m) { const int row = rowi + ai * HALF + m * 16;
;                         const float rs_ = ss_in ? rsqrtf(ss_in[row0 + ai * HALF + m * 16] * (1.f / DM) + EPS) : 1.f;
; #pragma unroll
;                         for (int bj = 0; bj < 2; ++bj)
; #pragma unroll
;                             for (int n = 0; n < 2; ++n)
; #pragma unroll
;                                 for (int j = 0; j < 4; ++j) base[(size_t)(col0 + bj * HALF + 4 * n + j) * ldt + row] = (bf16_t)f2bf(acc[ai][bj][m][n][j] * rs_); }
	global_store_dwordx4 v132, v[146:149], s[12:13]
	global_store_dwordx4 v133, v[150:153], s[12:13]
	v_mul_f32_e32 v134, v58, v236
	v_mul_f32_e32 v135, v59, v236
	v_mul_f32_e32 v136, v60, v236
	v_mul_f32_e32 v137, v61, v236
	v_cvt_pk_bf16_f32 v138, v134, v135
	v_cvt_pk_bf16_f32 v139, v136, v137
	ds_write_b16 v130, v138 offset:0
	ds_write_b16_d16_hi v130, v138 offset:136
	ds_write_b16 v130, v139 offset:272
	ds_write_b16_d16_hi v130, v139 offset:408
	v_mul_f32_e32 v140, v42, v237
	v_mul_f32_e32 v141, v43, v237
	v_mul_f32_e32 v142, v44, v237
	v_mul_f32_e32 v143, v45, v237
	v_cvt_pk_bf16_f32 v144, v140, v141
	v_cvt_pk_bf16_f32 v145, v142, v143
	ds_write_b16 v130, v144 offset:32
	ds_write_b16_d16_hi v130, v144 offset:168
	ds_write_b16 v130, v145 offset:304
	ds_write_b16_d16_hi v130, v145 offset:440
	v_mul_f32_e32 v134, v26, v238
	v_mul_f32_e32 v135, v27, v238
	v_mul_f32_e32 v136, v28, v238
	v_mul_f32_e32 v137, v29, v238
	v_cvt_pk_bf16_f32 v138, v134, v135
	v_cvt_pk_bf16_f32 v139, v136, v137
	ds_write_b16 v130, v138 offset:64
	ds_write_b16_d16_hi v130, v138 offset:200
	ds_write_b16 v130, v139 offset:336
	ds_write_b16_d16_hi v130, v139 offset:472
	v_mul_f32_e32 v140, v10, v239
	v_mul_f32_e32 v141, v11, v239
	v_mul_f32_e32 v142, v12, v239
	v_mul_f32_e32 v143, v13, v239
	v_cvt_pk_bf16_f32 v144, v140, v141
	v_cvt_pk_bf16_f32 v145, v142, v143
	ds_write_b16 v130, v144 offset:96
	ds_write_b16_d16_hi v130, v144 offset:232
	ds_write_b16 v130, v145 offset:368
	ds_write_b16_d16_hi v130, v145 offset:504
	ds_read2_b64 v[154:157], v131 offset1:1
	ds_read2_b64 v[158:161], v131 offset0:136 offset1:137
	s_waitcnt lgkmcnt(0)
	global_store_dwordx4 v132, v[154:157], s[12:13] offset:256
	global_store_dwordx4 v133, v[158:161], s[12:13] offset:256
	s_add_u32 s12, s16, 0x200000
	s_addc_u32 s13, s17, 0
	v_mul_f32_e32 v134, v118, v232
	v_mul_f32_e32 v135, v119, v232
	v_mul_f32_e32 v136, v120, v232
	v_mul_f32_e32 v137, v121, v232
	v_cvt_pk_bf16_f32 v138, v134, v135
	v_cvt_pk_bf16_f32 v139, v136, v137
	ds_write_b16 v130, v138 offset:0
	ds_write_b16_d16_hi v130, v138 offset:136
	ds_write_b16 v130, v139 offset:272
	ds_write_b16_d16_hi v130, v139 offset:408
	v_mul_f32_e32 v140, v102, v233
	v_mul_f32_e32 v141, v103, v233
	v_mul_f32_e32 v142, v104, v233
	v_mul_f32_e32 v143, v105, v233
	v_cvt_pk_bf16_f32 v144, v140, v141
	v_cvt_pk_bf16_f32 v145, v142, v143
	ds_write_b16 v130, v144 offset:32
	ds_write_b16_d16_hi v130, v144 offset:168
	ds_write_b16 v130, v145 offset:304
	ds_write_b16_d16_hi v130, v145 offset:440
	v_mul_f32_e32 v134, v86, v234
	v_mul_f32_e32 v135, v87, v234
	v_mul_f32_e32 v136, v88, v234
	v_mul_f32_e32 v137, v89, v234
	v_cvt_pk_bf16_f32 v138, v134, v135
	v_cvt_pk_bf16_f32 v139, v136, v137
	ds_write_b16 v130, v138 offset:64
	ds_write_b16_d16_hi v130, v138 offset:200
	ds_write_b16 v130, v139 offset:336
	ds_write_b16_d16_hi v130, v139 offset:472
	v_mul_f32_e32 v140, v70, v235
	v_mul_f32_e32 v141, v71, v235
	v_mul_f32_e32 v142, v72, v235
	v_mul_f32_e32 v143, v73, v235
	v_cvt_pk_bf16_f32 v144, v140, v141
	v_cvt_pk_bf16_f32 v145, v142, v143
	ds_write_b16 v130, v144 offset:96
	ds_write_b16_d16_hi v130, v144 offset:232
	ds_write_b16 v130, v145 offset:368
	ds_write_b16_d16_hi v130, v145 offset:504
	ds_read2_b64 v[146:149], v131 offset1:1
	ds_read2_b64 v[150:153], v131 offset0:136 offset1:137
	s_waitcnt lgkmcnt(0)
	global_store_dwordx4 v132, v[146:149], s[12:13]
	global_store_dwordx4 v133, v[150:153], s[12:13]
	v_mul_f32_e32 v134, v54, v236
	v_mul_f32_e32 v135, v55, v236
	v_mul_f32_e32 v136, v56, v236
	v_mul_f32_e32 v137, v57, v236
	v_cvt_pk_bf16_f32 v138, v134, v135
	v_cvt_pk_bf16_f32 v139, v136, v137
	ds_write_b16 v130, v138 offset:0
	ds_write_b16_d16_hi v130, v138 offset:136
	ds_write_b16 v130, v139 offset:272
	ds_write_b16_d16_hi v130, v139 offset:408
	v_mul_f32_e32 v140, v38, v237
	v_mul_f32_e32 v141, v39, v237
	v_mul_f32_e32 v142, v40, v237
	v_mul_f32_e32 v143, v41, v237
	v_cvt_pk_bf16_f32 v144, v140, v141
	v_cvt_pk_bf16_f32 v145, v142, v143
	ds_write_b16 v130, v144 offset:32
	ds_write_b16_d16_hi v130, v144 offset:168
	ds_write_b16 v130, v145 offset:304
	ds_write_b16_d16_hi v130, v145 offset:440
	v_mul_f32_e32 v134, v22, v238
	v_mul_f32_e32 v135, v23, v238
	v_mul_f32_e32 v136, v24, v238
	v_mul_f32_e32 v137, v25, v238
	v_cvt_pk_bf16_f32 v138, v134, v135
	v_cvt_pk_bf16_f32 v139, v136, v137
	ds_write_b16 v130, v138 offset:64
	ds_write_b16_d16_hi v130, v138 offset:200
	ds_write_b16 v130, v139 offset:336
	ds_write_b16_d16_hi v130, v139 offset:472
	v_mul_f32_e32 v140, v6, v239
	v_mul_f32_e32 v141, v7, v239
	v_mul_f32_e32 v142, v8, v239
	v_mul_f32_e32 v143, v9, v239
	v_cvt_pk_bf16_f32 v144, v140, v141
	v_cvt_pk_bf16_f32 v145, v142, v143
	ds_write_b16 v130, v144 offset:96
	ds_write_b16_d16_hi v130, v144 offset:232
	ds_write_b16 v130, v145 offset:368
	ds_write_b16_d16_hi v130, v145 offset:504
	ds_read2_b64 v[154:157], v131 offset1:1
	ds_read2_b64 v[158:161], v131 offset0:136 offset1:137
	s_waitcnt lgkmcnt(0)
; DI unsigned f2bf(float f) { unsigned u = __builtin_bit_cast(unsigned, f); return (u + 0x7fffu + ((u >> 16) & 1u)) >> 16; }
;     DI void operator()(const f32x4 (&acc)[2][2][4][2], const Unit& u, int wr, int wc, int fr, int fq) const {
;     ...
;                     for (int m = 0; m < 4; ++m) { const int row = rowi + ai * HALF + m * 16;
;                         const float rs_ = ss_in ? rsqrtf(ss_in[row0 + ai * HALF + m * 16] * (1.f / DM) + EPS) : 1.f;
; #pragma unroll
;                         for (int bj = 0; bj < 2; ++bj)
; #pragma unroll
;                             for (int n = 0; n < 2; ++n)
; #pragma unroll
;                                 for (int j = 0; j < 4; ++j) base[(size_t)(col0 + bj * HALF + 4 * n + j) * ldt + row] = (bf16_t)f2bf(acc[ai][bj][m][n][j] * rs_); }
	global_store_dwordx4 v132, v[154:157], s[12:13] offset:256
	global_store_dwordx4 v133, v[158:161], s[12:13] offset:256
	s_add_u32 s12, s16, 0x210000
	s_addc_u32 s13, s17, 0
	v_mul_f32_e32 v134, v114, v232
	v_mul_f32_e32 v135, v115, v232
	v_mul_f32_e32 v136, v116, v232
	v_mul_f32_e32 v137, v117, v232
	v_cvt_pk_bf16_f32 v138, v134, v135
	v_cvt_pk_bf16_f32 v139, v136, v137
	ds_write_b16 v130, v138 offset:0
	ds_write_b16_d16_hi v130, v138 offset:136
	ds_write_b16 v130, v139 offset:272
	ds_write_b16_d16_hi v130, v139 offset:408
	v_mul_f32_e32 v140, v98, v233
	v_mul_f32_e32 v141, v99, v233
	v_mul_f32_e32 v142, v100, v233
	v_mul_f32_e32 v143, v101, v233
	v_cvt_pk_bf16_f32 v144, v140, v141
	v_cvt_pk_bf16_f32 v145, v142, v143
	ds_write_b16 v130, v144 offset:32
	ds_write_b16_d16_hi v130, v144 offset:168
	ds_write_b16 v130, v145 offset:304
	ds_write_b16_d16_hi v130, v145 offset:440
	v_mul_f32_e32 v134, v82, v234
	v_mul_f32_e32 v135, v83, v234
	v_mul_f32_e32 v136, v84, v234
	v_mul_f32_e32 v137, v85, v234
	v_cvt_pk_bf16_f32 v138, v134, v135
	v_cvt_pk_bf16_f32 v139, v136, v137
	ds_write_b16 v130, v138 offset:64
	ds_write_b16_d16_hi v130, v138 offset:200
	ds_write_b16 v130, v139 offset:336
	ds_write_b16_d16_hi v130, v139 offset:472
	v_mul_f32_e32 v140, v66, v235
	v_mul_f32_e32 v141, v67, v235
	v_mul_f32_e32 v142, v68, v235
	v_mul_f32_e32 v143, v69, v235
	v_cvt_pk_bf16_f32 v144, v140, v141
	v_cvt_pk_bf16_f32 v145, v142, v143
	ds_write_b16 v130, v144 offset:96
	ds_write_b16_d16_hi v130, v144 offset:232
	ds_write_b16 v130, v145 offset:368
	ds_write_b16_d16_hi v130, v145 offset:504
	ds_read2_b64 v[146:149], v131 offset1:1
	ds_read2_b64 v[150:153], v131 offset0:136 offset1:137
	s_waitcnt lgkmcnt(0)
	global_store_dwordx4 v132, v[146:149], s[12:13]
	global_store_dwordx4 v133, v[150:153], s[12:13]
	v_mul_f32_e32 v134, v50, v236
	v_mul_f32_e32 v135, v51, v236
	v_mul_f32_e32 v136, v52, v236
	v_mul_f32_e32 v137, v53, v236
	v_cvt_pk_bf16_f32 v138, v134, v135
	v_cvt_pk_bf16_f32 v139, v136, v137
	ds_write_b16 v130, v138 offset:0
	ds_write_b16_d16_hi v130, v138 offset:136
	ds_write_b16 v130, v139 offset:272
	ds_write_b16_d16_hi v130, v139 offset:408
	v_mul_f32_e32 v140, v34, v237
	v_mul_f32_e32 v141, v35, v237
	v_mul_f32_e32 v142, v36, v237
	v_mul_f32_e32 v143, v37, v237
	v_cvt_pk_bf16_f32 v144, v140, v141
	v_cvt_pk_bf16_f32 v145, v142, v143
	ds_write_b16 v130, v144 offset:32
	ds_write_b16_d16_hi v130, v144 offset:168
	ds_write_b16 v130, v145 offset:304
	ds_write_b16_d16_hi v130, v145 offset:440
	v_mul_f32_e32 v134, v18, v238
	v_mul_f32_e32 v135, v19, v238
	v_mul_f32_e32 v136, v20, v238
	v_mul_f32_e32 v137, v21, v238
	v_cvt_pk_bf16_f32 v138, v134, v135
	v_cvt_pk_bf16_f32 v139, v136, v137
	ds_write_b16 v130, v138 offset:64
	ds_write_b16_d16_hi v130, v138 offset:200
	ds_write_b16 v130, v139 offset:336
	ds_write_b16_d16_hi v130, v139 offset:472
	v_mul_f32_e32 v140, v2, v239
	v_mul_f32_e32 v141, v3, v239
	v_mul_f32_e32 v142, v4, v239
	v_mul_f32_e32 v143, v5, v239
	v_cvt_pk_bf16_f32 v144, v140, v141
	v_cvt_pk_bf16_f32 v145, v142, v143
	ds_write_b16 v130, v144 offset:96
	ds_write_b16_d16_hi v130, v144 offset:232
	ds_write_b16 v130, v145 offset:368
	ds_write_b16_d16_hi v130, v145 offset:504
	ds_read2_b64 v[154:157], v131 offset1:1
	ds_read2_b64 v[158:161], v131 offset0:136 offset1:137
	s_waitcnt lgkmcnt(0)
	global_store_dwordx4 v132, v[154:157], s[12:13] offset:256
	global_store_dwordx4 v133, v[158:161], s[12:13] offset:256

; #define LAS __attribute__((address_space(3)))
;     DI void softmax_store(f32x4 (&acc)[2][2][4][2], const Unit& u, int wr, int wc, int fr, int fq, LAS unsigned char* lds) const {
;         LAS float* ex = (LAS float*)lds;
;         const float scl2 = 0.06375871541229934f;
;         const int rloc = wr * 64 + fr;
;         float mloc[2][4];
; #pragma unroll
;         for (int ai = 0; ai < 2; ++ai)
; #pragma unroll
;             for (int m = 0; m < 4; ++m) { const int rl = rloc + ai * HALF + m * 16;
;                 const float rs_ = rsqrtf(ss_in[u.pm * BM + rl] * (1.f / DM) + EPS) * scl2;
;                 float mx = -3.0e38f;
; #pragma unroll
;                 for (int bj = 0; bj < 2; ++bj)
; #pragma unroll
;                     for (int n = 0; n < 2; ++n)
; #pragma unroll
;                         for (int j = 0; j < 4; ++j) { const float v = acc[ai][bj][m][n][j] * rs_; acc[ai][bj][m][n][j] = v; mx = fmaxf(mx, v); }
;                 mx = fmaxf(mx, __shfl_xor(mx, 16)); mx = fmaxf(mx, __shfl_xor(mx, 32));
;                 float sm = 0.f;
; #pragma unroll
;                 for (int bj = 0; bj < 2; ++bj)
; #pragma unroll
;                     for (int n = 0; n < 2; ++n)
; #pragma unroll
;                         for (int j = 0; j < 4; ++j) { const float e = __builtin_amdgcn_exp2f(acc[ai][bj][m][n][j] - mx); acc[ai][bj][m][n][j] = e; sm += e; }
;                 sm += __shfl_xor(sm, 16); sm += __shfl_xor(sm, 32);
;                 mloc[ai][m] = mx;
;                 if (fq == 0) { ex[(rl * 4 + wc) * 2] = mx; ex[(rl * 4 + wc) * 2 + 1] = sm; } }
.LBB0_477:
	v_readlane_b32 s0, v255, 48
	v_readlane_b32 s88, v254, 50
	v_readlane_b32 s1, v255, 49
	v_readlane_b32 s89, v254, 51
	v_readlane_b32 s90, v254, 52
	s_andn2_b64 vcc, exec, s[0:1]
	v_readlane_b32 s28, v254, 48
	v_readlane_b32 s79, v254, 49
	v_readlane_b32 s91, v254, 53
	v_readlane_b32 s64, v254, 54
	v_readlane_b32 s89, v254, 55
	v_mov_b32_e32 v213, 0xfffe8000
	v_mov_b32_e32 v214, 0xfffe5000
	v_mov_b32_e32 v215, 0xfffe2000
	v_mov_b32_e32 v216, 0xfffdf000
	v_mov_b32_e32 v217, 0xfffdc000
	s_barrier
	s_cbranch_vccnz .LBB0_495
	s_waitcnt lgkmcnt(0)
	v_and_b32_e32 v130, 64, v231
	v_xor_b32_e32 v0, 16, v231
	v_add_u32_e32 v130, 64, v130
	v_cmp_lt_i32_e32 vcc, v0, v130
	v_xor_b32_e32 v131, 32, v231
	s_lshl_b32 s2, s76, 8
	v_cndmask_b32_e32 v0, v231, v0, vcc
	v_cmp_lt_i32_e32 vcc, v131, v130
	s_mov_b32 s4, 0xff61b1e6
	v_lshlrev_b32_e32 v0, 2, v0
	v_cndmask_b32_e32 v130, v231, v131, vcc
	v_lshlrev_b32_e32 v150, 2, v130
	v_add_u32_e32 v130, s2, v251
	v_ashrrev_i32_e32 v131, 31, v130
	v_lshl_add_u64 v[134:135], v[130:131], 2, s[74:75]
	global_load_dword v131, v[134:135], off
	v_readlane_b32 s0, v255, 36
	s_lshl_b32 s0, s0, 3
	s_add_i32 s3, s0, 0
	s_waitcnt vmcnt(0) lgkmcnt(0)
	v_fmamk_f32 v131, v131, 0x3a000000, v229
	v_cmp_gt_f32_e32 vcc, s33, v131
	v_mul_f32_e32 v132, 0x4b800000, v131
	s_nop 0
	v_cndmask_b32_e32 v131, v131, v132, vcc
	v_rsq_f32_e32 v131, v131
	s_nop 0
	v_mul_f32_e32 v132, 0x45800000, v131
	v_cndmask_b32_e32 v131, v131, v132, vcc
	v_mul_f32_e32 v131, 0x3d8293ee, v131
	v_mul_f32_e32 v132, v126, v131
	v_mul_f32_e32 v133, v127, v131
	v_max3_f32 v132, v132, s4, v133
	v_mul_f32_e32 v133, v128, v131
	v_mul_f32_e32 v136, v129, v131
	v_max3_f32 v132, v132, v133, v136
	v_mul_f32_e32 v133, v122, v131
	v_mul_f32_e32 v136, v123, v131
	v_max3_f32 v132, v132, v133, v136
	v_mul_f32_e32 v133, v124, v131
	v_mul_f32_e32 v136, v125, v131
	v_max3_f32 v132, v132, v133, v136
	v_mul_f32_e32 v133, v118, v131
	v_mul_f32_e32 v136, v119, v131
	v_max3_f32 v132, v132, v133, v136
	v_mul_f32_e32 v133, v120, v131
	v_mul_f32_e32 v136, v121, v131
	v_max3_f32 v132, v132, v133, v136
	v_mul_f32_e32 v133, v114, v131
	v_mul_f32_e32 v136, v115, v131
	v_max3_f32 v132, v132, v133, v136
	v_mul_f32_e32 v133, v116, v131
	v_mul_f32_e32 v136, v117, v131
	v_max3_f32 v132, v132, v133, v136
	ds_bpermute_b32 v133, v0, v132
	s_waitcnt lgkmcnt(0)
	v_max_f32_e32 v133, v133, v133
	v_max_f32_e32 v132, v132, v133
	ds_bpermute_b32 v133, v150, v132
	s_waitcnt lgkmcnt(0)
	v_max_f32_e32 v133, v133, v133
	v_max_f32_e32 v132, v132, v133
	v_fma_f32 v126, v126, v131, -v132
	v_exp_f32_e32 v126, v126
	v_fma_f32 v127, v127, v131, -v132
	v_exp_f32_e32 v127, v127
	v_fma_f32 v128, v128, v131, -v132
	v_exp_f32_e32 v128, v128
	v_fma_f32 v129, v129, v131, -v132
	v_exp_f32_e32 v129, v129
	v_fma_f32 v122, v122, v131, -v132
	v_add_f32_e32 v133, 0, v126
	v_exp_f32_e32 v122, v122
	v_fma_f32 v123, v123, v131, -v132
	v_add_f32_e32 v133, v127, v133
	v_exp_f32_e32 v123, v123
	v_fma_f32 v124, v124, v131, -v132
	v_add_f32_e32 v133, v128, v133
	v_exp_f32_e32 v124, v124
	v_fma_f32 v125, v125, v131, -v132
	v_add_f32_e32 v133, v129, v133
	v_exp_f32_e32 v125, v125
	v_fma_f32 v118, v118, v131, -v132
	v_add_f32_e32 v133, v122, v133
	v_exp_f32_e32 v118, v118
	v_fma_f32 v119, v119, v131, -v132
	v_add_f32_e32 v133, v123, v133
	v_exp_f32_e32 v119, v119
	v_fma_f32 v120, v120, v131, -v132
	v_add_f32_e32 v133, v124, v133
	v_exp_f32_e32 v120, v120
	v_fma_f32 v121, v121, v131, -v132
	v_add_f32_e32 v133, v125, v133
	v_exp_f32_e32 v121, v121
	v_fma_f32 v114, v114, v131, -v132
	v_add_f32_e32 v133, v118, v133
	v_exp_f32_e32 v114, v114
	v_fma_f32 v115, v115, v131, -v132
	v_add_f32_e32 v133, v119, v133
	v_exp_f32_e32 v115, v115
	v_fma_f32 v116, v116, v131, -v132
	v_add_f32_e32 v133, v120, v133
	v_exp_f32_e32 v116, v116
	v_fma_f32 v117, v117, v131, -v132
	v_add_f32_e32 v133, v121, v133
	v_exp_f32_e32 v117, v117
	v_add_f32_e32 v133, v114, v133
	v_add_f32_e32 v133, v115, v133
	v_add_f32_e32 v133, v116, v133
	v_add_f32_e32 v131, v117, v133
	ds_bpermute_b32 v133, v0, v131
	s_waitcnt lgkmcnt(0)
	v_add_f32_e32 v131, v131, v133
	ds_bpermute_b32 v133, v150, v131
	s_and_saveexec_b64 s[0:1], s[36:37]
	s_cbranch_execz .LBB0_480
	v_lshl_add_u32 v136, v251, 5, s3
	s_waitcnt lgkmcnt(0)
	v_add_f32_e32 v133, v131, v133
	ds_write_b64 v136, v[132:133]
;     DI void softmax_store(f32x4 (&acc)[2][2][4][2], const Unit& u, int wr, int wc, int fr, int fq, LAS unsigned char* lds) const {
;     ...
; #pragma unroll
;             for (int m = 0; m < 4; ++m) { const int rl = rloc + ai * HALF + m * 16;
;                 const float rs_ = rsqrtf(ss_in[u.pm * BM + rl] * (1.f / DM) + EPS) * scl2;
;                 float mx = -3.0e38f;
; #pragma unroll
;                 for (int bj = 0; bj < 2; ++bj)
; #pragma unroll
;                     for (int n = 0; n < 2; ++n)
; #pragma unroll
;                         for (int j = 0; j < 4; ++j) { const float v = acc[ai][bj][m][n][j] * rs_; acc[ai][bj][m][n][j] = v; mx = fmaxf(mx, v); }
;                 mx = fmaxf(mx, __shfl_xor(mx, 16)); mx = fmaxf(mx, __shfl_xor(mx, 32));
;                 float sm = 0.f;
; #pragma unroll
;                 for (int bj = 0; bj < 2; ++bj)
; #pragma unroll
;                     for (int n = 0; n < 2; ++n)
; #pragma unroll
;                         for (int j = 0; j < 4; ++j) { const float e = __builtin_amdgcn_exp2f(acc[ai][bj][m][n][j] - mx); acc[ai][bj][m][n][j] = e; sm += e; }
;                 sm += __shfl_xor(sm, 16); sm += __shfl_xor(sm, 32);
;                 mloc[ai][m] = mx;
;                 if (fq == 0) { ex[(rl * 4 + wc) * 2] = mx; ex[(rl * 4 + wc) * 2 + 1] = sm; } }
.LBB0_480:
	s_or_b64 exec, exec, s[0:1]
	s_waitcnt lgkmcnt(0)
	global_load_dword v133, v[134:135], off offset:64
	v_or_b32_e32 v131, 16, v251
	s_waitcnt vmcnt(0) lgkmcnt(0)
	v_fmamk_f32 v133, v133, 0x3a000000, v229
	v_cmp_gt_f32_e32 vcc, s33, v133
	v_mul_f32_e32 v136, 0x4b800000, v133
	s_nop 0
	v_cndmask_b32_e32 v133, v133, v136, vcc
	v_rsq_f32_e32 v133, v133
	s_nop 0
	v_mul_f32_e32 v136, 0x45800000, v133
	v_cndmask_b32_e32 v133, v133, v136, vcc
	v_mul_f32_e32 v133, 0x3d8293ee, v133
	v_mul_f32_e32 v136, v110, v133
	v_mul_f32_e32 v137, v111, v133
	v_max3_f32 v136, v136, s4, v137
	v_mul_f32_e32 v137, v112, v133
	v_mul_f32_e32 v138, v113, v133
	v_max3_f32 v136, v136, v137, v138
	v_mul_f32_e32 v137, v106, v133
	v_mul_f32_e32 v138, v107, v133
	v_max3_f32 v136, v136, v137, v138
	v_mul_f32_e32 v137, v108, v133
	v_mul_f32_e32 v138, v109, v133
	v_max3_f32 v136, v136, v137, v138
	v_mul_f32_e32 v137, v102, v133
	v_mul_f32_e32 v138, v103, v133
	v_max3_f32 v136, v136, v137, v138
	v_mul_f32_e32 v137, v104, v133
	v_mul_f32_e32 v138, v105, v133
	v_max3_f32 v136, v136, v137, v138
	v_mul_f32_e32 v137, v98, v133
	v_mul_f32_e32 v138, v99, v133
	v_max3_f32 v136, v136, v137, v138
	v_mul_f32_e32 v137, v100, v133
	v_mul_f32_e32 v138, v101, v133
	v_max3_f32 v136, v136, v137, v138
	ds_bpermute_b32 v137, v0, v136
	s_waitcnt lgkmcnt(0)
	v_max_f32_e32 v137, v137, v137
	v_max_f32_e32 v136, v136, v137
	ds_bpermute_b32 v137, v150, v136
	s_waitcnt lgkmcnt(0)
	v_max_f32_e32 v137, v137, v137
	v_max_f32_e32 v136, v136, v137
	v_fma_f32 v110, v110, v133, -v136
	v_exp_f32_e32 v110, v110
	v_fma_f32 v111, v111, v133, -v136
	v_exp_f32_e32 v111, v111
	v_fma_f32 v112, v112, v133, -v136
	v_exp_f32_e32 v112, v112
	v_fma_f32 v113, v113, v133, -v136
	v_exp_f32_e32 v113, v113
	v_fma_f32 v106, v106, v133, -v136
	v_add_f32_e32 v137, 0, v110
	v_exp_f32_e32 v106, v106
	v_fma_f32 v107, v107, v133, -v136
	v_add_f32_e32 v137, v111, v137
	v_exp_f32_e32 v107, v107
	v_fma_f32 v108, v108, v133, -v136
	v_add_f32_e32 v137, v112, v137
	v_exp_f32_e32 v108, v108
	v_fma_f32 v109, v109, v133, -v136
	v_add_f32_e32 v137, v113, v137
	v_exp_f32_e32 v109, v109
	v_fma_f32 v102, v102, v133, -v136
	v_add_f32_e32 v137, v106, v137
	v_exp_f32_e32 v102, v102
	v_fma_f32 v103, v103, v133, -v136
	v_add_f32_e32 v137, v107, v137
	v_exp_f32_e32 v103, v103
	v_fma_f32 v104, v104, v133, -v136
	v_add_f32_e32 v137, v108, v137
	v_exp_f32_e32 v104, v104
	v_fma_f32 v105, v105, v133, -v136
	v_add_f32_e32 v137, v109, v137
	v_exp_f32_e32 v105, v105
	v_fma_f32 v98, v98, v133, -v136
	v_add_f32_e32 v137, v102, v137
	v_exp_f32_e32 v98, v98
	v_fma_f32 v99, v99, v133, -v136
	v_add_f32_e32 v137, v103, v137
	v_exp_f32_e32 v99, v99
	v_fma_f32 v100, v100, v133, -v136
	v_add_f32_e32 v137, v104, v137
	v_exp_f32_e32 v100, v100
	v_fma_f32 v101, v101, v133, -v136
	v_add_f32_e32 v137, v105, v137
	v_exp_f32_e32 v101, v101
	v_add_f32_e32 v137, v98, v137
	v_add_f32_e32 v137, v99, v137
	v_add_f32_e32 v137, v100, v137
	v_add_f32_e32 v133, v101, v137
	ds_bpermute_b32 v137, v0, v133
	s_waitcnt lgkmcnt(0)
	v_add_f32_e32 v133, v133, v137
	ds_bpermute_b32 v137, v150, v133
	s_and_saveexec_b64 s[0:1], s[36:37]
	s_cbranch_execz .LBB0_482
	v_lshl_add_u32 v138, v131, 5, s3
	s_waitcnt lgkmcnt(0)
	v_add_f32_e32 v137, v133, v137
	ds_write_b64 v138, v[136:137]
.LBB0_482:
	s_or_b64 exec, exec, s[0:1]
	s_waitcnt lgkmcnt(0)
	global_load_dword v137, v[134:135], off offset:128
	v_or_b32_e32 v133, 32, v251
	s_waitcnt vmcnt(0) lgkmcnt(0)
	v_fmamk_f32 v137, v137, 0x3a000000, v229
	v_cmp_gt_f32_e32 vcc, s33, v137
	v_mul_f32_e32 v138, 0x4b800000, v137
	s_nop 0
	v_cndmask_b32_e32 v137, v137, v138, vcc
	v_rsq_f32_e32 v137, v137
	s_nop 0
	v_mul_f32_e32 v138, 0x45800000, v137
	v_cndmask_b32_e32 v137, v137, v138, vcc
	v_mul_f32_e32 v137, 0x3d8293ee, v137
	v_mul_f32_e32 v138, v94, v137
	v_mul_f32_e32 v139, v95, v137
	v_max3_f32 v138, v138, s4, v139
	v_mul_f32_e32 v139, v96, v137
	v_mul_f32_e32 v140, v97, v137
	v_max3_f32 v138, v138, v139, v140
	v_mul_f32_e32 v139, v90, v137
	v_mul_f32_e32 v140, v91, v137
	v_max3_f32 v138, v138, v139, v140
	v_mul_f32_e32 v139, v92, v137
	v_mul_f32_e32 v140, v93, v137
	v_max3_f32 v138, v138, v139, v140
	v_mul_f32_e32 v139, v86, v137
	v_mul_f32_e32 v140, v87, v137
	v_max3_f32 v138, v138, v139, v140
	v_mul_f32_e32 v139, v88, v137
	v_mul_f32_e32 v140, v89, v137
	v_max3_f32 v138, v138, v139, v140
	v_mul_f32_e32 v139, v82, v137
	v_mul_f32_e32 v140, v83, v137
	v_max3_f32 v138, v138, v139, v140
	v_mul_f32_e32 v139, v84, v137
	v_mul_f32_e32 v140, v85, v137
	v_max3_f32 v138, v138, v139, v140
	ds_bpermute_b32 v139, v0, v138
	s_waitcnt lgkmcnt(0)
	v_max_f32_e32 v139, v139, v139
	v_max_f32_e32 v138, v138, v139
	ds_bpermute_b32 v139, v150, v138
	s_waitcnt lgkmcnt(0)
	v_max_f32_e32 v139, v139, v139
	v_max_f32_e32 v138, v138, v139
	v_fma_f32 v94, v94, v137, -v138
	v_exp_f32_e32 v94, v94
	v_fma_f32 v95, v95, v137, -v138
	v_exp_f32_e32 v95, v95
	v_fma_f32 v96, v96, v137, -v138
	v_exp_f32_e32 v96, v96
	v_fma_f32 v97, v97, v137, -v138
	v_exp_f32_e32 v97, v97
	v_fma_f32 v90, v90, v137, -v138
	v_add_f32_e32 v139, 0, v94
	v_exp_f32_e32 v90, v90
	v_fma_f32 v91, v91, v137, -v138
	v_add_f32_e32 v139, v95, v139
	v_exp_f32_e32 v91, v91
	v_fma_f32 v92, v92, v137, -v138
	v_add_f32_e32 v139, v96, v139
	v_exp_f32_e32 v92, v92
	v_fma_f32 v93, v93, v137, -v138
	v_add_f32_e32 v139, v97, v139
	v_exp_f32_e32 v93, v93
	v_fma_f32 v86, v86, v137, -v138
	v_add_f32_e32 v139, v90, v139
	v_exp_f32_e32 v86, v86
	v_fma_f32 v87, v87, v137, -v138
	v_add_f32_e32 v139, v91, v139
	v_exp_f32_e32 v87, v87
	v_fma_f32 v88, v88, v137, -v138
	v_add_f32_e32 v139, v92, v139
	v_exp_f32_e32 v88, v88
	v_fma_f32 v89, v89, v137, -v138
	v_add_f32_e32 v139, v93, v139
	v_exp_f32_e32 v89, v89
	v_fma_f32 v82, v82, v137, -v138
	v_add_f32_e32 v139, v86, v139
	v_exp_f32_e32 v82, v82
	v_fma_f32 v83, v83, v137, -v138
	v_add_f32_e32 v139, v87, v139
	v_exp_f32_e32 v83, v83
	v_fma_f32 v84, v84, v137, -v138
	v_add_f32_e32 v139, v88, v139
	v_exp_f32_e32 v84, v84
	v_fma_f32 v85, v85, v137, -v138
	v_add_f32_e32 v139, v89, v139
	v_exp_f32_e32 v85, v85
	v_add_f32_e32 v139, v82, v139
	v_add_f32_e32 v139, v83, v139
	v_add_f32_e32 v139, v84, v139
	v_add_f32_e32 v137, v85, v139
	ds_bpermute_b32 v139, v0, v137
	s_waitcnt lgkmcnt(0)
	v_add_f32_e32 v137, v137, v139
	ds_bpermute_b32 v139, v150, v137
	s_and_saveexec_b64 s[0:1], s[36:37]
	s_cbranch_execz .LBB0_484
	v_lshl_add_u32 v140, v133, 5, s3
	s_waitcnt lgkmcnt(0)
	v_add_f32_e32 v139, v137, v139
	ds_write_b64 v140, v[138:139]
;     DI void softmax_store(f32x4 (&acc)[2][2][4][2], const Unit& u, int wr, int wc, int fr, int fq, LAS unsigned char* lds) const {
;     ...
; #pragma unroll
;             for (int m = 0; m < 4; ++m) { const int rl = rloc + ai * HALF + m * 16;
;                 const float rs_ = rsqrtf(ss_in[u.pm * BM + rl] * (1.f / DM) + EPS) * scl2;
;                 float mx = -3.0e38f;
; #pragma unroll
;                 for (int bj = 0; bj < 2; ++bj)
; #pragma unroll
;                     for (int n = 0; n < 2; ++n)
; #pragma unroll
;                         for (int j = 0; j < 4; ++j) { const float v = acc[ai][bj][m][n][j] * rs_; acc[ai][bj][m][n][j] = v; mx = fmaxf(mx, v); }
;                 mx = fmaxf(mx, __shfl_xor(mx, 16)); mx = fmaxf(mx, __shfl_xor(mx, 32));
;                 float sm = 0.f;
; #pragma unroll
;                 for (int bj = 0; bj < 2; ++bj)
; #pragma unroll
;                     for (int n = 0; n < 2; ++n)
; #pragma unroll
;                         for (int j = 0; j < 4; ++j) { const float e = __builtin_amdgcn_exp2f(acc[ai][bj][m][n][j] - mx); acc[ai][bj][m][n][j] = e; sm += e; }
;                 sm += __shfl_xor(sm, 16); sm += __shfl_xor(sm, 32);
;                 mloc[ai][m] = mx;
;                 if (fq == 0) { ex[(rl * 4 + wc) * 2] = mx; ex[(rl * 4 + wc) * 2 + 1] = sm; } }
.LBB0_484:
	s_or_b64 exec, exec, s[0:1]
	global_load_dword v137, v[134:135], off offset:192
	s_waitcnt vmcnt(0) lgkmcnt(0)
	v_fmamk_f32 v137, v137, 0x3a000000, v229
	v_mul_f32_e32 v139, 0x4b800000, v137
	v_cmp_gt_f32_e32 vcc, s33, v137
	s_nop 1
	v_cndmask_b32_e32 v137, v137, v139, vcc
	v_rsq_f32_e32 v137, v137
	s_nop 0
	v_mul_f32_e32 v139, 0x45800000, v137
	v_cndmask_b32_e32 v137, v137, v139, vcc
	v_mul_f32_e32 v137, 0x3d8293ee, v137
	v_mul_f32_e32 v139, v78, v137
	v_mul_f32_e32 v140, v79, v137
	v_mul_f32_e32 v141, v80, v137
	v_mul_f32_e32 v142, v81, v137
	v_max3_f32 v139, v139, s4, v140
	v_mul_f32_e32 v143, v74, v137
	v_mul_f32_e32 v144, v75, v137
	v_max3_f32 v139, v139, v141, v142
	v_mul_f32_e32 v145, v76, v137
	v_mul_f32_e32 v146, v77, v137
	v_max3_f32 v139, v139, v143, v144
	v_mul_f32_e32 v147, v70, v137
	v_mul_f32_e32 v148, v71, v137
	v_max3_f32 v139, v139, v145, v146
	v_mul_f32_e32 v149, v72, v137
	v_mul_f32_e32 v151, v73, v137
	v_max3_f32 v139, v139, v147, v148
	v_mul_f32_e32 v152, v66, v137
	v_mul_f32_e32 v153, v67, v137
	v_max3_f32 v139, v139, v149, v151
	v_mul_f32_e32 v154, v68, v137
	v_mul_f32_e32 v155, v69, v137
	v_max3_f32 v139, v139, v152, v153
	v_max3_f32 v139, v139, v154, v155
	ds_bpermute_b32 v140, v0, v139
	s_waitcnt lgkmcnt(0)
	v_max_f32_e32 v140, v140, v140
	v_max_f32_e32 v139, v139, v140
	ds_bpermute_b32 v140, v150, v139
	s_waitcnt lgkmcnt(0)
	v_max_f32_e32 v140, v140, v140
	v_max_f32_e32 v140, v139, v140
	v_fma_f32 v78, v78, v137, -v140
	v_fma_f32 v79, v79, v137, -v140
	v_exp_f32_e32 v144, v78
	v_fma_f32 v80, v80, v137, -v140
	v_exp_f32_e32 v145, v79
	v_fma_f32 v81, v81, v137, -v140
	v_exp_f32_e32 v148, v80
	v_fma_f32 v74, v74, v137, -v140
	v_fma_f32 v70, v70, v137, -v140
	v_exp_f32_e32 v149, v81
	v_fma_f32 v75, v75, v137, -v140
	v_fma_f32 v139, v68, v137, -v140
	v_exp_f32_e32 v142, v74
	v_exp_f32_e32 v68, v70
	v_add_f32_e32 v70, 0, v144
	v_fma_f32 v76, v76, v137, -v140
	v_exp_f32_e32 v143, v75
	v_add_f32_e32 v70, v145, v70
	v_fma_f32 v77, v77, v137, -v140
	v_exp_f32_e32 v146, v76
	v_add_f32_e32 v70, v148, v70
	v_exp_f32_e32 v147, v77
	v_add_f32_e32 v70, v149, v70
	v_fma_f32 v71, v71, v137, -v140
	v_add_f32_e32 v70, v142, v70
	v_fma_f32 v72, v72, v137, -v140
	v_fma_f32 v73, v73, v137, -v140
	v_fma_f32 v66, v66, v137, -v140
	v_fma_f32 v67, v67, v137, -v140
	v_fma_f32 v137, v69, v137, -v140
	v_exp_f32_e32 v69, v71
	v_add_f32_e32 v70, v143, v70
	v_exp_f32_e32 v74, v72
	v_add_f32_e32 v70, v146, v70
	v_exp_f32_e32 v75, v73
	v_add_f32_e32 v70, v147, v70
	v_exp_f32_e32 v66, v66
	v_add_f32_e32 v70, v68, v70
	v_exp_f32_e32 v67, v67
	v_add_f32_e32 v70, v69, v70
	v_exp_f32_e32 v72, v139
	v_add_f32_e32 v70, v74, v70
	v_add_f32_e32 v70, v75, v70
	v_exp_f32_e32 v73, v137
	v_add_f32_e32 v70, v66, v70
	v_add_f32_e32 v70, v67, v70
	v_add_f32_e32 v70, v72, v70
	v_add_f32_e32 v70, v73, v70
	ds_bpermute_b32 v71, v0, v70
	v_or_b32_e32 v139, 48, v251
	s_waitcnt lgkmcnt(0)
	v_add_f32_e32 v70, v70, v71
	ds_bpermute_b32 v71, v150, v70
	s_and_saveexec_b64 s[0:1], s[36:37]
	s_cbranch_execz .LBB0_486
	v_lshl_add_u32 v76, v139, 5, s3
	s_waitcnt lgkmcnt(0)
	v_add_f32_e32 v141, v70, v71
	ds_write_b64 v76, v[140:141]
.LBB0_486:
	s_or_b64 exec, exec, s[0:1]
	global_load_dword v70, v[134:135], off offset:512
	s_waitcnt vmcnt(0) lgkmcnt(0)
	v_fmamk_f32 v70, v70, 0x3a000000, v229
	v_mul_f32_e32 v71, 0x4b800000, v70
	v_cmp_gt_f32_e32 vcc, s33, v70
	s_nop 1
	v_cndmask_b32_e32 v70, v70, v71, vcc
	v_rsq_f32_e32 v70, v70
	s_nop 0
	v_mul_f32_e32 v71, 0x45800000, v70
	v_cndmask_b32_e32 v70, v70, v71, vcc
	v_mul_f32_e32 v71, 0x3d8293ee, v70
	v_mul_f32_e32 v70, v62, v71
	v_mul_f32_e32 v76, v63, v71
	v_mul_f32_e32 v77, v64, v71
	v_mul_f32_e32 v78, v65, v71
	v_max3_f32 v70, v70, s4, v76
	v_mul_f32_e32 v79, v58, v71
	v_mul_f32_e32 v80, v59, v71
	v_max3_f32 v70, v70, v77, v78
	v_mul_f32_e32 v81, v60, v71
	v_mul_f32_e32 v137, v61, v71
	v_max3_f32 v70, v70, v79, v80
	v_mul_f32_e32 v141, v54, v71
	v_mul_f32_e32 v151, v55, v71
	v_max3_f32 v70, v70, v81, v137
	v_mul_f32_e32 v152, v56, v71
	v_mul_f32_e32 v153, v57, v71
	v_max3_f32 v70, v70, v141, v151
	v_mul_f32_e32 v154, v50, v71
	v_mul_f32_e32 v155, v51, v71
	v_max3_f32 v70, v70, v152, v153
	v_mul_f32_e32 v156, v52, v71
	v_mul_f32_e32 v157, v53, v71
	v_max3_f32 v70, v70, v154, v155
	v_max3_f32 v70, v70, v156, v157
	ds_bpermute_b32 v76, v0, v70
	s_waitcnt lgkmcnt(0)
	v_max_f32_e32 v76, v76, v76
	v_max_f32_e32 v70, v70, v76
	ds_bpermute_b32 v76, v150, v70
	s_waitcnt lgkmcnt(0)
	v_max_f32_e32 v76, v76, v76
	v_max_f32_e32 v70, v70, v76
	v_fma_f32 v62, v62, v71, -v70
	v_fma_f32 v63, v63, v71, -v70
	v_exp_f32_e32 v76, v62
	v_fma_f32 v64, v64, v71, -v70
	v_exp_f32_e32 v77, v63
	v_fma_f32 v65, v65, v71, -v70
	v_exp_f32_e32 v80, v64
	v_fma_f32 v58, v58, v71, -v70
	v_fma_f32 v54, v54, v71, -v70
	v_exp_f32_e32 v81, v65
	v_fma_f32 v59, v59, v71, -v70
	v_fma_f32 v137, v52, v71, -v70
	v_exp_f32_e32 v64, v58
	v_exp_f32_e32 v52, v54
	v_add_f32_e32 v54, 0, v76
	v_fma_f32 v60, v60, v71, -v70
	v_exp_f32_e32 v65, v59
	v_add_f32_e32 v54, v77, v54
	v_fma_f32 v61, v61, v71, -v70
	v_exp_f32_e32 v78, v60
	v_add_f32_e32 v54, v80, v54
	v_exp_f32_e32 v79, v61
	v_add_f32_e32 v54, v81, v54
	v_fma_f32 v55, v55, v71, -v70
	v_add_f32_e32 v54, v64, v54
	v_fma_f32 v56, v56, v71, -v70
	v_fma_f32 v57, v57, v71, -v70
	v_fma_f32 v50, v50, v71, -v70
	v_fma_f32 v51, v51, v71, -v70
	v_fma_f32 v71, v53, v71, -v70
	v_exp_f32_e32 v53, v55
	v_add_f32_e32 v54, v65, v54
	v_exp_f32_e32 v58, v56
	v_add_f32_e32 v54, v78, v54
	v_exp_f32_e32 v59, v57
	v_add_f32_e32 v54, v79, v54
	v_exp_f32_e32 v50, v50
	v_add_f32_e32 v54, v52, v54
	v_exp_f32_e32 v51, v51
	v_add_f32_e32 v54, v53, v54
	v_exp_f32_e32 v56, v137
	v_add_f32_e32 v54, v58, v54
	v_add_f32_e32 v54, v59, v54
	v_exp_f32_e32 v57, v71
	v_add_f32_e32 v54, v50, v54
	v_add_f32_e32 v54, v51, v54
	v_add_f32_e32 v54, v56, v54
	v_add_f32_e32 v54, v57, v54
	ds_bpermute_b32 v55, v0, v54
	v_add_u32_e32 v137, 0x80, v251
	s_waitcnt lgkmcnt(0)
	v_add_f32_e32 v54, v54, v55
	ds_bpermute_b32 v55, v150, v54
	s_and_saveexec_b64 s[0:1], s[36:37]
	s_cbranch_execz .LBB0_488
	v_lshl_add_u32 v60, v137, 5, s3
	s_waitcnt lgkmcnt(0)
	v_add_f32_e32 v71, v54, v55
	ds_write_b64 v60, v[70:71]
;     DI void softmax_store(f32x4 (&acc)[2][2][4][2], const Unit& u, int wr, int wc, int fr, int fq, LAS unsigned char* lds) const {
;     ...
; #pragma unroll
;             for (int m = 0; m < 4; ++m) { const int rl = rloc + ai * HALF + m * 16;
;                 const float rs_ = rsqrtf(ss_in[u.pm * BM + rl] * (1.f / DM) + EPS) * scl2;
;                 float mx = -3.0e38f;
; #pragma unroll
;                 for (int bj = 0; bj < 2; ++bj)
; #pragma unroll
;                     for (int n = 0; n < 2; ++n)
; #pragma unroll
;                         for (int j = 0; j < 4; ++j) { const float v = acc[ai][bj][m][n][j] * rs_; acc[ai][bj][m][n][j] = v; mx = fmaxf(mx, v); }
;                 mx = fmaxf(mx, __shfl_xor(mx, 16)); mx = fmaxf(mx, __shfl_xor(mx, 32));
;                 float sm = 0.f;
; #pragma unroll
;                 for (int bj = 0; bj < 2; ++bj)
; #pragma unroll
;                     for (int n = 0; n < 2; ++n)
; #pragma unroll
;                         for (int j = 0; j < 4; ++j) { const float e = __builtin_amdgcn_exp2f(acc[ai][bj][m][n][j] - mx); acc[ai][bj][m][n][j] = e; sm += e; }
;                 sm += __shfl_xor(sm, 16); sm += __shfl_xor(sm, 32);
;                 mloc[ai][m] = mx;
;                 if (fq == 0) { ex[(rl * 4 + wc) * 2] = mx; ex[(rl * 4 + wc) * 2 + 1] = sm; } }
.LBB0_488:
	s_or_b64 exec, exec, s[0:1]
	global_load_dword v54, v[134:135], off offset:576
	s_waitcnt vmcnt(0) lgkmcnt(0)
	v_fmamk_f32 v54, v54, 0x3a000000, v229
	v_mul_f32_e32 v55, 0x4b800000, v54
	v_cmp_gt_f32_e32 vcc, s33, v54
	s_nop 1
	v_cndmask_b32_e32 v54, v54, v55, vcc
	v_rsq_f32_e32 v54, v54
	s_nop 0
	v_mul_f32_e32 v55, 0x45800000, v54
	v_cndmask_b32_e32 v54, v54, v55, vcc
	v_mul_f32_e32 v55, 0x3d8293ee, v54
	v_mul_f32_e32 v54, v46, v55
	v_mul_f32_e32 v60, v47, v55
	v_mul_f32_e32 v61, v48, v55
	v_mul_f32_e32 v62, v49, v55
	v_max3_f32 v54, v54, s4, v60
	v_mul_f32_e32 v63, v42, v55
	v_mul_f32_e32 v71, v43, v55
	v_max3_f32 v54, v54, v61, v62
	v_mul_f32_e32 v141, v44, v55
	v_mul_f32_e32 v151, v45, v55
	v_max3_f32 v54, v54, v63, v71
	v_mul_f32_e32 v152, v38, v55
	v_mul_f32_e32 v153, v39, v55
	v_max3_f32 v54, v54, v141, v151
	v_mul_f32_e32 v154, v40, v55
	v_mul_f32_e32 v155, v41, v55
	v_max3_f32 v54, v54, v152, v153
	v_mul_f32_e32 v156, v34, v55
	v_mul_f32_e32 v157, v35, v55
	v_max3_f32 v54, v54, v154, v155
	v_mul_f32_e32 v158, v36, v55
	v_mul_f32_e32 v159, v37, v55
	v_max3_f32 v54, v54, v156, v157
	v_max3_f32 v54, v54, v158, v159
	ds_bpermute_b32 v60, v0, v54
	s_waitcnt lgkmcnt(0)
	v_max_f32_e32 v60, v60, v60
	v_max_f32_e32 v54, v54, v60
	ds_bpermute_b32 v60, v150, v54
	s_waitcnt lgkmcnt(0)
	v_max_f32_e32 v60, v60, v60
	v_max_f32_e32 v54, v54, v60
	v_fma_f32 v46, v46, v55, -v54
	v_fma_f32 v47, v47, v55, -v54
	v_fma_f32 v60, v48, v55, -v54
	v_exp_f32_e32 v48, v46
	v_fma_f32 v61, v49, v55, -v54
	v_exp_f32_e32 v49, v47
	v_exp_f32_e32 v62, v60
	v_fma_f32 v42, v42, v55, -v54
	v_fma_f32 v38, v38, v55, -v54
	v_exp_f32_e32 v63, v61
	v_fma_f32 v43, v43, v55, -v54
	v_fma_f32 v71, v36, v55, -v54
	v_exp_f32_e32 v46, v42
	v_exp_f32_e32 v36, v38
	v_add_f32_e32 v38, 0, v48
	v_fma_f32 v44, v44, v55, -v54
	v_exp_f32_e32 v47, v43
	v_add_f32_e32 v38, v49, v38
	v_fma_f32 v45, v45, v55, -v54
	v_exp_f32_e32 v60, v44
	v_add_f32_e32 v38, v62, v38
	v_exp_f32_e32 v61, v45
	v_add_f32_e32 v38, v63, v38
	v_fma_f32 v39, v39, v55, -v54
	v_add_f32_e32 v38, v46, v38
	v_fma_f32 v40, v40, v55, -v54
	v_fma_f32 v41, v41, v55, -v54
	v_fma_f32 v34, v34, v55, -v54
	v_fma_f32 v35, v35, v55, -v54
	v_fma_f32 v55, v37, v55, -v54
	v_exp_f32_e32 v37, v39
	v_add_f32_e32 v38, v47, v38
	v_exp_f32_e32 v42, v40
	v_add_f32_e32 v38, v60, v38
	v_exp_f32_e32 v43, v41
	v_add_f32_e32 v38, v61, v38
	v_exp_f32_e32 v34, v34
	v_add_f32_e32 v38, v36, v38
	v_exp_f32_e32 v35, v35
	v_add_f32_e32 v38, v37, v38
	v_exp_f32_e32 v40, v71
	v_add_f32_e32 v38, v42, v38
	v_add_f32_e32 v38, v43, v38
	v_exp_f32_e32 v41, v55
	v_add_f32_e32 v38, v34, v38
	v_add_f32_e32 v38, v35, v38
	v_add_f32_e32 v38, v40, v38
	v_add_f32_e32 v38, v41, v38
	ds_bpermute_b32 v39, v0, v38
	v_add_u32_e32 v71, 0x90, v251
	s_waitcnt lgkmcnt(0)
	v_add_f32_e32 v38, v38, v39
	ds_bpermute_b32 v39, v150, v38
	s_and_saveexec_b64 s[0:1], s[36:37]
	s_cbranch_execz .LBB0_490
	v_lshl_add_u32 v44, v71, 5, s3
	s_waitcnt lgkmcnt(0)
	v_add_f32_e32 v55, v38, v39
	ds_write_b64 v44, v[54:55]
.LBB0_490:
	s_or_b64 exec, exec, s[0:1]
	global_load_dword v38, v[134:135], off offset:640
	s_waitcnt vmcnt(0) lgkmcnt(0)
	v_fmamk_f32 v38, v38, 0x3a000000, v229
	v_mul_f32_e32 v39, 0x4b800000, v38
	v_cmp_gt_f32_e32 vcc, s33, v38
	s_nop 1
	v_cndmask_b32_e32 v38, v38, v39, vcc
	v_rsq_f32_e32 v38, v38
	s_nop 0
	v_mul_f32_e32 v39, 0x45800000, v38
	v_cndmask_b32_e32 v38, v38, v39, vcc
	v_mul_f32_e32 v39, 0x3d8293ee, v38
	v_mul_f32_e32 v38, v30, v39
	v_mul_f32_e32 v44, v31, v39
	v_mul_f32_e32 v45, v32, v39
	v_mul_f32_e32 v55, v33, v39
	v_max3_f32 v38, v38, s4, v44
	v_mul_f32_e32 v141, v26, v39
	v_mul_f32_e32 v151, v27, v39
	v_max3_f32 v38, v38, v45, v55
	v_mul_f32_e32 v152, v28, v39
	v_mul_f32_e32 v153, v29, v39
	v_max3_f32 v38, v38, v141, v151
	v_mul_f32_e32 v154, v22, v39
	v_mul_f32_e32 v155, v23, v39
	v_max3_f32 v38, v38, v152, v153
	v_mul_f32_e32 v156, v24, v39
	v_mul_f32_e32 v157, v25, v39
	v_max3_f32 v38, v38, v154, v155
	v_mul_f32_e32 v158, v18, v39
	v_mul_f32_e32 v159, v19, v39
	v_max3_f32 v38, v38, v156, v157
	v_mul_f32_e32 v160, v20, v39
	v_mul_f32_e32 v161, v21, v39
	v_max3_f32 v38, v38, v158, v159
	v_max3_f32 v38, v38, v160, v161
	ds_bpermute_b32 v44, v0, v38
	s_waitcnt lgkmcnt(0)
	v_max_f32_e32 v44, v44, v44
	v_max_f32_e32 v38, v38, v44
	ds_bpermute_b32 v44, v150, v38
	s_waitcnt lgkmcnt(0)
	v_max_f32_e32 v44, v44, v44
	v_max_f32_e32 v38, v38, v44
	v_fma_f32 v30, v30, v39, -v38
	v_fma_f32 v31, v31, v39, -v38
	v_exp_f32_e32 v30, v30
	v_fma_f32 v32, v32, v39, -v38
	v_exp_f32_e32 v31, v31
	v_fma_f32 v33, v33, v39, -v38
	v_exp_f32_e32 v44, v32
	v_fma_f32 v26, v26, v39, -v38
	v_fma_f32 v23, v23, v39, -v38
	v_exp_f32_e32 v45, v33
	v_fma_f32 v27, v27, v39, -v38
	v_fma_f32 v55, v28, v39, -v38
	v_fma_f32 v141, v29, v39, -v38
	v_fma_f32 v22, v22, v39, -v38
	v_fma_f32 v24, v24, v39, -v38
	v_fma_f32 v25, v25, v39, -v38
	v_fma_f32 v18, v18, v39, -v38
	v_fma_f32 v19, v19, v39, -v38
	v_fma_f32 v151, v20, v39, -v38
	v_fma_f32 v39, v21, v39, -v38
	v_exp_f32_e32 v28, v26
	v_exp_f32_e32 v21, v23
	v_add_f32_e32 v23, 0, v30
	v_exp_f32_e32 v29, v27
	v_add_f32_e32 v23, v31, v23
	v_exp_f32_e32 v32, v55
	v_add_f32_e32 v23, v44, v23
	v_exp_f32_e32 v33, v141
	v_add_f32_e32 v23, v45, v23
	v_exp_f32_e32 v20, v22
	v_add_f32_e32 v23, v28, v23
	v_add_f32_e32 v23, v29, v23
	v_exp_f32_e32 v26, v24
	v_add_f32_e32 v23, v32, v23
	v_exp_f32_e32 v27, v25
	v_add_f32_e32 v23, v33, v23
	v_exp_f32_e32 v18, v18
	v_add_f32_e32 v23, v20, v23
	v_exp_f32_e32 v19, v19
	v_add_f32_e32 v23, v21, v23
	v_exp_f32_e32 v22, v151
	v_add_f32_e32 v23, v26, v23
	v_add_f32_e32 v24, v27, v23
	v_exp_f32_e32 v23, v39
	v_add_f32_e32 v24, v18, v24
	v_add_f32_e32 v24, v19, v24
	v_add_f32_e32 v24, v22, v24
	v_add_f32_e32 v24, v23, v24
	ds_bpermute_b32 v25, v0, v24
	v_add_u32_e32 v55, 0xa0, v251
	s_waitcnt lgkmcnt(0)
	v_add_f32_e32 v24, v24, v25
	ds_bpermute_b32 v25, v150, v24
	s_and_saveexec_b64 s[0:1], s[36:37]
	s_cbranch_execz .LBB0_492
	v_lshl_add_u32 v141, v55, 5, s3
	s_waitcnt lgkmcnt(0)
	v_add_f32_e32 v39, v24, v25
	ds_write_b64 v141, v[38:39]
;     DI void softmax_store(f32x4 (&acc)[2][2][4][2], const Unit& u, int wr, int wc, int fr, int fq, LAS unsigned char* lds) const {
;     ...
;             for (int m = 0; m < 4; ++m) { const int rl = rloc + ai * HALF + m * 16;
;                 const float rs_ = rsqrtf(ss_in[u.pm * BM + rl] * (1.f / DM) + EPS) * scl2;
;                 float mx = -3.0e38f;
; #pragma unroll
;                 for (int bj = 0; bj < 2; ++bj)
; #pragma unroll
;                     for (int n = 0; n < 2; ++n)
; #pragma unroll
;                         for (int j = 0; j < 4; ++j) { const float v = acc[ai][bj][m][n][j] * rs_; acc[ai][bj][m][n][j] = v; mx = fmaxf(mx, v); }
;                 mx = fmaxf(mx, __shfl_xor(mx, 16)); mx = fmaxf(mx, __shfl_xor(mx, 32));
;                 float sm = 0.f;
; #pragma unroll
;                 for (int bj = 0; bj < 2; ++bj)
; #pragma unroll
;                     for (int n = 0; n < 2; ++n)
; #pragma unroll
;                         for (int j = 0; j < 4; ++j) { const float e = __builtin_amdgcn_exp2f(acc[ai][bj][m][n][j] - mx); acc[ai][bj][m][n][j] = e; sm += e; }
;                 sm += __shfl_xor(sm, 16); sm += __shfl_xor(sm, 32);
;                 mloc[ai][m] = mx;
;                 if (fq == 0) { ex[(rl * 4 + wc) * 2] = mx; ex[(rl * 4 + wc) * 2 + 1] = sm; } }
;         __syncthreads();
; #pragma unroll
;         for (int ai = 0; ai < 2; ++ai)
; #pragma unroll
;             for (int m = 0; m < 4; ++m) { const int rl = rloc + ai * HALF + m * 16;
;                 const f32x4 p0 = *(const LAS f32x4*)(ex + rl * 8), p1 = *(const LAS f32x4*)(ex + rl * 8 + 4);
;                 const float M = fmaxf(fmaxf(p0[0], p0[2]), fmaxf(p1[0], p1[2]));
;                 const float tot = p0[1] * __builtin_amdgcn_exp2f(p0[0] - M) + p0[3] * __builtin_amdgcn_exp2f(p0[2] - M) + p1[1] * __builtin_amdgcn_exp2f(p1[0] - M) + p1[3] * __builtin_amdgcn_exp2f(p1[2] - M);
;                 const float f = __builtin_amdgcn_exp2f(mloc[ai][m] - M) / tot;
;                 bf16_t* rowp = O + (size_t)(u.pm * BM + rl) * ldc + u.pn * BM + wc * 32 + 8 * fq;
; #pragma unroll
;                 for (int bj = 0; bj < 2; ++bj) { const f32x4 v0 = acc[ai][bj][m][0] * f, v1 = acc[ai][bj][m][1] * f;
;                     u32x4 w; w.x = cvt_pk_bf16(v0[0], v0[1]); w.y = cvt_pk_bf16(v0[2], v0[3]); w.z = cvt_pk_bf16(v1[0], v1[1]); w.w = cvt_pk_bf16(v1[2], v1[3]);
.LBB0_492:
	s_or_b64 exec, exec, s[0:1]
	global_load_dword v24, v[134:135], off offset:704
	s_waitcnt vmcnt(0) lgkmcnt(0)
	v_fmamk_f32 v24, v24, 0x3a000000, v229
	v_mul_f32_e32 v25, 0x4b800000, v24
	v_cmp_gt_f32_e32 vcc, s33, v24
	s_nop 1
	v_cndmask_b32_e32 v24, v24, v25, vcc
	v_rsq_f32_e32 v24, v24
	s_nop 0
	v_mul_f32_e32 v25, 0x45800000, v24
	v_cndmask_b32_e32 v24, v24, v25, vcc
	v_mul_f32_e32 v25, 0x3d8293ee, v24
	v_mul_f32_e32 v24, v14, v25
	v_mul_f32_e32 v39, v15, v25
	v_mul_f32_e32 v134, v16, v25
	v_mul_f32_e32 v135, v17, v25
	v_max3_f32 v24, v24, s4, v39
	v_mul_f32_e32 v141, v10, v25
	v_mul_f32_e32 v151, v11, v25
	v_max3_f32 v24, v24, v134, v135
	v_mul_f32_e32 v152, v12, v25
	v_mul_f32_e32 v153, v13, v25
	v_max3_f32 v24, v24, v141, v151
	v_mul_f32_e32 v154, v6, v25
	v_mul_f32_e32 v155, v7, v25
	v_max3_f32 v24, v24, v152, v153
	v_mul_f32_e32 v156, v8, v25
	v_mul_f32_e32 v157, v9, v25
	v_max3_f32 v24, v24, v154, v155
	v_mul_f32_e32 v158, v2, v25
	v_mul_f32_e32 v159, v3, v25
	v_max3_f32 v24, v24, v156, v157
	v_mul_f32_e32 v160, v4, v25
	v_mul_f32_e32 v161, v5, v25
	v_max3_f32 v24, v24, v158, v159
	v_max3_f32 v24, v24, v160, v161
	ds_bpermute_b32 v39, v0, v24
	s_waitcnt lgkmcnt(0)
	v_max_f32_e32 v39, v39, v39
	v_max_f32_e32 v24, v24, v39
	ds_bpermute_b32 v39, v150, v24
	s_waitcnt lgkmcnt(0)
	v_max_f32_e32 v39, v39, v39
	v_max_f32_e32 v24, v24, v39
	v_fma_f32 v14, v14, v25, -v24
	v_fma_f32 v15, v15, v25, -v24
	v_fma_f32 v39, v12, v25, -v24
	v_exp_f32_e32 v12, v14
	v_fma_f32 v16, v16, v25, -v24
	v_fma_f32 v134, v13, v25, -v24
	v_exp_f32_e32 v13, v15
	v_fma_f32 v17, v17, v25, -v24
	v_exp_f32_e32 v16, v16
	v_fma_f32 v10, v10, v25, -v24
	v_fma_f32 v7, v7, v25, -v24
	v_exp_f32_e32 v17, v17
	v_fma_f32 v11, v11, v25, -v24
	v_fma_f32 v6, v6, v25, -v24
	v_fma_f32 v8, v8, v25, -v24
	v_fma_f32 v9, v9, v25, -v24
	v_fma_f32 v2, v2, v25, -v24
	v_fma_f32 v3, v3, v25, -v24
	v_fma_f32 v135, v4, v25, -v24
	v_fma_f32 v25, v5, v25, -v24
	v_exp_f32_e32 v10, v10
	v_exp_f32_e32 v5, v7
	v_add_f32_e32 v7, 0, v12
	v_exp_f32_e32 v11, v11
	v_add_f32_e32 v7, v13, v7
	v_exp_f32_e32 v14, v39
	v_add_f32_e32 v7, v16, v7
	v_exp_f32_e32 v15, v134
	v_add_f32_e32 v7, v17, v7
	v_exp_f32_e32 v4, v6
	v_add_f32_e32 v7, v10, v7
	v_add_f32_e32 v7, v11, v7
	v_exp_f32_e32 v8, v8
	v_add_f32_e32 v7, v14, v7
	v_exp_f32_e32 v9, v9
	v_add_f32_e32 v7, v15, v7
	v_exp_f32_e32 v2, v2
	v_add_f32_e32 v7, v4, v7
	v_exp_f32_e32 v3, v3
	v_add_f32_e32 v7, v5, v7
	v_exp_f32_e32 v6, v135
	v_add_f32_e32 v7, v8, v7
	v_add_f32_e32 v39, v9, v7
	v_exp_f32_e32 v7, v25
	v_add_f32_e32 v25, v2, v39
	v_add_f32_e32 v25, v3, v25
	v_add_f32_e32 v25, v6, v25
	v_add_f32_e32 v25, v7, v25
	ds_bpermute_b32 v0, v0, v25
	s_waitcnt lgkmcnt(0)
	v_add_f32_e32 v25, v25, v0
	ds_bpermute_b32 v134, v150, v25
	v_add_u32_e32 v0, 0xb0, v251
	v_lshlrev_b32_e32 v39, 5, v0
	s_and_saveexec_b64 s[0:1], s[36:37]
	s_cbranch_execz .LBB0_494
	v_add_u32_e32 v135, s3, v39
	s_waitcnt lgkmcnt(0)
	v_add_f32_e32 v25, v25, v134
	ds_write_b64 v135, v[24:25]
.LBB0_494:
	s_or_b64 exec, exec, s[0:1]
	v_add_u32_e32 v25, s2, v0
	v_lshl_add_u32 v0, v251, 5, 0
	s_waitcnt lgkmcnt(0)
	s_barrier
	ds_read_b128 v[152:155], v0
	ds_read_b128 v[156:159], v0 offset:16
	v_add_u32_e32 v134, s2, v55
	v_add_u32_e32 v135, s2, v71
	v_add_u32_e32 v141, s2, v137
	v_add_u32_e32 v150, s2, v139
	s_waitcnt lgkmcnt(0)
	v_max_f32_e32 v0, v158, v158
	v_max_f32_e32 v160, v156, v156
	v_max_f32_e32 v0, v160, v0
	v_max3_f32 v0, v152, v154, v0
	v_sub_f32_e32 v152, v152, v0
	v_exp_f32_e32 v160, v152
	v_sub_f32_e32 v152, v154, v0
	v_exp_f32_e32 v161, v152
	v_mov_b32_e32 v154, v153
	v_add_u32_e32 v151, s2, v133
	v_add_u32_e32 v162, s2, v131
	v_pk_mul_f32 v[152:153], v[154:155], v[160:161]
	v_sub_f32_e32 v154, v156, v0
	v_exp_f32_e32 v155, v154
	v_sub_f32_e32 v154, v158, v0
	v_exp_f32_e32 v154, v154
	v_sub_f32_e32 v0, v132, v0
	v_mov_b32_e32 v156, v159
	v_exp_f32_e32 v0, v0
	v_pk_mul_f32 v[154:155], v[156:157], v[154:155]
	v_add_f32_e32 v152, v152, v153
	v_add_f32_e32 v152, v155, v152
	v_add_f32_e32 v152, v154, v152
	v_div_scale_f32 v132, s[2:3], v152, v152, v0
	v_rcp_f32_e32 v153, v132
	s_lshl_b32 s0, s18, 8
	s_ashr_i32 s1, s0, 31
	s_lshl_b64 s[0:1], s[0:1], 1
	v_fma_f32 v154, -v132, v153, 1.0
	v_fmac_f32_e32 v153, v154, v153
	v_div_scale_f32 v154, vcc, v0, v152, v0
	v_mul_f32_e32 v155, v154, v153
	v_fma_f32 v156, -v132, v155, v154
	v_fmac_f32_e32 v155, v156, v153
	v_fma_f32 v132, -v132, v155, v154
	v_div_fmas_f32 v132, v132, v153, v155
	v_div_fixup_f32 v132, v132, v152, v0
	v_mad_i64_i32 v[152:153], s[2:3], s48, v130, 0
	v_lshl_add_u64 v[152:153], v[152:153], 1, s[20:21]
	v_readlane_b32 s2, v255, 50
	v_lshl_add_u64 v[152:153], v[152:153], 0, s[0:1]
	s_lshl_b32 s10, s2, 1
	v_lshl_add_u64 v[152:153], v[152:153], 0, s[10:11]
	v_lshlrev_b32_e32 v0, 1, v250
	v_lshl_add_u64 v[152:153], v[152:153], 0, v[0:1]
	v_pk_mul_f32 v[128:129], v[128:129], v[132:133] op_sel_hi:[1,0]
	v_pk_mul_f32 v[126:127], v[126:127], v[132:133] op_sel_hi:[1,0]
	v_pk_mul_f32 v[154:155], v[124:125], v[132:133] op_sel_hi:[1,0]
	v_pk_mul_f32 v[124:125], v[122:123], v[132:133] op_sel_hi:[1,0]
	v_cvt_pk_bf16_f32 v122, v126, v127
	v_cvt_pk_bf16_f32 v123, v128, v129
	v_pk_mul_f32 v[118:119], v[118:119], v[132:133] op_sel_hi:[1,0]
	v_cvt_pk_bf16_f32 v124, v124, v125
	v_cvt_pk_bf16_f32 v125, v154, v155
	global_store_dwordx4 v[152:153], v[122:125], off
	v_pk_mul_f32 v[120:121], v[120:121], v[132:133] op_sel_hi:[1,0]
	s_nop 0
	v_pk_mul_f32 v[122:123], v[116:117], v[132:133] op_sel_hi:[1,0]
	v_pk_mul_f32 v[116:117], v[114:115], v[132:133] op_sel_hi:[1,0]
	v_cvt_pk_bf16_f32 v114, v118, v119
	v_cvt_pk_bf16_f32 v115, v120, v121
	v_lshl_add_u32 v118, v131, 5, 0
	v_cvt_pk_bf16_f32 v116, v116, v117
	v_cvt_pk_bf16_f32 v117, v122, v123
	global_store_dwordx4 v[152:153], v[114:117], off offset:256
	ds_read_b128 v[114:117], v118
	ds_read_b128 v[118:121], v118 offset:16
	s_waitcnt lgkmcnt(0)
; #define LAS __attribute__((address_space(3)))
; DI unsigned cvt_pk_bf16(float lo, float hi) { unsigned r; asm volatile("v_cvt_pk_bf16_f32 %0, %1, %2" : "=v"(r) : "v"(lo), "v"(hi)); return r; }
;     DI void softmax_store(f32x4 (&acc)[2][2][4][2], const Unit& u, int wr, int wc, int fr, int fq, LAS unsigned char* lds) const {
;     ...
; #pragma unroll
;         for (int ai = 0; ai < 2; ++ai)
; #pragma unroll
;             for (int m = 0; m < 4; ++m) { const int rl = rloc + ai * HALF + m * 16;
;                 const f32x4 p0 = *(const LAS f32x4*)(ex + rl * 8), p1 = *(const LAS f32x4*)(ex + rl * 8 + 4);
;                 const float M = fmaxf(fmaxf(p0[0], p0[2]), fmaxf(p1[0], p1[2]));
;                 const float tot = p0[1] * __builtin_amdgcn_exp2f(p0[0] - M) + p0[3] * __builtin_amdgcn_exp2f(p0[2] - M) + p1[1] * __builtin_amdgcn_exp2f(p1[0] - M) + p1[3] * __builtin_amdgcn_exp2f(p1[2] - M);
;                 const float f = __builtin_amdgcn_exp2f(mloc[ai][m] - M) / tot;
;                 bf16_t* rowp = O + (size_t)(u.pm * BM + rl) * ldc + u.pn * BM + wc * 32 + 8 * fq;
; #pragma unroll
;                 for (int bj = 0; bj < 2; ++bj) { const f32x4 v0 = acc[ai][bj][m][0] * f, v1 = acc[ai][bj][m][1] * f;
;                     u32x4 w; w.x = cvt_pk_bf16(v0[0], v0[1]); w.y = cvt_pk_bf16(v0[2], v0[3]); w.z = cvt_pk_bf16(v1[0], v1[1]); w.w = cvt_pk_bf16(v1[2], v1[3]);
;                     *(u32x4*)(rowp + bj * HALF) = w; } }
	v_max_f32_e32 v122, v120, v120
	v_max_f32_e32 v123, v118, v118
	v_max_f32_e32 v122, v123, v122
	v_max3_f32 v124, v114, v116, v122
	v_sub_f32_e32 v114, v114, v124
	v_exp_f32_e32 v122, v114
	v_sub_f32_e32 v114, v116, v124
	v_exp_f32_e32 v123, v114
	v_mov_b32_e32 v116, v115
	v_pk_mul_f32 v[114:115], v[116:117], v[122:123]
	v_sub_f32_e32 v116, v118, v124
	v_exp_f32_e32 v117, v116
	v_sub_f32_e32 v116, v120, v124
	v_exp_f32_e32 v116, v116
	v_add_f32_e32 v114, v114, v115
	v_sub_f32_e32 v115, v136, v124
	v_mov_b32_e32 v118, v121
	v_exp_f32_e32 v115, v115
	v_pk_mul_f32 v[116:117], v[118:119], v[116:117]
	s_nop 0
	v_add_f32_e32 v114, v117, v114
	v_add_f32_e32 v114, v116, v114
	v_div_scale_f32 v116, s[2:3], v114, v114, v115
	v_rcp_f32_e32 v117, v116
	s_nop 0
	v_fma_f32 v118, -v116, v117, 1.0
	v_fmac_f32_e32 v117, v118, v117
	v_div_scale_f32 v118, vcc, v115, v114, v115
	v_mul_f32_e32 v119, v118, v117
	v_fma_f32 v120, -v116, v119, v118
	v_fmac_f32_e32 v119, v120, v117
	v_fma_f32 v116, -v116, v119, v118
	v_div_fmas_f32 v116, v116, v117, v119
	v_div_fixup_f32 v114, v116, v114, v115
	v_mad_i64_i32 v[116:117], s[2:3], s48, v162, 0
	v_lshl_add_u64 v[116:117], v[116:117], 1, s[20:21]
	v_lshl_add_u64 v[116:117], v[116:117], 0, s[0:1]
	v_lshl_add_u64 v[116:117], v[116:117], 0, s[10:11]
	v_lshl_add_u64 v[116:117], v[116:117], 0, v[0:1]
	v_pk_mul_f32 v[112:113], v[112:113], v[114:115] op_sel_hi:[1,0]
	v_pk_mul_f32 v[110:111], v[110:111], v[114:115] op_sel_hi:[1,0]
	v_pk_mul_f32 v[118:119], v[108:109], v[114:115] op_sel_hi:[1,0]
	v_pk_mul_f32 v[108:109], v[106:107], v[114:115] op_sel_hi:[1,0]
	v_cvt_pk_bf16_f32 v106, v110, v111
	v_cvt_pk_bf16_f32 v107, v112, v113
	v_pk_mul_f32 v[102:103], v[102:103], v[114:115] op_sel_hi:[1,0]
	v_cvt_pk_bf16_f32 v108, v108, v109
	v_cvt_pk_bf16_f32 v109, v118, v119
	global_store_dwordx4 v[116:117], v[106:109], off
	v_pk_mul_f32 v[104:105], v[104:105], v[114:115] op_sel_hi:[1,0]
	s_nop 0
	v_pk_mul_f32 v[106:107], v[100:101], v[114:115] op_sel_hi:[1,0]
	v_pk_mul_f32 v[100:101], v[98:99], v[114:115] op_sel_hi:[1,0]
	v_cvt_pk_bf16_f32 v98, v102, v103
	v_cvt_pk_bf16_f32 v99, v104, v105
	v_lshl_add_u32 v102, v133, 5, 0
	v_cvt_pk_bf16_f32 v100, v100, v101
	v_cvt_pk_bf16_f32 v101, v106, v107
	global_store_dwordx4 v[116:117], v[98:101], off offset:256
	ds_read_b128 v[98:101], v102
	ds_read_b128 v[102:105], v102 offset:16
	s_waitcnt lgkmcnt(0)
	v_max_f32_e32 v106, v104, v104
	v_max_f32_e32 v107, v102, v102
	v_max_f32_e32 v106, v107, v106
	v_max3_f32 v108, v98, v100, v106
	v_sub_f32_e32 v98, v98, v108
	v_exp_f32_e32 v106, v98
	v_sub_f32_e32 v98, v100, v108
	v_exp_f32_e32 v107, v98
	v_mov_b32_e32 v100, v99
	v_pk_mul_f32 v[98:99], v[100:101], v[106:107]
	v_sub_f32_e32 v100, v102, v108
	v_exp_f32_e32 v101, v100
	v_sub_f32_e32 v100, v104, v108
	v_exp_f32_e32 v100, v100
	v_add_f32_e32 v98, v98, v99
	v_sub_f32_e32 v99, v138, v108
	v_mov_b32_e32 v102, v105
	v_exp_f32_e32 v99, v99
	v_pk_mul_f32 v[100:101], v[102:103], v[100:101]
	s_nop 0
	v_add_f32_e32 v98, v101, v98
	v_add_f32_e32 v98, v100, v98
	v_div_scale_f32 v100, s[2:3], v98, v98, v99
	v_rcp_f32_e32 v101, v100
	s_nop 0
	v_fma_f32 v102, -v100, v101, 1.0
	v_fmac_f32_e32 v101, v102, v101
	v_div_scale_f32 v102, vcc, v99, v98, v99
	v_mul_f32_e32 v103, v102, v101
	v_fma_f32 v104, -v100, v103, v102
	v_fmac_f32_e32 v103, v104, v101
	v_fma_f32 v100, -v100, v103, v102
	v_div_fmas_f32 v100, v100, v101, v103
	v_div_fixup_f32 v98, v100, v98, v99
	v_mad_i64_i32 v[100:101], s[2:3], s48, v151, 0
	v_lshl_add_u64 v[100:101], v[100:101], 1, s[20:21]
	v_lshl_add_u64 v[100:101], v[100:101], 0, s[0:1]
	v_lshl_add_u64 v[100:101], v[100:101], 0, s[10:11]
	v_lshl_add_u64 v[100:101], v[100:101], 0, v[0:1]
	v_pk_mul_f32 v[96:97], v[96:97], v[98:99] op_sel_hi:[1,0]
	v_pk_mul_f32 v[94:95], v[94:95], v[98:99] op_sel_hi:[1,0]
	v_pk_mul_f32 v[102:103], v[92:93], v[98:99] op_sel_hi:[1,0]
	v_pk_mul_f32 v[92:93], v[90:91], v[98:99] op_sel_hi:[1,0]
	v_cvt_pk_bf16_f32 v90, v94, v95
	v_cvt_pk_bf16_f32 v91, v96, v97
	v_pk_mul_f32 v[86:87], v[86:87], v[98:99] op_sel_hi:[1,0]
	v_cvt_pk_bf16_f32 v92, v92, v93
	v_cvt_pk_bf16_f32 v93, v102, v103
	global_store_dwordx4 v[100:101], v[90:93], off
	v_pk_mul_f32 v[88:89], v[88:89], v[98:99] op_sel_hi:[1,0]
	s_nop 0
	v_pk_mul_f32 v[90:91], v[84:85], v[98:99] op_sel_hi:[1,0]
	v_pk_mul_f32 v[84:85], v[82:83], v[98:99] op_sel_hi:[1,0]
	v_cvt_pk_bf16_f32 v82, v86, v87
	v_cvt_pk_bf16_f32 v83, v88, v89
	v_lshl_add_u32 v86, v139, 5, 0
	v_cvt_pk_bf16_f32 v84, v84, v85
	v_cvt_pk_bf16_f32 v85, v90, v91
	global_store_dwordx4 v[100:101], v[82:85], off offset:256
	ds_read_b128 v[82:85], v86
	ds_read_b128 v[86:89], v86 offset:16
	s_waitcnt lgkmcnt(0)
; #define LAS __attribute__((address_space(3)))
; DI unsigned cvt_pk_bf16(float lo, float hi) { unsigned r; asm volatile("v_cvt_pk_bf16_f32 %0, %1, %2" : "=v"(r) : "v"(lo), "v"(hi)); return r; }
;     DI void softmax_store(f32x4 (&acc)[2][2][4][2], const Unit& u, int wr, int wc, int fr, int fq, LAS unsigned char* lds) const {
;     ...
; #pragma unroll
;         for (int ai = 0; ai < 2; ++ai)
; #pragma unroll
;             for (int m = 0; m < 4; ++m) { const int rl = rloc + ai * HALF + m * 16;
;                 const f32x4 p0 = *(const LAS f32x4*)(ex + rl * 8), p1 = *(const LAS f32x4*)(ex + rl * 8 + 4);
;                 const float M = fmaxf(fmaxf(p0[0], p0[2]), fmaxf(p1[0], p1[2]));
;                 const float tot = p0[1] * __builtin_amdgcn_exp2f(p0[0] - M) + p0[3] * __builtin_amdgcn_exp2f(p0[2] - M) + p1[1] * __builtin_amdgcn_exp2f(p1[0] - M) + p1[3] * __builtin_amdgcn_exp2f(p1[2] - M);
;                 const float f = __builtin_amdgcn_exp2f(mloc[ai][m] - M) / tot;
;                 bf16_t* rowp = O + (size_t)(u.pm * BM + rl) * ldc + u.pn * BM + wc * 32 + 8 * fq;
; #pragma unroll
;                 for (int bj = 0; bj < 2; ++bj) { const f32x4 v0 = acc[ai][bj][m][0] * f, v1 = acc[ai][bj][m][1] * f;
;                     u32x4 w; w.x = cvt_pk_bf16(v0[0], v0[1]); w.y = cvt_pk_bf16(v0[2], v0[3]); w.z = cvt_pk_bf16(v1[0], v1[1]); w.w = cvt_pk_bf16(v1[2], v1[3]);
;                     *(u32x4*)(rowp + bj * HALF) = w; } }
	v_max_f32_e32 v90, v88, v88
	v_max_f32_e32 v91, v86, v86
	v_max_f32_e32 v90, v91, v90
	v_max3_f32 v92, v82, v84, v90
	v_sub_f32_e32 v82, v82, v92
	v_exp_f32_e32 v90, v82
	v_sub_f32_e32 v82, v84, v92
	v_exp_f32_e32 v91, v82
	v_mov_b32_e32 v84, v83
	v_pk_mul_f32 v[82:83], v[84:85], v[90:91]
	v_sub_f32_e32 v84, v86, v92
	v_exp_f32_e32 v85, v84
	v_sub_f32_e32 v84, v88, v92
	v_exp_f32_e32 v84, v84
	v_add_f32_e32 v82, v82, v83
	v_sub_f32_e32 v83, v140, v92
	v_mov_b32_e32 v86, v89
	v_exp_f32_e32 v83, v83
	v_pk_mul_f32 v[84:85], v[86:87], v[84:85]
	s_nop 0
	v_add_f32_e32 v82, v85, v82
	v_add_f32_e32 v82, v84, v82
	v_div_scale_f32 v84, s[2:3], v82, v82, v83
	v_rcp_f32_e32 v85, v84
	s_nop 0
	v_fma_f32 v86, -v84, v85, 1.0
	v_fmac_f32_e32 v85, v86, v85
	v_div_scale_f32 v86, vcc, v83, v82, v83
	v_mul_f32_e32 v87, v86, v85
	v_fma_f32 v88, -v84, v87, v86
	v_fmac_f32_e32 v87, v88, v85
	v_fma_f32 v84, -v84, v87, v86
	v_div_fmas_f32 v84, v84, v85, v87
	v_div_fixup_f32 v86, v84, v82, v83
	v_mad_i64_i32 v[82:83], s[2:3], s48, v150, 0
	v_lshl_add_u64 v[82:83], v[82:83], 1, s[20:21]
	v_lshl_add_u64 v[82:83], v[82:83], 0, s[0:1]
	v_lshl_add_u64 v[82:83], v[82:83], 0, s[10:11]
	v_lshl_add_u64 v[88:89], v[82:83], 0, v[0:1]
	v_pk_mul_f32 v[82:83], v[144:145], v[86:87] op_sel_hi:[1,0]
	v_pk_mul_f32 v[84:85], v[148:149], v[86:87] op_sel_hi:[1,0]
	v_cvt_pk_bf16_f32 v82, v82, v83
	v_pk_mul_f32 v[68:69], v[68:69], v[86:87] op_sel_hi:[1,0]
	v_cvt_pk_bf16_f32 v83, v84, v85
	v_pk_mul_f32 v[72:73], v[72:73], v[86:87] op_sel_hi:[1,0]
	v_pk_mul_f32 v[90:91], v[146:147], v[86:87] op_sel_hi:[1,0]
	v_pk_mul_f32 v[92:93], v[142:143], v[86:87] op_sel_hi:[1,0]
	v_pk_mul_f32 v[74:75], v[74:75], v[86:87] op_sel_hi:[1,0]
	v_cvt_pk_bf16_f32 v84, v92, v93
	v_cvt_pk_bf16_f32 v85, v90, v91
	global_store_dwordx4 v[88:89], v[82:85], off
	s_nop 1
	v_pk_mul_f32 v[82:83], v[66:67], v[86:87] op_sel_hi:[1,0]
	v_cvt_pk_bf16_f32 v66, v68, v69
	v_cvt_pk_bf16_f32 v67, v74, v75
	s_nop 0
	v_cvt_pk_bf16_f32 v68, v82, v83
	v_cvt_pk_bf16_f32 v69, v72, v73
	global_store_dwordx4 v[88:89], v[66:69], off offset:256
	v_lshl_add_u32 v72, v137, 5, 0
	ds_read_b128 v[66:69], v72
	ds_read_b128 v[72:75], v72 offset:16
	s_waitcnt lgkmcnt(0)
	v_max_f32_e32 v82, v74, v74
	v_max_f32_e32 v83, v72, v72
	v_max_f32_e32 v82, v83, v82
	v_max3_f32 v84, v66, v68, v82
	v_sub_f32_e32 v66, v66, v84
	v_exp_f32_e32 v82, v66
	v_sub_f32_e32 v66, v68, v84
	v_exp_f32_e32 v83, v66
	v_mov_b32_e32 v68, v67
	v_pk_mul_f32 v[66:67], v[68:69], v[82:83]
	v_sub_f32_e32 v68, v72, v84
	v_exp_f32_e32 v69, v68
	v_sub_f32_e32 v68, v74, v84
	v_exp_f32_e32 v68, v68
	v_add_f32_e32 v66, v66, v67
	v_sub_f32_e32 v67, v70, v84
	v_mov_b32_e32 v72, v75
	v_exp_f32_e32 v67, v67
	v_pk_mul_f32 v[68:69], v[72:73], v[68:69]
	s_nop 0
	v_add_f32_e32 v66, v69, v66
	v_add_f32_e32 v66, v68, v66
	v_div_scale_f32 v68, s[2:3], v66, v66, v67
	v_rcp_f32_e32 v69, v68
	s_nop 0
	v_fma_f32 v70, -v68, v69, 1.0
	v_fmac_f32_e32 v69, v70, v69
	v_div_scale_f32 v70, vcc, v67, v66, v67
	v_mul_f32_e32 v72, v70, v69
	v_fma_f32 v73, -v68, v72, v70
	v_fmac_f32_e32 v72, v73, v69
	v_fma_f32 v68, -v68, v72, v70
	v_div_fmas_f32 v68, v68, v69, v72
	v_div_fixup_f32 v68, v68, v66, v67
	v_mad_i64_i32 v[66:67], s[2:3], s48, v141, 0
	v_lshl_add_u64 v[66:67], v[66:67], 1, s[20:21]
	v_lshl_add_u64 v[66:67], v[66:67], 0, s[0:1]
	v_lshl_add_u64 v[66:67], v[66:67], 0, s[10:11]
	v_lshl_add_u64 v[72:73], v[66:67], 0, v[0:1]
	v_pk_mul_f32 v[66:67], v[80:81], v[68:69] op_sel_hi:[1,0]
	v_pk_mul_f32 v[74:75], v[76:77], v[68:69] op_sel_hi:[1,0]
	v_pk_mul_f32 v[76:77], v[78:79], v[68:69] op_sel_hi:[1,0]
	v_pk_mul_f32 v[78:79], v[64:65], v[68:69] op_sel_hi:[1,0]
	v_cvt_pk_bf16_f32 v64, v74, v75
	v_cvt_pk_bf16_f32 v65, v66, v67
	v_pk_mul_f32 v[52:53], v[52:53], v[68:69] op_sel_hi:[1,0]
	v_pk_mul_f32 v[56:57], v[56:57], v[68:69] op_sel_hi:[1,0]
	v_cvt_pk_bf16_f32 v66, v78, v79
	v_cvt_pk_bf16_f32 v67, v76, v77
	global_store_dwordx4 v[72:73], v[64:67], off
	v_pk_mul_f32 v[58:59], v[58:59], v[68:69] op_sel_hi:[1,0]
	s_nop 0
	v_pk_mul_f32 v[64:65], v[50:51], v[68:69] op_sel_hi:[1,0]
	v_cvt_pk_bf16_f32 v50, v52, v53
	v_cvt_pk_bf16_f32 v51, v58, v59
	s_nop 0
	v_cvt_pk_bf16_f32 v52, v64, v65
	v_cvt_pk_bf16_f32 v53, v56, v57
	global_store_dwordx4 v[72:73], v[50:53], off offset:256
	v_lshl_add_u32 v56, v71, 5, 0
	ds_read_b128 v[50:53], v56
	ds_read_b128 v[56:59], v56 offset:16
	s_waitcnt lgkmcnt(0)
; #define LAS __attribute__((address_space(3)))
; DI unsigned cvt_pk_bf16(float lo, float hi) { unsigned r; asm volatile("v_cvt_pk_bf16_f32 %0, %1, %2" : "=v"(r) : "v"(lo), "v"(hi)); return r; }
;     DI void softmax_store(f32x4 (&acc)[2][2][4][2], const Unit& u, int wr, int wc, int fr, int fq, LAS unsigned char* lds) const {
;     ...
; #pragma unroll
;         for (int ai = 0; ai < 2; ++ai)
; #pragma unroll
;             for (int m = 0; m < 4; ++m) { const int rl = rloc + ai * HALF + m * 16;
;                 const f32x4 p0 = *(const LAS f32x4*)(ex + rl * 8), p1 = *(const LAS f32x4*)(ex + rl * 8 + 4);
;                 const float M = fmaxf(fmaxf(p0[0], p0[2]), fmaxf(p1[0], p1[2]));
;                 const float tot = p0[1] * __builtin_amdgcn_exp2f(p0[0] - M) + p0[3] * __builtin_amdgcn_exp2f(p0[2] - M) + p1[1] * __builtin_amdgcn_exp2f(p1[0] - M) + p1[3] * __builtin_amdgcn_exp2f(p1[2] - M);
;                 const float f = __builtin_amdgcn_exp2f(mloc[ai][m] - M) / tot;
;                 bf16_t* rowp = O + (size_t)(u.pm * BM + rl) * ldc + u.pn * BM + wc * 32 + 8 * fq;
; #pragma unroll
;                 for (int bj = 0; bj < 2; ++bj) { const f32x4 v0 = acc[ai][bj][m][0] * f, v1 = acc[ai][bj][m][1] * f;
;                     u32x4 w; w.x = cvt_pk_bf16(v0[0], v0[1]); w.y = cvt_pk_bf16(v0[2], v0[3]); w.z = cvt_pk_bf16(v1[0], v1[1]); w.w = cvt_pk_bf16(v1[2], v1[3]);
;                     *(u32x4*)(rowp + bj * HALF) = w; } }
	v_max_f32_e32 v64, v58, v58
	v_max_f32_e32 v65, v56, v56
	v_max_f32_e32 v64, v65, v64
	v_max3_f32 v66, v50, v52, v64
	v_sub_f32_e32 v50, v50, v66
	v_exp_f32_e32 v64, v50
	v_sub_f32_e32 v50, v52, v66
	v_exp_f32_e32 v65, v50
	v_mov_b32_e32 v52, v51
	v_pk_mul_f32 v[50:51], v[52:53], v[64:65]
	v_sub_f32_e32 v52, v56, v66
	v_exp_f32_e32 v53, v52
	v_sub_f32_e32 v52, v58, v66
	v_exp_f32_e32 v52, v52
	v_add_f32_e32 v50, v50, v51
	v_sub_f32_e32 v51, v54, v66
	v_mov_b32_e32 v56, v59
	v_exp_f32_e32 v51, v51
	v_pk_mul_f32 v[52:53], v[56:57], v[52:53]
	s_nop 0
	v_add_f32_e32 v50, v53, v50
	v_add_f32_e32 v50, v52, v50
	v_div_scale_f32 v52, s[2:3], v50, v50, v51
	v_rcp_f32_e32 v53, v52
	s_nop 0
	v_fma_f32 v54, -v52, v53, 1.0
	v_fmac_f32_e32 v53, v54, v53
	v_div_scale_f32 v54, vcc, v51, v50, v51
	v_mul_f32_e32 v56, v54, v53
	v_fma_f32 v57, -v52, v56, v54
	v_fmac_f32_e32 v56, v57, v53
	v_fma_f32 v52, -v52, v56, v54
	v_div_fmas_f32 v52, v52, v53, v56
	v_div_fixup_f32 v50, v52, v50, v51
	v_mad_i64_i32 v[52:53], s[2:3], s48, v135, 0
	v_lshl_add_u64 v[52:53], v[52:53], 1, s[20:21]
	v_lshl_add_u64 v[52:53], v[52:53], 0, s[0:1]
	v_lshl_add_u64 v[52:53], v[52:53], 0, s[10:11]
	v_lshl_add_u64 v[52:53], v[52:53], 0, v[0:1]
	v_pk_mul_f32 v[56:57], v[62:63], v[50:51] op_sel_hi:[1,0]
	v_pk_mul_f32 v[48:49], v[48:49], v[50:51] op_sel_hi:[1,0]
	v_pk_mul_f32 v[58:59], v[60:61], v[50:51] op_sel_hi:[1,0]
	v_pk_mul_f32 v[60:61], v[46:47], v[50:51] op_sel_hi:[1,0]
	v_cvt_pk_bf16_f32 v46, v48, v49
	v_cvt_pk_bf16_f32 v47, v56, v57
	v_pk_mul_f32 v[36:37], v[36:37], v[50:51] op_sel_hi:[1,0]
	v_pk_mul_f32 v[40:41], v[40:41], v[50:51] op_sel_hi:[1,0]
	v_cvt_pk_bf16_f32 v48, v60, v61
	v_cvt_pk_bf16_f32 v49, v58, v59
	global_store_dwordx4 v[52:53], v[46:49], off
	v_pk_mul_f32 v[42:43], v[42:43], v[50:51] op_sel_hi:[1,0]
	s_nop 0
	v_pk_mul_f32 v[46:47], v[34:35], v[50:51] op_sel_hi:[1,0]
	v_cvt_pk_bf16_f32 v34, v36, v37
	v_cvt_pk_bf16_f32 v35, v42, v43
	s_nop 0
	v_cvt_pk_bf16_f32 v36, v46, v47
	v_cvt_pk_bf16_f32 v37, v40, v41
	global_store_dwordx4 v[52:53], v[34:37], off offset:256
	v_lshl_add_u32 v40, v55, 5, 0
	ds_read_b128 v[34:37], v40
	ds_read_b128 v[40:43], v40 offset:16
	s_waitcnt lgkmcnt(0)
	v_max_f32_e32 v46, v42, v42
	v_max_f32_e32 v47, v40, v40
	v_max_f32_e32 v46, v47, v46
	v_max3_f32 v48, v34, v36, v46
	v_sub_f32_e32 v34, v34, v48
	v_exp_f32_e32 v46, v34
	v_sub_f32_e32 v34, v36, v48
	v_exp_f32_e32 v47, v34
	v_mov_b32_e32 v36, v35
	v_pk_mul_f32 v[34:35], v[36:37], v[46:47]
	v_sub_f32_e32 v36, v40, v48
	v_exp_f32_e32 v37, v36
	v_sub_f32_e32 v36, v42, v48
	v_exp_f32_e32 v36, v36
	v_add_f32_e32 v34, v34, v35
	v_sub_f32_e32 v35, v38, v48
	v_mov_b32_e32 v40, v43
	v_exp_f32_e32 v35, v35
	v_pk_mul_f32 v[36:37], v[40:41], v[36:37]
	s_nop 0
	v_add_f32_e32 v34, v37, v34
	v_add_f32_e32 v34, v36, v34
	v_div_scale_f32 v36, s[2:3], v34, v34, v35
	v_rcp_f32_e32 v37, v36
	s_nop 0
	v_fma_f32 v38, -v36, v37, 1.0
	v_fmac_f32_e32 v37, v38, v37
	v_div_scale_f32 v38, vcc, v35, v34, v35
	v_mul_f32_e32 v40, v38, v37
	v_fma_f32 v41, -v36, v40, v38
	v_fmac_f32_e32 v40, v41, v37
	v_fma_f32 v36, -v36, v40, v38
	v_div_fmas_f32 v36, v36, v37, v40
	v_div_fixup_f32 v34, v36, v34, v35
	v_mad_i64_i32 v[36:37], s[2:3], s48, v134, 0
	v_lshl_add_u64 v[36:37], v[36:37], 1, s[20:21]
	v_lshl_add_u64 v[36:37], v[36:37], 0, s[0:1]
	v_lshl_add_u64 v[36:37], v[36:37], 0, s[10:11]
	v_lshl_add_u64 v[36:37], v[36:37], 0, v[0:1]
	v_pk_mul_f32 v[40:41], v[44:45], v[34:35] op_sel_hi:[1,0]
	v_pk_mul_f32 v[30:31], v[30:31], v[34:35] op_sel_hi:[1,0]
	v_pk_mul_f32 v[42:43], v[28:29], v[34:35] op_sel_hi:[1,0]
	v_cvt_pk_bf16_f32 v28, v30, v31
	v_cvt_pk_bf16_f32 v29, v40, v41
	v_pk_mul_f32 v[20:21], v[20:21], v[34:35] op_sel_hi:[1,0]
	v_pk_mul_f32 v[22:23], v[22:23], v[34:35] op_sel_hi:[1,0]
	v_pk_mul_f32 v[32:33], v[32:33], v[34:35] op_sel_hi:[1,0]
	v_cvt_pk_bf16_f32 v30, v42, v43
	v_pk_mul_f32 v[26:27], v[26:27], v[34:35] op_sel_hi:[1,0]
	v_cvt_pk_bf16_f32 v31, v32, v33
	global_store_dwordx4 v[36:37], v[28:31], off
	s_nop 1
	v_pk_mul_f32 v[28:29], v[18:19], v[34:35] op_sel_hi:[1,0]
	v_cvt_pk_bf16_f32 v18, v20, v21
	v_cvt_pk_bf16_f32 v19, v26, v27
	s_nop 0
	v_cvt_pk_bf16_f32 v20, v28, v29
	v_cvt_pk_bf16_f32 v21, v22, v23
	global_store_dwordx4 v[36:37], v[18:21], off offset:256
	v_add_u32_e32 v22, 0, v39
	ds_read_b128 v[18:21], v22
	ds_read_b128 v[26:29], v22 offset:16
	s_waitcnt lgkmcnt(0)
	v_max_f32_e32 v22, v28, v28
	v_max_f32_e32 v23, v26, v26
	v_max_f32_e32 v22, v23, v22
	v_max3_f32 v30, v18, v20, v22
	v_sub_f32_e32 v18, v18, v30
	v_exp_f32_e32 v22, v18
	v_sub_f32_e32 v18, v20, v30
	v_exp_f32_e32 v23, v18
	v_mov_b32_e32 v20, v19
	v_pk_mul_f32 v[18:19], v[20:21], v[22:23]
	v_sub_f32_e32 v20, v26, v30
	v_exp_f32_e32 v21, v20
	v_sub_f32_e32 v20, v28, v30
	v_exp_f32_e32 v20, v20
	v_add_f32_e32 v18, v18, v19
	v_sub_f32_e32 v19, v24, v30
	v_mov_b32_e32 v26, v29
	v_exp_f32_e32 v19, v19
	v_pk_mul_f32 v[20:21], v[26:27], v[20:21]
	s_nop 0
	v_add_f32_e32 v18, v21, v18
	v_add_f32_e32 v18, v20, v18
	v_div_scale_f32 v20, s[2:3], v18, v18, v19
	v_rcp_f32_e32 v21, v20
	s_nop 0
	v_fma_f32 v22, -v20, v21, 1.0
	v_fmac_f32_e32 v21, v22, v21
	v_div_scale_f32 v22, vcc, v19, v18, v19
	v_mul_f32_e32 v23, v22, v21
	v_fma_f32 v24, -v20, v23, v22
	v_fmac_f32_e32 v23, v24, v21
	v_fma_f32 v20, -v20, v23, v22
	v_div_fmas_f32 v20, v20, v21, v23
	v_div_fixup_f32 v18, v20, v18, v19
	v_mad_i64_i32 v[20:21], s[2:3], s48, v25, 0
	v_lshl_add_u64 v[20:21], v[20:21], 1, s[20:21]
	v_lshl_add_u64 v[20:21], v[20:21], 0, s[0:1]
	v_lshl_add_u64 v[20:21], v[20:21], 0, s[10:11]
	v_lshl_add_u64 v[20:21], v[20:21], 0, v[0:1]
	v_pk_mul_f32 v[16:17], v[16:17], v[18:19] op_sel_hi:[1,0]
	v_pk_mul_f32 v[12:13], v[12:13], v[18:19] op_sel_hi:[1,0]
	v_pk_mul_f32 v[22:23], v[10:11], v[18:19] op_sel_hi:[1,0]
	v_cvt_pk_bf16_f32 v10, v12, v13
	v_cvt_pk_bf16_f32 v11, v16, v17
	v_pk_mul_f32 v[4:5], v[4:5], v[18:19] op_sel_hi:[1,0]
	v_pk_mul_f32 v[14:15], v[14:15], v[18:19] op_sel_hi:[1,0]
	v_cvt_pk_bf16_f32 v12, v22, v23
	v_pk_mul_f32 v[8:9], v[8:9], v[18:19] op_sel_hi:[1,0]
	v_cvt_pk_bf16_f32 v13, v14, v15
	global_store_dwordx4 v[20:21], v[10:13], off
	v_pk_mul_f32 v[6:7], v[6:7], v[18:19] op_sel_hi:[1,0]
	s_nop 0
	v_pk_mul_f32 v[10:11], v[2:3], v[18:19] op_sel_hi:[1,0]
	v_cvt_pk_bf16_f32 v2, v4, v5
	v_cvt_pk_bf16_f32 v3, v8, v9
	s_nop 0
	v_cvt_pk_bf16_f32 v4, v10, v11
	v_cvt_pk_bf16_f32 v5, v6, v7
	global_store_dwordx4 v[20:21], v[2:5], off offset:256

; __global__ void __launch_bounds__(NTH, 2) fwd_megakernel(Params P0) {
;     extern __shared__ __attribute__((aligned(16))) unsigned char lds_raw[];
	.amdhsa_kernel _Z14fwd_megakernel6Params
		.amdhsa_group_segment_fixed_size 4096
		.amdhsa_private_segment_fixed_size 0
		.amdhsa_kernarg_size 416
		.amdhsa_user_sgpr_count 2
		.amdhsa_user_sgpr_dispatch_ptr 0
		.amdhsa_user_sgpr_queue_ptr 0
		.amdhsa_user_sgpr_kernarg_segment_ptr 1
		.amdhsa_user_sgpr_dispatch_id 0
		.amdhsa_user_sgpr_kernarg_preload_length 0
		.amdhsa_user_sgpr_kernarg_preload_offset 0
		.amdhsa_user_sgpr_private_segment_size 0
		.amdhsa_uses_dynamic_stack 0
		.amdhsa_enable_private_segment 0
		.amdhsa_system_sgpr_workgroup_id_x 1
		.amdhsa_system_sgpr_workgroup_id_y 0
		.amdhsa_system_sgpr_workgroup_id_z 0
		.amdhsa_system_sgpr_workgroup_info 0
		.amdhsa_system_vgpr_workitem_id 2
		.amdhsa_next_free_vgpr 256
		.amdhsa_next_free_sgpr 100
		.amdhsa_accum_offset 256
		.amdhsa_reserve_vcc 1
		.amdhsa_float_round_mode_32 0
		.amdhsa_float_round_mode_16_64 0
		.amdhsa_float_denorm_mode_32 3
		.amdhsa_float_denorm_mode_16_64 3
		.amdhsa_dx10_clamp 1
		.amdhsa_ieee_mode 1
		.amdhsa_fp16_overflow 0
		.amdhsa_tg_split 0
		.amdhsa_exception_fp_ieee_invalid_op 0
		.amdhsa_exception_fp_denorm_src 0
		.amdhsa_exception_fp_ieee_div_zero 0
		.amdhsa_exception_fp_ieee_overflow 0
		.amdhsa_exception_fp_ieee_underflow 0
		.amdhsa_exception_fp_ieee_inexact 0
		.amdhsa_exception_int_div_zero 0
	.end_amdhsa_kernel

; __global__ void __launch_bounds__(NTH, 2) fwd_megakernel(Params P0) {
;     extern __shared__ __attribute__((aligned(16))) unsigned char lds_raw[];
amdhsa.kernels:
  - .agpr_count:     0
    .args:
      - .offset:         0
        .size:           160
        .value_kind:     by_value
      - .offset:         160
        .size:           4
        .value_kind:     hidden_block_count_x
      - .offset:         164
        .size:           4
        .value_kind:     hidden_block_count_y
      - .offset:         168
        .size:           4
        .value_kind:     hidden_block_count_z
      - .offset:         172
        .size:           2
        .value_kind:     hidden_group_size_x
      - .offset:         174
        .size:           2
        .value_kind:     hidden_group_size_y
      - .offset:         176
        .size:           2
        .value_kind:     hidden_group_size_z
      - .offset:         178
        .size:           2
        .value_kind:     hidden_remainder_x
      - .offset:         180
        .size:           2
        .value_kind:     hidden_remainder_y
      - .offset:         182
        .size:           2
        .value_kind:     hidden_remainder_z
      - .offset:         200
        .size:           8
        .value_kind:     hidden_global_offset_x
      - .offset:         208
        .size:           8
        .value_kind:     hidden_global_offset_y
      - .offset:         216
        .size:           8
        .value_kind:     hidden_global_offset_z
      - .offset:         224
        .size:           2
        .value_kind:     hidden_grid_dims
      - .offset:         248
        .size:           8
        .value_kind:     hidden_multigrid_sync_arg
      - .offset:         280
        .size:           4
        .value_kind:     hidden_dynamic_lds_size
    .group_segment_fixed_size: 4096
    .kernarg_segment_align: 8
    .kernarg_segment_size: 416
    .language:       OpenCL C
    .language_version:
      - 2
      - 0
    .max_flat_workgroup_size: 512
    .name:           _Z14fwd_megakernel6Params
    .private_segment_fixed_size: 0
    .sgpr_count:     106
    .sgpr_spill_count: 206
    .symbol:         _Z14fwd_megakernel6Params.kd
    .uniform_work_group_size: 1
    .uses_dynamic_stack: false
    .vgpr_count:     256
    .vgpr_spill_count: 0
    .wavefront_size: 64
